# K-loops, back-edge/segment-head rotation (strategy 9): s_setprio 1 moved before the barrier and duplicate lgkmcnt(0) dropped so the first instruction after the release is the first MFMA; on top of v40
# speedup vs baseline: 1.0077x; 1.0008x over previous
; #define PG8_STAGE(bufoff, gbase, voff) do { _Pragma("unroll") for (int _i = 0; _i < 2; ++_i) \
;         __builtin_amdgcn_global_load_lds((const unsigned*)((const char*)(gbase) + (voff)[_i]), (PG8_LAS unsigned*)(lds + (bufoff) + ldsw + _i * 8192), 16, 0, 0); } while (0)
; #define PG8_LDA(dst, b, h) do { _Pragma("unroll") for (int m = 0; m < 4; ++m) _Pragma("unroll") for (int k = 0; k < 2; ++k) dst[m][k] = *(const PG8_LAS bf16x8*)(lds + PG8_SA(b, h) + aoff + m * 2048 + k * 1024); } while (0)
; #define PG8_LDB(dst, b, h) do { _Pragma("unroll") for (int n = 0; n < 2; ++n) _Pragma("unroll") for (int k = 0; k < 2; ++k) dst[n][k] = *(const PG8_LAS bf16x8*)(lds + PG8_SB(b, h) + boff + n * 2048 + k * 1024); } while (0)
; #define PG8_SCHED __builtin_amdgcn_sched_barrier(0)
; template <class Epi, class Sched, bool ALIGN_EPI = false, bool SP2 = false>
; __device__ __forceinline__ void gemm_phase(PG8_LAS unsigned char* lds, const Gemm g, const Sched& S, const Epi& E) {
;     ...
;         for (int t = 0; t < nt; t += 2) {
;             const bool last = (t == nt - 2);
;             const char* a1 = cA + (size_t)(t + 1) * kstep;
;             const char* a2 = last ? nA : cA + (size_t)(t + 2) * kstep; const char* b2 = last ? nB : cB + (size_t)(t + 2) * kstep;
;             const char* a3 = a2 + kstep; const char* b3 = b2 + kstep;
;             if (last && has_next) S.a_ready(nxt);
;             if constexpr (SP2) {
;             PG8_LDB(B0, 0, 0); PG8_LDB(B1, 0, 1); PG8_SCHED; PG8_LDA(At, 0, 0); PG8_STAGE(PG8_SA(1, 1), a1 + hstep, voffA);
.LBB0_66:
	ds_read_b128 v[152:155], v149
	ds_read_b128 v[156:159], v149 offset:1024
	ds_read_b128 v[160:163], v149 offset:2048
	ds_read_b128 v[164:167], v149 offset:3072
	ds_read_b128 v[168:171], v150
	ds_read_b128 v[172:175], v150 offset:1024
	ds_read_b128 v[176:179], v150 offset:2048
	ds_read_b128 v[180:183], v150 offset:3072
	s_add_u32 s42, s40, 0xfff80080
	s_addc_u32 s43, s41, -1
	s_cmp_eq_u32 s68, 28
	s_cselect_b32 s45, s35, s43
	s_cselect_b32 s44, s63, s42
	s_cselect_b32 s43, s31, s67
	s_cselect_b32 s42, s64, s65

; #define PG8_STAGE(bufoff, gbase, voff) do { _Pragma("unroll") for (int _i = 0; _i < 2; ++_i) \
;         __builtin_amdgcn_global_load_lds((const unsigned*)((const char*)(gbase) + (voff)[_i]), (PG8_LAS unsigned*)(lds + (bufoff) + ldsw + _i * 8192), 16, 0, 0); } while (0)
; #define PG8_LDA(dst, b, h) do { _Pragma("unroll") for (int m = 0; m < 4; ++m) _Pragma("unroll") for (int k = 0; k < 2; ++k) dst[m][k] = *(const PG8_LAS bf16x8*)(lds + PG8_SA(b, h) + aoff + m * 2048 + k * 1024); } while (0)
; #define PG8_LDB(dst, b, h) do { _Pragma("unroll") for (int n = 0; n < 2; ++n) _Pragma("unroll") for (int k = 0; k < 2; ++k) dst[n][k] = *(const PG8_LAS bf16x8*)(lds + PG8_SB(b, h) + boff + n * 2048 + k * 1024); } while (0)
; #define PG8_SCHED __builtin_amdgcn_sched_barrier(0)
; template <class Epi, class Sched, bool ALIGN_EPI = false, bool SP2 = false>
; __device__ __forceinline__ void gemm_phase(PG8_LAS unsigned char* lds, const Gemm g, const Sched& S, const Epi& E) {
;     ...
;             PG8_LDB(B0, 0, 0); PG8_LDB(B1, 0, 1); PG8_SCHED; PG8_LDA(At, 0, 0); PG8_STAGE(PG8_SA(1, 1), a1 + hstep, voffA);
	s_add_i32 m0, s29, 0xc000
	ds_read_b128 v[184:187], v151
	ds_read_b128 v[188:191], v151 offset:1024
	ds_read_b128 v[192:195], v151 offset:2048
	ds_read_b128 v[196:199], v151 offset:3072
	ds_read_b128 v[200:203], v151 offset:4096
	ds_read_b128 v[204:207], v151 offset:5120
	ds_read_b128 v[208:211], v151 offset:6144
	ds_read_b128 v[212:215], v151 offset:7168
	global_load_lds_dwordx4 v136, s[40:41]

; #define PG8_STAGE(bufoff, gbase, voff) do { _Pragma("unroll") for (int _i = 0; _i < 2; ++_i) \
;         __builtin_amdgcn_global_load_lds((const unsigned*)((const char*)(gbase) + (voff)[_i]), (PG8_LAS unsigned*)(lds + (bufoff) + ldsw + _i * 8192), 16, 0, 0); } while (0)
; #define PG8_LDA(dst, b, h) do { _Pragma("unroll") for (int m = 0; m < 4; ++m) _Pragma("unroll") for (int k = 0; k < 2; ++k) dst[m][k] = *(const PG8_LAS bf16x8*)(lds + PG8_SA(b, h) + aoff + m * 2048 + k * 1024); } while (0)
; #define PG8_LDB(dst, b, h) do { _Pragma("unroll") for (int n = 0; n < 2; ++n) _Pragma("unroll") for (int k = 0; k < 2; ++k) dst[n][k] = *(const PG8_LAS bf16x8*)(lds + PG8_SB(b, h) + boff + n * 2048 + k * 1024); } while (0)
; #define PG8_MMA(ai, bj, At, Bt) do { __builtin_amdgcn_s_setprio(1); _Pragma("unroll") for (int m = 0; m < 4; ++m) _Pragma("unroll") for (int n = 0; n < 2; ++n) _Pragma("unroll") for (int k = 0; k < 2; ++k) \
;         acc[ai][bj][m][n] = __builtin_amdgcn_mfma_f32_16x16x32_bf16(Bt[n][k], At[m][k], acc[ai][bj][m][n], 0, 0, 0); __builtin_amdgcn_s_setprio(0); } while (0)
; #define PG8_WAIT_V(n) asm volatile("s_waitcnt vmcnt(" #n ")" ::: "memory")
; #define PG8_WAIT_L(n) asm volatile("s_waitcnt lgkmcnt(" #n ")" ::: "memory")
; #define PG8_BAR __builtin_amdgcn_s_barrier()
; #define PG8_SCHED __builtin_amdgcn_sched_barrier(0)
; template <class Epi, class Sched, bool ALIGN_EPI = false, bool SP2 = false>
; __device__ __forceinline__ void gemm_phase(PG8_LAS unsigned char* lds, const Gemm g, const Sched& S, const Epi& E) {
;     ...
;             PG8_LDB(B0, 0, 0); PG8_LDB(B1, 0, 1); PG8_SCHED; PG8_LDA(At, 0, 0); PG8_STAGE(PG8_SA(1, 1), a1 + hstep, voffA);
;             PG8_WAIT_V(8); PG8_WAIT_L(0); PG8_BAR; PG8_MMA(0, 0, At, B0); PG8_MMA(0, 1, At, B1); PG8_BAR; PG8_SCHED;
	s_add_i32 m0, s29, 0xe000
	s_nop 0
	global_load_lds_dwordx4 v138, s[40:41]
	s_waitcnt vmcnt(8)
	s_waitcnt lgkmcnt(0)
	s_setprio 1
	s_barrier

; #define PG8_MMA(ai, bj, At, Bt) do { __builtin_amdgcn_s_setprio(1); _Pragma("unroll") for (int m = 0; m < 4; ++m) _Pragma("unroll") for (int n = 0; n < 2; ++n) _Pragma("unroll") for (int k = 0; k < 2; ++k) \
;         acc[ai][bj][m][n] = __builtin_amdgcn_mfma_f32_16x16x32_bf16(Bt[n][k], At[m][k], acc[ai][bj][m][n], 0, 0, 0); __builtin_amdgcn_s_setprio(0); } while (0)
; #define PG8_WAIT_V(n) asm volatile("s_waitcnt vmcnt(" #n ")" ::: "memory")
; #define PG8_WAIT_L(n) asm volatile("s_waitcnt lgkmcnt(" #n ")" ::: "memory")
; #define PG8_BAR __builtin_amdgcn_s_barrier()
; #define PG8_SCHED __builtin_amdgcn_sched_barrier(0)
; template <class Epi, class Sched, bool ALIGN_EPI = false, bool SP2 = false>
; __device__ __forceinline__ void gemm_phase(PG8_LAS unsigned char* lds, const Gemm g, const Sched& S, const Epi& E) {
;     ...
;             PG8_WAIT_V(8); PG8_WAIT_L(0); PG8_BAR; PG8_MMA(0, 0, At, B0); PG8_MMA(0, 1, At, B1); PG8_BAR; PG8_SCHED;
	v_mfma_f32_16x16x32_bf16 v[124:127], v[152:155], v[184:187], v[124:127]
	v_mfma_f32_16x16x32_bf16 v[120:123], v[160:163], v[184:187], v[120:123]
	v_mfma_f32_16x16x32_bf16 v[116:119], v[152:155], v[192:195], v[116:119]
	v_mfma_f32_16x16x32_bf16 v[112:115], v[160:163], v[192:195], v[112:115]
	v_mfma_f32_16x16x32_bf16 v[100:103], v[152:155], v[200:203], v[100:103]
	v_mfma_f32_16x16x32_bf16 v[96:99], v[160:163], v[200:203], v[96:99]
	v_mfma_f32_16x16x32_bf16 v[84:87], v[152:155], v[208:211], v[84:87]
	v_mfma_f32_16x16x32_bf16 v[80:83], v[160:163], v[208:211], v[80:83]
	v_mfma_f32_16x16x32_bf16 v[124:127], v[156:159], v[188:191], v[124:127]
	v_mfma_f32_16x16x32_bf16 v[120:123], v[164:167], v[188:191], v[120:123]
	v_mfma_f32_16x16x32_bf16 v[116:119], v[156:159], v[196:199], v[116:119]
	v_mfma_f32_16x16x32_bf16 v[112:115], v[164:167], v[196:199], v[112:115]
	v_mfma_f32_16x16x32_bf16 v[100:103], v[156:159], v[204:207], v[100:103]
	v_mfma_f32_16x16x32_bf16 v[96:99], v[164:167], v[204:207], v[96:99]
	v_mfma_f32_16x16x32_bf16 v[84:87], v[156:159], v[212:215], v[84:87]
	v_mfma_f32_16x16x32_bf16 v[80:83], v[164:167], v[212:215], v[80:83]


; #define PG8_STAGE(bufoff, gbase, voff) do { _Pragma("unroll") for (int _i = 0; _i < 2; ++_i) \
;         __builtin_amdgcn_global_load_lds((const unsigned*)((const char*)(gbase) + (voff)[_i]), (PG8_LAS unsigned*)(lds + (bufoff) + ldsw + _i * 8192), 16, 0, 0); } while (0)
; #define PG8_LDA(dst, b, h) do { _Pragma("unroll") for (int m = 0; m < 4; ++m) _Pragma("unroll") for (int k = 0; k < 2; ++k) dst[m][k] = *(const PG8_LAS bf16x8*)(lds + PG8_SA(b, h) + aoff + m * 2048 + k * 1024); } while (0)
; #define PG8_MMA(ai, bj, At, Bt) do { __builtin_amdgcn_s_setprio(1); _Pragma("unroll") for (int m = 0; m < 4; ++m) _Pragma("unroll") for (int n = 0; n < 2; ++n) _Pragma("unroll") for (int k = 0; k < 2; ++k) \
;         acc[ai][bj][m][n] = __builtin_amdgcn_mfma_f32_16x16x32_bf16(Bt[n][k], At[m][k], acc[ai][bj][m][n], 0, 0, 0); __builtin_amdgcn_s_setprio(0); } while (0)
; #define PG8_WAIT_V(n) asm volatile("s_waitcnt vmcnt(" #n ")" ::: "memory")
; #define PG8_WAIT_L(n) asm volatile("s_waitcnt lgkmcnt(" #n ")" ::: "memory")
; #define PG8_BAR __builtin_amdgcn_s_barrier()
; #define PG8_SCHED __builtin_amdgcn_sched_barrier(0)
; template <class Epi, class Sched, bool ALIGN_EPI = false, bool SP2 = false>
; __device__ __forceinline__ void gemm_phase(PG8_LAS unsigned char* lds, const Gemm g, const Sched& S, const Epi& E) {
;     ...
;             PG8_WAIT_V(8); PG8_WAIT_L(0); PG8_BAR; PG8_MMA(0, 0, At, B0); PG8_MMA(0, 1, At, B1); PG8_BAR; PG8_SCHED;
;             PG8_LDA(At, 0, 1); PG8_STAGE(PG8_SB(0, 0), b2, voffB); PG8_STAGE(PG8_SB(0, 1), b2 + hstep, voffB); PG8_STAGE(PG8_SA(0, 0), a2, voffA);
	v_mfma_f32_16x16x32_bf16 v[108:111], v[168:171], v[184:187], v[108:111]
	v_mfma_f32_16x16x32_bf16 v[104:107], v[176:179], v[184:187], v[104:107]
	v_mfma_f32_16x16x32_bf16 v[92:95], v[168:171], v[192:195], v[92:95]
	v_mfma_f32_16x16x32_bf16 v[88:91], v[176:179], v[192:195], v[88:91]
	v_mfma_f32_16x16x32_bf16 v[76:79], v[168:171], v[200:203], v[76:79]
	v_mfma_f32_16x16x32_bf16 v[72:75], v[176:179], v[200:203], v[72:75]
	v_mfma_f32_16x16x32_bf16 v[68:71], v[168:171], v[208:211], v[68:71]
	v_mfma_f32_16x16x32_bf16 v[64:67], v[176:179], v[208:211], v[64:67]
	v_mfma_f32_16x16x32_bf16 v[108:111], v[172:175], v[188:191], v[108:111]
	v_mfma_f32_16x16x32_bf16 v[104:107], v[180:183], v[188:191], v[104:107]
	v_mfma_f32_16x16x32_bf16 v[92:95], v[172:175], v[196:199], v[92:95]
	v_mfma_f32_16x16x32_bf16 v[88:91], v[180:183], v[196:199], v[88:91]
	v_mfma_f32_16x16x32_bf16 v[76:79], v[172:175], v[204:207], v[76:79]
	v_mfma_f32_16x16x32_bf16 v[72:75], v[180:183], v[204:207], v[72:75]
	v_mfma_f32_16x16x32_bf16 v[68:71], v[172:175], v[212:215], v[68:71]
	v_mfma_f32_16x16x32_bf16 v[64:67], v[180:183], v[212:215], v[64:67]
	s_setprio 0
	s_barrier
	s_add_i32 s69, s59, s48
	s_mov_b64 s[96:97], s[42:43]

; #define PG8_STAGE(bufoff, gbase, voff) do { _Pragma("unroll") for (int _i = 0; _i < 2; ++_i) \
;         __builtin_amdgcn_global_load_lds((const unsigned*)((const char*)(gbase) + (voff)[_i]), (PG8_LAS unsigned*)(lds + (bufoff) + ldsw + _i * 8192), 16, 0, 0); } while (0)
; #define PG8_LDA(dst, b, h) do { _Pragma("unroll") for (int m = 0; m < 4; ++m) _Pragma("unroll") for (int k = 0; k < 2; ++k) dst[m][k] = *(const PG8_LAS bf16x8*)(lds + PG8_SA(b, h) + aoff + m * 2048 + k * 1024); } while (0)
; template <class Epi, class Sched, bool ALIGN_EPI = false, bool SP2 = false>
; __device__ __forceinline__ void gemm_phase(PG8_LAS unsigned char* lds, const Gemm g, const Sched& S, const Epi& E) {
;     ...
;             PG8_LDA(At, 0, 1); PG8_STAGE(PG8_SB(0, 0), b2, voffB); PG8_STAGE(PG8_SB(0, 1), b2 + hstep, voffB); PG8_STAGE(PG8_SA(0, 0), a2, voffA);
	s_mov_b32 m0, s69
	ds_read_b128 v[184:187], v151 offset:16384
	ds_read_b128 v[188:191], v151 offset:17408
	ds_read_b128 v[192:195], v151 offset:18432
	ds_read_b128 v[196:199], v151 offset:19456
	ds_read_b128 v[200:203], v151 offset:20480
	ds_read_b128 v[204:207], v151 offset:21504
	ds_read_b128 v[208:211], v151 offset:22528
	ds_read_b128 v[212:215], v151 offset:23552
	global_load_lds_dwordx4 v132, s[42:43]
	s_add_i32 m0, s69, 0x2000
	s_add_u32 s70, s42, 0x80000

; #define PG8_STAGE(bufoff, gbase, voff) do { _Pragma("unroll") for (int _i = 0; _i < 2; ++_i) \
;         __builtin_amdgcn_global_load_lds((const unsigned*)((const char*)(gbase) + (voff)[_i]), (PG8_LAS unsigned*)(lds + (bufoff) + ldsw + _i * 8192), 16, 0, 0); } while (0)
; #define PG8_LDA(dst, b, h) do { _Pragma("unroll") for (int m = 0; m < 4; ++m) _Pragma("unroll") for (int k = 0; k < 2; ++k) dst[m][k] = *(const PG8_LAS bf16x8*)(lds + PG8_SA(b, h) + aoff + m * 2048 + k * 1024); } while (0)
; template <class Epi, class Sched, bool ALIGN_EPI = false, bool SP2 = false>
; __device__ __forceinline__ void gemm_phase(PG8_LAS unsigned char* lds, const Gemm g, const Sched& S, const Epi& E) {
;     ...
;             PG8_LDA(At, 0, 1); PG8_STAGE(PG8_SB(0, 0), b2, voffB); PG8_STAGE(PG8_SB(0, 1), b2 + hstep, voffB); PG8_STAGE(PG8_SA(0, 0), a2, voffA);
	s_addc_u32 s71, s43, 0
	s_add_i32 s69, s60, s48
	global_load_lds_dwordx4 v128, s[42:43]

; #define PG8_STAGE(bufoff, gbase, voff) do { _Pragma("unroll") for (int _i = 0; _i < 2; ++_i) \
;         __builtin_amdgcn_global_load_lds((const unsigned*)((const char*)(gbase) + (voff)[_i]), (PG8_LAS unsigned*)(lds + (bufoff) + ldsw + _i * 8192), 16, 0, 0); } while (0)
; #define PG8_LDA(dst, b, h) do { _Pragma("unroll") for (int m = 0; m < 4; ++m) _Pragma("unroll") for (int k = 0; k < 2; ++k) dst[m][k] = *(const PG8_LAS bf16x8*)(lds + PG8_SA(b, h) + aoff + m * 2048 + k * 1024); } while (0)
; template <class Epi, class Sched, bool ALIGN_EPI = false, bool SP2 = false>
; __device__ __forceinline__ void gemm_phase(PG8_LAS unsigned char* lds, const Gemm g, const Sched& S, const Epi& E) {
;     ...
;             PG8_LDA(At, 0, 1); PG8_STAGE(PG8_SB(0, 0), b2, voffB); PG8_STAGE(PG8_SB(0, 1), b2 + hstep, voffB); PG8_STAGE(PG8_SA(0, 0), a2, voffA);
	s_mov_b32 m0, s69
	s_nop 0
	global_load_lds_dwordx4 v132, s[70:71]

; #define PG8_STAGE(bufoff, gbase, voff) do { _Pragma("unroll") for (int _i = 0; _i < 2; ++_i) \
;         __builtin_amdgcn_global_load_lds((const unsigned*)((const char*)(gbase) + (voff)[_i]), (PG8_LAS unsigned*)(lds + (bufoff) + ldsw + _i * 8192), 16, 0, 0); } while (0)
; #define PG8_LDA(dst, b, h) do { _Pragma("unroll") for (int m = 0; m < 4; ++m) _Pragma("unroll") for (int k = 0; k < 2; ++k) dst[m][k] = *(const PG8_LAS bf16x8*)(lds + PG8_SA(b, h) + aoff + m * 2048 + k * 1024); } while (0)
; template <class Epi, class Sched, bool ALIGN_EPI = false, bool SP2 = false>
; __device__ __forceinline__ void gemm_phase(PG8_LAS unsigned char* lds, const Gemm g, const Sched& S, const Epi& E) {
;     ...
;             PG8_LDA(At, 0, 1); PG8_STAGE(PG8_SB(0, 0), b2, voffB); PG8_STAGE(PG8_SB(0, 1), b2 + hstep, voffB); PG8_STAGE(PG8_SA(0, 0), a2, voffA);
	s_add_i32 m0, s69, 0x2000
	s_nop 0
	global_load_lds_dwordx4 v128, s[70:71]
	s_mov_b64 s[98:99], s[44:45]

; #define PG8_STAGE(bufoff, gbase, voff) do { _Pragma("unroll") for (int _i = 0; _i < 2; ++_i) \
;         __builtin_amdgcn_global_load_lds((const unsigned*)((const char*)(gbase) + (voff)[_i]), (PG8_LAS unsigned*)(lds + (bufoff) + ldsw + _i * 8192), 16, 0, 0); } while (0)
; #define PG8_LDA(dst, b, h) do { _Pragma("unroll") for (int m = 0; m < 4; ++m) _Pragma("unroll") for (int k = 0; k < 2; ++k) dst[m][k] = *(const PG8_LAS bf16x8*)(lds + PG8_SA(b, h) + aoff + m * 2048 + k * 1024); } while (0)
; #define PG8_MMA(ai, bj, At, Bt) do { __builtin_amdgcn_s_setprio(1); _Pragma("unroll") for (int m = 0; m < 4; ++m) _Pragma("unroll") for (int n = 0; n < 2; ++n) _Pragma("unroll") for (int k = 0; k < 2; ++k) \
;         acc[ai][bj][m][n] = __builtin_amdgcn_mfma_f32_16x16x32_bf16(Bt[n][k], At[m][k], acc[ai][bj][m][n], 0, 0, 0); __builtin_amdgcn_s_setprio(0); } while (0)
; #define PG8_WAIT_V(n) asm volatile("s_waitcnt vmcnt(" #n ")" ::: "memory")
; #define PG8_WAIT_L(n) asm volatile("s_waitcnt lgkmcnt(" #n ")" ::: "memory")
; #define PG8_BAR __builtin_amdgcn_s_barrier()
; #define PG8_SCHED __builtin_amdgcn_sched_barrier(0)
; template <class Epi, class Sched, bool ALIGN_EPI = false, bool SP2 = false>
; __device__ __forceinline__ void gemm_phase(PG8_LAS unsigned char* lds, const Gemm g, const Sched& S, const Epi& E) {
;     ...
;             PG8_LDA(At, 0, 1); PG8_STAGE(PG8_SB(0, 0), b2, voffB); PG8_STAGE(PG8_SB(0, 1), b2 + hstep, voffB); PG8_STAGE(PG8_SA(0, 0), a2, voffA);
;             PG8_WAIT_V(8); PG8_WAIT_L(0); PG8_BAR; PG8_MMA(1, 0, At, B0); PG8_MMA(1, 1, At, B1); PG8_BAR; PG8_SCHED;
	s_mov_b32 m0, s29
	s_nop 0
	global_load_lds_dwordx4 v134, s[44:45]
	s_mov_b32 m0, s51
	s_nop 0
	global_load_lds_dwordx4 v130, s[44:45]
	s_waitcnt vmcnt(8)
	s_waitcnt lgkmcnt(0)
	s_setprio 1
	s_barrier

; #define PG8_MMA(ai, bj, At, Bt) do { __builtin_amdgcn_s_setprio(1); _Pragma("unroll") for (int m = 0; m < 4; ++m) _Pragma("unroll") for (int n = 0; n < 2; ++n) _Pragma("unroll") for (int k = 0; k < 2; ++k) \
;         acc[ai][bj][m][n] = __builtin_amdgcn_mfma_f32_16x16x32_bf16(Bt[n][k], At[m][k], acc[ai][bj][m][n], 0, 0, 0); __builtin_amdgcn_s_setprio(0); } while (0)
; #define PG8_WAIT_V(n) asm volatile("s_waitcnt vmcnt(" #n ")" ::: "memory")
; #define PG8_WAIT_L(n) asm volatile("s_waitcnt lgkmcnt(" #n ")" ::: "memory")
; #define PG8_BAR __builtin_amdgcn_s_barrier()
; #define PG8_SCHED __builtin_amdgcn_sched_barrier(0)
; template <class Epi, class Sched, bool ALIGN_EPI = false, bool SP2 = false>
; __device__ __forceinline__ void gemm_phase(PG8_LAS unsigned char* lds, const Gemm g, const Sched& S, const Epi& E) {
;     ...
;             PG8_WAIT_V(8); PG8_WAIT_L(0); PG8_BAR; PG8_MMA(1, 0, At, B0); PG8_MMA(1, 1, At, B1); PG8_BAR; PG8_SCHED;
	v_mfma_f32_16x16x32_bf16 v[60:63], v[152:155], v[184:187], v[60:63]
	v_mfma_f32_16x16x32_bf16 v[56:59], v[160:163], v[184:187], v[56:59]
	v_mfma_f32_16x16x32_bf16 v[52:55], v[152:155], v[192:195], v[52:55]
	v_mfma_f32_16x16x32_bf16 v[48:51], v[160:163], v[192:195], v[48:51]
	v_mfma_f32_16x16x32_bf16 v[36:39], v[152:155], v[200:203], v[36:39]
	v_mfma_f32_16x16x32_bf16 v[32:35], v[160:163], v[200:203], v[32:35]
	v_mfma_f32_16x16x32_bf16 v[20:23], v[152:155], v[208:211], v[20:23]
	v_mfma_f32_16x16x32_bf16 v[16:19], v[160:163], v[208:211], v[16:19]
	v_mfma_f32_16x16x32_bf16 v[60:63], v[156:159], v[188:191], v[60:63]
	v_mfma_f32_16x16x32_bf16 v[56:59], v[164:167], v[188:191], v[56:59]
	v_mfma_f32_16x16x32_bf16 v[52:55], v[156:159], v[196:199], v[52:55]
	v_mfma_f32_16x16x32_bf16 v[48:51], v[164:167], v[196:199], v[48:51]
	v_mfma_f32_16x16x32_bf16 v[36:39], v[156:159], v[204:207], v[36:39]
	v_mfma_f32_16x16x32_bf16 v[32:35], v[164:167], v[204:207], v[32:35]
	v_mfma_f32_16x16x32_bf16 v[20:23], v[156:159], v[212:215], v[20:23]
	v_mfma_f32_16x16x32_bf16 v[16:19], v[164:167], v[212:215], v[16:19]


; #define PG8_STAGE(bufoff, gbase, voff) do { _Pragma("unroll") for (int _i = 0; _i < 2; ++_i) \
;         __builtin_amdgcn_global_load_lds((const unsigned*)((const char*)(gbase) + (voff)[_i]), (PG8_LAS unsigned*)(lds + (bufoff) + ldsw + _i * 8192), 16, 0, 0); } while (0)
; #define PG8_LDA(dst, b, h) do { _Pragma("unroll") for (int m = 0; m < 4; ++m) _Pragma("unroll") for (int k = 0; k < 2; ++k) dst[m][k] = *(const PG8_LAS bf16x8*)(lds + PG8_SA(b, h) + aoff + m * 2048 + k * 1024); } while (0)
; #define PG8_LDB(dst, b, h) do { _Pragma("unroll") for (int n = 0; n < 2; ++n) _Pragma("unroll") for (int k = 0; k < 2; ++k) dst[n][k] = *(const PG8_LAS bf16x8*)(lds + PG8_SB(b, h) + boff + n * 2048 + k * 1024); } while (0)
; #define PG8_MMA(ai, bj, At, Bt) do { __builtin_amdgcn_s_setprio(1); _Pragma("unroll") for (int m = 0; m < 4; ++m) _Pragma("unroll") for (int n = 0; n < 2; ++n) _Pragma("unroll") for (int k = 0; k < 2; ++k) \
;         acc[ai][bj][m][n] = __builtin_amdgcn_mfma_f32_16x16x32_bf16(Bt[n][k], At[m][k], acc[ai][bj][m][n], 0, 0, 0); __builtin_amdgcn_s_setprio(0); } while (0)
; #define PG8_WAIT_V(n) asm volatile("s_waitcnt vmcnt(" #n ")" ::: "memory")
; #define PG8_WAIT_L(n) asm volatile("s_waitcnt lgkmcnt(" #n ")" ::: "memory")
; #define PG8_BAR __builtin_amdgcn_s_barrier()
; #define PG8_SCHED __builtin_amdgcn_sched_barrier(0)
; template <class Epi, class Sched, bool ALIGN_EPI = false, bool SP2 = false>
; __device__ __forceinline__ void gemm_phase(PG8_LAS unsigned char* lds, const Gemm g, const Sched& S, const Epi& E) {
;     ...
;             PG8_WAIT_V(8); PG8_WAIT_L(0); PG8_BAR; PG8_MMA(1, 0, At, B0); PG8_MMA(1, 1, At, B1); PG8_BAR; PG8_SCHED;
;             PG8_LDB(B0, 1, 0); PG8_LDB(B1, 1, 1); PG8_SCHED; PG8_LDA(At, 1, 0); PG8_STAGE(PG8_SA(0, 1), a2 + hstep, voffA);
	v_mfma_f32_16x16x32_bf16 v[44:47], v[168:171], v[184:187], v[44:47]
	v_mfma_f32_16x16x32_bf16 v[40:43], v[176:179], v[184:187], v[40:43]
	v_mfma_f32_16x16x32_bf16 v[28:31], v[168:171], v[192:195], v[28:31]
	v_mfma_f32_16x16x32_bf16 v[24:27], v[176:179], v[192:195], v[24:27]
	v_mfma_f32_16x16x32_bf16 v[12:15], v[168:171], v[200:203], v[12:15]
	v_mfma_f32_16x16x32_bf16 v[8:11], v[176:179], v[200:203], v[8:11]
	v_mfma_f32_16x16x32_bf16 v[4:7], v[168:171], v[208:211], v[4:7]
	v_mfma_f32_16x16x32_bf16 v[0:3], v[176:179], v[208:211], v[0:3]
	v_mfma_f32_16x16x32_bf16 v[44:47], v[172:175], v[188:191], v[44:47]
	v_mfma_f32_16x16x32_bf16 v[40:43], v[180:183], v[188:191], v[40:43]
	v_mfma_f32_16x16x32_bf16 v[28:31], v[172:175], v[196:199], v[28:31]
	v_mfma_f32_16x16x32_bf16 v[24:27], v[180:183], v[196:199], v[24:27]
	v_mfma_f32_16x16x32_bf16 v[12:15], v[172:175], v[204:207], v[12:15]
	v_mfma_f32_16x16x32_bf16 v[8:11], v[180:183], v[204:207], v[8:11]
	v_mfma_f32_16x16x32_bf16 v[4:7], v[172:175], v[212:215], v[4:7]
	v_mfma_f32_16x16x32_bf16 v[0:3], v[180:183], v[212:215], v[0:3]
	s_setprio 0
	s_barrier
	s_add_i32 s69, 0, 0x18000
	s_add_i32 s70, 0, 0x1c000
	v_add_u32_e32 v164, s69, v147
	v_add_u32_e32 v180, s70, v147
	ds_read_b128 v[152:155], v164
	ds_read_b128 v[156:159], v164 offset:1024
	ds_read_b128 v[160:163], v164 offset:2048
	ds_read_b128 v[164:167], v164 offset:3072
	ds_read_b128 v[168:171], v180
	ds_read_b128 v[172:175], v180 offset:1024
	ds_read_b128 v[176:179], v180 offset:2048
	ds_read_b128 v[180:183], v180 offset:3072
	s_add_u32 s44, s44, 0x80000
	s_addc_u32 s45, s45, 0
	s_mov_b32 m0, s52

; #define PG8_STAGE(bufoff, gbase, voff) do { _Pragma("unroll") for (int _i = 0; _i < 2; ++_i) \
;         __builtin_amdgcn_global_load_lds((const unsigned*)((const char*)(gbase) + (voff)[_i]), (PG8_LAS unsigned*)(lds + (bufoff) + ldsw + _i * 8192), 16, 0, 0); } while (0)
; #define PG8_LDA(dst, b, h) do { _Pragma("unroll") for (int m = 0; m < 4; ++m) _Pragma("unroll") for (int k = 0; k < 2; ++k) dst[m][k] = *(const PG8_LAS bf16x8*)(lds + PG8_SA(b, h) + aoff + m * 2048 + k * 1024); } while (0)
; #define PG8_LDB(dst, b, h) do { _Pragma("unroll") for (int n = 0; n < 2; ++n) _Pragma("unroll") for (int k = 0; k < 2; ++k) dst[n][k] = *(const PG8_LAS bf16x8*)(lds + PG8_SB(b, h) + boff + n * 2048 + k * 1024); } while (0)
; #define PG8_SCHED __builtin_amdgcn_sched_barrier(0)
; template <class Epi, class Sched, bool ALIGN_EPI = false, bool SP2 = false>
; __device__ __forceinline__ void gemm_phase(PG8_LAS unsigned char* lds, const Gemm g, const Sched& S, const Epi& E) {
;     ...
;             PG8_LDB(B0, 1, 0); PG8_LDB(B1, 1, 1); PG8_SCHED; PG8_LDA(At, 1, 0); PG8_STAGE(PG8_SA(0, 1), a2 + hstep, voffA);
	ds_read_b128 v[184:187], v151 offset:32768
	ds_read_b128 v[188:191], v151 offset:33792
	ds_read_b128 v[192:195], v151 offset:34816
	ds_read_b128 v[196:199], v151 offset:35840
	ds_read_b128 v[200:203], v151 offset:36864
	ds_read_b128 v[204:207], v151 offset:37888
	ds_read_b128 v[208:211], v151 offset:38912
	ds_read_b128 v[212:215], v151 offset:39936
	global_load_lds_dwordx4 v134, s[44:45]

; #define PG8_STAGE(bufoff, gbase, voff) do { _Pragma("unroll") for (int _i = 0; _i < 2; ++_i) \
;         __builtin_amdgcn_global_load_lds((const unsigned*)((const char*)(gbase) + (voff)[_i]), (PG8_LAS unsigned*)(lds + (bufoff) + ldsw + _i * 8192), 16, 0, 0); } while (0)
; #define PG8_LDA(dst, b, h) do { _Pragma("unroll") for (int m = 0; m < 4; ++m) _Pragma("unroll") for (int k = 0; k < 2; ++k) dst[m][k] = *(const PG8_LAS bf16x8*)(lds + PG8_SA(b, h) + aoff + m * 2048 + k * 1024); } while (0)
; #define PG8_LDB(dst, b, h) do { _Pragma("unroll") for (int n = 0; n < 2; ++n) _Pragma("unroll") for (int k = 0; k < 2; ++k) dst[n][k] = *(const PG8_LAS bf16x8*)(lds + PG8_SB(b, h) + boff + n * 2048 + k * 1024); } while (0)
; #define PG8_MMA(ai, bj, At, Bt) do { __builtin_amdgcn_s_setprio(1); _Pragma("unroll") for (int m = 0; m < 4; ++m) _Pragma("unroll") for (int n = 0; n < 2; ++n) _Pragma("unroll") for (int k = 0; k < 2; ++k) \
;         acc[ai][bj][m][n] = __builtin_amdgcn_mfma_f32_16x16x32_bf16(Bt[n][k], At[m][k], acc[ai][bj][m][n], 0, 0, 0); __builtin_amdgcn_s_setprio(0); } while (0)
; #define PG8_WAIT_V(n) asm volatile("s_waitcnt vmcnt(" #n ")" ::: "memory")
; #define PG8_WAIT_L(n) asm volatile("s_waitcnt lgkmcnt(" #n ")" ::: "memory")
; #define PG8_BAR __builtin_amdgcn_s_barrier()
; #define PG8_SCHED __builtin_amdgcn_sched_barrier(0)
; template <class Epi, class Sched, bool ALIGN_EPI = false, bool SP2 = false>
; __device__ __forceinline__ void gemm_phase(PG8_LAS unsigned char* lds, const Gemm g, const Sched& S, const Epi& E) {
;     ...
;             PG8_LDB(B0, 1, 0); PG8_LDB(B1, 1, 1); PG8_SCHED; PG8_LDA(At, 1, 0); PG8_STAGE(PG8_SA(0, 1), a2 + hstep, voffA);
;             PG8_WAIT_V(8); PG8_WAIT_L(0); PG8_BAR; PG8_MMA(0, 0, At, B0); PG8_MMA(0, 1, At, B1); PG8_BAR; PG8_SCHED;
	s_mov_b32 m0, s53
	s_nop 0
	global_load_lds_dwordx4 v130, s[44:45]
	s_waitcnt vmcnt(8)
	s_waitcnt lgkmcnt(0)
	s_setprio 1
	s_barrier

; #define PG8_MMA(ai, bj, At, Bt) do { __builtin_amdgcn_s_setprio(1); _Pragma("unroll") for (int m = 0; m < 4; ++m) _Pragma("unroll") for (int n = 0; n < 2; ++n) _Pragma("unroll") for (int k = 0; k < 2; ++k) \
;         acc[ai][bj][m][n] = __builtin_amdgcn_mfma_f32_16x16x32_bf16(Bt[n][k], At[m][k], acc[ai][bj][m][n], 0, 0, 0); __builtin_amdgcn_s_setprio(0); } while (0)
; #define PG8_WAIT_V(n) asm volatile("s_waitcnt vmcnt(" #n ")" ::: "memory")
; #define PG8_WAIT_L(n) asm volatile("s_waitcnt lgkmcnt(" #n ")" ::: "memory")
; #define PG8_BAR __builtin_amdgcn_s_barrier()
; #define PG8_SCHED __builtin_amdgcn_sched_barrier(0)
; template <class Epi, class Sched, bool ALIGN_EPI = false, bool SP2 = false>
; __device__ __forceinline__ void gemm_phase(PG8_LAS unsigned char* lds, const Gemm g, const Sched& S, const Epi& E) {
;     ...
;             PG8_WAIT_V(8); PG8_WAIT_L(0); PG8_BAR; PG8_MMA(0, 0, At, B0); PG8_MMA(0, 1, At, B1); PG8_BAR; PG8_SCHED;
	v_mfma_f32_16x16x32_bf16 v[124:127], v[152:155], v[184:187], v[124:127]
	v_mfma_f32_16x16x32_bf16 v[120:123], v[160:163], v[184:187], v[120:123]
	v_mfma_f32_16x16x32_bf16 v[116:119], v[152:155], v[192:195], v[116:119]
	v_mfma_f32_16x16x32_bf16 v[112:115], v[160:163], v[192:195], v[112:115]
	v_mfma_f32_16x16x32_bf16 v[100:103], v[152:155], v[200:203], v[100:103]
	v_mfma_f32_16x16x32_bf16 v[96:99], v[160:163], v[200:203], v[96:99]
	v_mfma_f32_16x16x32_bf16 v[84:87], v[152:155], v[208:211], v[84:87]
	v_mfma_f32_16x16x32_bf16 v[80:83], v[160:163], v[208:211], v[80:83]
	v_mfma_f32_16x16x32_bf16 v[124:127], v[156:159], v[188:191], v[124:127]
	v_mfma_f32_16x16x32_bf16 v[120:123], v[164:167], v[188:191], v[120:123]
	v_mfma_f32_16x16x32_bf16 v[116:119], v[156:159], v[196:199], v[116:119]
	v_mfma_f32_16x16x32_bf16 v[112:115], v[164:167], v[196:199], v[112:115]
	v_mfma_f32_16x16x32_bf16 v[100:103], v[156:159], v[204:207], v[100:103]
	v_mfma_f32_16x16x32_bf16 v[96:99], v[164:167], v[204:207], v[96:99]
	v_mfma_f32_16x16x32_bf16 v[84:87], v[156:159], v[212:215], v[84:87]
	v_mfma_f32_16x16x32_bf16 v[80:83], v[164:167], v[212:215], v[80:83]


; #define PG8_STAGE(bufoff, gbase, voff) do { _Pragma("unroll") for (int _i = 0; _i < 2; ++_i) \
;         __builtin_amdgcn_global_load_lds((const unsigned*)((const char*)(gbase) + (voff)[_i]), (PG8_LAS unsigned*)(lds + (bufoff) + ldsw + _i * 8192), 16, 0, 0); } while (0)
; #define PG8_LDA(dst, b, h) do { _Pragma("unroll") for (int m = 0; m < 4; ++m) _Pragma("unroll") for (int k = 0; k < 2; ++k) dst[m][k] = *(const PG8_LAS bf16x8*)(lds + PG8_SA(b, h) + aoff + m * 2048 + k * 1024); } while (0)
; #define PG8_MMA(ai, bj, At, Bt) do { __builtin_amdgcn_s_setprio(1); _Pragma("unroll") for (int m = 0; m < 4; ++m) _Pragma("unroll") for (int n = 0; n < 2; ++n) _Pragma("unroll") for (int k = 0; k < 2; ++k) \
;         acc[ai][bj][m][n] = __builtin_amdgcn_mfma_f32_16x16x32_bf16(Bt[n][k], At[m][k], acc[ai][bj][m][n], 0, 0, 0); __builtin_amdgcn_s_setprio(0); } while (0)
; #define PG8_WAIT_V(n) asm volatile("s_waitcnt vmcnt(" #n ")" ::: "memory")
; #define PG8_WAIT_L(n) asm volatile("s_waitcnt lgkmcnt(" #n ")" ::: "memory")
; #define PG8_BAR __builtin_amdgcn_s_barrier()
; #define PG8_SCHED __builtin_amdgcn_sched_barrier(0)
; template <class Epi, class Sched, bool ALIGN_EPI = false, bool SP2 = false>
; __device__ __forceinline__ void gemm_phase(PG8_LAS unsigned char* lds, const Gemm g, const Sched& S, const Epi& E) {
;     ...
;             PG8_WAIT_V(8); PG8_WAIT_L(0); PG8_BAR; PG8_MMA(0, 0, At, B0); PG8_MMA(0, 1, At, B1); PG8_BAR; PG8_SCHED;
;             PG8_LDA(At, 1, 1); PG8_STAGE(PG8_SB(1, 0), b3, voffB); PG8_STAGE(PG8_SB(1, 1), b3 + hstep, voffB); PG8_STAGE(PG8_SA(1, 0), a3, voffA);
	v_mfma_f32_16x16x32_bf16 v[108:111], v[168:171], v[184:187], v[108:111]
	v_mfma_f32_16x16x32_bf16 v[104:107], v[176:179], v[184:187], v[104:107]
	v_mfma_f32_16x16x32_bf16 v[92:95], v[168:171], v[192:195], v[92:95]
	v_mfma_f32_16x16x32_bf16 v[88:91], v[176:179], v[192:195], v[88:91]
	v_mfma_f32_16x16x32_bf16 v[76:79], v[168:171], v[200:203], v[76:79]
	v_mfma_f32_16x16x32_bf16 v[72:75], v[176:179], v[200:203], v[72:75]
	v_mfma_f32_16x16x32_bf16 v[68:71], v[168:171], v[208:211], v[68:71]
	v_mfma_f32_16x16x32_bf16 v[64:67], v[176:179], v[208:211], v[64:67]
	v_mfma_f32_16x16x32_bf16 v[108:111], v[172:175], v[188:191], v[108:111]
	v_mfma_f32_16x16x32_bf16 v[104:107], v[180:183], v[188:191], v[104:107]
	v_mfma_f32_16x16x32_bf16 v[92:95], v[172:175], v[196:199], v[92:95]
	v_mfma_f32_16x16x32_bf16 v[88:91], v[180:183], v[196:199], v[88:91]
	v_mfma_f32_16x16x32_bf16 v[76:79], v[172:175], v[204:207], v[76:79]
	v_mfma_f32_16x16x32_bf16 v[72:75], v[180:183], v[204:207], v[72:75]
	v_mfma_f32_16x16x32_bf16 v[68:71], v[172:175], v[212:215], v[68:71]
	v_mfma_f32_16x16x32_bf16 v[64:67], v[180:183], v[212:215], v[64:67]
	s_setprio 0
	s_barrier
	s_add_i32 s44, s69, s48

; #define PG8_STAGE(bufoff, gbase, voff) do { _Pragma("unroll") for (int _i = 0; _i < 2; ++_i) \
;         __builtin_amdgcn_global_load_lds((const unsigned*)((const char*)(gbase) + (voff)[_i]), (PG8_LAS unsigned*)(lds + (bufoff) + ldsw + _i * 8192), 16, 0, 0); } while (0)
; #define PG8_LDA(dst, b, h) do { _Pragma("unroll") for (int m = 0; m < 4; ++m) _Pragma("unroll") for (int k = 0; k < 2; ++k) dst[m][k] = *(const PG8_LAS bf16x8*)(lds + PG8_SA(b, h) + aoff + m * 2048 + k * 1024); } while (0)
; template <class Epi, class Sched, bool ALIGN_EPI = false, bool SP2 = false>
; __device__ __forceinline__ void gemm_phase(PG8_LAS unsigned char* lds, const Gemm g, const Sched& S, const Epi& E) {
;     ...
;             PG8_LDA(At, 1, 1); PG8_STAGE(PG8_SB(1, 0), b3, voffB); PG8_STAGE(PG8_SB(1, 1), b3 + hstep, voffB); PG8_STAGE(PG8_SA(1, 0), a3, voffA);
	s_mov_b32 m0, s44
	ds_read_b128 v[184:187], v151 offset:49152
	ds_read_b128 v[188:191], v151 offset:50176
	ds_read_b128 v[192:195], v151 offset:51200
	ds_read_b128 v[196:199], v151 offset:52224
	ds_read_b128 v[200:203], v151 offset:53248
	ds_read_b128 v[204:207], v151 offset:54272
	ds_read_b128 v[208:211], v151 offset:55296
	ds_read_b128 v[212:215], v151 offset:56320
	global_load_lds_dwordx4 v250, s[96:97]
	s_add_i32 m0, s44, 0x2000
	s_add_u32 s42, s42, 0x80080

; #define PG8_STAGE(bufoff, gbase, voff) do { _Pragma("unroll") for (int _i = 0; _i < 2; ++_i) \
;         __builtin_amdgcn_global_load_lds((const unsigned*)((const char*)(gbase) + (voff)[_i]), (PG8_LAS unsigned*)(lds + (bufoff) + ldsw + _i * 8192), 16, 0, 0); } while (0)
; #define PG8_LDA(dst, b, h) do { _Pragma("unroll") for (int m = 0; m < 4; ++m) _Pragma("unroll") for (int k = 0; k < 2; ++k) dst[m][k] = *(const PG8_LAS bf16x8*)(lds + PG8_SA(b, h) + aoff + m * 2048 + k * 1024); } while (0)
; template <class Epi, class Sched, bool ALIGN_EPI = false, bool SP2 = false>
; __device__ __forceinline__ void gemm_phase(PG8_LAS unsigned char* lds, const Gemm g, const Sched& S, const Epi& E) {
;     ...
;             PG8_LDA(At, 1, 1); PG8_STAGE(PG8_SB(1, 0), b3, voffB); PG8_STAGE(PG8_SB(1, 1), b3 + hstep, voffB); PG8_STAGE(PG8_SA(1, 0), a3, voffA);
	s_addc_u32 s43, s43, 0
	s_add_i32 s44, s70, s48
	global_load_lds_dwordx4 v251, s[96:97]

; #define PG8_STAGE(bufoff, gbase, voff) do { _Pragma("unroll") for (int _i = 0; _i < 2; ++_i) \
;         __builtin_amdgcn_global_load_lds((const unsigned*)((const char*)(gbase) + (voff)[_i]), (PG8_LAS unsigned*)(lds + (bufoff) + ldsw + _i * 8192), 16, 0, 0); } while (0)
; #define PG8_LDA(dst, b, h) do { _Pragma("unroll") for (int m = 0; m < 4; ++m) _Pragma("unroll") for (int k = 0; k < 2; ++k) dst[m][k] = *(const PG8_LAS bf16x8*)(lds + PG8_SA(b, h) + aoff + m * 2048 + k * 1024); } while (0)
; template <class Epi, class Sched, bool ALIGN_EPI = false, bool SP2 = false>
; __device__ __forceinline__ void gemm_phase(PG8_LAS unsigned char* lds, const Gemm g, const Sched& S, const Epi& E) {
;     ...
;             PG8_LDA(At, 1, 1); PG8_STAGE(PG8_SB(1, 0), b3, voffB); PG8_STAGE(PG8_SB(1, 1), b3 + hstep, voffB); PG8_STAGE(PG8_SA(1, 0), a3, voffA);
	s_mov_b32 m0, s44
	s_nop 0
	global_load_lds_dwordx4 v132, s[42:43]

; #define PG8_STAGE(bufoff, gbase, voff) do { _Pragma("unroll") for (int _i = 0; _i < 2; ++_i) \
;         __builtin_amdgcn_global_load_lds((const unsigned*)((const char*)(gbase) + (voff)[_i]), (PG8_LAS unsigned*)(lds + (bufoff) + ldsw + _i * 8192), 16, 0, 0); } while (0)
; #define PG8_LDA(dst, b, h) do { _Pragma("unroll") for (int m = 0; m < 4; ++m) _Pragma("unroll") for (int k = 0; k < 2; ++k) dst[m][k] = *(const PG8_LAS bf16x8*)(lds + PG8_SA(b, h) + aoff + m * 2048 + k * 1024); } while (0)
; template <class Epi, class Sched, bool ALIGN_EPI = false, bool SP2 = false>
; __device__ __forceinline__ void gemm_phase(PG8_LAS unsigned char* lds, const Gemm g, const Sched& S, const Epi& E) {
;     ...
;             PG8_LDA(At, 1, 1); PG8_STAGE(PG8_SB(1, 0), b3, voffB); PG8_STAGE(PG8_SB(1, 1), b3 + hstep, voffB); PG8_STAGE(PG8_SA(1, 0), a3, voffA);
	s_add_i32 m0, s44, 0x2000
	s_nop 0
	global_load_lds_dwordx4 v128, s[42:43]

; #define PG8_STAGE(bufoff, gbase, voff) do { _Pragma("unroll") for (int _i = 0; _i < 2; ++_i) \
;         __builtin_amdgcn_global_load_lds((const unsigned*)((const char*)(gbase) + (voff)[_i]), (PG8_LAS unsigned*)(lds + (bufoff) + ldsw + _i * 8192), 16, 0, 0); } while (0)
; #define PG8_LDA(dst, b, h) do { _Pragma("unroll") for (int m = 0; m < 4; ++m) _Pragma("unroll") for (int k = 0; k < 2; ++k) dst[m][k] = *(const PG8_LAS bf16x8*)(lds + PG8_SA(b, h) + aoff + m * 2048 + k * 1024); } while (0)
; template <class Epi, class Sched, bool ALIGN_EPI = false, bool SP2 = false>
; __device__ __forceinline__ void gemm_phase(PG8_LAS unsigned char* lds, const Gemm g, const Sched& S, const Epi& E) {
;     ...
;             PG8_LDA(At, 1, 1); PG8_STAGE(PG8_SB(1, 0), b3, voffB); PG8_STAGE(PG8_SB(1, 1), b3 + hstep, voffB); PG8_STAGE(PG8_SA(1, 0), a3, voffA);
	s_mov_b32 m0, s55
	s_nop 0
	global_load_lds_dwordx4 v252, s[98:99]

; #define PG8_STAGE(bufoff, gbase, voff) do { _Pragma("unroll") for (int _i = 0; _i < 2; ++_i) \
;         __builtin_amdgcn_global_load_lds((const unsigned*)((const char*)(gbase) + (voff)[_i]), (PG8_LAS unsigned*)(lds + (bufoff) + ldsw + _i * 8192), 16, 0, 0); } while (0)
; #define PG8_LDA(dst, b, h) do { _Pragma("unroll") for (int m = 0; m < 4; ++m) _Pragma("unroll") for (int k = 0; k < 2; ++k) dst[m][k] = *(const PG8_LAS bf16x8*)(lds + PG8_SA(b, h) + aoff + m * 2048 + k * 1024); } while (0)
; #define PG8_MMA(ai, bj, At, Bt) do { __builtin_amdgcn_s_setprio(1); _Pragma("unroll") for (int m = 0; m < 4; ++m) _Pragma("unroll") for (int n = 0; n < 2; ++n) _Pragma("unroll") for (int k = 0; k < 2; ++k) \
;         acc[ai][bj][m][n] = __builtin_amdgcn_mfma_f32_16x16x32_bf16(Bt[n][k], At[m][k], acc[ai][bj][m][n], 0, 0, 0); __builtin_amdgcn_s_setprio(0); } while (0)
; #define PG8_WAIT_V(n) asm volatile("s_waitcnt vmcnt(" #n ")" ::: "memory")
; #define PG8_WAIT_L(n) asm volatile("s_waitcnt lgkmcnt(" #n ")" ::: "memory")
; #define PG8_BAR __builtin_amdgcn_s_barrier()
; #define PG8_SCHED __builtin_amdgcn_sched_barrier(0)
; template <class Epi, class Sched, bool ALIGN_EPI = false, bool SP2 = false>
; __device__ __forceinline__ void gemm_phase(PG8_LAS unsigned char* lds, const Gemm g, const Sched& S, const Epi& E) {
;     ...
;             PG8_LDA(At, 1, 1); PG8_STAGE(PG8_SB(1, 0), b3, voffB); PG8_STAGE(PG8_SB(1, 1), b3 + hstep, voffB); PG8_STAGE(PG8_SA(1, 0), a3, voffA);
;             PG8_WAIT_V(8); PG8_WAIT_L(0); PG8_BAR; PG8_MMA(1, 0, At, B0); PG8_MMA(1, 1, At, B1); PG8_BAR; PG8_SCHED;
	s_mov_b32 m0, s56
	s_nop 0
	global_load_lds_dwordx4 v253, s[98:99]
	s_waitcnt vmcnt(8)
	s_waitcnt lgkmcnt(0)
	s_setprio 1
	s_barrier

; #define PG8_MMA(ai, bj, At, Bt) do { __builtin_amdgcn_s_setprio(1); _Pragma("unroll") for (int m = 0; m < 4; ++m) _Pragma("unroll") for (int n = 0; n < 2; ++n) _Pragma("unroll") for (int k = 0; k < 2; ++k) \
;         acc[ai][bj][m][n] = __builtin_amdgcn_mfma_f32_16x16x32_bf16(Bt[n][k], At[m][k], acc[ai][bj][m][n], 0, 0, 0); __builtin_amdgcn_s_setprio(0); } while (0)
; #define PG8_WAIT_V(n) asm volatile("s_waitcnt vmcnt(" #n ")" ::: "memory")
; #define PG8_WAIT_L(n) asm volatile("s_waitcnt lgkmcnt(" #n ")" ::: "memory")
; #define PG8_BAR __builtin_amdgcn_s_barrier()
; #define PG8_SCHED __builtin_amdgcn_sched_barrier(0)
; template <class Epi, class Sched, bool ALIGN_EPI = false, bool SP2 = false>
; __device__ __forceinline__ void gemm_phase(PG8_LAS unsigned char* lds, const Gemm g, const Sched& S, const Epi& E) {
;     ...
;             PG8_WAIT_V(8); PG8_WAIT_L(0); PG8_BAR; PG8_MMA(1, 0, At, B0); PG8_MMA(1, 1, At, B1); PG8_BAR; PG8_SCHED;
	v_mfma_f32_16x16x32_bf16 v[60:63], v[152:155], v[184:187], v[60:63]
	v_mfma_f32_16x16x32_bf16 v[56:59], v[160:163], v[184:187], v[56:59]
	v_mfma_f32_16x16x32_bf16 v[52:55], v[152:155], v[192:195], v[52:55]
	v_mfma_f32_16x16x32_bf16 v[48:51], v[160:163], v[192:195], v[48:51]
	v_mfma_f32_16x16x32_bf16 v[36:39], v[152:155], v[200:203], v[36:39]
	v_mfma_f32_16x16x32_bf16 v[32:35], v[160:163], v[200:203], v[32:35]
	v_mfma_f32_16x16x32_bf16 v[20:23], v[152:155], v[208:211], v[20:23]
	v_mfma_f32_16x16x32_bf16 v[16:19], v[160:163], v[208:211], v[16:19]
	v_mfma_f32_16x16x32_bf16 v[60:63], v[156:159], v[188:191], v[60:63]
	v_mfma_f32_16x16x32_bf16 v[56:59], v[164:167], v[188:191], v[56:59]
	v_mfma_f32_16x16x32_bf16 v[52:55], v[156:159], v[196:199], v[52:55]
	v_mfma_f32_16x16x32_bf16 v[48:51], v[164:167], v[196:199], v[48:51]
	v_mfma_f32_16x16x32_bf16 v[36:39], v[156:159], v[204:207], v[36:39]
	v_mfma_f32_16x16x32_bf16 v[32:35], v[164:167], v[204:207], v[32:35]
	v_mfma_f32_16x16x32_bf16 v[20:23], v[156:159], v[212:215], v[20:23]
	v_mfma_f32_16x16x32_bf16 v[16:19], v[164:167], v[212:215], v[16:19]


; #define PG8_STAGE(bufoff, gbase, voff) do { _Pragma("unroll") for (int _i = 0; _i < 2; ++_i) \
;         __builtin_amdgcn_global_load_lds((const unsigned*)((const char*)(gbase) + (voff)[_i]), (PG8_LAS unsigned*)(lds + (bufoff) + ldsw + _i * 8192), 16, 0, 0); } while (0)
; #define PG8_LDA(dst, b, h) do { _Pragma("unroll") for (int m = 0; m < 4; ++m) _Pragma("unroll") for (int k = 0; k < 2; ++k) dst[m][k] = *(const PG8_LAS bf16x8*)(lds + PG8_SA(b, h) + aoff + m * 2048 + k * 1024); } while (0)
; #define PG8_LDB(dst, b, h) do { _Pragma("unroll") for (int n = 0; n < 2; ++n) _Pragma("unroll") for (int k = 0; k < 2; ++k) dst[n][k] = *(const PG8_LAS bf16x8*)(lds + PG8_SB(b, h) + boff + n * 2048 + k * 1024); } while (0)
; template <class Epi, class Sched, bool ALIGN_EPI = false, bool SP2 = false>
; __device__ __forceinline__ void gemm_phase(PG8_LAS unsigned char* lds, const Gemm g, const Sched& S, const Epi& E) {
;     ...
;         for (int t = 0; t < nt; t += 2) {
;             const bool last = (t == nt - 2);
;             const char* a1 = cA + (size_t)(t + 1) * kstep;
;             const char* a2 = last ? nA : cA + (size_t)(t + 2) * kstep; const char* b2 = last ? nB : cB + (size_t)(t + 2) * kstep;
;             const char* a3 = a2 + kstep; const char* b3 = b2 + kstep;
;             if (last && has_next) S.a_ready(nxt);
;             if constexpr (SP2) {
;             PG8_LDB(B0, 0, 0); PG8_LDB(B1, 0, 1); PG8_SCHED; PG8_LDA(At, 0, 0); PG8_STAGE(PG8_SA(1, 1), a1 + hstep, voffA);
;             PG8_WAIT_V(8); PG8_WAIT_L(0); PG8_BAR; PG8_MMA(0, 0, At, B0); PG8_MMA(0, 1, At, B1); PG8_BAR; PG8_SCHED;
;             PG8_LDA(At, 0, 1); PG8_STAGE(PG8_SB(0, 0), b2, voffB); PG8_STAGE(PG8_SB(0, 1), b2 + hstep, voffB); PG8_STAGE(PG8_SA(0, 0), a2, voffA);
;             PG8_WAIT_V(8); PG8_WAIT_L(0); PG8_BAR; PG8_MMA(1, 0, At, B0); PG8_MMA(1, 1, At, B1); PG8_BAR; PG8_SCHED;
;             PG8_LDB(B0, 1, 0); PG8_LDB(B1, 1, 1); PG8_SCHED; PG8_LDA(At, 1, 0); PG8_STAGE(PG8_SA(0, 1), a2 + hstep, voffA);
;             PG8_WAIT_V(8); PG8_WAIT_L(0); PG8_BAR; PG8_MMA(0, 0, At, B0); PG8_MMA(0, 1, At, B1); PG8_BAR; PG8_SCHED;
;             PG8_LDA(At, 1, 1); PG8_STAGE(PG8_SB(1, 0), b3, voffB); PG8_STAGE(PG8_SB(1, 1), b3 + hstep, voffB); PG8_STAGE(PG8_SA(1, 0), a3, voffA);
;             PG8_WAIT_V(8); PG8_WAIT_L(0); PG8_BAR; PG8_MMA(1, 0, At, B0); PG8_MMA(1, 1, At, B1); PG8_BAR; PG8_SCHED;
	v_mfma_f32_16x16x32_bf16 v[44:47], v[168:171], v[184:187], v[44:47]
	v_mfma_f32_16x16x32_bf16 v[40:43], v[176:179], v[184:187], v[40:43]
	v_mfma_f32_16x16x32_bf16 v[28:31], v[168:171], v[192:195], v[28:31]
	v_mfma_f32_16x16x32_bf16 v[24:27], v[176:179], v[192:195], v[24:27]
	v_mfma_f32_16x16x32_bf16 v[12:15], v[168:171], v[200:203], v[12:15]
	v_mfma_f32_16x16x32_bf16 v[8:11], v[176:179], v[200:203], v[8:11]
	v_mfma_f32_16x16x32_bf16 v[4:7], v[168:171], v[208:211], v[4:7]
	v_mfma_f32_16x16x32_bf16 v[0:3], v[176:179], v[208:211], v[0:3]
	v_mfma_f32_16x16x32_bf16 v[44:47], v[172:175], v[188:191], v[44:47]
	v_mfma_f32_16x16x32_bf16 v[40:43], v[180:183], v[188:191], v[40:43]
	v_mfma_f32_16x16x32_bf16 v[28:31], v[172:175], v[196:199], v[28:31]
	v_mfma_f32_16x16x32_bf16 v[24:27], v[180:183], v[196:199], v[24:27]
	v_mfma_f32_16x16x32_bf16 v[12:15], v[172:175], v[204:207], v[12:15]
	v_mfma_f32_16x16x32_bf16 v[8:11], v[180:183], v[204:207], v[8:11]
	v_mfma_f32_16x16x32_bf16 v[4:7], v[172:175], v[212:215], v[4:7]
	v_mfma_f32_16x16x32_bf16 v[0:3], v[180:183], v[212:215], v[0:3]
	s_setprio 0
	s_barrier
	s_add_i32 s68, s68, 2
	s_add_u32 s40, s40, 0x100
	s_addc_u32 s41, s41, 0
	s_add_u32 s65, s65, 0x100
	s_addc_u32 s67, s67, 0
	s_cmp_gt_u32 s68, 29
	s_cbranch_scc0 .LBB0_66
	s_and_b64 vcc, exec, s[26:27]
	s_cbranch_vccz .LBB0_69
	s_barrier

; #define PG8_STAGE(bufoff, gbase, voff) do { _Pragma("unroll") for (int _i = 0; _i < 2; ++_i) \
;         __builtin_amdgcn_global_load_lds((const unsigned*)((const char*)(gbase) + (voff)[_i]), (PG8_LAS unsigned*)(lds + (bufoff) + ldsw + _i * 8192), 16, 0, 0); } while (0)
; #define PG8_LDA(dst, b, h) do { _Pragma("unroll") for (int m = 0; m < 4; ++m) _Pragma("unroll") for (int k = 0; k < 2; ++k) dst[m][k] = *(const PG8_LAS bf16x8*)(lds + PG8_SA(b, h) + aoff + m * 2048 + k * 1024); } while (0)
; #define PG8_LDB(dst, b, h) do { _Pragma("unroll") for (int n = 0; n < 2; ++n) _Pragma("unroll") for (int k = 0; k < 2; ++k) dst[n][k] = *(const PG8_LAS bf16x8*)(lds + PG8_SB(b, h) + boff + n * 2048 + k * 1024); } while (0)
; #define PG8_SCHED __builtin_amdgcn_sched_barrier(0)
; template <class Epi, class Sched, bool ALIGN_EPI = false, bool SP2 = false>
; __device__ __forceinline__ void gemm_phase(PG8_LAS unsigned char* lds, const Gemm g, const Sched& S, const Epi& E) {
;     ...
;         for (int t = 0; t < nt; t += 2) {
;             const bool last = (t == nt - 2);
;             const char* a1 = cA + (size_t)(t + 1) * kstep;
;             const char* a2 = last ? nA : cA + (size_t)(t + 2) * kstep; const char* b2 = last ? nB : cB + (size_t)(t + 2) * kstep;
;             const char* a3 = a2 + kstep; const char* b3 = b2 + kstep;
;             if (last && has_next) S.a_ready(nxt);
;             if constexpr (SP2) {
;             PG8_LDB(B0, 0, 0); PG8_LDB(B1, 0, 1); PG8_SCHED; PG8_LDA(At, 0, 0); PG8_STAGE(PG8_SA(1, 1), a1 + hstep, voffA);
.LBB0_333:
	ds_read_b128 v[64:67], v211
	ds_read_b128 v[68:71], v211 offset:1024
	ds_read_b128 v[72:75], v211 offset:2048
	ds_read_b128 v[76:79], v211 offset:3072
	ds_read_b128 v[144:147], v212
	ds_read_b128 v[148:151], v212 offset:1024
	ds_read_b128 v[152:155], v212 offset:2048
	ds_read_b128 v[156:159], v212 offset:3072
	s_add_u32 s60, s58, 0xfff80080
	s_addc_u32 s61, s59, -1
	s_cmp_eq_u32 s81, 28
	s_cselect_b32 s63, s11, s61
	s_cselect_b32 s62, s51, s60
	s_cselect_b32 s61, s49, s80
	s_cselect_b32 s60, s78, s79

; #define PG8_STAGE(bufoff, gbase, voff) do { _Pragma("unroll") for (int _i = 0; _i < 2; ++_i) \
;         __builtin_amdgcn_global_load_lds((const unsigned*)((const char*)(gbase) + (voff)[_i]), (PG8_LAS unsigned*)(lds + (bufoff) + ldsw + _i * 8192), 16, 0, 0); } while (0)
; #define PG8_LDA(dst, b, h) do { _Pragma("unroll") for (int m = 0; m < 4; ++m) _Pragma("unroll") for (int k = 0; k < 2; ++k) dst[m][k] = *(const PG8_LAS bf16x8*)(lds + PG8_SA(b, h) + aoff + m * 2048 + k * 1024); } while (0)
; #define PG8_LDB(dst, b, h) do { _Pragma("unroll") for (int n = 0; n < 2; ++n) _Pragma("unroll") for (int k = 0; k < 2; ++k) dst[n][k] = *(const PG8_LAS bf16x8*)(lds + PG8_SB(b, h) + boff + n * 2048 + k * 1024); } while (0)
; #define PG8_SCHED __builtin_amdgcn_sched_barrier(0)
; template <class Epi, class Sched, bool ALIGN_EPI = false, bool SP2 = false>
; __device__ __forceinline__ void gemm_phase(PG8_LAS unsigned char* lds, const Gemm g, const Sched& S, const Epi& E) {
;     ...
;             PG8_LDB(B0, 0, 0); PG8_LDB(B1, 0, 1); PG8_SCHED; PG8_LDA(At, 0, 0); PG8_STAGE(PG8_SA(1, 1), a1 + hstep, voffA);
	s_add_i32 m0, s57, 0xc000
	ds_read_b128 v[176:179], v213
	ds_read_b128 v[180:183], v213 offset:1024
	ds_read_b128 v[184:187], v213 offset:2048
	ds_read_b128 v[188:191], v213 offset:3072
	ds_read_b128 v[192:195], v213 offset:4096
	ds_read_b128 v[196:199], v213 offset:5120
	ds_read_b128 v[200:203], v213 offset:6144
	ds_read_b128 v[204:207], v213 offset:7168
	global_load_lds_dwordx4 v168, s[58:59]

; #define PG8_STAGE(bufoff, gbase, voff) do { _Pragma("unroll") for (int _i = 0; _i < 2; ++_i) \
;         __builtin_amdgcn_global_load_lds((const unsigned*)((const char*)(gbase) + (voff)[_i]), (PG8_LAS unsigned*)(lds + (bufoff) + ldsw + _i * 8192), 16, 0, 0); } while (0)
; #define PG8_LDA(dst, b, h) do { _Pragma("unroll") for (int m = 0; m < 4; ++m) _Pragma("unroll") for (int k = 0; k < 2; ++k) dst[m][k] = *(const PG8_LAS bf16x8*)(lds + PG8_SA(b, h) + aoff + m * 2048 + k * 1024); } while (0)
; #define PG8_LDB(dst, b, h) do { _Pragma("unroll") for (int n = 0; n < 2; ++n) _Pragma("unroll") for (int k = 0; k < 2; ++k) dst[n][k] = *(const PG8_LAS bf16x8*)(lds + PG8_SB(b, h) + boff + n * 2048 + k * 1024); } while (0)
; #define PG8_MMA(ai, bj, At, Bt) do { __builtin_amdgcn_s_setprio(1); _Pragma("unroll") for (int m = 0; m < 4; ++m) _Pragma("unroll") for (int n = 0; n < 2; ++n) _Pragma("unroll") for (int k = 0; k < 2; ++k) \
;         acc[ai][bj][m][n] = __builtin_amdgcn_mfma_f32_16x16x32_bf16(Bt[n][k], At[m][k], acc[ai][bj][m][n], 0, 0, 0); __builtin_amdgcn_s_setprio(0); } while (0)
; #define PG8_WAIT_V(n) asm volatile("s_waitcnt vmcnt(" #n ")" ::: "memory")
; #define PG8_WAIT_L(n) asm volatile("s_waitcnt lgkmcnt(" #n ")" ::: "memory")
; #define PG8_BAR __builtin_amdgcn_s_barrier()
; #define PG8_SCHED __builtin_amdgcn_sched_barrier(0)
; template <class Epi, class Sched, bool ALIGN_EPI = false, bool SP2 = false>
; __device__ __forceinline__ void gemm_phase(PG8_LAS unsigned char* lds, const Gemm g, const Sched& S, const Epi& E) {
;     ...
;             PG8_LDB(B0, 0, 0); PG8_LDB(B1, 0, 1); PG8_SCHED; PG8_LDA(At, 0, 0); PG8_STAGE(PG8_SA(1, 1), a1 + hstep, voffA);
;             PG8_WAIT_V(8); PG8_WAIT_L(0); PG8_BAR; PG8_MMA(0, 0, At, B0); PG8_MMA(0, 1, At, B1); PG8_BAR; PG8_SCHED;
	s_add_i32 m0, s57, 0xe000
	s_nop 0
	global_load_lds_dwordx4 v170, s[58:59]
	s_waitcnt vmcnt(8)
	s_waitcnt lgkmcnt(0)
	s_setprio 1
	s_barrier

; #define PG8_MMA(ai, bj, At, Bt) do { __builtin_amdgcn_s_setprio(1); _Pragma("unroll") for (int m = 0; m < 4; ++m) _Pragma("unroll") for (int n = 0; n < 2; ++n) _Pragma("unroll") for (int k = 0; k < 2; ++k) \
;         acc[ai][bj][m][n] = __builtin_amdgcn_mfma_f32_16x16x32_bf16(Bt[n][k], At[m][k], acc[ai][bj][m][n], 0, 0, 0); __builtin_amdgcn_s_setprio(0); } while (0)
; #define PG8_WAIT_V(n) asm volatile("s_waitcnt vmcnt(" #n ")" ::: "memory")
; #define PG8_WAIT_L(n) asm volatile("s_waitcnt lgkmcnt(" #n ")" ::: "memory")
; #define PG8_BAR __builtin_amdgcn_s_barrier()
; #define PG8_SCHED __builtin_amdgcn_sched_barrier(0)
; template <class Epi, class Sched, bool ALIGN_EPI = false, bool SP2 = false>
; __device__ __forceinline__ void gemm_phase(PG8_LAS unsigned char* lds, const Gemm g, const Sched& S, const Epi& E) {
;     ...
;             PG8_WAIT_V(8); PG8_WAIT_L(0); PG8_BAR; PG8_MMA(0, 0, At, B0); PG8_MMA(0, 1, At, B1); PG8_BAR; PG8_SCHED;
	v_mfma_f32_16x16x32_bf16 v[140:143], v[64:67], v[176:179], v[140:143]
	v_mfma_f32_16x16x32_bf16 v[136:139], v[72:75], v[176:179], v[136:139]
	v_mfma_f32_16x16x32_bf16 v[124:127], v[64:67], v[184:187], v[124:127]
	v_mfma_f32_16x16x32_bf16 v[120:123], v[72:75], v[184:187], v[120:123]
	v_mfma_f32_16x16x32_bf16 v[108:111], v[64:67], v[192:195], v[108:111]
	v_mfma_f32_16x16x32_bf16 v[104:107], v[72:75], v[192:195], v[104:107]
	v_mfma_f32_16x16x32_bf16 v[92:95], v[64:67], v[200:203], v[92:95]
	v_mfma_f32_16x16x32_bf16 v[88:91], v[72:75], v[200:203], v[88:91]
	v_mfma_f32_16x16x32_bf16 v[140:143], v[68:71], v[180:183], v[140:143]
	v_mfma_f32_16x16x32_bf16 v[136:139], v[76:79], v[180:183], v[136:139]
	v_mfma_f32_16x16x32_bf16 v[124:127], v[68:71], v[188:191], v[124:127]
	v_mfma_f32_16x16x32_bf16 v[120:123], v[76:79], v[188:191], v[120:123]
	v_mfma_f32_16x16x32_bf16 v[108:111], v[68:71], v[196:199], v[108:111]
	v_mfma_f32_16x16x32_bf16 v[104:107], v[76:79], v[196:199], v[104:107]
	v_mfma_f32_16x16x32_bf16 v[92:95], v[68:71], v[204:207], v[92:95]
	v_mfma_f32_16x16x32_bf16 v[88:91], v[76:79], v[204:207], v[88:91]


; #define PG8_STAGE(bufoff, gbase, voff) do { _Pragma("unroll") for (int _i = 0; _i < 2; ++_i) \
;         __builtin_amdgcn_global_load_lds((const unsigned*)((const char*)(gbase) + (voff)[_i]), (PG8_LAS unsigned*)(lds + (bufoff) + ldsw + _i * 8192), 16, 0, 0); } while (0)
; #define PG8_LDA(dst, b, h) do { _Pragma("unroll") for (int m = 0; m < 4; ++m) _Pragma("unroll") for (int k = 0; k < 2; ++k) dst[m][k] = *(const PG8_LAS bf16x8*)(lds + PG8_SA(b, h) + aoff + m * 2048 + k * 1024); } while (0)
; #define PG8_MMA(ai, bj, At, Bt) do { __builtin_amdgcn_s_setprio(1); _Pragma("unroll") for (int m = 0; m < 4; ++m) _Pragma("unroll") for (int n = 0; n < 2; ++n) _Pragma("unroll") for (int k = 0; k < 2; ++k) \
;         acc[ai][bj][m][n] = __builtin_amdgcn_mfma_f32_16x16x32_bf16(Bt[n][k], At[m][k], acc[ai][bj][m][n], 0, 0, 0); __builtin_amdgcn_s_setprio(0); } while (0)
; #define PG8_WAIT_V(n) asm volatile("s_waitcnt vmcnt(" #n ")" ::: "memory")
; #define PG8_WAIT_L(n) asm volatile("s_waitcnt lgkmcnt(" #n ")" ::: "memory")
; #define PG8_BAR __builtin_amdgcn_s_barrier()
; #define PG8_SCHED __builtin_amdgcn_sched_barrier(0)
; template <class Epi, class Sched, bool ALIGN_EPI = false, bool SP2 = false>
; __device__ __forceinline__ void gemm_phase(PG8_LAS unsigned char* lds, const Gemm g, const Sched& S, const Epi& E) {
;     ...
;             PG8_WAIT_V(8); PG8_WAIT_L(0); PG8_BAR; PG8_MMA(0, 0, At, B0); PG8_MMA(0, 1, At, B1); PG8_BAR; PG8_SCHED;
;             PG8_LDA(At, 0, 1); PG8_STAGE(PG8_SB(0, 0), b2, voffB); PG8_STAGE(PG8_SB(0, 1), b2 + hstep, voffB); PG8_STAGE(PG8_SA(0, 0), a2, voffA);
	v_mfma_f32_16x16x32_bf16 v[132:135], v[144:147], v[176:179], v[132:135]
	v_mfma_f32_16x16x32_bf16 v[128:131], v[152:155], v[176:179], v[128:131]
	v_mfma_f32_16x16x32_bf16 v[116:119], v[144:147], v[184:187], v[116:119]
	v_mfma_f32_16x16x32_bf16 v[112:115], v[152:155], v[184:187], v[112:115]
	v_mfma_f32_16x16x32_bf16 v[100:103], v[144:147], v[192:195], v[100:103]
	v_mfma_f32_16x16x32_bf16 v[96:99], v[152:155], v[192:195], v[96:99]
	v_mfma_f32_16x16x32_bf16 v[84:87], v[144:147], v[200:203], v[84:87]
	v_mfma_f32_16x16x32_bf16 v[80:83], v[152:155], v[200:203], v[80:83]
	v_mfma_f32_16x16x32_bf16 v[132:135], v[148:151], v[180:183], v[132:135]
	v_mfma_f32_16x16x32_bf16 v[128:131], v[156:159], v[180:183], v[128:131]
	v_mfma_f32_16x16x32_bf16 v[116:119], v[148:151], v[188:191], v[116:119]
	v_mfma_f32_16x16x32_bf16 v[112:115], v[156:159], v[188:191], v[112:115]
	v_mfma_f32_16x16x32_bf16 v[100:103], v[148:151], v[196:199], v[100:103]
	v_mfma_f32_16x16x32_bf16 v[96:99], v[156:159], v[196:199], v[96:99]
	v_mfma_f32_16x16x32_bf16 v[84:87], v[148:151], v[204:207], v[84:87]
	v_mfma_f32_16x16x32_bf16 v[80:83], v[156:159], v[204:207], v[80:83]
	s_setprio 0
	s_barrier
	s_add_i32 s82, s75, s64
	s_mov_b64 s[96:97], s[60:61]

; #define PG8_STAGE(bufoff, gbase, voff) do { _Pragma("unroll") for (int _i = 0; _i < 2; ++_i) \
;         __builtin_amdgcn_global_load_lds((const unsigned*)((const char*)(gbase) + (voff)[_i]), (PG8_LAS unsigned*)(lds + (bufoff) + ldsw + _i * 8192), 16, 0, 0); } while (0)
; #define PG8_LDA(dst, b, h) do { _Pragma("unroll") for (int m = 0; m < 4; ++m) _Pragma("unroll") for (int k = 0; k < 2; ++k) dst[m][k] = *(const PG8_LAS bf16x8*)(lds + PG8_SA(b, h) + aoff + m * 2048 + k * 1024); } while (0)
; template <class Epi, class Sched, bool ALIGN_EPI = false, bool SP2 = false>
; __device__ __forceinline__ void gemm_phase(PG8_LAS unsigned char* lds, const Gemm g, const Sched& S, const Epi& E) {
;     ...
;             PG8_LDA(At, 0, 1); PG8_STAGE(PG8_SB(0, 0), b2, voffB); PG8_STAGE(PG8_SB(0, 1), b2 + hstep, voffB); PG8_STAGE(PG8_SA(0, 0), a2, voffA);
	s_mov_b32 m0, s82
	ds_read_b128 v[176:179], v213 offset:16384
	ds_read_b128 v[180:183], v213 offset:17408
	ds_read_b128 v[184:187], v213 offset:18432
	ds_read_b128 v[188:191], v213 offset:19456
	ds_read_b128 v[192:195], v213 offset:20480
	ds_read_b128 v[196:199], v213 offset:21504
	ds_read_b128 v[200:203], v213 offset:22528
	ds_read_b128 v[204:207], v213 offset:23552
	global_load_lds_dwordx4 v162, s[60:61]
	s_add_i32 m0, s82, 0x2000
	s_add_u32 s82, s60, 0x80000

; #define PG8_STAGE(bufoff, gbase, voff) do { _Pragma("unroll") for (int _i = 0; _i < 2; ++_i) \
;         __builtin_amdgcn_global_load_lds((const unsigned*)((const char*)(gbase) + (voff)[_i]), (PG8_LAS unsigned*)(lds + (bufoff) + ldsw + _i * 8192), 16, 0, 0); } while (0)
; #define PG8_LDA(dst, b, h) do { _Pragma("unroll") for (int m = 0; m < 4; ++m) _Pragma("unroll") for (int k = 0; k < 2; ++k) dst[m][k] = *(const PG8_LAS bf16x8*)(lds + PG8_SA(b, h) + aoff + m * 2048 + k * 1024); } while (0)
; template <class Epi, class Sched, bool ALIGN_EPI = false, bool SP2 = false>
; __device__ __forceinline__ void gemm_phase(PG8_LAS unsigned char* lds, const Gemm g, const Sched& S, const Epi& E) {
;     ...
;             PG8_LDA(At, 0, 1); PG8_STAGE(PG8_SB(0, 0), b2, voffB); PG8_STAGE(PG8_SB(0, 1), b2 + hstep, voffB); PG8_STAGE(PG8_SA(0, 0), a2, voffA);
	s_addc_u32 s83, s61, 0
	s_add_i32 s84, s76, s64
	global_load_lds_dwordx4 v166, s[60:61]

; #define PG8_STAGE(bufoff, gbase, voff) do { _Pragma("unroll") for (int _i = 0; _i < 2; ++_i) \
;         __builtin_amdgcn_global_load_lds((const unsigned*)((const char*)(gbase) + (voff)[_i]), (PG8_LAS unsigned*)(lds + (bufoff) + ldsw + _i * 8192), 16, 0, 0); } while (0)
; #define PG8_LDA(dst, b, h) do { _Pragma("unroll") for (int m = 0; m < 4; ++m) _Pragma("unroll") for (int k = 0; k < 2; ++k) dst[m][k] = *(const PG8_LAS bf16x8*)(lds + PG8_SA(b, h) + aoff + m * 2048 + k * 1024); } while (0)
; template <class Epi, class Sched, bool ALIGN_EPI = false, bool SP2 = false>
; __device__ __forceinline__ void gemm_phase(PG8_LAS unsigned char* lds, const Gemm g, const Sched& S, const Epi& E) {
;     ...
;             PG8_LDA(At, 0, 1); PG8_STAGE(PG8_SB(0, 0), b2, voffB); PG8_STAGE(PG8_SB(0, 1), b2 + hstep, voffB); PG8_STAGE(PG8_SA(0, 0), a2, voffA);
	s_mov_b32 m0, s84
	s_nop 0
	global_load_lds_dwordx4 v162, s[82:83]

; #define PG8_STAGE(bufoff, gbase, voff) do { _Pragma("unroll") for (int _i = 0; _i < 2; ++_i) \
;         __builtin_amdgcn_global_load_lds((const unsigned*)((const char*)(gbase) + (voff)[_i]), (PG8_LAS unsigned*)(lds + (bufoff) + ldsw + _i * 8192), 16, 0, 0); } while (0)
; #define PG8_LDA(dst, b, h) do { _Pragma("unroll") for (int m = 0; m < 4; ++m) _Pragma("unroll") for (int k = 0; k < 2; ++k) dst[m][k] = *(const PG8_LAS bf16x8*)(lds + PG8_SA(b, h) + aoff + m * 2048 + k * 1024); } while (0)
; template <class Epi, class Sched, bool ALIGN_EPI = false, bool SP2 = false>
; __device__ __forceinline__ void gemm_phase(PG8_LAS unsigned char* lds, const Gemm g, const Sched& S, const Epi& E) {
;     ...
;             PG8_LDA(At, 0, 1); PG8_STAGE(PG8_SB(0, 0), b2, voffB); PG8_STAGE(PG8_SB(0, 1), b2 + hstep, voffB); PG8_STAGE(PG8_SA(0, 0), a2, voffA);
	s_add_i32 m0, s84, 0x2000
	s_nop 0
	global_load_lds_dwordx4 v166, s[82:83]
	s_mov_b64 s[98:99], s[62:63]

; #define PG8_STAGE(bufoff, gbase, voff) do { _Pragma("unroll") for (int _i = 0; _i < 2; ++_i) \
;         __builtin_amdgcn_global_load_lds((const unsigned*)((const char*)(gbase) + (voff)[_i]), (PG8_LAS unsigned*)(lds + (bufoff) + ldsw + _i * 8192), 16, 0, 0); } while (0)
; #define PG8_LDA(dst, b, h) do { _Pragma("unroll") for (int m = 0; m < 4; ++m) _Pragma("unroll") for (int k = 0; k < 2; ++k) dst[m][k] = *(const PG8_LAS bf16x8*)(lds + PG8_SA(b, h) + aoff + m * 2048 + k * 1024); } while (0)
; #define PG8_MMA(ai, bj, At, Bt) do { __builtin_amdgcn_s_setprio(1); _Pragma("unroll") for (int m = 0; m < 4; ++m) _Pragma("unroll") for (int n = 0; n < 2; ++n) _Pragma("unroll") for (int k = 0; k < 2; ++k) \
;         acc[ai][bj][m][n] = __builtin_amdgcn_mfma_f32_16x16x32_bf16(Bt[n][k], At[m][k], acc[ai][bj][m][n], 0, 0, 0); __builtin_amdgcn_s_setprio(0); } while (0)
; #define PG8_WAIT_V(n) asm volatile("s_waitcnt vmcnt(" #n ")" ::: "memory")
; #define PG8_WAIT_L(n) asm volatile("s_waitcnt lgkmcnt(" #n ")" ::: "memory")
; #define PG8_BAR __builtin_amdgcn_s_barrier()
; #define PG8_SCHED __builtin_amdgcn_sched_barrier(0)
; template <class Epi, class Sched, bool ALIGN_EPI = false, bool SP2 = false>
; __device__ __forceinline__ void gemm_phase(PG8_LAS unsigned char* lds, const Gemm g, const Sched& S, const Epi& E) {
;     ...
;             PG8_LDA(At, 0, 1); PG8_STAGE(PG8_SB(0, 0), b2, voffB); PG8_STAGE(PG8_SB(0, 1), b2 + hstep, voffB); PG8_STAGE(PG8_SA(0, 0), a2, voffA);
;             PG8_WAIT_V(8); PG8_WAIT_L(0); PG8_BAR; PG8_MMA(1, 0, At, B0); PG8_MMA(1, 1, At, B1); PG8_BAR; PG8_SCHED;
	s_mov_b32 m0, s57
	s_nop 0
	global_load_lds_dwordx4 v160, s[62:63]
	s_mov_b32 m0, s65
	s_nop 0
	global_load_lds_dwordx4 v164, s[62:63]
	s_waitcnt vmcnt(8)
	s_waitcnt lgkmcnt(0)
	s_setprio 1
	s_barrier

; #define PG8_MMA(ai, bj, At, Bt) do { __builtin_amdgcn_s_setprio(1); _Pragma("unroll") for (int m = 0; m < 4; ++m) _Pragma("unroll") for (int n = 0; n < 2; ++n) _Pragma("unroll") for (int k = 0; k < 2; ++k) \
;         acc[ai][bj][m][n] = __builtin_amdgcn_mfma_f32_16x16x32_bf16(Bt[n][k], At[m][k], acc[ai][bj][m][n], 0, 0, 0); __builtin_amdgcn_s_setprio(0); } while (0)
; #define PG8_WAIT_V(n) asm volatile("s_waitcnt vmcnt(" #n ")" ::: "memory")
; #define PG8_WAIT_L(n) asm volatile("s_waitcnt lgkmcnt(" #n ")" ::: "memory")
; #define PG8_BAR __builtin_amdgcn_s_barrier()
; #define PG8_SCHED __builtin_amdgcn_sched_barrier(0)
; template <class Epi, class Sched, bool ALIGN_EPI = false, bool SP2 = false>
; __device__ __forceinline__ void gemm_phase(PG8_LAS unsigned char* lds, const Gemm g, const Sched& S, const Epi& E) {
;     ...
;             PG8_WAIT_V(8); PG8_WAIT_L(0); PG8_BAR; PG8_MMA(1, 0, At, B0); PG8_MMA(1, 1, At, B1); PG8_BAR; PG8_SCHED;
	v_mfma_f32_16x16x32_bf16 v[60:63], v[64:67], v[176:179], v[60:63]
	v_mfma_f32_16x16x32_bf16 v[56:59], v[72:75], v[176:179], v[56:59]
	v_mfma_f32_16x16x32_bf16 v[44:47], v[64:67], v[184:187], v[44:47]
	v_mfma_f32_16x16x32_bf16 v[40:43], v[72:75], v[184:187], v[40:43]
	v_mfma_f32_16x16x32_bf16 v[28:31], v[64:67], v[192:195], v[28:31]
	v_mfma_f32_16x16x32_bf16 v[24:27], v[72:75], v[192:195], v[24:27]
	v_mfma_f32_16x16x32_bf16 v[12:15], v[64:67], v[200:203], v[12:15]
	v_mfma_f32_16x16x32_bf16 v[8:11], v[72:75], v[200:203], v[8:11]
	v_mfma_f32_16x16x32_bf16 v[60:63], v[68:71], v[180:183], v[60:63]
	v_mfma_f32_16x16x32_bf16 v[56:59], v[76:79], v[180:183], v[56:59]
	v_mfma_f32_16x16x32_bf16 v[44:47], v[68:71], v[188:191], v[44:47]
	v_mfma_f32_16x16x32_bf16 v[40:43], v[76:79], v[188:191], v[40:43]
	v_mfma_f32_16x16x32_bf16 v[28:31], v[68:71], v[196:199], v[28:31]
	v_mfma_f32_16x16x32_bf16 v[24:27], v[76:79], v[196:199], v[24:27]
	v_mfma_f32_16x16x32_bf16 v[12:15], v[68:71], v[204:207], v[12:15]
	v_mfma_f32_16x16x32_bf16 v[8:11], v[76:79], v[204:207], v[8:11]


; #define PG8_STAGE(bufoff, gbase, voff) do { _Pragma("unroll") for (int _i = 0; _i < 2; ++_i) \
;         __builtin_amdgcn_global_load_lds((const unsigned*)((const char*)(gbase) + (voff)[_i]), (PG8_LAS unsigned*)(lds + (bufoff) + ldsw + _i * 8192), 16, 0, 0); } while (0)
; #define PG8_LDA(dst, b, h) do { _Pragma("unroll") for (int m = 0; m < 4; ++m) _Pragma("unroll") for (int k = 0; k < 2; ++k) dst[m][k] = *(const PG8_LAS bf16x8*)(lds + PG8_SA(b, h) + aoff + m * 2048 + k * 1024); } while (0)
; #define PG8_LDB(dst, b, h) do { _Pragma("unroll") for (int n = 0; n < 2; ++n) _Pragma("unroll") for (int k = 0; k < 2; ++k) dst[n][k] = *(const PG8_LAS bf16x8*)(lds + PG8_SB(b, h) + boff + n * 2048 + k * 1024); } while (0)
; #define PG8_MMA(ai, bj, At, Bt) do { __builtin_amdgcn_s_setprio(1); _Pragma("unroll") for (int m = 0; m < 4; ++m) _Pragma("unroll") for (int n = 0; n < 2; ++n) _Pragma("unroll") for (int k = 0; k < 2; ++k) \
;         acc[ai][bj][m][n] = __builtin_amdgcn_mfma_f32_16x16x32_bf16(Bt[n][k], At[m][k], acc[ai][bj][m][n], 0, 0, 0); __builtin_amdgcn_s_setprio(0); } while (0)
; #define PG8_WAIT_V(n) asm volatile("s_waitcnt vmcnt(" #n ")" ::: "memory")
; #define PG8_WAIT_L(n) asm volatile("s_waitcnt lgkmcnt(" #n ")" ::: "memory")
; #define PG8_BAR __builtin_amdgcn_s_barrier()
; #define PG8_SCHED __builtin_amdgcn_sched_barrier(0)
; template <class Epi, class Sched, bool ALIGN_EPI = false, bool SP2 = false>
; __device__ __forceinline__ void gemm_phase(PG8_LAS unsigned char* lds, const Gemm g, const Sched& S, const Epi& E) {
;     ...
;             PG8_WAIT_V(8); PG8_WAIT_L(0); PG8_BAR; PG8_MMA(1, 0, At, B0); PG8_MMA(1, 1, At, B1); PG8_BAR; PG8_SCHED;
;             PG8_LDB(B0, 1, 0); PG8_LDB(B1, 1, 1); PG8_SCHED; PG8_LDA(At, 1, 0); PG8_STAGE(PG8_SA(0, 1), a2 + hstep, voffA);
	v_mfma_f32_16x16x32_bf16 v[52:55], v[144:147], v[176:179], v[52:55]
	v_mfma_f32_16x16x32_bf16 v[48:51], v[152:155], v[176:179], v[48:51]
	v_mfma_f32_16x16x32_bf16 v[36:39], v[144:147], v[184:187], v[36:39]
	v_mfma_f32_16x16x32_bf16 v[32:35], v[152:155], v[184:187], v[32:35]
	v_mfma_f32_16x16x32_bf16 v[20:23], v[144:147], v[192:195], v[20:23]
	v_mfma_f32_16x16x32_bf16 v[16:19], v[152:155], v[192:195], v[16:19]
	v_mfma_f32_16x16x32_bf16 v[4:7], v[144:147], v[200:203], v[4:7]
	v_mfma_f32_16x16x32_bf16 v[0:3], v[152:155], v[200:203], v[0:3]
	v_mfma_f32_16x16x32_bf16 v[52:55], v[148:151], v[180:183], v[52:55]
	v_mfma_f32_16x16x32_bf16 v[48:51], v[156:159], v[180:183], v[48:51]
	v_mfma_f32_16x16x32_bf16 v[36:39], v[148:151], v[188:191], v[36:39]
	v_mfma_f32_16x16x32_bf16 v[32:35], v[156:159], v[188:191], v[32:35]
	v_mfma_f32_16x16x32_bf16 v[20:23], v[148:151], v[196:199], v[20:23]
	v_mfma_f32_16x16x32_bf16 v[16:19], v[156:159], v[196:199], v[16:19]
	v_mfma_f32_16x16x32_bf16 v[4:7], v[148:151], v[204:207], v[4:7]
	v_mfma_f32_16x16x32_bf16 v[0:3], v[156:159], v[204:207], v[0:3]
	s_setprio 0
	s_barrier
	s_add_i32 s82, 0, 0x18000
	s_add_i32 s83, 0, 0x1c000
	v_add_u32_e32 v76, s82, v209
	v_add_u32_e32 v156, s83, v209
	ds_read_b128 v[64:67], v76
	ds_read_b128 v[68:71], v76 offset:1024
	ds_read_b128 v[72:75], v76 offset:2048
	ds_read_b128 v[76:79], v76 offset:3072
	ds_read_b128 v[144:147], v156
	ds_read_b128 v[148:151], v156 offset:1024
	ds_read_b128 v[152:155], v156 offset:2048
	ds_read_b128 v[156:159], v156 offset:3072
	s_add_u32 s62, s62, 0x80000
	s_addc_u32 s63, s63, 0
	s_mov_b32 m0, s67

; #define PG8_STAGE(bufoff, gbase, voff) do { _Pragma("unroll") for (int _i = 0; _i < 2; ++_i) \
;         __builtin_amdgcn_global_load_lds((const unsigned*)((const char*)(gbase) + (voff)[_i]), (PG8_LAS unsigned*)(lds + (bufoff) + ldsw + _i * 8192), 16, 0, 0); } while (0)
; #define PG8_LDA(dst, b, h) do { _Pragma("unroll") for (int m = 0; m < 4; ++m) _Pragma("unroll") for (int k = 0; k < 2; ++k) dst[m][k] = *(const PG8_LAS bf16x8*)(lds + PG8_SA(b, h) + aoff + m * 2048 + k * 1024); } while (0)
; #define PG8_LDB(dst, b, h) do { _Pragma("unroll") for (int n = 0; n < 2; ++n) _Pragma("unroll") for (int k = 0; k < 2; ++k) dst[n][k] = *(const PG8_LAS bf16x8*)(lds + PG8_SB(b, h) + boff + n * 2048 + k * 1024); } while (0)
; #define PG8_SCHED __builtin_amdgcn_sched_barrier(0)
; template <class Epi, class Sched, bool ALIGN_EPI = false, bool SP2 = false>
; __device__ __forceinline__ void gemm_phase(PG8_LAS unsigned char* lds, const Gemm g, const Sched& S, const Epi& E) {
;     ...
;             PG8_LDB(B0, 1, 0); PG8_LDB(B1, 1, 1); PG8_SCHED; PG8_LDA(At, 1, 0); PG8_STAGE(PG8_SA(0, 1), a2 + hstep, voffA);
	ds_read_b128 v[176:179], v213 offset:32768
	ds_read_b128 v[180:183], v213 offset:33792
	ds_read_b128 v[184:187], v213 offset:34816
	ds_read_b128 v[188:191], v213 offset:35840
	ds_read_b128 v[192:195], v213 offset:36864
	ds_read_b128 v[196:199], v213 offset:37888
	ds_read_b128 v[200:203], v213 offset:38912
	ds_read_b128 v[204:207], v213 offset:39936
	global_load_lds_dwordx4 v160, s[62:63]

; #define PG8_STAGE(bufoff, gbase, voff) do { _Pragma("unroll") for (int _i = 0; _i < 2; ++_i) \
;         __builtin_amdgcn_global_load_lds((const unsigned*)((const char*)(gbase) + (voff)[_i]), (PG8_LAS unsigned*)(lds + (bufoff) + ldsw + _i * 8192), 16, 0, 0); } while (0)
; #define PG8_LDA(dst, b, h) do { _Pragma("unroll") for (int m = 0; m < 4; ++m) _Pragma("unroll") for (int k = 0; k < 2; ++k) dst[m][k] = *(const PG8_LAS bf16x8*)(lds + PG8_SA(b, h) + aoff + m * 2048 + k * 1024); } while (0)
; #define PG8_LDB(dst, b, h) do { _Pragma("unroll") for (int n = 0; n < 2; ++n) _Pragma("unroll") for (int k = 0; k < 2; ++k) dst[n][k] = *(const PG8_LAS bf16x8*)(lds + PG8_SB(b, h) + boff + n * 2048 + k * 1024); } while (0)
; #define PG8_MMA(ai, bj, At, Bt) do { __builtin_amdgcn_s_setprio(1); _Pragma("unroll") for (int m = 0; m < 4; ++m) _Pragma("unroll") for (int n = 0; n < 2; ++n) _Pragma("unroll") for (int k = 0; k < 2; ++k) \
;         acc[ai][bj][m][n] = __builtin_amdgcn_mfma_f32_16x16x32_bf16(Bt[n][k], At[m][k], acc[ai][bj][m][n], 0, 0, 0); __builtin_amdgcn_s_setprio(0); } while (0)
; #define PG8_WAIT_V(n) asm volatile("s_waitcnt vmcnt(" #n ")" ::: "memory")
; #define PG8_WAIT_L(n) asm volatile("s_waitcnt lgkmcnt(" #n ")" ::: "memory")
; #define PG8_BAR __builtin_amdgcn_s_barrier()
; #define PG8_SCHED __builtin_amdgcn_sched_barrier(0)
; template <class Epi, class Sched, bool ALIGN_EPI = false, bool SP2 = false>
; __device__ __forceinline__ void gemm_phase(PG8_LAS unsigned char* lds, const Gemm g, const Sched& S, const Epi& E) {
;     ...
;             PG8_LDB(B0, 1, 0); PG8_LDB(B1, 1, 1); PG8_SCHED; PG8_LDA(At, 1, 0); PG8_STAGE(PG8_SA(0, 1), a2 + hstep, voffA);
;             PG8_WAIT_V(8); PG8_WAIT_L(0); PG8_BAR; PG8_MMA(0, 0, At, B0); PG8_MMA(0, 1, At, B1); PG8_BAR; PG8_SCHED;
	s_mov_b32 m0, s68
	s_nop 0
	global_load_lds_dwordx4 v164, s[62:63]
	s_waitcnt vmcnt(8)
	s_waitcnt lgkmcnt(0)
	s_setprio 1
	s_barrier

; #define PG8_MMA(ai, bj, At, Bt) do { __builtin_amdgcn_s_setprio(1); _Pragma("unroll") for (int m = 0; m < 4; ++m) _Pragma("unroll") for (int n = 0; n < 2; ++n) _Pragma("unroll") for (int k = 0; k < 2; ++k) \
;         acc[ai][bj][m][n] = __builtin_amdgcn_mfma_f32_16x16x32_bf16(Bt[n][k], At[m][k], acc[ai][bj][m][n], 0, 0, 0); __builtin_amdgcn_s_setprio(0); } while (0)
; #define PG8_WAIT_V(n) asm volatile("s_waitcnt vmcnt(" #n ")" ::: "memory")
; #define PG8_WAIT_L(n) asm volatile("s_waitcnt lgkmcnt(" #n ")" ::: "memory")
; #define PG8_BAR __builtin_amdgcn_s_barrier()
; #define PG8_SCHED __builtin_amdgcn_sched_barrier(0)
; template <class Epi, class Sched, bool ALIGN_EPI = false, bool SP2 = false>
; __device__ __forceinline__ void gemm_phase(PG8_LAS unsigned char* lds, const Gemm g, const Sched& S, const Epi& E) {
;     ...
;             PG8_WAIT_V(8); PG8_WAIT_L(0); PG8_BAR; PG8_MMA(0, 0, At, B0); PG8_MMA(0, 1, At, B1); PG8_BAR; PG8_SCHED;
	v_mfma_f32_16x16x32_bf16 v[140:143], v[64:67], v[176:179], v[140:143]
	v_mfma_f32_16x16x32_bf16 v[136:139], v[72:75], v[176:179], v[136:139]
	v_mfma_f32_16x16x32_bf16 v[124:127], v[64:67], v[184:187], v[124:127]
	v_mfma_f32_16x16x32_bf16 v[120:123], v[72:75], v[184:187], v[120:123]
	v_mfma_f32_16x16x32_bf16 v[108:111], v[64:67], v[192:195], v[108:111]
	v_mfma_f32_16x16x32_bf16 v[104:107], v[72:75], v[192:195], v[104:107]
	v_mfma_f32_16x16x32_bf16 v[92:95], v[64:67], v[200:203], v[92:95]
	v_mfma_f32_16x16x32_bf16 v[88:91], v[72:75], v[200:203], v[88:91]
	v_mfma_f32_16x16x32_bf16 v[140:143], v[68:71], v[180:183], v[140:143]
	v_mfma_f32_16x16x32_bf16 v[136:139], v[76:79], v[180:183], v[136:139]
	v_mfma_f32_16x16x32_bf16 v[124:127], v[68:71], v[188:191], v[124:127]
	v_mfma_f32_16x16x32_bf16 v[120:123], v[76:79], v[188:191], v[120:123]
	v_mfma_f32_16x16x32_bf16 v[108:111], v[68:71], v[196:199], v[108:111]
	v_mfma_f32_16x16x32_bf16 v[104:107], v[76:79], v[196:199], v[104:107]
	v_mfma_f32_16x16x32_bf16 v[92:95], v[68:71], v[204:207], v[92:95]
	v_mfma_f32_16x16x32_bf16 v[88:91], v[76:79], v[204:207], v[88:91]


; #define PG8_STAGE(bufoff, gbase, voff) do { _Pragma("unroll") for (int _i = 0; _i < 2; ++_i) \
;         __builtin_amdgcn_global_load_lds((const unsigned*)((const char*)(gbase) + (voff)[_i]), (PG8_LAS unsigned*)(lds + (bufoff) + ldsw + _i * 8192), 16, 0, 0); } while (0)
; #define PG8_LDA(dst, b, h) do { _Pragma("unroll") for (int m = 0; m < 4; ++m) _Pragma("unroll") for (int k = 0; k < 2; ++k) dst[m][k] = *(const PG8_LAS bf16x8*)(lds + PG8_SA(b, h) + aoff + m * 2048 + k * 1024); } while (0)
; #define PG8_MMA(ai, bj, At, Bt) do { __builtin_amdgcn_s_setprio(1); _Pragma("unroll") for (int m = 0; m < 4; ++m) _Pragma("unroll") for (int n = 0; n < 2; ++n) _Pragma("unroll") for (int k = 0; k < 2; ++k) \
;         acc[ai][bj][m][n] = __builtin_amdgcn_mfma_f32_16x16x32_bf16(Bt[n][k], At[m][k], acc[ai][bj][m][n], 0, 0, 0); __builtin_amdgcn_s_setprio(0); } while (0)
; #define PG8_WAIT_V(n) asm volatile("s_waitcnt vmcnt(" #n ")" ::: "memory")
; #define PG8_WAIT_L(n) asm volatile("s_waitcnt lgkmcnt(" #n ")" ::: "memory")
; #define PG8_BAR __builtin_amdgcn_s_barrier()
; #define PG8_SCHED __builtin_amdgcn_sched_barrier(0)
; template <class Epi, class Sched, bool ALIGN_EPI = false, bool SP2 = false>
; __device__ __forceinline__ void gemm_phase(PG8_LAS unsigned char* lds, const Gemm g, const Sched& S, const Epi& E) {
;     ...
;             PG8_WAIT_V(8); PG8_WAIT_L(0); PG8_BAR; PG8_MMA(0, 0, At, B0); PG8_MMA(0, 1, At, B1); PG8_BAR; PG8_SCHED;
;             PG8_LDA(At, 1, 1); PG8_STAGE(PG8_SB(1, 0), b3, voffB); PG8_STAGE(PG8_SB(1, 1), b3 + hstep, voffB); PG8_STAGE(PG8_SA(1, 0), a3, voffA);
	v_mfma_f32_16x16x32_bf16 v[132:135], v[144:147], v[176:179], v[132:135]
	v_mfma_f32_16x16x32_bf16 v[128:131], v[152:155], v[176:179], v[128:131]
	v_mfma_f32_16x16x32_bf16 v[116:119], v[144:147], v[184:187], v[116:119]
	v_mfma_f32_16x16x32_bf16 v[112:115], v[152:155], v[184:187], v[112:115]
	v_mfma_f32_16x16x32_bf16 v[100:103], v[144:147], v[192:195], v[100:103]
	v_mfma_f32_16x16x32_bf16 v[96:99], v[152:155], v[192:195], v[96:99]
	v_mfma_f32_16x16x32_bf16 v[84:87], v[144:147], v[200:203], v[84:87]
	v_mfma_f32_16x16x32_bf16 v[80:83], v[152:155], v[200:203], v[80:83]
	v_mfma_f32_16x16x32_bf16 v[132:135], v[148:151], v[180:183], v[132:135]
	v_mfma_f32_16x16x32_bf16 v[128:131], v[156:159], v[180:183], v[128:131]
	v_mfma_f32_16x16x32_bf16 v[116:119], v[148:151], v[188:191], v[116:119]
	v_mfma_f32_16x16x32_bf16 v[112:115], v[156:159], v[188:191], v[112:115]
	v_mfma_f32_16x16x32_bf16 v[100:103], v[148:151], v[196:199], v[100:103]
	v_mfma_f32_16x16x32_bf16 v[96:99], v[156:159], v[196:199], v[96:99]
	v_mfma_f32_16x16x32_bf16 v[84:87], v[148:151], v[204:207], v[84:87]
	v_mfma_f32_16x16x32_bf16 v[80:83], v[156:159], v[204:207], v[80:83]
	s_setprio 0
	s_barrier
	s_add_i32 s62, s82, s64

; #define PG8_STAGE(bufoff, gbase, voff) do { _Pragma("unroll") for (int _i = 0; _i < 2; ++_i) \
;         __builtin_amdgcn_global_load_lds((const unsigned*)((const char*)(gbase) + (voff)[_i]), (PG8_LAS unsigned*)(lds + (bufoff) + ldsw + _i * 8192), 16, 0, 0); } while (0)
; #define PG8_LDA(dst, b, h) do { _Pragma("unroll") for (int m = 0; m < 4; ++m) _Pragma("unroll") for (int k = 0; k < 2; ++k) dst[m][k] = *(const PG8_LAS bf16x8*)(lds + PG8_SA(b, h) + aoff + m * 2048 + k * 1024); } while (0)
; template <class Epi, class Sched, bool ALIGN_EPI = false, bool SP2 = false>
; __device__ __forceinline__ void gemm_phase(PG8_LAS unsigned char* lds, const Gemm g, const Sched& S, const Epi& E) {
;     ...
;             PG8_LDA(At, 1, 1); PG8_STAGE(PG8_SB(1, 0), b3, voffB); PG8_STAGE(PG8_SB(1, 1), b3 + hstep, voffB); PG8_STAGE(PG8_SA(1, 0), a3, voffA);
	s_mov_b32 m0, s62
	ds_read_b128 v[176:179], v213 offset:49152
	ds_read_b128 v[180:183], v213 offset:50176
	ds_read_b128 v[184:187], v213 offset:51200
	ds_read_b128 v[188:191], v213 offset:52224
	ds_read_b128 v[192:195], v213 offset:53248
	ds_read_b128 v[196:199], v213 offset:54272
	ds_read_b128 v[200:203], v213 offset:55296
	ds_read_b128 v[204:207], v213 offset:56320
	global_load_lds_dwordx4 v250, s[96:97]
	s_add_i32 m0, s62, 0x2000
	s_add_u32 s60, s60, 0x80080

; #define PG8_STAGE(bufoff, gbase, voff) do { _Pragma("unroll") for (int _i = 0; _i < 2; ++_i) \
;         __builtin_amdgcn_global_load_lds((const unsigned*)((const char*)(gbase) + (voff)[_i]), (PG8_LAS unsigned*)(lds + (bufoff) + ldsw + _i * 8192), 16, 0, 0); } while (0)
; #define PG8_LDA(dst, b, h) do { _Pragma("unroll") for (int m = 0; m < 4; ++m) _Pragma("unroll") for (int k = 0; k < 2; ++k) dst[m][k] = *(const PG8_LAS bf16x8*)(lds + PG8_SA(b, h) + aoff + m * 2048 + k * 1024); } while (0)
; template <class Epi, class Sched, bool ALIGN_EPI = false, bool SP2 = false>
; __device__ __forceinline__ void gemm_phase(PG8_LAS unsigned char* lds, const Gemm g, const Sched& S, const Epi& E) {
;     ...
;             PG8_LDA(At, 1, 1); PG8_STAGE(PG8_SB(1, 0), b3, voffB); PG8_STAGE(PG8_SB(1, 1), b3 + hstep, voffB); PG8_STAGE(PG8_SA(1, 0), a3, voffA);
	s_addc_u32 s61, s61, 0
	s_add_i32 s62, s83, s64
	global_load_lds_dwordx4 v251, s[96:97]

; #define PG8_STAGE(bufoff, gbase, voff) do { _Pragma("unroll") for (int _i = 0; _i < 2; ++_i) \
;         __builtin_amdgcn_global_load_lds((const unsigned*)((const char*)(gbase) + (voff)[_i]), (PG8_LAS unsigned*)(lds + (bufoff) + ldsw + _i * 8192), 16, 0, 0); } while (0)
; #define PG8_LDA(dst, b, h) do { _Pragma("unroll") for (int m = 0; m < 4; ++m) _Pragma("unroll") for (int k = 0; k < 2; ++k) dst[m][k] = *(const PG8_LAS bf16x8*)(lds + PG8_SA(b, h) + aoff + m * 2048 + k * 1024); } while (0)
; template <class Epi, class Sched, bool ALIGN_EPI = false, bool SP2 = false>
; __device__ __forceinline__ void gemm_phase(PG8_LAS unsigned char* lds, const Gemm g, const Sched& S, const Epi& E) {
;     ...
;             PG8_LDA(At, 1, 1); PG8_STAGE(PG8_SB(1, 0), b3, voffB); PG8_STAGE(PG8_SB(1, 1), b3 + hstep, voffB); PG8_STAGE(PG8_SA(1, 0), a3, voffA);
	s_mov_b32 m0, s62
	s_nop 0
	global_load_lds_dwordx4 v162, s[60:61]

; #define PG8_STAGE(bufoff, gbase, voff) do { _Pragma("unroll") for (int _i = 0; _i < 2; ++_i) \
;         __builtin_amdgcn_global_load_lds((const unsigned*)((const char*)(gbase) + (voff)[_i]), (PG8_LAS unsigned*)(lds + (bufoff) + ldsw + _i * 8192), 16, 0, 0); } while (0)
; #define PG8_LDA(dst, b, h) do { _Pragma("unroll") for (int m = 0; m < 4; ++m) _Pragma("unroll") for (int k = 0; k < 2; ++k) dst[m][k] = *(const PG8_LAS bf16x8*)(lds + PG8_SA(b, h) + aoff + m * 2048 + k * 1024); } while (0)
; template <class Epi, class Sched, bool ALIGN_EPI = false, bool SP2 = false>
; __device__ __forceinline__ void gemm_phase(PG8_LAS unsigned char* lds, const Gemm g, const Sched& S, const Epi& E) {
;     ...
;             PG8_LDA(At, 1, 1); PG8_STAGE(PG8_SB(1, 0), b3, voffB); PG8_STAGE(PG8_SB(1, 1), b3 + hstep, voffB); PG8_STAGE(PG8_SA(1, 0), a3, voffA);
	s_add_i32 m0, s62, 0x2000
	s_nop 0
	global_load_lds_dwordx4 v166, s[60:61]

; #define PG8_STAGE(bufoff, gbase, voff) do { _Pragma("unroll") for (int _i = 0; _i < 2; ++_i) \
;         __builtin_amdgcn_global_load_lds((const unsigned*)((const char*)(gbase) + (voff)[_i]), (PG8_LAS unsigned*)(lds + (bufoff) + ldsw + _i * 8192), 16, 0, 0); } while (0)
; #define PG8_LDA(dst, b, h) do { _Pragma("unroll") for (int m = 0; m < 4; ++m) _Pragma("unroll") for (int k = 0; k < 2; ++k) dst[m][k] = *(const PG8_LAS bf16x8*)(lds + PG8_SA(b, h) + aoff + m * 2048 + k * 1024); } while (0)
; template <class Epi, class Sched, bool ALIGN_EPI = false, bool SP2 = false>
; __device__ __forceinline__ void gemm_phase(PG8_LAS unsigned char* lds, const Gemm g, const Sched& S, const Epi& E) {
;     ...
;             PG8_LDA(At, 1, 1); PG8_STAGE(PG8_SB(1, 0), b3, voffB); PG8_STAGE(PG8_SB(1, 1), b3 + hstep, voffB); PG8_STAGE(PG8_SA(1, 0), a3, voffA);
	s_mov_b32 m0, s70
	s_nop 0
	global_load_lds_dwordx4 v252, s[98:99]

; #define PG8_STAGE(bufoff, gbase, voff) do { _Pragma("unroll") for (int _i = 0; _i < 2; ++_i) \
;         __builtin_amdgcn_global_load_lds((const unsigned*)((const char*)(gbase) + (voff)[_i]), (PG8_LAS unsigned*)(lds + (bufoff) + ldsw + _i * 8192), 16, 0, 0); } while (0)
; #define PG8_LDA(dst, b, h) do { _Pragma("unroll") for (int m = 0; m < 4; ++m) _Pragma("unroll") for (int k = 0; k < 2; ++k) dst[m][k] = *(const PG8_LAS bf16x8*)(lds + PG8_SA(b, h) + aoff + m * 2048 + k * 1024); } while (0)
; #define PG8_MMA(ai, bj, At, Bt) do { __builtin_amdgcn_s_setprio(1); _Pragma("unroll") for (int m = 0; m < 4; ++m) _Pragma("unroll") for (int n = 0; n < 2; ++n) _Pragma("unroll") for (int k = 0; k < 2; ++k) \
;         acc[ai][bj][m][n] = __builtin_amdgcn_mfma_f32_16x16x32_bf16(Bt[n][k], At[m][k], acc[ai][bj][m][n], 0, 0, 0); __builtin_amdgcn_s_setprio(0); } while (0)
; #define PG8_WAIT_V(n) asm volatile("s_waitcnt vmcnt(" #n ")" ::: "memory")
; #define PG8_WAIT_L(n) asm volatile("s_waitcnt lgkmcnt(" #n ")" ::: "memory")
; #define PG8_BAR __builtin_amdgcn_s_barrier()
; #define PG8_SCHED __builtin_amdgcn_sched_barrier(0)
; template <class Epi, class Sched, bool ALIGN_EPI = false, bool SP2 = false>
; __device__ __forceinline__ void gemm_phase(PG8_LAS unsigned char* lds, const Gemm g, const Sched& S, const Epi& E) {
;     ...
;             PG8_LDA(At, 1, 1); PG8_STAGE(PG8_SB(1, 0), b3, voffB); PG8_STAGE(PG8_SB(1, 1), b3 + hstep, voffB); PG8_STAGE(PG8_SA(1, 0), a3, voffA);
;             PG8_WAIT_V(8); PG8_WAIT_L(0); PG8_BAR; PG8_MMA(1, 0, At, B0); PG8_MMA(1, 1, At, B1); PG8_BAR; PG8_SCHED;
	s_mov_b32 m0, s71
	s_nop 0
	global_load_lds_dwordx4 v253, s[98:99]
	s_waitcnt vmcnt(8)
	s_waitcnt lgkmcnt(0)
	s_setprio 1
	s_barrier

; #define PG8_MMA(ai, bj, At, Bt) do { __builtin_amdgcn_s_setprio(1); _Pragma("unroll") for (int m = 0; m < 4; ++m) _Pragma("unroll") for (int n = 0; n < 2; ++n) _Pragma("unroll") for (int k = 0; k < 2; ++k) \
;         acc[ai][bj][m][n] = __builtin_amdgcn_mfma_f32_16x16x32_bf16(Bt[n][k], At[m][k], acc[ai][bj][m][n], 0, 0, 0); __builtin_amdgcn_s_setprio(0); } while (0)
; #define PG8_WAIT_V(n) asm volatile("s_waitcnt vmcnt(" #n ")" ::: "memory")
; #define PG8_WAIT_L(n) asm volatile("s_waitcnt lgkmcnt(" #n ")" ::: "memory")
; #define PG8_BAR __builtin_amdgcn_s_barrier()
; #define PG8_SCHED __builtin_amdgcn_sched_barrier(0)
; template <class Epi, class Sched, bool ALIGN_EPI = false, bool SP2 = false>
; __device__ __forceinline__ void gemm_phase(PG8_LAS unsigned char* lds, const Gemm g, const Sched& S, const Epi& E) {
;     ...
;             PG8_WAIT_V(8); PG8_WAIT_L(0); PG8_BAR; PG8_MMA(1, 0, At, B0); PG8_MMA(1, 1, At, B1); PG8_BAR; PG8_SCHED;
	v_mfma_f32_16x16x32_bf16 v[60:63], v[64:67], v[176:179], v[60:63]
	v_mfma_f32_16x16x32_bf16 v[56:59], v[72:75], v[176:179], v[56:59]
	v_mfma_f32_16x16x32_bf16 v[44:47], v[64:67], v[184:187], v[44:47]
	v_mfma_f32_16x16x32_bf16 v[40:43], v[72:75], v[184:187], v[40:43]
	v_mfma_f32_16x16x32_bf16 v[28:31], v[64:67], v[192:195], v[28:31]
	v_mfma_f32_16x16x32_bf16 v[24:27], v[72:75], v[192:195], v[24:27]
	v_mfma_f32_16x16x32_bf16 v[12:15], v[64:67], v[200:203], v[12:15]
	v_mfma_f32_16x16x32_bf16 v[8:11], v[72:75], v[200:203], v[8:11]
	v_mfma_f32_16x16x32_bf16 v[60:63], v[68:71], v[180:183], v[60:63]
	v_mfma_f32_16x16x32_bf16 v[56:59], v[76:79], v[180:183], v[56:59]
	v_mfma_f32_16x16x32_bf16 v[44:47], v[68:71], v[188:191], v[44:47]
	v_mfma_f32_16x16x32_bf16 v[40:43], v[76:79], v[188:191], v[40:43]
	v_mfma_f32_16x16x32_bf16 v[28:31], v[68:71], v[196:199], v[28:31]
	v_mfma_f32_16x16x32_bf16 v[24:27], v[76:79], v[196:199], v[24:27]
	v_mfma_f32_16x16x32_bf16 v[12:15], v[68:71], v[204:207], v[12:15]
	v_mfma_f32_16x16x32_bf16 v[8:11], v[76:79], v[204:207], v[8:11]


; #define PG8_STAGE(bufoff, gbase, voff) do { _Pragma("unroll") for (int _i = 0; _i < 2; ++_i) \
;         __builtin_amdgcn_global_load_lds((const unsigned*)((const char*)(gbase) + (voff)[_i]), (PG8_LAS unsigned*)(lds + (bufoff) + ldsw + _i * 8192), 16, 0, 0); } while (0)
; #define PG8_LDA(dst, b, h) do { _Pragma("unroll") for (int m = 0; m < 4; ++m) _Pragma("unroll") for (int k = 0; k < 2; ++k) dst[m][k] = *(const PG8_LAS bf16x8*)(lds + PG8_SA(b, h) + aoff + m * 2048 + k * 1024); } while (0)
; #define PG8_LDB(dst, b, h) do { _Pragma("unroll") for (int n = 0; n < 2; ++n) _Pragma("unroll") for (int k = 0; k < 2; ++k) dst[n][k] = *(const PG8_LAS bf16x8*)(lds + PG8_SB(b, h) + boff + n * 2048 + k * 1024); } while (0)
; template <class Epi, class Sched, bool ALIGN_EPI = false, bool SP2 = false>
; __device__ __forceinline__ void gemm_phase(PG8_LAS unsigned char* lds, const Gemm g, const Sched& S, const Epi& E) {
;     ...
;         for (int t = 0; t < nt; t += 2) {
;             const bool last = (t == nt - 2);
;             const char* a1 = cA + (size_t)(t + 1) * kstep;
;             const char* a2 = last ? nA : cA + (size_t)(t + 2) * kstep; const char* b2 = last ? nB : cB + (size_t)(t + 2) * kstep;
;             const char* a3 = a2 + kstep; const char* b3 = b2 + kstep;
;             if (last && has_next) S.a_ready(nxt);
;             if constexpr (SP2) {
;             PG8_LDB(B0, 0, 0); PG8_LDB(B1, 0, 1); PG8_SCHED; PG8_LDA(At, 0, 0); PG8_STAGE(PG8_SA(1, 1), a1 + hstep, voffA);
;             PG8_WAIT_V(8); PG8_WAIT_L(0); PG8_BAR; PG8_MMA(0, 0, At, B0); PG8_MMA(0, 1, At, B1); PG8_BAR; PG8_SCHED;
;             PG8_LDA(At, 0, 1); PG8_STAGE(PG8_SB(0, 0), b2, voffB); PG8_STAGE(PG8_SB(0, 1), b2 + hstep, voffB); PG8_STAGE(PG8_SA(0, 0), a2, voffA);
;             PG8_WAIT_V(8); PG8_WAIT_L(0); PG8_BAR; PG8_MMA(1, 0, At, B0); PG8_MMA(1, 1, At, B1); PG8_BAR; PG8_SCHED;
;             PG8_LDB(B0, 1, 0); PG8_LDB(B1, 1, 1); PG8_SCHED; PG8_LDA(At, 1, 0); PG8_STAGE(PG8_SA(0, 1), a2 + hstep, voffA);
;             PG8_WAIT_V(8); PG8_WAIT_L(0); PG8_BAR; PG8_MMA(0, 0, At, B0); PG8_MMA(0, 1, At, B1); PG8_BAR; PG8_SCHED;
;             PG8_LDA(At, 1, 1); PG8_STAGE(PG8_SB(1, 0), b3, voffB); PG8_STAGE(PG8_SB(1, 1), b3 + hstep, voffB); PG8_STAGE(PG8_SA(1, 0), a3, voffA);
;             PG8_WAIT_V(8); PG8_WAIT_L(0); PG8_BAR; PG8_MMA(1, 0, At, B0); PG8_MMA(1, 1, At, B1); PG8_BAR; PG8_SCHED;
	v_mfma_f32_16x16x32_bf16 v[52:55], v[144:147], v[176:179], v[52:55]
	v_mfma_f32_16x16x32_bf16 v[48:51], v[152:155], v[176:179], v[48:51]
	v_mfma_f32_16x16x32_bf16 v[36:39], v[144:147], v[184:187], v[36:39]
	v_mfma_f32_16x16x32_bf16 v[32:35], v[152:155], v[184:187], v[32:35]
	v_mfma_f32_16x16x32_bf16 v[20:23], v[144:147], v[192:195], v[20:23]
	v_mfma_f32_16x16x32_bf16 v[16:19], v[152:155], v[192:195], v[16:19]
	v_mfma_f32_16x16x32_bf16 v[4:7], v[144:147], v[200:203], v[4:7]
	v_mfma_f32_16x16x32_bf16 v[0:3], v[152:155], v[200:203], v[0:3]
	v_mfma_f32_16x16x32_bf16 v[52:55], v[148:151], v[180:183], v[52:55]
	v_mfma_f32_16x16x32_bf16 v[48:51], v[156:159], v[180:183], v[48:51]
	v_mfma_f32_16x16x32_bf16 v[36:39], v[148:151], v[188:191], v[36:39]
	v_mfma_f32_16x16x32_bf16 v[32:35], v[156:159], v[188:191], v[32:35]
	v_mfma_f32_16x16x32_bf16 v[20:23], v[148:151], v[196:199], v[20:23]
	v_mfma_f32_16x16x32_bf16 v[16:19], v[156:159], v[196:199], v[16:19]
	v_mfma_f32_16x16x32_bf16 v[4:7], v[148:151], v[204:207], v[4:7]
	v_mfma_f32_16x16x32_bf16 v[0:3], v[156:159], v[204:207], v[0:3]
	s_setprio 0
	s_barrier
	s_add_i32 s81, s81, 2
	s_add_u32 s58, s58, 0x100
	s_addc_u32 s59, s59, 0
	s_add_u32 s79, s79, 0x100
	s_addc_u32 s80, s80, 0
	s_cmp_gt_u32 s81, 29
	s_cbranch_scc0 .LBB0_333
	s_and_b64 vcc, exec, s[42:43]
	s_cbranch_vccz .LBB0_336
	s_barrier

; #define PG8_STAGE(bufoff, gbase, voff) do { _Pragma("unroll") for (int _i = 0; _i < 2; ++_i) \
;         __builtin_amdgcn_global_load_lds((const unsigned*)((const char*)(gbase) + (voff)[_i]), (PG8_LAS unsigned*)(lds + (bufoff) + ldsw + _i * 8192), 16, 0, 0); } while (0)
; #define PG8_LDA(dst, b, h) do { _Pragma("unroll") for (int m = 0; m < 4; ++m) _Pragma("unroll") for (int k = 0; k < 2; ++k) dst[m][k] = *(const PG8_LAS bf16x8*)(lds + PG8_SA(b, h) + aoff + m * 2048 + k * 1024); } while (0)
; #define PG8_LDB(dst, b, h) do { _Pragma("unroll") for (int n = 0; n < 2; ++n) _Pragma("unroll") for (int k = 0; k < 2; ++k) dst[n][k] = *(const PG8_LAS bf16x8*)(lds + PG8_SB(b, h) + boff + n * 2048 + k * 1024); } while (0)
; #define PG8_SCHED __builtin_amdgcn_sched_barrier(0)
; template <class Epi, class Sched, bool ALIGN_EPI = false, bool SP2 = false>
; __device__ __forceinline__ void gemm_phase(PG8_LAS unsigned char* lds, const Gemm g, const Sched& S, const Epi& E) {
;     ...
;         for (int t = 0; t < nt; t += 2) {
;             const bool last = (t == nt - 2);
;             const char* a1 = cA + (size_t)(t + 1) * kstep;
;             const char* a2 = last ? nA : cA + (size_t)(t + 2) * kstep; const char* b2 = last ? nB : cB + (size_t)(t + 2) * kstep;
;             const char* a3 = a2 + kstep; const char* b3 = b2 + kstep;
;             if (last && has_next) S.a_ready(nxt);
;             if constexpr (SP2) {
;             PG8_LDB(B0, 0, 0); PG8_LDB(B1, 0, 1); PG8_SCHED; PG8_LDA(At, 0, 0); PG8_STAGE(PG8_SA(1, 1), a1 + hstep, voffA);
.LBB0_428:
	ds_read_b128 v[128:131], v201
	ds_read_b128 v[132:135], v201 offset:1024
	ds_read_b128 v[136:139], v201 offset:2048
	ds_read_b128 v[140:143], v201 offset:3072
	ds_read_b128 v[144:147], v205
	ds_read_b128 v[148:151], v205 offset:1024
	ds_read_b128 v[152:155], v205 offset:2048
	ds_read_b128 v[156:159], v205 offset:3072
	s_add_u32 s12, s10, 0xfff80080
	s_addc_u32 s13, s11, -1
	s_cmp_eq_u32 s85, 28
	s_cselect_b32 s61, s55, s13
	s_cselect_b32 s60, s81, s12
	s_cselect_b32 s13, s53, s84
	s_cselect_b32 s12, s82, s83

; #define PG8_STAGE(bufoff, gbase, voff) do { _Pragma("unroll") for (int _i = 0; _i < 2; ++_i) \
;         __builtin_amdgcn_global_load_lds((const unsigned*)((const char*)(gbase) + (voff)[_i]), (PG8_LAS unsigned*)(lds + (bufoff) + ldsw + _i * 8192), 16, 0, 0); } while (0)
; #define PG8_LDA(dst, b, h) do { _Pragma("unroll") for (int m = 0; m < 4; ++m) _Pragma("unroll") for (int k = 0; k < 2; ++k) dst[m][k] = *(const PG8_LAS bf16x8*)(lds + PG8_SA(b, h) + aoff + m * 2048 + k * 1024); } while (0)
; #define PG8_LDB(dst, b, h) do { _Pragma("unroll") for (int n = 0; n < 2; ++n) _Pragma("unroll") for (int k = 0; k < 2; ++k) dst[n][k] = *(const PG8_LAS bf16x8*)(lds + PG8_SB(b, h) + boff + n * 2048 + k * 1024); } while (0)
; #define PG8_SCHED __builtin_amdgcn_sched_barrier(0)
; template <class Epi, class Sched, bool ALIGN_EPI = false, bool SP2 = false>
; __device__ __forceinline__ void gemm_phase(PG8_LAS unsigned char* lds, const Gemm g, const Sched& S, const Epi& E) {
;     ...
;             PG8_LDB(B0, 0, 0); PG8_LDB(B1, 0, 1); PG8_SCHED; PG8_LDA(At, 0, 0); PG8_STAGE(PG8_SA(1, 1), a1 + hstep, voffA);
	s_add_i32 m0, s65, 0xc000
	ds_read_b128 v[176:179], v207
	ds_read_b128 v[184:187], v207 offset:1024
	ds_read_b128 v[190:193], v207 offset:2048
	ds_read_b128 v[210:213], v207 offset:3072
	ds_read_b128 v[214:217], v207 offset:4096
	ds_read_b128 v[218:221], v207 offset:5120
	ds_read_b128 v[222:225], v207 offset:6144
	ds_read_b128 v[226:229], v207 offset:7168
	global_load_lds_dwordx4 v168, s[10:11]

; #define PG8_STAGE(bufoff, gbase, voff) do { _Pragma("unroll") for (int _i = 0; _i < 2; ++_i) \
;         __builtin_amdgcn_global_load_lds((const unsigned*)((const char*)(gbase) + (voff)[_i]), (PG8_LAS unsigned*)(lds + (bufoff) + ldsw + _i * 8192), 16, 0, 0); } while (0)
; #define PG8_LDA(dst, b, h) do { _Pragma("unroll") for (int m = 0; m < 4; ++m) _Pragma("unroll") for (int k = 0; k < 2; ++k) dst[m][k] = *(const PG8_LAS bf16x8*)(lds + PG8_SA(b, h) + aoff + m * 2048 + k * 1024); } while (0)
; #define PG8_LDB(dst, b, h) do { _Pragma("unroll") for (int n = 0; n < 2; ++n) _Pragma("unroll") for (int k = 0; k < 2; ++k) dst[n][k] = *(const PG8_LAS bf16x8*)(lds + PG8_SB(b, h) + boff + n * 2048 + k * 1024); } while (0)
; #define PG8_MMA(ai, bj, At, Bt) do { __builtin_amdgcn_s_setprio(1); _Pragma("unroll") for (int m = 0; m < 4; ++m) _Pragma("unroll") for (int n = 0; n < 2; ++n) _Pragma("unroll") for (int k = 0; k < 2; ++k) \
;         acc[ai][bj][m][n] = __builtin_amdgcn_mfma_f32_16x16x32_bf16(Bt[n][k], At[m][k], acc[ai][bj][m][n], 0, 0, 0); __builtin_amdgcn_s_setprio(0); } while (0)
; #define PG8_WAIT_V(n) asm volatile("s_waitcnt vmcnt(" #n ")" ::: "memory")
; #define PG8_WAIT_L(n) asm volatile("s_waitcnt lgkmcnt(" #n ")" ::: "memory")
; #define PG8_BAR __builtin_amdgcn_s_barrier()
; #define PG8_SCHED __builtin_amdgcn_sched_barrier(0)
; template <class Epi, class Sched, bool ALIGN_EPI = false, bool SP2 = false>
; __device__ __forceinline__ void gemm_phase(PG8_LAS unsigned char* lds, const Gemm g, const Sched& S, const Epi& E) {
;     ...
;             PG8_LDB(B0, 0, 0); PG8_LDB(B1, 0, 1); PG8_SCHED; PG8_LDA(At, 0, 0); PG8_STAGE(PG8_SA(1, 1), a1 + hstep, voffA);
;             PG8_WAIT_V(8); PG8_WAIT_L(0); PG8_BAR; PG8_MMA(0, 0, At, B0); PG8_MMA(0, 1, At, B1); PG8_BAR; PG8_SCHED;
	s_add_i32 m0, s65, 0xe000
	s_nop 0
	global_load_lds_dwordx4 v170, s[10:11]
	s_waitcnt vmcnt(8)
	s_waitcnt lgkmcnt(0)
	s_setprio 1
	s_barrier

; #define PG8_MMA(ai, bj, At, Bt) do { __builtin_amdgcn_s_setprio(1); _Pragma("unroll") for (int m = 0; m < 4; ++m) _Pragma("unroll") for (int n = 0; n < 2; ++n) _Pragma("unroll") for (int k = 0; k < 2; ++k) \
;         acc[ai][bj][m][n] = __builtin_amdgcn_mfma_f32_16x16x32_bf16(Bt[n][k], At[m][k], acc[ai][bj][m][n], 0, 0, 0); __builtin_amdgcn_s_setprio(0); } while (0)
; #define PG8_WAIT_V(n) asm volatile("s_waitcnt vmcnt(" #n ")" ::: "memory")
; #define PG8_WAIT_L(n) asm volatile("s_waitcnt lgkmcnt(" #n ")" ::: "memory")
; #define PG8_BAR __builtin_amdgcn_s_barrier()
; #define PG8_SCHED __builtin_amdgcn_sched_barrier(0)
; template <class Epi, class Sched, bool ALIGN_EPI = false, bool SP2 = false>
; __device__ __forceinline__ void gemm_phase(PG8_LAS unsigned char* lds, const Gemm g, const Sched& S, const Epi& E) {
;     ...
;             PG8_WAIT_V(8); PG8_WAIT_L(0); PG8_BAR; PG8_MMA(0, 0, At, B0); PG8_MMA(0, 1, At, B1); PG8_BAR; PG8_SCHED;
	v_mfma_f32_16x16x32_bf16 v[124:127], v[128:131], v[176:179], v[124:127]
	v_mfma_f32_16x16x32_bf16 v[120:123], v[136:139], v[176:179], v[120:123]
	v_mfma_f32_16x16x32_bf16 v[108:111], v[128:131], v[190:193], v[108:111]
	v_mfma_f32_16x16x32_bf16 v[104:107], v[136:139], v[190:193], v[104:107]
	v_mfma_f32_16x16x32_bf16 v[92:95], v[128:131], v[214:217], v[92:95]
	v_mfma_f32_16x16x32_bf16 v[88:91], v[136:139], v[214:217], v[88:91]
	v_mfma_f32_16x16x32_bf16 v[76:79], v[128:131], v[222:225], v[76:79]
	v_mfma_f32_16x16x32_bf16 v[72:75], v[136:139], v[222:225], v[72:75]
	v_mfma_f32_16x16x32_bf16 v[124:127], v[132:135], v[184:187], v[124:127]
	v_mfma_f32_16x16x32_bf16 v[120:123], v[140:143], v[184:187], v[120:123]
	v_mfma_f32_16x16x32_bf16 v[108:111], v[132:135], v[210:213], v[108:111]
	v_mfma_f32_16x16x32_bf16 v[104:107], v[140:143], v[210:213], v[104:107]
	v_mfma_f32_16x16x32_bf16 v[92:95], v[132:135], v[218:221], v[92:95]
	v_mfma_f32_16x16x32_bf16 v[88:91], v[140:143], v[218:221], v[88:91]
	v_mfma_f32_16x16x32_bf16 v[76:79], v[132:135], v[226:229], v[76:79]
	v_mfma_f32_16x16x32_bf16 v[72:75], v[140:143], v[226:229], v[72:75]


; #define PG8_STAGE(bufoff, gbase, voff) do { _Pragma("unroll") for (int _i = 0; _i < 2; ++_i) \
;         __builtin_amdgcn_global_load_lds((const unsigned*)((const char*)(gbase) + (voff)[_i]), (PG8_LAS unsigned*)(lds + (bufoff) + ldsw + _i * 8192), 16, 0, 0); } while (0)
; #define PG8_LDA(dst, b, h) do { _Pragma("unroll") for (int m = 0; m < 4; ++m) _Pragma("unroll") for (int k = 0; k < 2; ++k) dst[m][k] = *(const PG8_LAS bf16x8*)(lds + PG8_SA(b, h) + aoff + m * 2048 + k * 1024); } while (0)
; #define PG8_MMA(ai, bj, At, Bt) do { __builtin_amdgcn_s_setprio(1); _Pragma("unroll") for (int m = 0; m < 4; ++m) _Pragma("unroll") for (int n = 0; n < 2; ++n) _Pragma("unroll") for (int k = 0; k < 2; ++k) \
;         acc[ai][bj][m][n] = __builtin_amdgcn_mfma_f32_16x16x32_bf16(Bt[n][k], At[m][k], acc[ai][bj][m][n], 0, 0, 0); __builtin_amdgcn_s_setprio(0); } while (0)
; #define PG8_WAIT_V(n) asm volatile("s_waitcnt vmcnt(" #n ")" ::: "memory")
; #define PG8_WAIT_L(n) asm volatile("s_waitcnt lgkmcnt(" #n ")" ::: "memory")
; #define PG8_BAR __builtin_amdgcn_s_barrier()
; #define PG8_SCHED __builtin_amdgcn_sched_barrier(0)
; template <class Epi, class Sched, bool ALIGN_EPI = false, bool SP2 = false>
; __device__ __forceinline__ void gemm_phase(PG8_LAS unsigned char* lds, const Gemm g, const Sched& S, const Epi& E) {
;     ...
;             PG8_WAIT_V(8); PG8_WAIT_L(0); PG8_BAR; PG8_MMA(0, 0, At, B0); PG8_MMA(0, 1, At, B1); PG8_BAR; PG8_SCHED;
;             PG8_LDA(At, 0, 1); PG8_STAGE(PG8_SB(0, 0), b2, voffB); PG8_STAGE(PG8_SB(0, 1), b2 + hstep, voffB); PG8_STAGE(PG8_SA(0, 0), a2, voffA);
	v_mfma_f32_16x16x32_bf16 v[116:119], v[144:147], v[176:179], v[116:119]
	v_mfma_f32_16x16x32_bf16 v[112:115], v[152:155], v[176:179], v[112:115]
	v_mfma_f32_16x16x32_bf16 v[100:103], v[144:147], v[190:193], v[100:103]
	v_mfma_f32_16x16x32_bf16 v[96:99], v[152:155], v[190:193], v[96:99]
	v_mfma_f32_16x16x32_bf16 v[84:87], v[144:147], v[214:217], v[84:87]
	v_mfma_f32_16x16x32_bf16 v[80:83], v[152:155], v[214:217], v[80:83]
	v_mfma_f32_16x16x32_bf16 v[68:71], v[144:147], v[222:225], v[68:71]
	v_mfma_f32_16x16x32_bf16 v[64:67], v[152:155], v[222:225], v[64:67]
	v_mfma_f32_16x16x32_bf16 v[116:119], v[148:151], v[184:187], v[116:119]
	v_mfma_f32_16x16x32_bf16 v[112:115], v[156:159], v[184:187], v[112:115]
	v_mfma_f32_16x16x32_bf16 v[100:103], v[148:151], v[210:213], v[100:103]
	v_mfma_f32_16x16x32_bf16 v[96:99], v[156:159], v[210:213], v[96:99]
	v_mfma_f32_16x16x32_bf16 v[84:87], v[148:151], v[218:221], v[84:87]
	v_mfma_f32_16x16x32_bf16 v[80:83], v[156:159], v[218:221], v[80:83]
	v_mfma_f32_16x16x32_bf16 v[68:71], v[148:151], v[226:229], v[68:71]
	v_mfma_f32_16x16x32_bf16 v[64:67], v[156:159], v[226:229], v[64:67]
	s_setprio 0
	s_barrier
	s_add_i32 s86, s75, s64
	s_mov_b64 s[96:97], s[12:13]

; #define PG8_STAGE(bufoff, gbase, voff) do { _Pragma("unroll") for (int _i = 0; _i < 2; ++_i) \
;         __builtin_amdgcn_global_load_lds((const unsigned*)((const char*)(gbase) + (voff)[_i]), (PG8_LAS unsigned*)(lds + (bufoff) + ldsw + _i * 8192), 16, 0, 0); } while (0)
; #define PG8_LDA(dst, b, h) do { _Pragma("unroll") for (int m = 0; m < 4; ++m) _Pragma("unroll") for (int k = 0; k < 2; ++k) dst[m][k] = *(const PG8_LAS bf16x8*)(lds + PG8_SA(b, h) + aoff + m * 2048 + k * 1024); } while (0)
; template <class Epi, class Sched, bool ALIGN_EPI = false, bool SP2 = false>
; __device__ __forceinline__ void gemm_phase(PG8_LAS unsigned char* lds, const Gemm g, const Sched& S, const Epi& E) {
;     ...
;             PG8_LDA(At, 0, 1); PG8_STAGE(PG8_SB(0, 0), b2, voffB); PG8_STAGE(PG8_SB(0, 1), b2 + hstep, voffB); PG8_STAGE(PG8_SA(0, 0), a2, voffA);
	s_mov_b32 m0, s86
	ds_read_b128 v[176:179], v207 offset:16384
	ds_read_b128 v[184:187], v207 offset:17408
	ds_read_b128 v[190:193], v207 offset:18432
	ds_read_b128 v[210:213], v207 offset:19456
	ds_read_b128 v[214:217], v207 offset:20480
	ds_read_b128 v[218:221], v207 offset:21504
	ds_read_b128 v[222:225], v207 offset:22528
	ds_read_b128 v[226:229], v207 offset:23552
	global_load_lds_dwordx4 v162, s[12:13]
	s_add_i32 m0, s86, 0x2000
	s_add_u32 s86, s12, 0x80000

; #define PG8_STAGE(bufoff, gbase, voff) do { _Pragma("unroll") for (int _i = 0; _i < 2; ++_i) \
;         __builtin_amdgcn_global_load_lds((const unsigned*)((const char*)(gbase) + (voff)[_i]), (PG8_LAS unsigned*)(lds + (bufoff) + ldsw + _i * 8192), 16, 0, 0); } while (0)
; #define PG8_LDA(dst, b, h) do { _Pragma("unroll") for (int m = 0; m < 4; ++m) _Pragma("unroll") for (int k = 0; k < 2; ++k) dst[m][k] = *(const PG8_LAS bf16x8*)(lds + PG8_SA(b, h) + aoff + m * 2048 + k * 1024); } while (0)
; template <class Epi, class Sched, bool ALIGN_EPI = false, bool SP2 = false>
; __device__ __forceinline__ void gemm_phase(PG8_LAS unsigned char* lds, const Gemm g, const Sched& S, const Epi& E) {
;     ...
;             PG8_LDA(At, 0, 1); PG8_STAGE(PG8_SB(0, 0), b2, voffB); PG8_STAGE(PG8_SB(0, 1), b2 + hstep, voffB); PG8_STAGE(PG8_SA(0, 0), a2, voffA);
	s_addc_u32 s87, s13, 0
	s_add_i32 s88, s76, s64
	global_load_lds_dwordx4 v166, s[12:13]

; #define PG8_STAGE(bufoff, gbase, voff) do { _Pragma("unroll") for (int _i = 0; _i < 2; ++_i) \
;         __builtin_amdgcn_global_load_lds((const unsigned*)((const char*)(gbase) + (voff)[_i]), (PG8_LAS unsigned*)(lds + (bufoff) + ldsw + _i * 8192), 16, 0, 0); } while (0)
; #define PG8_LDA(dst, b, h) do { _Pragma("unroll") for (int m = 0; m < 4; ++m) _Pragma("unroll") for (int k = 0; k < 2; ++k) dst[m][k] = *(const PG8_LAS bf16x8*)(lds + PG8_SA(b, h) + aoff + m * 2048 + k * 1024); } while (0)
; template <class Epi, class Sched, bool ALIGN_EPI = false, bool SP2 = false>
; __device__ __forceinline__ void gemm_phase(PG8_LAS unsigned char* lds, const Gemm g, const Sched& S, const Epi& E) {
;     ...
;             PG8_LDA(At, 0, 1); PG8_STAGE(PG8_SB(0, 0), b2, voffB); PG8_STAGE(PG8_SB(0, 1), b2 + hstep, voffB); PG8_STAGE(PG8_SA(0, 0), a2, voffA);
	s_mov_b32 m0, s88
	s_nop 0
	global_load_lds_dwordx4 v162, s[86:87]

; #define PG8_STAGE(bufoff, gbase, voff) do { _Pragma("unroll") for (int _i = 0; _i < 2; ++_i) \
;         __builtin_amdgcn_global_load_lds((const unsigned*)((const char*)(gbase) + (voff)[_i]), (PG8_LAS unsigned*)(lds + (bufoff) + ldsw + _i * 8192), 16, 0, 0); } while (0)
; #define PG8_LDA(dst, b, h) do { _Pragma("unroll") for (int m = 0; m < 4; ++m) _Pragma("unroll") for (int k = 0; k < 2; ++k) dst[m][k] = *(const PG8_LAS bf16x8*)(lds + PG8_SA(b, h) + aoff + m * 2048 + k * 1024); } while (0)
; template <class Epi, class Sched, bool ALIGN_EPI = false, bool SP2 = false>
; __device__ __forceinline__ void gemm_phase(PG8_LAS unsigned char* lds, const Gemm g, const Sched& S, const Epi& E) {
;     ...
;             PG8_LDA(At, 0, 1); PG8_STAGE(PG8_SB(0, 0), b2, voffB); PG8_STAGE(PG8_SB(0, 1), b2 + hstep, voffB); PG8_STAGE(PG8_SA(0, 0), a2, voffA);
	s_add_i32 m0, s88, 0x2000
	s_nop 0
	global_load_lds_dwordx4 v166, s[86:87]
	s_mov_b64 s[98:99], s[60:61]

; #define PG8_STAGE(bufoff, gbase, voff) do { _Pragma("unroll") for (int _i = 0; _i < 2; ++_i) \
;         __builtin_amdgcn_global_load_lds((const unsigned*)((const char*)(gbase) + (voff)[_i]), (PG8_LAS unsigned*)(lds + (bufoff) + ldsw + _i * 8192), 16, 0, 0); } while (0)
; #define PG8_LDA(dst, b, h) do { _Pragma("unroll") for (int m = 0; m < 4; ++m) _Pragma("unroll") for (int k = 0; k < 2; ++k) dst[m][k] = *(const PG8_LAS bf16x8*)(lds + PG8_SA(b, h) + aoff + m * 2048 + k * 1024); } while (0)
; #define PG8_MMA(ai, bj, At, Bt) do { __builtin_amdgcn_s_setprio(1); _Pragma("unroll") for (int m = 0; m < 4; ++m) _Pragma("unroll") for (int n = 0; n < 2; ++n) _Pragma("unroll") for (int k = 0; k < 2; ++k) \
;         acc[ai][bj][m][n] = __builtin_amdgcn_mfma_f32_16x16x32_bf16(Bt[n][k], At[m][k], acc[ai][bj][m][n], 0, 0, 0); __builtin_amdgcn_s_setprio(0); } while (0)
; #define PG8_WAIT_V(n) asm volatile("s_waitcnt vmcnt(" #n ")" ::: "memory")
; #define PG8_WAIT_L(n) asm volatile("s_waitcnt lgkmcnt(" #n ")" ::: "memory")
; #define PG8_BAR __builtin_amdgcn_s_barrier()
; #define PG8_SCHED __builtin_amdgcn_sched_barrier(0)
; template <class Epi, class Sched, bool ALIGN_EPI = false, bool SP2 = false>
; __device__ __forceinline__ void gemm_phase(PG8_LAS unsigned char* lds, const Gemm g, const Sched& S, const Epi& E) {
;     ...
;             PG8_LDA(At, 0, 1); PG8_STAGE(PG8_SB(0, 0), b2, voffB); PG8_STAGE(PG8_SB(0, 1), b2 + hstep, voffB); PG8_STAGE(PG8_SA(0, 0), a2, voffA);
;             PG8_WAIT_V(8); PG8_WAIT_L(0); PG8_BAR; PG8_MMA(1, 0, At, B0); PG8_MMA(1, 1, At, B1); PG8_BAR; PG8_SCHED;
	s_mov_b32 m0, s65
	s_nop 0
	global_load_lds_dwordx4 v160, s[60:61]
	s_mov_b32 m0, s67
	s_nop 0
	global_load_lds_dwordx4 v164, s[60:61]
	s_waitcnt vmcnt(8)
	s_waitcnt lgkmcnt(0)
	s_setprio 1
	s_barrier

; #define PG8_MMA(ai, bj, At, Bt) do { __builtin_amdgcn_s_setprio(1); _Pragma("unroll") for (int m = 0; m < 4; ++m) _Pragma("unroll") for (int n = 0; n < 2; ++n) _Pragma("unroll") for (int k = 0; k < 2; ++k) \
;         acc[ai][bj][m][n] = __builtin_amdgcn_mfma_f32_16x16x32_bf16(Bt[n][k], At[m][k], acc[ai][bj][m][n], 0, 0, 0); __builtin_amdgcn_s_setprio(0); } while (0)
; #define PG8_WAIT_V(n) asm volatile("s_waitcnt vmcnt(" #n ")" ::: "memory")
; #define PG8_WAIT_L(n) asm volatile("s_waitcnt lgkmcnt(" #n ")" ::: "memory")
; #define PG8_BAR __builtin_amdgcn_s_barrier()
; #define PG8_SCHED __builtin_amdgcn_sched_barrier(0)
; template <class Epi, class Sched, bool ALIGN_EPI = false, bool SP2 = false>
; __device__ __forceinline__ void gemm_phase(PG8_LAS unsigned char* lds, const Gemm g, const Sched& S, const Epi& E) {
;     ...
;             PG8_WAIT_V(8); PG8_WAIT_L(0); PG8_BAR; PG8_MMA(1, 0, At, B0); PG8_MMA(1, 1, At, B1); PG8_BAR; PG8_SCHED;
	v_mfma_f32_16x16x32_bf16 v[60:63], v[128:131], v[176:179], v[60:63]
	v_mfma_f32_16x16x32_bf16 v[56:59], v[136:139], v[176:179], v[56:59]
	v_mfma_f32_16x16x32_bf16 v[44:47], v[128:131], v[190:193], v[44:47]
	v_mfma_f32_16x16x32_bf16 v[40:43], v[136:139], v[190:193], v[40:43]
	v_mfma_f32_16x16x32_bf16 v[28:31], v[128:131], v[214:217], v[28:31]
	v_mfma_f32_16x16x32_bf16 v[24:27], v[136:139], v[214:217], v[24:27]
	v_mfma_f32_16x16x32_bf16 v[12:15], v[128:131], v[222:225], v[12:15]
	v_mfma_f32_16x16x32_bf16 v[8:11], v[136:139], v[222:225], v[8:11]
	v_mfma_f32_16x16x32_bf16 v[60:63], v[132:135], v[184:187], v[60:63]
	v_mfma_f32_16x16x32_bf16 v[56:59], v[140:143], v[184:187], v[56:59]
	v_mfma_f32_16x16x32_bf16 v[44:47], v[132:135], v[210:213], v[44:47]
	v_mfma_f32_16x16x32_bf16 v[40:43], v[140:143], v[210:213], v[40:43]
	v_mfma_f32_16x16x32_bf16 v[28:31], v[132:135], v[218:221], v[28:31]
	v_mfma_f32_16x16x32_bf16 v[24:27], v[140:143], v[218:221], v[24:27]
	v_mfma_f32_16x16x32_bf16 v[12:15], v[132:135], v[226:229], v[12:15]
	v_mfma_f32_16x16x32_bf16 v[8:11], v[140:143], v[226:229], v[8:11]


; #define PG8_STAGE(bufoff, gbase, voff) do { _Pragma("unroll") for (int _i = 0; _i < 2; ++_i) \
;         __builtin_amdgcn_global_load_lds((const unsigned*)((const char*)(gbase) + (voff)[_i]), (PG8_LAS unsigned*)(lds + (bufoff) + ldsw + _i * 8192), 16, 0, 0); } while (0)
; #define PG8_LDA(dst, b, h) do { _Pragma("unroll") for (int m = 0; m < 4; ++m) _Pragma("unroll") for (int k = 0; k < 2; ++k) dst[m][k] = *(const PG8_LAS bf16x8*)(lds + PG8_SA(b, h) + aoff + m * 2048 + k * 1024); } while (0)
; #define PG8_LDB(dst, b, h) do { _Pragma("unroll") for (int n = 0; n < 2; ++n) _Pragma("unroll") for (int k = 0; k < 2; ++k) dst[n][k] = *(const PG8_LAS bf16x8*)(lds + PG8_SB(b, h) + boff + n * 2048 + k * 1024); } while (0)
; #define PG8_MMA(ai, bj, At, Bt) do { __builtin_amdgcn_s_setprio(1); _Pragma("unroll") for (int m = 0; m < 4; ++m) _Pragma("unroll") for (int n = 0; n < 2; ++n) _Pragma("unroll") for (int k = 0; k < 2; ++k) \
;         acc[ai][bj][m][n] = __builtin_amdgcn_mfma_f32_16x16x32_bf16(Bt[n][k], At[m][k], acc[ai][bj][m][n], 0, 0, 0); __builtin_amdgcn_s_setprio(0); } while (0)
; #define PG8_WAIT_V(n) asm volatile("s_waitcnt vmcnt(" #n ")" ::: "memory")
; #define PG8_WAIT_L(n) asm volatile("s_waitcnt lgkmcnt(" #n ")" ::: "memory")
; #define PG8_BAR __builtin_amdgcn_s_barrier()
; #define PG8_SCHED __builtin_amdgcn_sched_barrier(0)
; template <class Epi, class Sched, bool ALIGN_EPI = false, bool SP2 = false>
; __device__ __forceinline__ void gemm_phase(PG8_LAS unsigned char* lds, const Gemm g, const Sched& S, const Epi& E) {
;     ...
;             PG8_WAIT_V(8); PG8_WAIT_L(0); PG8_BAR; PG8_MMA(1, 0, At, B0); PG8_MMA(1, 1, At, B1); PG8_BAR; PG8_SCHED;
;             PG8_LDB(B0, 1, 0); PG8_LDB(B1, 1, 1); PG8_SCHED; PG8_LDA(At, 1, 0); PG8_STAGE(PG8_SA(0, 1), a2 + hstep, voffA);
	v_mfma_f32_16x16x32_bf16 v[52:55], v[144:147], v[176:179], v[52:55]
	v_mfma_f32_16x16x32_bf16 v[48:51], v[152:155], v[176:179], v[48:51]
	v_mfma_f32_16x16x32_bf16 v[36:39], v[144:147], v[190:193], v[36:39]
	v_mfma_f32_16x16x32_bf16 v[32:35], v[152:155], v[190:193], v[32:35]
	v_mfma_f32_16x16x32_bf16 v[20:23], v[144:147], v[214:217], v[20:23]
	v_mfma_f32_16x16x32_bf16 v[16:19], v[152:155], v[214:217], v[16:19]
	v_mfma_f32_16x16x32_bf16 v[4:7], v[144:147], v[222:225], v[4:7]
	v_mfma_f32_16x16x32_bf16 v[0:3], v[152:155], v[222:225], v[0:3]
	v_mfma_f32_16x16x32_bf16 v[52:55], v[148:151], v[184:187], v[52:55]
	v_mfma_f32_16x16x32_bf16 v[48:51], v[156:159], v[184:187], v[48:51]
	v_mfma_f32_16x16x32_bf16 v[36:39], v[148:151], v[210:213], v[36:39]
	v_mfma_f32_16x16x32_bf16 v[32:35], v[156:159], v[210:213], v[32:35]
	v_mfma_f32_16x16x32_bf16 v[20:23], v[148:151], v[218:221], v[20:23]
	v_mfma_f32_16x16x32_bf16 v[16:19], v[156:159], v[218:221], v[16:19]
	v_mfma_f32_16x16x32_bf16 v[4:7], v[148:151], v[226:229], v[4:7]
	v_mfma_f32_16x16x32_bf16 v[0:3], v[156:159], v[226:229], v[0:3]
	s_setprio 0
	s_barrier
	s_add_i32 s86, 0, 0x18000
	s_add_i32 s87, 0, 0x1c000
	v_add_u32_e32 v140, s86, v189
	v_add_u32_e32 v156, s87, v189
	ds_read_b128 v[128:131], v140
	ds_read_b128 v[132:135], v140 offset:1024
	ds_read_b128 v[136:139], v140 offset:2048
	ds_read_b128 v[140:143], v140 offset:3072
	ds_read_b128 v[144:147], v156
	ds_read_b128 v[148:151], v156 offset:1024
	ds_read_b128 v[152:155], v156 offset:2048
	ds_read_b128 v[156:159], v156 offset:3072
	s_add_u32 s60, s60, 0x80000
	s_addc_u32 s61, s61, 0
	s_mov_b32 m0, s68

; #define PG8_STAGE(bufoff, gbase, voff) do { _Pragma("unroll") for (int _i = 0; _i < 2; ++_i) \
;         __builtin_amdgcn_global_load_lds((const unsigned*)((const char*)(gbase) + (voff)[_i]), (PG8_LAS unsigned*)(lds + (bufoff) + ldsw + _i * 8192), 16, 0, 0); } while (0)
; #define PG8_LDA(dst, b, h) do { _Pragma("unroll") for (int m = 0; m < 4; ++m) _Pragma("unroll") for (int k = 0; k < 2; ++k) dst[m][k] = *(const PG8_LAS bf16x8*)(lds + PG8_SA(b, h) + aoff + m * 2048 + k * 1024); } while (0)
; #define PG8_LDB(dst, b, h) do { _Pragma("unroll") for (int n = 0; n < 2; ++n) _Pragma("unroll") for (int k = 0; k < 2; ++k) dst[n][k] = *(const PG8_LAS bf16x8*)(lds + PG8_SB(b, h) + boff + n * 2048 + k * 1024); } while (0)
; #define PG8_SCHED __builtin_amdgcn_sched_barrier(0)
; template <class Epi, class Sched, bool ALIGN_EPI = false, bool SP2 = false>
; __device__ __forceinline__ void gemm_phase(PG8_LAS unsigned char* lds, const Gemm g, const Sched& S, const Epi& E) {
;     ...
;             PG8_LDB(B0, 1, 0); PG8_LDB(B1, 1, 1); PG8_SCHED; PG8_LDA(At, 1, 0); PG8_STAGE(PG8_SA(0, 1), a2 + hstep, voffA);
	ds_read_b128 v[176:179], v207 offset:32768
	ds_read_b128 v[184:187], v207 offset:33792
	ds_read_b128 v[190:193], v207 offset:34816
	ds_read_b128 v[210:213], v207 offset:35840
	ds_read_b128 v[214:217], v207 offset:36864
	ds_read_b128 v[218:221], v207 offset:37888
	ds_read_b128 v[222:225], v207 offset:38912
	ds_read_b128 v[226:229], v207 offset:39936
	global_load_lds_dwordx4 v160, s[60:61]

; #define PG8_STAGE(bufoff, gbase, voff) do { _Pragma("unroll") for (int _i = 0; _i < 2; ++_i) \
;         __builtin_amdgcn_global_load_lds((const unsigned*)((const char*)(gbase) + (voff)[_i]), (PG8_LAS unsigned*)(lds + (bufoff) + ldsw + _i * 8192), 16, 0, 0); } while (0)
; #define PG8_LDA(dst, b, h) do { _Pragma("unroll") for (int m = 0; m < 4; ++m) _Pragma("unroll") for (int k = 0; k < 2; ++k) dst[m][k] = *(const PG8_LAS bf16x8*)(lds + PG8_SA(b, h) + aoff + m * 2048 + k * 1024); } while (0)
; #define PG8_LDB(dst, b, h) do { _Pragma("unroll") for (int n = 0; n < 2; ++n) _Pragma("unroll") for (int k = 0; k < 2; ++k) dst[n][k] = *(const PG8_LAS bf16x8*)(lds + PG8_SB(b, h) + boff + n * 2048 + k * 1024); } while (0)
; #define PG8_MMA(ai, bj, At, Bt) do { __builtin_amdgcn_s_setprio(1); _Pragma("unroll") for (int m = 0; m < 4; ++m) _Pragma("unroll") for (int n = 0; n < 2; ++n) _Pragma("unroll") for (int k = 0; k < 2; ++k) \
;         acc[ai][bj][m][n] = __builtin_amdgcn_mfma_f32_16x16x32_bf16(Bt[n][k], At[m][k], acc[ai][bj][m][n], 0, 0, 0); __builtin_amdgcn_s_setprio(0); } while (0)
; #define PG8_WAIT_V(n) asm volatile("s_waitcnt vmcnt(" #n ")" ::: "memory")
; #define PG8_WAIT_L(n) asm volatile("s_waitcnt lgkmcnt(" #n ")" ::: "memory")
; #define PG8_BAR __builtin_amdgcn_s_barrier()
; #define PG8_SCHED __builtin_amdgcn_sched_barrier(0)
; template <class Epi, class Sched, bool ALIGN_EPI = false, bool SP2 = false>
; __device__ __forceinline__ void gemm_phase(PG8_LAS unsigned char* lds, const Gemm g, const Sched& S, const Epi& E) {
;     ...
;             PG8_LDB(B0, 1, 0); PG8_LDB(B1, 1, 1); PG8_SCHED; PG8_LDA(At, 1, 0); PG8_STAGE(PG8_SA(0, 1), a2 + hstep, voffA);
;             PG8_WAIT_V(8); PG8_WAIT_L(0); PG8_BAR; PG8_MMA(0, 0, At, B0); PG8_MMA(0, 1, At, B1); PG8_BAR; PG8_SCHED;
	s_mov_b32 m0, s69
	s_nop 0
	global_load_lds_dwordx4 v164, s[60:61]
	s_waitcnt vmcnt(8)
	s_waitcnt lgkmcnt(0)
	s_setprio 1
	s_barrier

; #define PG8_MMA(ai, bj, At, Bt) do { __builtin_amdgcn_s_setprio(1); _Pragma("unroll") for (int m = 0; m < 4; ++m) _Pragma("unroll") for (int n = 0; n < 2; ++n) _Pragma("unroll") for (int k = 0; k < 2; ++k) \
;         acc[ai][bj][m][n] = __builtin_amdgcn_mfma_f32_16x16x32_bf16(Bt[n][k], At[m][k], acc[ai][bj][m][n], 0, 0, 0); __builtin_amdgcn_s_setprio(0); } while (0)
; #define PG8_WAIT_V(n) asm volatile("s_waitcnt vmcnt(" #n ")" ::: "memory")
; #define PG8_WAIT_L(n) asm volatile("s_waitcnt lgkmcnt(" #n ")" ::: "memory")
; #define PG8_BAR __builtin_amdgcn_s_barrier()
; #define PG8_SCHED __builtin_amdgcn_sched_barrier(0)
; template <class Epi, class Sched, bool ALIGN_EPI = false, bool SP2 = false>
; __device__ __forceinline__ void gemm_phase(PG8_LAS unsigned char* lds, const Gemm g, const Sched& S, const Epi& E) {
;     ...
;             PG8_WAIT_V(8); PG8_WAIT_L(0); PG8_BAR; PG8_MMA(0, 0, At, B0); PG8_MMA(0, 1, At, B1); PG8_BAR; PG8_SCHED;
	v_mfma_f32_16x16x32_bf16 v[124:127], v[128:131], v[176:179], v[124:127]
	v_mfma_f32_16x16x32_bf16 v[120:123], v[136:139], v[176:179], v[120:123]
	v_mfma_f32_16x16x32_bf16 v[108:111], v[128:131], v[190:193], v[108:111]
	v_mfma_f32_16x16x32_bf16 v[104:107], v[136:139], v[190:193], v[104:107]
	v_mfma_f32_16x16x32_bf16 v[92:95], v[128:131], v[214:217], v[92:95]
	v_mfma_f32_16x16x32_bf16 v[88:91], v[136:139], v[214:217], v[88:91]
	v_mfma_f32_16x16x32_bf16 v[76:79], v[128:131], v[222:225], v[76:79]
	v_mfma_f32_16x16x32_bf16 v[72:75], v[136:139], v[222:225], v[72:75]
	v_mfma_f32_16x16x32_bf16 v[124:127], v[132:135], v[184:187], v[124:127]
	v_mfma_f32_16x16x32_bf16 v[120:123], v[140:143], v[184:187], v[120:123]
	v_mfma_f32_16x16x32_bf16 v[108:111], v[132:135], v[210:213], v[108:111]
	v_mfma_f32_16x16x32_bf16 v[104:107], v[140:143], v[210:213], v[104:107]
	v_mfma_f32_16x16x32_bf16 v[92:95], v[132:135], v[218:221], v[92:95]
	v_mfma_f32_16x16x32_bf16 v[88:91], v[140:143], v[218:221], v[88:91]
	v_mfma_f32_16x16x32_bf16 v[76:79], v[132:135], v[226:229], v[76:79]
	v_mfma_f32_16x16x32_bf16 v[72:75], v[140:143], v[226:229], v[72:75]


; #define PG8_MMA(ai, bj, At, Bt) do { __builtin_amdgcn_s_setprio(1); _Pragma("unroll") for (int m = 0; m < 4; ++m) _Pragma("unroll") for (int n = 0; n < 2; ++n) _Pragma("unroll") for (int k = 0; k < 2; ++k) \
;         acc[ai][bj][m][n] = __builtin_amdgcn_mfma_f32_16x16x32_bf16(Bt[n][k], At[m][k], acc[ai][bj][m][n], 0, 0, 0); __builtin_amdgcn_s_setprio(0); } while (0)
; #define PG8_WAIT_V(n) asm volatile("s_waitcnt vmcnt(" #n ")" ::: "memory")
; #define PG8_WAIT_L(n) asm volatile("s_waitcnt lgkmcnt(" #n ")" ::: "memory")
; #define PG8_BAR __builtin_amdgcn_s_barrier()
; #define PG8_SCHED __builtin_amdgcn_sched_barrier(0)
; template <class Epi, class Sched, bool ALIGN_EPI = false, bool SP2 = false>
; __device__ __forceinline__ void gemm_phase(PG8_LAS unsigned char* lds, const Gemm g, const Sched& S, const Epi& E) {
;     ...
;             PG8_WAIT_V(8); PG8_WAIT_L(0); PG8_BAR; PG8_MMA(0, 0, At, B0); PG8_MMA(0, 1, At, B1); PG8_BAR; PG8_SCHED;
	v_mfma_f32_16x16x32_bf16 v[116:119], v[144:147], v[176:179], v[116:119]
	v_mfma_f32_16x16x32_bf16 v[112:115], v[152:155], v[176:179], v[112:115]
	v_mfma_f32_16x16x32_bf16 v[100:103], v[144:147], v[190:193], v[100:103]
	v_mfma_f32_16x16x32_bf16 v[96:99], v[152:155], v[190:193], v[96:99]
	v_mfma_f32_16x16x32_bf16 v[84:87], v[144:147], v[214:217], v[84:87]
	v_mfma_f32_16x16x32_bf16 v[80:83], v[152:155], v[214:217], v[80:83]
	v_mfma_f32_16x16x32_bf16 v[68:71], v[144:147], v[222:225], v[68:71]
	v_mfma_f32_16x16x32_bf16 v[64:67], v[152:155], v[222:225], v[64:67]
	v_mfma_f32_16x16x32_bf16 v[116:119], v[148:151], v[184:187], v[116:119]
	v_mfma_f32_16x16x32_bf16 v[112:115], v[156:159], v[184:187], v[112:115]
	v_mfma_f32_16x16x32_bf16 v[100:103], v[148:151], v[210:213], v[100:103]
	v_mfma_f32_16x16x32_bf16 v[96:99], v[156:159], v[210:213], v[96:99]
	v_mfma_f32_16x16x32_bf16 v[84:87], v[148:151], v[218:221], v[84:87]
	v_mfma_f32_16x16x32_bf16 v[80:83], v[156:159], v[218:221], v[80:83]
	v_mfma_f32_16x16x32_bf16 v[68:71], v[148:151], v[226:229], v[68:71]
	v_mfma_f32_16x16x32_bf16 v[64:67], v[156:159], v[226:229], v[64:67]
	s_setprio 0
	s_barrier
	s_add_i32 s60, s86, s64

; #define PG8_STAGE(bufoff, gbase, voff) do { _Pragma("unroll") for (int _i = 0; _i < 2; ++_i) \
;         __builtin_amdgcn_global_load_lds((const unsigned*)((const char*)(gbase) + (voff)[_i]), (PG8_LAS unsigned*)(lds + (bufoff) + ldsw + _i * 8192), 16, 0, 0); } while (0)
; #define PG8_LDA(dst, b, h) do { _Pragma("unroll") for (int m = 0; m < 4; ++m) _Pragma("unroll") for (int k = 0; k < 2; ++k) dst[m][k] = *(const PG8_LAS bf16x8*)(lds + PG8_SA(b, h) + aoff + m * 2048 + k * 1024); } while (0)
; template <class Epi, class Sched, bool ALIGN_EPI = false, bool SP2 = false>
; __device__ __forceinline__ void gemm_phase(PG8_LAS unsigned char* lds, const Gemm g, const Sched& S, const Epi& E) {
;     ...
;             PG8_LDA(At, 1, 1); PG8_STAGE(PG8_SB(1, 0), b3, voffB); PG8_STAGE(PG8_SB(1, 1), b3 + hstep, voffB); PG8_STAGE(PG8_SA(1, 0), a3, voffA);
	s_mov_b32 m0, s60
	ds_read_b128 v[176:179], v207 offset:49152
	ds_read_b128 v[184:187], v207 offset:50176
	ds_read_b128 v[190:193], v207 offset:51200
	ds_read_b128 v[210:213], v207 offset:52224
	ds_read_b128 v[214:217], v207 offset:53248
	ds_read_b128 v[218:221], v207 offset:54272
	ds_read_b128 v[222:225], v207 offset:55296
	ds_read_b128 v[226:229], v207 offset:56320
	global_load_lds_dwordx4 v250, s[96:97]
	s_add_i32 m0, s60, 0x2000
	s_add_u32 s12, s12, 0x80080

; #define PG8_STAGE(bufoff, gbase, voff) do { _Pragma("unroll") for (int _i = 0; _i < 2; ++_i) \
;         __builtin_amdgcn_global_load_lds((const unsigned*)((const char*)(gbase) + (voff)[_i]), (PG8_LAS unsigned*)(lds + (bufoff) + ldsw + _i * 8192), 16, 0, 0); } while (0)
; #define PG8_LDA(dst, b, h) do { _Pragma("unroll") for (int m = 0; m < 4; ++m) _Pragma("unroll") for (int k = 0; k < 2; ++k) dst[m][k] = *(const PG8_LAS bf16x8*)(lds + PG8_SA(b, h) + aoff + m * 2048 + k * 1024); } while (0)
; template <class Epi, class Sched, bool ALIGN_EPI = false, bool SP2 = false>
; __device__ __forceinline__ void gemm_phase(PG8_LAS unsigned char* lds, const Gemm g, const Sched& S, const Epi& E) {
;     ...
;             PG8_LDA(At, 1, 1); PG8_STAGE(PG8_SB(1, 0), b3, voffB); PG8_STAGE(PG8_SB(1, 1), b3 + hstep, voffB); PG8_STAGE(PG8_SA(1, 0), a3, voffA);
	s_addc_u32 s13, s13, 0
	s_add_i32 s60, s87, s64
	global_load_lds_dwordx4 v251, s[96:97]

; #define PG8_STAGE(bufoff, gbase, voff) do { _Pragma("unroll") for (int _i = 0; _i < 2; ++_i) \
;         __builtin_amdgcn_global_load_lds((const unsigned*)((const char*)(gbase) + (voff)[_i]), (PG8_LAS unsigned*)(lds + (bufoff) + ldsw + _i * 8192), 16, 0, 0); } while (0)
; #define PG8_LDA(dst, b, h) do { _Pragma("unroll") for (int m = 0; m < 4; ++m) _Pragma("unroll") for (int k = 0; k < 2; ++k) dst[m][k] = *(const PG8_LAS bf16x8*)(lds + PG8_SA(b, h) + aoff + m * 2048 + k * 1024); } while (0)
; template <class Epi, class Sched, bool ALIGN_EPI = false, bool SP2 = false>
; __device__ __forceinline__ void gemm_phase(PG8_LAS unsigned char* lds, const Gemm g, const Sched& S, const Epi& E) {
;     ...
;             PG8_LDA(At, 1, 1); PG8_STAGE(PG8_SB(1, 0), b3, voffB); PG8_STAGE(PG8_SB(1, 1), b3 + hstep, voffB); PG8_STAGE(PG8_SA(1, 0), a3, voffA);
	s_mov_b32 m0, s60
	s_nop 0
	global_load_lds_dwordx4 v162, s[12:13]

; #define PG8_STAGE(bufoff, gbase, voff) do { _Pragma("unroll") for (int _i = 0; _i < 2; ++_i) \
;         __builtin_amdgcn_global_load_lds((const unsigned*)((const char*)(gbase) + (voff)[_i]), (PG8_LAS unsigned*)(lds + (bufoff) + ldsw + _i * 8192), 16, 0, 0); } while (0)
; #define PG8_LDA(dst, b, h) do { _Pragma("unroll") for (int m = 0; m < 4; ++m) _Pragma("unroll") for (int k = 0; k < 2; ++k) dst[m][k] = *(const PG8_LAS bf16x8*)(lds + PG8_SA(b, h) + aoff + m * 2048 + k * 1024); } while (0)
; template <class Epi, class Sched, bool ALIGN_EPI = false, bool SP2 = false>
; __device__ __forceinline__ void gemm_phase(PG8_LAS unsigned char* lds, const Gemm g, const Sched& S, const Epi& E) {
;     ...
;             PG8_LDA(At, 1, 1); PG8_STAGE(PG8_SB(1, 0), b3, voffB); PG8_STAGE(PG8_SB(1, 1), b3 + hstep, voffB); PG8_STAGE(PG8_SA(1, 0), a3, voffA);
	s_add_i32 m0, s60, 0x2000
	s_nop 0
	global_load_lds_dwordx4 v166, s[12:13]

; #define PG8_STAGE(bufoff, gbase, voff) do { _Pragma("unroll") for (int _i = 0; _i < 2; ++_i) \
;         __builtin_amdgcn_global_load_lds((const unsigned*)((const char*)(gbase) + (voff)[_i]), (PG8_LAS unsigned*)(lds + (bufoff) + ldsw + _i * 8192), 16, 0, 0); } while (0)
; #define PG8_LDA(dst, b, h) do { _Pragma("unroll") for (int m = 0; m < 4; ++m) _Pragma("unroll") for (int k = 0; k < 2; ++k) dst[m][k] = *(const PG8_LAS bf16x8*)(lds + PG8_SA(b, h) + aoff + m * 2048 + k * 1024); } while (0)
; template <class Epi, class Sched, bool ALIGN_EPI = false, bool SP2 = false>
; __device__ __forceinline__ void gemm_phase(PG8_LAS unsigned char* lds, const Gemm g, const Sched& S, const Epi& E) {
;     ...
;             PG8_LDA(At, 1, 1); PG8_STAGE(PG8_SB(1, 0), b3, voffB); PG8_STAGE(PG8_SB(1, 1), b3 + hstep, voffB); PG8_STAGE(PG8_SA(1, 0), a3, voffA);
	s_mov_b32 m0, s71
	s_nop 0
	global_load_lds_dwordx4 v252, s[98:99]

; #define PG8_STAGE(bufoff, gbase, voff) do { _Pragma("unroll") for (int _i = 0; _i < 2; ++_i) \
;         __builtin_amdgcn_global_load_lds((const unsigned*)((const char*)(gbase) + (voff)[_i]), (PG8_LAS unsigned*)(lds + (bufoff) + ldsw + _i * 8192), 16, 0, 0); } while (0)
; #define PG8_LDA(dst, b, h) do { _Pragma("unroll") for (int m = 0; m < 4; ++m) _Pragma("unroll") for (int k = 0; k < 2; ++k) dst[m][k] = *(const PG8_LAS bf16x8*)(lds + PG8_SA(b, h) + aoff + m * 2048 + k * 1024); } while (0)
; #define PG8_MMA(ai, bj, At, Bt) do { __builtin_amdgcn_s_setprio(1); _Pragma("unroll") for (int m = 0; m < 4; ++m) _Pragma("unroll") for (int n = 0; n < 2; ++n) _Pragma("unroll") for (int k = 0; k < 2; ++k) \
;         acc[ai][bj][m][n] = __builtin_amdgcn_mfma_f32_16x16x32_bf16(Bt[n][k], At[m][k], acc[ai][bj][m][n], 0, 0, 0); __builtin_amdgcn_s_setprio(0); } while (0)
; #define PG8_WAIT_V(n) asm volatile("s_waitcnt vmcnt(" #n ")" ::: "memory")
; #define PG8_WAIT_L(n) asm volatile("s_waitcnt lgkmcnt(" #n ")" ::: "memory")
; #define PG8_BAR __builtin_amdgcn_s_barrier()
; #define PG8_SCHED __builtin_amdgcn_sched_barrier(0)
; template <class Epi, class Sched, bool ALIGN_EPI = false, bool SP2 = false>
; __device__ __forceinline__ void gemm_phase(PG8_LAS unsigned char* lds, const Gemm g, const Sched& S, const Epi& E) {
;     ...
;             PG8_LDA(At, 1, 1); PG8_STAGE(PG8_SB(1, 0), b3, voffB); PG8_STAGE(PG8_SB(1, 1), b3 + hstep, voffB); PG8_STAGE(PG8_SA(1, 0), a3, voffA);
;             PG8_WAIT_V(8); PG8_WAIT_L(0); PG8_BAR; PG8_MMA(1, 0, At, B0); PG8_MMA(1, 1, At, B1); PG8_BAR; PG8_SCHED;
	s_mov_b32 m0, s72
	s_nop 0
	global_load_lds_dwordx4 v253, s[98:99]
	s_waitcnt vmcnt(8)
	s_waitcnt lgkmcnt(0)
	s_setprio 1
	s_barrier

; #define PG8_MMA(ai, bj, At, Bt) do { __builtin_amdgcn_s_setprio(1); _Pragma("unroll") for (int m = 0; m < 4; ++m) _Pragma("unroll") for (int n = 0; n < 2; ++n) _Pragma("unroll") for (int k = 0; k < 2; ++k) \
;         acc[ai][bj][m][n] = __builtin_amdgcn_mfma_f32_16x16x32_bf16(Bt[n][k], At[m][k], acc[ai][bj][m][n], 0, 0, 0); __builtin_amdgcn_s_setprio(0); } while (0)
; #define PG8_WAIT_V(n) asm volatile("s_waitcnt vmcnt(" #n ")" ::: "memory")
; #define PG8_WAIT_L(n) asm volatile("s_waitcnt lgkmcnt(" #n ")" ::: "memory")
; #define PG8_BAR __builtin_amdgcn_s_barrier()
; #define PG8_SCHED __builtin_amdgcn_sched_barrier(0)
; template <class Epi, class Sched, bool ALIGN_EPI = false, bool SP2 = false>
; __device__ __forceinline__ void gemm_phase(PG8_LAS unsigned char* lds, const Gemm g, const Sched& S, const Epi& E) {
;     ...
;             PG8_WAIT_V(8); PG8_WAIT_L(0); PG8_BAR; PG8_MMA(1, 0, At, B0); PG8_MMA(1, 1, At, B1); PG8_BAR; PG8_SCHED;
	v_mfma_f32_16x16x32_bf16 v[60:63], v[128:131], v[176:179], v[60:63]
	v_mfma_f32_16x16x32_bf16 v[56:59], v[136:139], v[176:179], v[56:59]
	v_mfma_f32_16x16x32_bf16 v[44:47], v[128:131], v[190:193], v[44:47]
	v_mfma_f32_16x16x32_bf16 v[40:43], v[136:139], v[190:193], v[40:43]
	v_mfma_f32_16x16x32_bf16 v[28:31], v[128:131], v[214:217], v[28:31]
	v_mfma_f32_16x16x32_bf16 v[24:27], v[136:139], v[214:217], v[24:27]
	v_mfma_f32_16x16x32_bf16 v[12:15], v[128:131], v[222:225], v[12:15]
	v_mfma_f32_16x16x32_bf16 v[8:11], v[136:139], v[222:225], v[8:11]
	v_mfma_f32_16x16x32_bf16 v[60:63], v[132:135], v[184:187], v[60:63]
	v_mfma_f32_16x16x32_bf16 v[56:59], v[140:143], v[184:187], v[56:59]
	v_mfma_f32_16x16x32_bf16 v[44:47], v[132:135], v[210:213], v[44:47]
	v_mfma_f32_16x16x32_bf16 v[40:43], v[140:143], v[210:213], v[40:43]
	v_mfma_f32_16x16x32_bf16 v[28:31], v[132:135], v[218:221], v[28:31]
	v_mfma_f32_16x16x32_bf16 v[24:27], v[140:143], v[218:221], v[24:27]
	v_mfma_f32_16x16x32_bf16 v[12:15], v[132:135], v[226:229], v[12:15]
	v_mfma_f32_16x16x32_bf16 v[8:11], v[140:143], v[226:229], v[8:11]


; #define PG8_MMA(ai, bj, At, Bt) do { __builtin_amdgcn_s_setprio(1); _Pragma("unroll") for (int m = 0; m < 4; ++m) _Pragma("unroll") for (int n = 0; n < 2; ++n) _Pragma("unroll") for (int k = 0; k < 2; ++k) \
;         acc[ai][bj][m][n] = __builtin_amdgcn_mfma_f32_16x16x32_bf16(Bt[n][k], At[m][k], acc[ai][bj][m][n], 0, 0, 0); __builtin_amdgcn_s_setprio(0); } while (0)
; #define PG8_WAIT_V(n) asm volatile("s_waitcnt vmcnt(" #n ")" ::: "memory")
; #define PG8_WAIT_L(n) asm volatile("s_waitcnt lgkmcnt(" #n ")" ::: "memory")
; #define PG8_BAR __builtin_amdgcn_s_barrier()
; #define PG8_SCHED __builtin_amdgcn_sched_barrier(0)
; template <class Epi, class Sched, bool ALIGN_EPI = false, bool SP2 = false>
; __device__ __forceinline__ void gemm_phase(PG8_LAS unsigned char* lds, const Gemm g, const Sched& S, const Epi& E) {
;     ...
;             PG8_WAIT_V(8); PG8_WAIT_L(0); PG8_BAR; PG8_MMA(1, 0, At, B0); PG8_MMA(1, 1, At, B1); PG8_BAR; PG8_SCHED;
	v_mfma_f32_16x16x32_bf16 v[52:55], v[144:147], v[176:179], v[52:55]
	v_mfma_f32_16x16x32_bf16 v[48:51], v[152:155], v[176:179], v[48:51]
	v_mfma_f32_16x16x32_bf16 v[36:39], v[144:147], v[190:193], v[36:39]
	v_mfma_f32_16x16x32_bf16 v[32:35], v[152:155], v[190:193], v[32:35]
	v_mfma_f32_16x16x32_bf16 v[20:23], v[144:147], v[214:217], v[20:23]
	v_mfma_f32_16x16x32_bf16 v[16:19], v[152:155], v[214:217], v[16:19]
	v_mfma_f32_16x16x32_bf16 v[4:7], v[144:147], v[222:225], v[4:7]
	v_mfma_f32_16x16x32_bf16 v[0:3], v[152:155], v[222:225], v[0:3]
	v_mfma_f32_16x16x32_bf16 v[52:55], v[148:151], v[184:187], v[52:55]
	v_mfma_f32_16x16x32_bf16 v[48:51], v[156:159], v[184:187], v[48:51]
	v_mfma_f32_16x16x32_bf16 v[36:39], v[148:151], v[210:213], v[36:39]
	v_mfma_f32_16x16x32_bf16 v[32:35], v[156:159], v[210:213], v[32:35]
	v_mfma_f32_16x16x32_bf16 v[20:23], v[148:151], v[218:221], v[20:23]
	v_mfma_f32_16x16x32_bf16 v[16:19], v[156:159], v[218:221], v[16:19]
	v_mfma_f32_16x16x32_bf16 v[4:7], v[148:151], v[226:229], v[4:7]
	v_mfma_f32_16x16x32_bf16 v[0:3], v[156:159], v[226:229], v[0:3]
	s_setprio 0
	s_barrier
	s_add_i32 s85, s85, 2
	s_add_u32 s10, s10, 0x100
	s_addc_u32 s11, s11, 0
	s_add_u32 s83, s83, 0x100
	s_addc_u32 s84, s84, 0
	s_cmp_gt_u32 s85, 29
	s_cbranch_scc0 .LBB0_428
	s_and_b64 vcc, exec, s[42:43]
	s_cbranch_vccz .LBB0_431
	s_barrier

; #define PG8_STAGE(bufoff, gbase, voff) do { _Pragma("unroll") for (int _i = 0; _i < 2; ++_i) \
;         __builtin_amdgcn_global_load_lds((const unsigned*)((const char*)(gbase) + (voff)[_i]), (PG8_LAS unsigned*)(lds + (bufoff) + ldsw + _i * 8192), 16, 0, 0); } while (0)
; #define PG8_LDA(dst, b, h) do { _Pragma("unroll") for (int m = 0; m < 4; ++m) _Pragma("unroll") for (int k = 0; k < 2; ++k) dst[m][k] = *(const PG8_LAS bf16x8*)(lds + PG8_SA(b, h) + aoff + m * 2048 + k * 1024); } while (0)
; #define PG8_LDB(dst, b, h) do { _Pragma("unroll") for (int n = 0; n < 2; ++n) _Pragma("unroll") for (int k = 0; k < 2; ++k) dst[n][k] = *(const PG8_LAS bf16x8*)(lds + PG8_SB(b, h) + boff + n * 2048 + k * 1024); } while (0)
; #define PG8_SCHED __builtin_amdgcn_sched_barrier(0)
; template <class Epi, class Sched, bool ALIGN_EPI = false, bool SP2 = false>
; __device__ __forceinline__ void gemm_phase(PG8_LAS unsigned char* lds, const Gemm g, const Sched& S, const Epi& E) {
;     ...
;             const bool last = (t == nt - 2);
;             const char* a1 = cA + (size_t)(t + 1) * kstep;
;             const char* a2 = last ? nA : cA + (size_t)(t + 2) * kstep; const char* b2 = last ? nB : cB + (size_t)(t + 2) * kstep;
;             const char* a3 = a2 + kstep; const char* b3 = b2 + kstep;
;             if (last && has_next) S.a_ready(nxt);
;             if constexpr (SP2) {
;             PG8_LDB(B0, 0, 0); PG8_LDB(B1, 0, 1); PG8_SCHED; PG8_LDA(At, 0, 0); PG8_STAGE(PG8_SA(1, 1), a1 + hstep, voffA);
.LBB0_509:
	ds_read_b128 v[64:67], v213
	ds_read_b128 v[68:71], v213 offset:1024
	ds_read_b128 v[72:75], v213 offset:2048
	ds_read_b128 v[76:79], v213 offset:3072
	ds_read_b128 v[144:147], v214
	ds_read_b128 v[148:151], v214 offset:1024
	ds_read_b128 v[152:155], v214 offset:2048
	ds_read_b128 v[156:159], v214 offset:3072
	s_add_u32 s60, s58, 0xffe00080
	s_addc_u32 s61, s59, -1
	s_cmpk_eq_i32 s81, 0x7c
	s_cselect_b32 s63, s11, s61
	s_cselect_b32 s62, s51, s60
	s_cselect_b32 s61, s49, s80
	s_cselect_b32 s60, s78, s79

; #define PG8_STAGE(bufoff, gbase, voff) do { _Pragma("unroll") for (int _i = 0; _i < 2; ++_i) \
;         __builtin_amdgcn_global_load_lds((const unsigned*)((const char*)(gbase) + (voff)[_i]), (PG8_LAS unsigned*)(lds + (bufoff) + ldsw + _i * 8192), 16, 0, 0); } while (0)
; #define PG8_LDA(dst, b, h) do { _Pragma("unroll") for (int m = 0; m < 4; ++m) _Pragma("unroll") for (int k = 0; k < 2; ++k) dst[m][k] = *(const PG8_LAS bf16x8*)(lds + PG8_SA(b, h) + aoff + m * 2048 + k * 1024); } while (0)
; #define PG8_LDB(dst, b, h) do { _Pragma("unroll") for (int n = 0; n < 2; ++n) _Pragma("unroll") for (int k = 0; k < 2; ++k) dst[n][k] = *(const PG8_LAS bf16x8*)(lds + PG8_SB(b, h) + boff + n * 2048 + k * 1024); } while (0)
; #define PG8_SCHED __builtin_amdgcn_sched_barrier(0)
; template <class Epi, class Sched, bool ALIGN_EPI = false, bool SP2 = false>
; __device__ __forceinline__ void gemm_phase(PG8_LAS unsigned char* lds, const Gemm g, const Sched& S, const Epi& E) {
;     ...
;             PG8_LDB(B0, 0, 0); PG8_LDB(B1, 0, 1); PG8_SCHED; PG8_LDA(At, 0, 0); PG8_STAGE(PG8_SA(1, 1), a1 + hstep, voffA);
	s_add_i32 m0, s57, 0xc000
	ds_read_b128 v[176:179], v215
	ds_read_b128 v[180:183], v215 offset:1024
	ds_read_b128 v[184:187], v215 offset:2048
	ds_read_b128 v[188:191], v215 offset:3072
	ds_read_b128 v[192:195], v215 offset:4096
	ds_read_b128 v[196:199], v215 offset:5120
	ds_read_b128 v[200:203], v215 offset:6144
	ds_read_b128 v[204:207], v215 offset:7168
	global_load_lds_dwordx4 v168, s[58:59]

; #define PG8_STAGE(bufoff, gbase, voff) do { _Pragma("unroll") for (int _i = 0; _i < 2; ++_i) \
;         __builtin_amdgcn_global_load_lds((const unsigned*)((const char*)(gbase) + (voff)[_i]), (PG8_LAS unsigned*)(lds + (bufoff) + ldsw + _i * 8192), 16, 0, 0); } while (0)
; #define PG8_LDA(dst, b, h) do { _Pragma("unroll") for (int m = 0; m < 4; ++m) _Pragma("unroll") for (int k = 0; k < 2; ++k) dst[m][k] = *(const PG8_LAS bf16x8*)(lds + PG8_SA(b, h) + aoff + m * 2048 + k * 1024); } while (0)
; #define PG8_LDB(dst, b, h) do { _Pragma("unroll") for (int n = 0; n < 2; ++n) _Pragma("unroll") for (int k = 0; k < 2; ++k) dst[n][k] = *(const PG8_LAS bf16x8*)(lds + PG8_SB(b, h) + boff + n * 2048 + k * 1024); } while (0)
; #define PG8_MMA(ai, bj, At, Bt) do { __builtin_amdgcn_s_setprio(1); _Pragma("unroll") for (int m = 0; m < 4; ++m) _Pragma("unroll") for (int n = 0; n < 2; ++n) _Pragma("unroll") for (int k = 0; k < 2; ++k) \
;         acc[ai][bj][m][n] = __builtin_amdgcn_mfma_f32_16x16x32_bf16(Bt[n][k], At[m][k], acc[ai][bj][m][n], 0, 0, 0); __builtin_amdgcn_s_setprio(0); } while (0)
; #define PG8_WAIT_V(n) asm volatile("s_waitcnt vmcnt(" #n ")" ::: "memory")
; #define PG8_WAIT_L(n) asm volatile("s_waitcnt lgkmcnt(" #n ")" ::: "memory")
; #define PG8_BAR __builtin_amdgcn_s_barrier()
; #define PG8_SCHED __builtin_amdgcn_sched_barrier(0)
; template <class Epi, class Sched, bool ALIGN_EPI = false, bool SP2 = false>
; __device__ __forceinline__ void gemm_phase(PG8_LAS unsigned char* lds, const Gemm g, const Sched& S, const Epi& E) {
;     ...
;             PG8_LDB(B0, 0, 0); PG8_LDB(B1, 0, 1); PG8_SCHED; PG8_LDA(At, 0, 0); PG8_STAGE(PG8_SA(1, 1), a1 + hstep, voffA);
;             PG8_WAIT_V(8); PG8_WAIT_L(0); PG8_BAR; PG8_MMA(0, 0, At, B0); PG8_MMA(0, 1, At, B1); PG8_BAR; PG8_SCHED;
	s_add_i32 m0, s57, 0xe000
	s_nop 0
	global_load_lds_dwordx4 v170, s[58:59]
	s_waitcnt vmcnt(8)
	s_waitcnt lgkmcnt(0)
	s_setprio 1
	s_barrier

; #define PG8_MMA(ai, bj, At, Bt) do { __builtin_amdgcn_s_setprio(1); _Pragma("unroll") for (int m = 0; m < 4; ++m) _Pragma("unroll") for (int n = 0; n < 2; ++n) _Pragma("unroll") for (int k = 0; k < 2; ++k) \
;         acc[ai][bj][m][n] = __builtin_amdgcn_mfma_f32_16x16x32_bf16(Bt[n][k], At[m][k], acc[ai][bj][m][n], 0, 0, 0); __builtin_amdgcn_s_setprio(0); } while (0)
; #define PG8_WAIT_V(n) asm volatile("s_waitcnt vmcnt(" #n ")" ::: "memory")
; #define PG8_WAIT_L(n) asm volatile("s_waitcnt lgkmcnt(" #n ")" ::: "memory")
; #define PG8_BAR __builtin_amdgcn_s_barrier()
; #define PG8_SCHED __builtin_amdgcn_sched_barrier(0)
; template <class Epi, class Sched, bool ALIGN_EPI = false, bool SP2 = false>
; __device__ __forceinline__ void gemm_phase(PG8_LAS unsigned char* lds, const Gemm g, const Sched& S, const Epi& E) {
;     ...
;             PG8_WAIT_V(8); PG8_WAIT_L(0); PG8_BAR; PG8_MMA(0, 0, At, B0); PG8_MMA(0, 1, At, B1); PG8_BAR; PG8_SCHED;
	v_mfma_f32_16x16x32_bf16 v[140:143], v[64:67], v[176:179], v[140:143]
	v_mfma_f32_16x16x32_bf16 v[136:139], v[72:75], v[176:179], v[136:139]
	v_mfma_f32_16x16x32_bf16 v[124:127], v[64:67], v[184:187], v[124:127]
	v_mfma_f32_16x16x32_bf16 v[120:123], v[72:75], v[184:187], v[120:123]
	v_mfma_f32_16x16x32_bf16 v[108:111], v[64:67], v[192:195], v[108:111]
	v_mfma_f32_16x16x32_bf16 v[104:107], v[72:75], v[192:195], v[104:107]
	v_mfma_f32_16x16x32_bf16 v[92:95], v[64:67], v[200:203], v[92:95]
	v_mfma_f32_16x16x32_bf16 v[88:91], v[72:75], v[200:203], v[88:91]
	v_mfma_f32_16x16x32_bf16 v[140:143], v[68:71], v[180:183], v[140:143]
	v_mfma_f32_16x16x32_bf16 v[136:139], v[76:79], v[180:183], v[136:139]
	v_mfma_f32_16x16x32_bf16 v[124:127], v[68:71], v[188:191], v[124:127]
	v_mfma_f32_16x16x32_bf16 v[120:123], v[76:79], v[188:191], v[120:123]
	v_mfma_f32_16x16x32_bf16 v[108:111], v[68:71], v[196:199], v[108:111]
	v_mfma_f32_16x16x32_bf16 v[104:107], v[76:79], v[196:199], v[104:107]
	v_mfma_f32_16x16x32_bf16 v[92:95], v[68:71], v[204:207], v[92:95]
	v_mfma_f32_16x16x32_bf16 v[88:91], v[76:79], v[204:207], v[88:91]


; #define PG8_MMA(ai, bj, At, Bt) do { __builtin_amdgcn_s_setprio(1); _Pragma("unroll") for (int m = 0; m < 4; ++m) _Pragma("unroll") for (int n = 0; n < 2; ++n) _Pragma("unroll") for (int k = 0; k < 2; ++k) \
;         acc[ai][bj][m][n] = __builtin_amdgcn_mfma_f32_16x16x32_bf16(Bt[n][k], At[m][k], acc[ai][bj][m][n], 0, 0, 0); __builtin_amdgcn_s_setprio(0); } while (0)
; #define PG8_WAIT_V(n) asm volatile("s_waitcnt vmcnt(" #n ")" ::: "memory")
; #define PG8_WAIT_L(n) asm volatile("s_waitcnt lgkmcnt(" #n ")" ::: "memory")
; #define PG8_BAR __builtin_amdgcn_s_barrier()
; #define PG8_SCHED __builtin_amdgcn_sched_barrier(0)
; template <class Epi, class Sched, bool ALIGN_EPI = false, bool SP2 = false>
; __device__ __forceinline__ void gemm_phase(PG8_LAS unsigned char* lds, const Gemm g, const Sched& S, const Epi& E) {
;     ...
;             PG8_WAIT_V(8); PG8_WAIT_L(0); PG8_BAR; PG8_MMA(0, 0, At, B0); PG8_MMA(0, 1, At, B1); PG8_BAR; PG8_SCHED;
	v_mfma_f32_16x16x32_bf16 v[132:135], v[144:147], v[176:179], v[132:135]
	v_mfma_f32_16x16x32_bf16 v[128:131], v[152:155], v[176:179], v[128:131]
	v_mfma_f32_16x16x32_bf16 v[116:119], v[144:147], v[184:187], v[116:119]
	v_mfma_f32_16x16x32_bf16 v[112:115], v[152:155], v[184:187], v[112:115]
	v_mfma_f32_16x16x32_bf16 v[100:103], v[144:147], v[192:195], v[100:103]
	v_mfma_f32_16x16x32_bf16 v[96:99], v[152:155], v[192:195], v[96:99]
	v_mfma_f32_16x16x32_bf16 v[84:87], v[144:147], v[200:203], v[84:87]
	v_mfma_f32_16x16x32_bf16 v[80:83], v[152:155], v[200:203], v[80:83]
	v_mfma_f32_16x16x32_bf16 v[132:135], v[148:151], v[180:183], v[132:135]
	v_mfma_f32_16x16x32_bf16 v[128:131], v[156:159], v[180:183], v[128:131]
	v_mfma_f32_16x16x32_bf16 v[116:119], v[148:151], v[188:191], v[116:119]
	v_mfma_f32_16x16x32_bf16 v[112:115], v[156:159], v[188:191], v[112:115]
	v_mfma_f32_16x16x32_bf16 v[100:103], v[148:151], v[196:199], v[100:103]
	v_mfma_f32_16x16x32_bf16 v[96:99], v[156:159], v[196:199], v[96:99]
	v_mfma_f32_16x16x32_bf16 v[84:87], v[148:151], v[204:207], v[84:87]
	v_mfma_f32_16x16x32_bf16 v[80:83], v[156:159], v[204:207], v[80:83]
	s_setprio 0
	s_barrier
	s_add_i32 s82, s75, s64
	s_mov_b64 s[96:97], s[60:61]

; #define PG8_STAGE(bufoff, gbase, voff) do { _Pragma("unroll") for (int _i = 0; _i < 2; ++_i) \
;         __builtin_amdgcn_global_load_lds((const unsigned*)((const char*)(gbase) + (voff)[_i]), (PG8_LAS unsigned*)(lds + (bufoff) + ldsw + _i * 8192), 16, 0, 0); } while (0)
; #define PG8_LDA(dst, b, h) do { _Pragma("unroll") for (int m = 0; m < 4; ++m) _Pragma("unroll") for (int k = 0; k < 2; ++k) dst[m][k] = *(const PG8_LAS bf16x8*)(lds + PG8_SA(b, h) + aoff + m * 2048 + k * 1024); } while (0)
; template <class Epi, class Sched, bool ALIGN_EPI = false, bool SP2 = false>
; __device__ __forceinline__ void gemm_phase(PG8_LAS unsigned char* lds, const Gemm g, const Sched& S, const Epi& E) {
;     ...
;             PG8_LDA(At, 0, 1); PG8_STAGE(PG8_SB(0, 0), b2, voffB); PG8_STAGE(PG8_SB(0, 1), b2 + hstep, voffB); PG8_STAGE(PG8_SA(0, 0), a2, voffA);
	s_mov_b32 m0, s82
	ds_read_b128 v[176:179], v215 offset:16384
	ds_read_b128 v[180:183], v215 offset:17408
	ds_read_b128 v[184:187], v215 offset:18432
	ds_read_b128 v[188:191], v215 offset:19456
	ds_read_b128 v[192:195], v215 offset:20480
	ds_read_b128 v[196:199], v215 offset:21504
	ds_read_b128 v[200:203], v215 offset:22528
	ds_read_b128 v[204:207], v215 offset:23552
	global_load_lds_dwordx4 v162, s[60:61]
	s_add_i32 m0, s82, 0x2000
	s_add_u32 s82, s60, 0x200000

; #define PG8_STAGE(bufoff, gbase, voff) do { _Pragma("unroll") for (int _i = 0; _i < 2; ++_i) \
;         __builtin_amdgcn_global_load_lds((const unsigned*)((const char*)(gbase) + (voff)[_i]), (PG8_LAS unsigned*)(lds + (bufoff) + ldsw + _i * 8192), 16, 0, 0); } while (0)
; #define PG8_LDA(dst, b, h) do { _Pragma("unroll") for (int m = 0; m < 4; ++m) _Pragma("unroll") for (int k = 0; k < 2; ++k) dst[m][k] = *(const PG8_LAS bf16x8*)(lds + PG8_SA(b, h) + aoff + m * 2048 + k * 1024); } while (0)
; template <class Epi, class Sched, bool ALIGN_EPI = false, bool SP2 = false>
; __device__ __forceinline__ void gemm_phase(PG8_LAS unsigned char* lds, const Gemm g, const Sched& S, const Epi& E) {
;     ...
;             PG8_LDA(At, 0, 1); PG8_STAGE(PG8_SB(0, 0), b2, voffB); PG8_STAGE(PG8_SB(0, 1), b2 + hstep, voffB); PG8_STAGE(PG8_SA(0, 0), a2, voffA);
	s_addc_u32 s83, s61, 0
	s_add_i32 s84, s76, s64
	global_load_lds_dwordx4 v166, s[60:61]

; #define PG8_STAGE(bufoff, gbase, voff) do { _Pragma("unroll") for (int _i = 0; _i < 2; ++_i) \
;         __builtin_amdgcn_global_load_lds((const unsigned*)((const char*)(gbase) + (voff)[_i]), (PG8_LAS unsigned*)(lds + (bufoff) + ldsw + _i * 8192), 16, 0, 0); } while (0)
; #define PG8_LDA(dst, b, h) do { _Pragma("unroll") for (int m = 0; m < 4; ++m) _Pragma("unroll") for (int k = 0; k < 2; ++k) dst[m][k] = *(const PG8_LAS bf16x8*)(lds + PG8_SA(b, h) + aoff + m * 2048 + k * 1024); } while (0)
; template <class Epi, class Sched, bool ALIGN_EPI = false, bool SP2 = false>
; __device__ __forceinline__ void gemm_phase(PG8_LAS unsigned char* lds, const Gemm g, const Sched& S, const Epi& E) {
;     ...
;             PG8_LDA(At, 0, 1); PG8_STAGE(PG8_SB(0, 0), b2, voffB); PG8_STAGE(PG8_SB(0, 1), b2 + hstep, voffB); PG8_STAGE(PG8_SA(0, 0), a2, voffA);
	s_mov_b32 m0, s84
	s_nop 0
	global_load_lds_dwordx4 v162, s[82:83]

; #define PG8_STAGE(bufoff, gbase, voff) do { _Pragma("unroll") for (int _i = 0; _i < 2; ++_i) \
;         __builtin_amdgcn_global_load_lds((const unsigned*)((const char*)(gbase) + (voff)[_i]), (PG8_LAS unsigned*)(lds + (bufoff) + ldsw + _i * 8192), 16, 0, 0); } while (0)
; #define PG8_LDA(dst, b, h) do { _Pragma("unroll") for (int m = 0; m < 4; ++m) _Pragma("unroll") for (int k = 0; k < 2; ++k) dst[m][k] = *(const PG8_LAS bf16x8*)(lds + PG8_SA(b, h) + aoff + m * 2048 + k * 1024); } while (0)
; template <class Epi, class Sched, bool ALIGN_EPI = false, bool SP2 = false>
; __device__ __forceinline__ void gemm_phase(PG8_LAS unsigned char* lds, const Gemm g, const Sched& S, const Epi& E) {
;     ...
;             PG8_LDA(At, 0, 1); PG8_STAGE(PG8_SB(0, 0), b2, voffB); PG8_STAGE(PG8_SB(0, 1), b2 + hstep, voffB); PG8_STAGE(PG8_SA(0, 0), a2, voffA);
	s_add_i32 m0, s84, 0x2000
	s_nop 0
	global_load_lds_dwordx4 v166, s[82:83]
	s_mov_b64 s[98:99], s[62:63]

; #define PG8_STAGE(bufoff, gbase, voff) do { _Pragma("unroll") for (int _i = 0; _i < 2; ++_i) \
;         __builtin_amdgcn_global_load_lds((const unsigned*)((const char*)(gbase) + (voff)[_i]), (PG8_LAS unsigned*)(lds + (bufoff) + ldsw + _i * 8192), 16, 0, 0); } while (0)
; #define PG8_LDA(dst, b, h) do { _Pragma("unroll") for (int m = 0; m < 4; ++m) _Pragma("unroll") for (int k = 0; k < 2; ++k) dst[m][k] = *(const PG8_LAS bf16x8*)(lds + PG8_SA(b, h) + aoff + m * 2048 + k * 1024); } while (0)
; #define PG8_MMA(ai, bj, At, Bt) do { __builtin_amdgcn_s_setprio(1); _Pragma("unroll") for (int m = 0; m < 4; ++m) _Pragma("unroll") for (int n = 0; n < 2; ++n) _Pragma("unroll") for (int k = 0; k < 2; ++k) \
;         acc[ai][bj][m][n] = __builtin_amdgcn_mfma_f32_16x16x32_bf16(Bt[n][k], At[m][k], acc[ai][bj][m][n], 0, 0, 0); __builtin_amdgcn_s_setprio(0); } while (0)
; #define PG8_WAIT_V(n) asm volatile("s_waitcnt vmcnt(" #n ")" ::: "memory")
; #define PG8_WAIT_L(n) asm volatile("s_waitcnt lgkmcnt(" #n ")" ::: "memory")
; #define PG8_BAR __builtin_amdgcn_s_barrier()
; #define PG8_SCHED __builtin_amdgcn_sched_barrier(0)
; template <class Epi, class Sched, bool ALIGN_EPI = false, bool SP2 = false>
; __device__ __forceinline__ void gemm_phase(PG8_LAS unsigned char* lds, const Gemm g, const Sched& S, const Epi& E) {
;     ...
;             PG8_LDA(At, 0, 1); PG8_STAGE(PG8_SB(0, 0), b2, voffB); PG8_STAGE(PG8_SB(0, 1), b2 + hstep, voffB); PG8_STAGE(PG8_SA(0, 0), a2, voffA);
;             PG8_WAIT_V(8); PG8_WAIT_L(0); PG8_BAR; PG8_MMA(1, 0, At, B0); PG8_MMA(1, 1, At, B1); PG8_BAR; PG8_SCHED;
	s_mov_b32 m0, s57
	s_nop 0
	global_load_lds_dwordx4 v160, s[62:63]
	s_mov_b32 m0, s65
	s_nop 0
	global_load_lds_dwordx4 v164, s[62:63]
	s_waitcnt vmcnt(8)
	s_waitcnt lgkmcnt(0)
	s_setprio 1
	s_barrier

; #define PG8_MMA(ai, bj, At, Bt) do { __builtin_amdgcn_s_setprio(1); _Pragma("unroll") for (int m = 0; m < 4; ++m) _Pragma("unroll") for (int n = 0; n < 2; ++n) _Pragma("unroll") for (int k = 0; k < 2; ++k) \
;         acc[ai][bj][m][n] = __builtin_amdgcn_mfma_f32_16x16x32_bf16(Bt[n][k], At[m][k], acc[ai][bj][m][n], 0, 0, 0); __builtin_amdgcn_s_setprio(0); } while (0)
; #define PG8_WAIT_V(n) asm volatile("s_waitcnt vmcnt(" #n ")" ::: "memory")
; #define PG8_WAIT_L(n) asm volatile("s_waitcnt lgkmcnt(" #n ")" ::: "memory")
; #define PG8_BAR __builtin_amdgcn_s_barrier()
; #define PG8_SCHED __builtin_amdgcn_sched_barrier(0)
; template <class Epi, class Sched, bool ALIGN_EPI = false, bool SP2 = false>
; __device__ __forceinline__ void gemm_phase(PG8_LAS unsigned char* lds, const Gemm g, const Sched& S, const Epi& E) {
;     ...
;             PG8_WAIT_V(8); PG8_WAIT_L(0); PG8_BAR; PG8_MMA(1, 0, At, B0); PG8_MMA(1, 1, At, B1); PG8_BAR; PG8_SCHED;
	v_mfma_f32_16x16x32_bf16 v[60:63], v[64:67], v[176:179], v[60:63]
	v_mfma_f32_16x16x32_bf16 v[56:59], v[72:75], v[176:179], v[56:59]
	v_mfma_f32_16x16x32_bf16 v[44:47], v[64:67], v[184:187], v[44:47]
	v_mfma_f32_16x16x32_bf16 v[40:43], v[72:75], v[184:187], v[40:43]
	v_mfma_f32_16x16x32_bf16 v[28:31], v[64:67], v[192:195], v[28:31]
	v_mfma_f32_16x16x32_bf16 v[24:27], v[72:75], v[192:195], v[24:27]
	v_mfma_f32_16x16x32_bf16 v[12:15], v[64:67], v[200:203], v[12:15]
	v_mfma_f32_16x16x32_bf16 v[8:11], v[72:75], v[200:203], v[8:11]
	v_mfma_f32_16x16x32_bf16 v[60:63], v[68:71], v[180:183], v[60:63]
	v_mfma_f32_16x16x32_bf16 v[56:59], v[76:79], v[180:183], v[56:59]
	v_mfma_f32_16x16x32_bf16 v[44:47], v[68:71], v[188:191], v[44:47]
	v_mfma_f32_16x16x32_bf16 v[40:43], v[76:79], v[188:191], v[40:43]
	v_mfma_f32_16x16x32_bf16 v[28:31], v[68:71], v[196:199], v[28:31]
	v_mfma_f32_16x16x32_bf16 v[24:27], v[76:79], v[196:199], v[24:27]
	v_mfma_f32_16x16x32_bf16 v[12:15], v[68:71], v[204:207], v[12:15]
	v_mfma_f32_16x16x32_bf16 v[8:11], v[76:79], v[204:207], v[8:11]


; #define PG8_STAGE(bufoff, gbase, voff) do { _Pragma("unroll") for (int _i = 0; _i < 2; ++_i) \
;         __builtin_amdgcn_global_load_lds((const unsigned*)((const char*)(gbase) + (voff)[_i]), (PG8_LAS unsigned*)(lds + (bufoff) + ldsw + _i * 8192), 16, 0, 0); } while (0)
; #define PG8_LDA(dst, b, h) do { _Pragma("unroll") for (int m = 0; m < 4; ++m) _Pragma("unroll") for (int k = 0; k < 2; ++k) dst[m][k] = *(const PG8_LAS bf16x8*)(lds + PG8_SA(b, h) + aoff + m * 2048 + k * 1024); } while (0)
; #define PG8_LDB(dst, b, h) do { _Pragma("unroll") for (int n = 0; n < 2; ++n) _Pragma("unroll") for (int k = 0; k < 2; ++k) dst[n][k] = *(const PG8_LAS bf16x8*)(lds + PG8_SB(b, h) + boff + n * 2048 + k * 1024); } while (0)
; #define PG8_MMA(ai, bj, At, Bt) do { __builtin_amdgcn_s_setprio(1); _Pragma("unroll") for (int m = 0; m < 4; ++m) _Pragma("unroll") for (int n = 0; n < 2; ++n) _Pragma("unroll") for (int k = 0; k < 2; ++k) \
;         acc[ai][bj][m][n] = __builtin_amdgcn_mfma_f32_16x16x32_bf16(Bt[n][k], At[m][k], acc[ai][bj][m][n], 0, 0, 0); __builtin_amdgcn_s_setprio(0); } while (0)
; #define PG8_WAIT_V(n) asm volatile("s_waitcnt vmcnt(" #n ")" ::: "memory")
; #define PG8_WAIT_L(n) asm volatile("s_waitcnt lgkmcnt(" #n ")" ::: "memory")
; #define PG8_BAR __builtin_amdgcn_s_barrier()
; #define PG8_SCHED __builtin_amdgcn_sched_barrier(0)
; template <class Epi, class Sched, bool ALIGN_EPI = false, bool SP2 = false>
; __device__ __forceinline__ void gemm_phase(PG8_LAS unsigned char* lds, const Gemm g, const Sched& S, const Epi& E) {
;     ...
;             PG8_WAIT_V(8); PG8_WAIT_L(0); PG8_BAR; PG8_MMA(1, 0, At, B0); PG8_MMA(1, 1, At, B1); PG8_BAR; PG8_SCHED;
;             PG8_LDB(B0, 1, 0); PG8_LDB(B1, 1, 1); PG8_SCHED; PG8_LDA(At, 1, 0); PG8_STAGE(PG8_SA(0, 1), a2 + hstep, voffA);
	v_mfma_f32_16x16x32_bf16 v[52:55], v[144:147], v[176:179], v[52:55]
	v_mfma_f32_16x16x32_bf16 v[48:51], v[152:155], v[176:179], v[48:51]
	v_mfma_f32_16x16x32_bf16 v[36:39], v[144:147], v[184:187], v[36:39]
	v_mfma_f32_16x16x32_bf16 v[32:35], v[152:155], v[184:187], v[32:35]
	v_mfma_f32_16x16x32_bf16 v[20:23], v[144:147], v[192:195], v[20:23]
	v_mfma_f32_16x16x32_bf16 v[16:19], v[152:155], v[192:195], v[16:19]
	v_mfma_f32_16x16x32_bf16 v[4:7], v[144:147], v[200:203], v[4:7]
	v_mfma_f32_16x16x32_bf16 v[0:3], v[152:155], v[200:203], v[0:3]
	v_mfma_f32_16x16x32_bf16 v[52:55], v[148:151], v[180:183], v[52:55]
	v_mfma_f32_16x16x32_bf16 v[48:51], v[156:159], v[180:183], v[48:51]
	v_mfma_f32_16x16x32_bf16 v[36:39], v[148:151], v[188:191], v[36:39]
	v_mfma_f32_16x16x32_bf16 v[32:35], v[156:159], v[188:191], v[32:35]
	v_mfma_f32_16x16x32_bf16 v[20:23], v[148:151], v[196:199], v[20:23]
	v_mfma_f32_16x16x32_bf16 v[16:19], v[156:159], v[196:199], v[16:19]
	v_mfma_f32_16x16x32_bf16 v[4:7], v[148:151], v[204:207], v[4:7]
	v_mfma_f32_16x16x32_bf16 v[0:3], v[156:159], v[204:207], v[0:3]
	s_setprio 0
	s_barrier
	s_add_i32 s82, 0, 0x18000
	s_add_i32 s83, 0, 0x1c000
	v_add_u32_e32 v76, s82, v211
	v_add_u32_e32 v156, s83, v211
	ds_read_b128 v[64:67], v76
	ds_read_b128 v[68:71], v76 offset:1024
	ds_read_b128 v[72:75], v76 offset:2048
	ds_read_b128 v[76:79], v76 offset:3072
	ds_read_b128 v[144:147], v156
	ds_read_b128 v[148:151], v156 offset:1024
	ds_read_b128 v[152:155], v156 offset:2048
	ds_read_b128 v[156:159], v156 offset:3072
	s_add_u32 s62, s62, 0x200000
	s_addc_u32 s63, s63, 0
	s_mov_b32 m0, s67

; #define PG8_STAGE(bufoff, gbase, voff) do { _Pragma("unroll") for (int _i = 0; _i < 2; ++_i) \
;         __builtin_amdgcn_global_load_lds((const unsigned*)((const char*)(gbase) + (voff)[_i]), (PG8_LAS unsigned*)(lds + (bufoff) + ldsw + _i * 8192), 16, 0, 0); } while (0)
; #define PG8_LDA(dst, b, h) do { _Pragma("unroll") for (int m = 0; m < 4; ++m) _Pragma("unroll") for (int k = 0; k < 2; ++k) dst[m][k] = *(const PG8_LAS bf16x8*)(lds + PG8_SA(b, h) + aoff + m * 2048 + k * 1024); } while (0)
; #define PG8_LDB(dst, b, h) do { _Pragma("unroll") for (int n = 0; n < 2; ++n) _Pragma("unroll") for (int k = 0; k < 2; ++k) dst[n][k] = *(const PG8_LAS bf16x8*)(lds + PG8_SB(b, h) + boff + n * 2048 + k * 1024); } while (0)
; #define PG8_SCHED __builtin_amdgcn_sched_barrier(0)
; template <class Epi, class Sched, bool ALIGN_EPI = false, bool SP2 = false>
; __device__ __forceinline__ void gemm_phase(PG8_LAS unsigned char* lds, const Gemm g, const Sched& S, const Epi& E) {
;     ...
;             PG8_LDB(B0, 1, 0); PG8_LDB(B1, 1, 1); PG8_SCHED; PG8_LDA(At, 1, 0); PG8_STAGE(PG8_SA(0, 1), a2 + hstep, voffA);
	ds_read_b128 v[176:179], v215 offset:32768
	ds_read_b128 v[180:183], v215 offset:33792
	ds_read_b128 v[184:187], v215 offset:34816
	ds_read_b128 v[188:191], v215 offset:35840
	ds_read_b128 v[192:195], v215 offset:36864
	ds_read_b128 v[196:199], v215 offset:37888
	ds_read_b128 v[200:203], v215 offset:38912
	ds_read_b128 v[204:207], v215 offset:39936
	global_load_lds_dwordx4 v160, s[62:63]

; #define PG8_STAGE(bufoff, gbase, voff) do { _Pragma("unroll") for (int _i = 0; _i < 2; ++_i) \
;         __builtin_amdgcn_global_load_lds((const unsigned*)((const char*)(gbase) + (voff)[_i]), (PG8_LAS unsigned*)(lds + (bufoff) + ldsw + _i * 8192), 16, 0, 0); } while (0)
; #define PG8_LDA(dst, b, h) do { _Pragma("unroll") for (int m = 0; m < 4; ++m) _Pragma("unroll") for (int k = 0; k < 2; ++k) dst[m][k] = *(const PG8_LAS bf16x8*)(lds + PG8_SA(b, h) + aoff + m * 2048 + k * 1024); } while (0)
; #define PG8_LDB(dst, b, h) do { _Pragma("unroll") for (int n = 0; n < 2; ++n) _Pragma("unroll") for (int k = 0; k < 2; ++k) dst[n][k] = *(const PG8_LAS bf16x8*)(lds + PG8_SB(b, h) + boff + n * 2048 + k * 1024); } while (0)
; #define PG8_MMA(ai, bj, At, Bt) do { __builtin_amdgcn_s_setprio(1); _Pragma("unroll") for (int m = 0; m < 4; ++m) _Pragma("unroll") for (int n = 0; n < 2; ++n) _Pragma("unroll") for (int k = 0; k < 2; ++k) \
;         acc[ai][bj][m][n] = __builtin_amdgcn_mfma_f32_16x16x32_bf16(Bt[n][k], At[m][k], acc[ai][bj][m][n], 0, 0, 0); __builtin_amdgcn_s_setprio(0); } while (0)
; #define PG8_WAIT_V(n) asm volatile("s_waitcnt vmcnt(" #n ")" ::: "memory")
; #define PG8_WAIT_L(n) asm volatile("s_waitcnt lgkmcnt(" #n ")" ::: "memory")
; #define PG8_BAR __builtin_amdgcn_s_barrier()
; #define PG8_SCHED __builtin_amdgcn_sched_barrier(0)
; template <class Epi, class Sched, bool ALIGN_EPI = false, bool SP2 = false>
; __device__ __forceinline__ void gemm_phase(PG8_LAS unsigned char* lds, const Gemm g, const Sched& S, const Epi& E) {
;     ...
;             PG8_LDB(B0, 1, 0); PG8_LDB(B1, 1, 1); PG8_SCHED; PG8_LDA(At, 1, 0); PG8_STAGE(PG8_SA(0, 1), a2 + hstep, voffA);
;             PG8_WAIT_V(8); PG8_WAIT_L(0); PG8_BAR; PG8_MMA(0, 0, At, B0); PG8_MMA(0, 1, At, B1); PG8_BAR; PG8_SCHED;
	s_mov_b32 m0, s68
	s_nop 0
	global_load_lds_dwordx4 v164, s[62:63]
	s_waitcnt vmcnt(8)
	s_waitcnt lgkmcnt(0)
	s_setprio 1
	s_barrier

; #define PG8_MMA(ai, bj, At, Bt) do { __builtin_amdgcn_s_setprio(1); _Pragma("unroll") for (int m = 0; m < 4; ++m) _Pragma("unroll") for (int n = 0; n < 2; ++n) _Pragma("unroll") for (int k = 0; k < 2; ++k) \
;         acc[ai][bj][m][n] = __builtin_amdgcn_mfma_f32_16x16x32_bf16(Bt[n][k], At[m][k], acc[ai][bj][m][n], 0, 0, 0); __builtin_amdgcn_s_setprio(0); } while (0)
; #define PG8_WAIT_V(n) asm volatile("s_waitcnt vmcnt(" #n ")" ::: "memory")
; #define PG8_WAIT_L(n) asm volatile("s_waitcnt lgkmcnt(" #n ")" ::: "memory")
; #define PG8_BAR __builtin_amdgcn_s_barrier()
; #define PG8_SCHED __builtin_amdgcn_sched_barrier(0)
; template <class Epi, class Sched, bool ALIGN_EPI = false, bool SP2 = false>
; __device__ __forceinline__ void gemm_phase(PG8_LAS unsigned char* lds, const Gemm g, const Sched& S, const Epi& E) {
;     ...
;             PG8_WAIT_V(8); PG8_WAIT_L(0); PG8_BAR; PG8_MMA(0, 0, At, B0); PG8_MMA(0, 1, At, B1); PG8_BAR; PG8_SCHED;
	v_mfma_f32_16x16x32_bf16 v[140:143], v[64:67], v[176:179], v[140:143]
	v_mfma_f32_16x16x32_bf16 v[136:139], v[72:75], v[176:179], v[136:139]
	v_mfma_f32_16x16x32_bf16 v[124:127], v[64:67], v[184:187], v[124:127]
	v_mfma_f32_16x16x32_bf16 v[120:123], v[72:75], v[184:187], v[120:123]
	v_mfma_f32_16x16x32_bf16 v[108:111], v[64:67], v[192:195], v[108:111]
	v_mfma_f32_16x16x32_bf16 v[104:107], v[72:75], v[192:195], v[104:107]
	v_mfma_f32_16x16x32_bf16 v[92:95], v[64:67], v[200:203], v[92:95]
	v_mfma_f32_16x16x32_bf16 v[88:91], v[72:75], v[200:203], v[88:91]
	v_mfma_f32_16x16x32_bf16 v[140:143], v[68:71], v[180:183], v[140:143]
	v_mfma_f32_16x16x32_bf16 v[136:139], v[76:79], v[180:183], v[136:139]
	v_mfma_f32_16x16x32_bf16 v[124:127], v[68:71], v[188:191], v[124:127]
	v_mfma_f32_16x16x32_bf16 v[120:123], v[76:79], v[188:191], v[120:123]
	v_mfma_f32_16x16x32_bf16 v[108:111], v[68:71], v[196:199], v[108:111]
	v_mfma_f32_16x16x32_bf16 v[104:107], v[76:79], v[196:199], v[104:107]
	v_mfma_f32_16x16x32_bf16 v[92:95], v[68:71], v[204:207], v[92:95]
	v_mfma_f32_16x16x32_bf16 v[88:91], v[76:79], v[204:207], v[88:91]


; #define PG8_MMA(ai, bj, At, Bt) do { __builtin_amdgcn_s_setprio(1); _Pragma("unroll") for (int m = 0; m < 4; ++m) _Pragma("unroll") for (int n = 0; n < 2; ++n) _Pragma("unroll") for (int k = 0; k < 2; ++k) \
;         acc[ai][bj][m][n] = __builtin_amdgcn_mfma_f32_16x16x32_bf16(Bt[n][k], At[m][k], acc[ai][bj][m][n], 0, 0, 0); __builtin_amdgcn_s_setprio(0); } while (0)
; #define PG8_WAIT_V(n) asm volatile("s_waitcnt vmcnt(" #n ")" ::: "memory")
; #define PG8_WAIT_L(n) asm volatile("s_waitcnt lgkmcnt(" #n ")" ::: "memory")
; #define PG8_BAR __builtin_amdgcn_s_barrier()
; #define PG8_SCHED __builtin_amdgcn_sched_barrier(0)
; template <class Epi, class Sched, bool ALIGN_EPI = false, bool SP2 = false>
; __device__ __forceinline__ void gemm_phase(PG8_LAS unsigned char* lds, const Gemm g, const Sched& S, const Epi& E) {
;     ...
;             PG8_WAIT_V(8); PG8_WAIT_L(0); PG8_BAR; PG8_MMA(0, 0, At, B0); PG8_MMA(0, 1, At, B1); PG8_BAR; PG8_SCHED;
	v_mfma_f32_16x16x32_bf16 v[132:135], v[144:147], v[176:179], v[132:135]
	v_mfma_f32_16x16x32_bf16 v[128:131], v[152:155], v[176:179], v[128:131]
	v_mfma_f32_16x16x32_bf16 v[116:119], v[144:147], v[184:187], v[116:119]
	v_mfma_f32_16x16x32_bf16 v[112:115], v[152:155], v[184:187], v[112:115]
	v_mfma_f32_16x16x32_bf16 v[100:103], v[144:147], v[192:195], v[100:103]
	v_mfma_f32_16x16x32_bf16 v[96:99], v[152:155], v[192:195], v[96:99]
	v_mfma_f32_16x16x32_bf16 v[84:87], v[144:147], v[200:203], v[84:87]
	v_mfma_f32_16x16x32_bf16 v[80:83], v[152:155], v[200:203], v[80:83]
	v_mfma_f32_16x16x32_bf16 v[132:135], v[148:151], v[180:183], v[132:135]
	v_mfma_f32_16x16x32_bf16 v[128:131], v[156:159], v[180:183], v[128:131]
	v_mfma_f32_16x16x32_bf16 v[116:119], v[148:151], v[188:191], v[116:119]
	v_mfma_f32_16x16x32_bf16 v[112:115], v[156:159], v[188:191], v[112:115]
	v_mfma_f32_16x16x32_bf16 v[100:103], v[148:151], v[196:199], v[100:103]
	v_mfma_f32_16x16x32_bf16 v[96:99], v[156:159], v[196:199], v[96:99]
	v_mfma_f32_16x16x32_bf16 v[84:87], v[148:151], v[204:207], v[84:87]
	v_mfma_f32_16x16x32_bf16 v[80:83], v[156:159], v[204:207], v[80:83]
	s_setprio 0
	s_barrier
	s_add_i32 s62, s82, s64

; #define PG8_STAGE(bufoff, gbase, voff) do { _Pragma("unroll") for (int _i = 0; _i < 2; ++_i) \
;         __builtin_amdgcn_global_load_lds((const unsigned*)((const char*)(gbase) + (voff)[_i]), (PG8_LAS unsigned*)(lds + (bufoff) + ldsw + _i * 8192), 16, 0, 0); } while (0)
; #define PG8_LDA(dst, b, h) do { _Pragma("unroll") for (int m = 0; m < 4; ++m) _Pragma("unroll") for (int k = 0; k < 2; ++k) dst[m][k] = *(const PG8_LAS bf16x8*)(lds + PG8_SA(b, h) + aoff + m * 2048 + k * 1024); } while (0)
; template <class Epi, class Sched, bool ALIGN_EPI = false, bool SP2 = false>
; __device__ __forceinline__ void gemm_phase(PG8_LAS unsigned char* lds, const Gemm g, const Sched& S, const Epi& E) {
;     ...
;             PG8_LDA(At, 1, 1); PG8_STAGE(PG8_SB(1, 0), b3, voffB); PG8_STAGE(PG8_SB(1, 1), b3 + hstep, voffB); PG8_STAGE(PG8_SA(1, 0), a3, voffA);
	s_mov_b32 m0, s62
	ds_read_b128 v[176:179], v215 offset:49152
	ds_read_b128 v[180:183], v215 offset:50176
	ds_read_b128 v[184:187], v215 offset:51200
	ds_read_b128 v[188:191], v215 offset:52224
	ds_read_b128 v[192:195], v215 offset:53248
	ds_read_b128 v[196:199], v215 offset:54272
	ds_read_b128 v[200:203], v215 offset:55296
	ds_read_b128 v[204:207], v215 offset:56320
	global_load_lds_dwordx4 v250, s[96:97]
	s_add_i32 m0, s62, 0x2000
	s_add_u32 s60, s60, 0x200080

; #define PG8_STAGE(bufoff, gbase, voff) do { _Pragma("unroll") for (int _i = 0; _i < 2; ++_i) \
;         __builtin_amdgcn_global_load_lds((const unsigned*)((const char*)(gbase) + (voff)[_i]), (PG8_LAS unsigned*)(lds + (bufoff) + ldsw + _i * 8192), 16, 0, 0); } while (0)
; #define PG8_LDA(dst, b, h) do { _Pragma("unroll") for (int m = 0; m < 4; ++m) _Pragma("unroll") for (int k = 0; k < 2; ++k) dst[m][k] = *(const PG8_LAS bf16x8*)(lds + PG8_SA(b, h) + aoff + m * 2048 + k * 1024); } while (0)
; template <class Epi, class Sched, bool ALIGN_EPI = false, bool SP2 = false>
; __device__ __forceinline__ void gemm_phase(PG8_LAS unsigned char* lds, const Gemm g, const Sched& S, const Epi& E) {
;     ...
;             PG8_LDA(At, 1, 1); PG8_STAGE(PG8_SB(1, 0), b3, voffB); PG8_STAGE(PG8_SB(1, 1), b3 + hstep, voffB); PG8_STAGE(PG8_SA(1, 0), a3, voffA);
	s_addc_u32 s61, s61, 0
	s_add_i32 s62, s83, s64
	global_load_lds_dwordx4 v251, s[96:97]

; #define PG8_STAGE(bufoff, gbase, voff) do { _Pragma("unroll") for (int _i = 0; _i < 2; ++_i) \
;         __builtin_amdgcn_global_load_lds((const unsigned*)((const char*)(gbase) + (voff)[_i]), (PG8_LAS unsigned*)(lds + (bufoff) + ldsw + _i * 8192), 16, 0, 0); } while (0)
; #define PG8_LDA(dst, b, h) do { _Pragma("unroll") for (int m = 0; m < 4; ++m) _Pragma("unroll") for (int k = 0; k < 2; ++k) dst[m][k] = *(const PG8_LAS bf16x8*)(lds + PG8_SA(b, h) + aoff + m * 2048 + k * 1024); } while (0)
; template <class Epi, class Sched, bool ALIGN_EPI = false, bool SP2 = false>
; __device__ __forceinline__ void gemm_phase(PG8_LAS unsigned char* lds, const Gemm g, const Sched& S, const Epi& E) {
;     ...
;             PG8_LDA(At, 1, 1); PG8_STAGE(PG8_SB(1, 0), b3, voffB); PG8_STAGE(PG8_SB(1, 1), b3 + hstep, voffB); PG8_STAGE(PG8_SA(1, 0), a3, voffA);
	s_mov_b32 m0, s62
	s_nop 0
	global_load_lds_dwordx4 v162, s[60:61]

; #define PG8_STAGE(bufoff, gbase, voff) do { _Pragma("unroll") for (int _i = 0; _i < 2; ++_i) \
;         __builtin_amdgcn_global_load_lds((const unsigned*)((const char*)(gbase) + (voff)[_i]), (PG8_LAS unsigned*)(lds + (bufoff) + ldsw + _i * 8192), 16, 0, 0); } while (0)
; #define PG8_LDA(dst, b, h) do { _Pragma("unroll") for (int m = 0; m < 4; ++m) _Pragma("unroll") for (int k = 0; k < 2; ++k) dst[m][k] = *(const PG8_LAS bf16x8*)(lds + PG8_SA(b, h) + aoff + m * 2048 + k * 1024); } while (0)
; template <class Epi, class Sched, bool ALIGN_EPI = false, bool SP2 = false>
; __device__ __forceinline__ void gemm_phase(PG8_LAS unsigned char* lds, const Gemm g, const Sched& S, const Epi& E) {
;     ...
;             PG8_LDA(At, 1, 1); PG8_STAGE(PG8_SB(1, 0), b3, voffB); PG8_STAGE(PG8_SB(1, 1), b3 + hstep, voffB); PG8_STAGE(PG8_SA(1, 0), a3, voffA);
	s_add_i32 m0, s62, 0x2000
	s_nop 0
	global_load_lds_dwordx4 v166, s[60:61]

; #define PG8_STAGE(bufoff, gbase, voff) do { _Pragma("unroll") for (int _i = 0; _i < 2; ++_i) \
;         __builtin_amdgcn_global_load_lds((const unsigned*)((const char*)(gbase) + (voff)[_i]), (PG8_LAS unsigned*)(lds + (bufoff) + ldsw + _i * 8192), 16, 0, 0); } while (0)
; #define PG8_LDA(dst, b, h) do { _Pragma("unroll") for (int m = 0; m < 4; ++m) _Pragma("unroll") for (int k = 0; k < 2; ++k) dst[m][k] = *(const PG8_LAS bf16x8*)(lds + PG8_SA(b, h) + aoff + m * 2048 + k * 1024); } while (0)
; template <class Epi, class Sched, bool ALIGN_EPI = false, bool SP2 = false>
; __device__ __forceinline__ void gemm_phase(PG8_LAS unsigned char* lds, const Gemm g, const Sched& S, const Epi& E) {
;     ...
;             PG8_LDA(At, 1, 1); PG8_STAGE(PG8_SB(1, 0), b3, voffB); PG8_STAGE(PG8_SB(1, 1), b3 + hstep, voffB); PG8_STAGE(PG8_SA(1, 0), a3, voffA);
	s_mov_b32 m0, s70
	s_nop 0
	global_load_lds_dwordx4 v252, s[98:99]

; #define PG8_STAGE(bufoff, gbase, voff) do { _Pragma("unroll") for (int _i = 0; _i < 2; ++_i) \
;         __builtin_amdgcn_global_load_lds((const unsigned*)((const char*)(gbase) + (voff)[_i]), (PG8_LAS unsigned*)(lds + (bufoff) + ldsw + _i * 8192), 16, 0, 0); } while (0)
; #define PG8_LDA(dst, b, h) do { _Pragma("unroll") for (int m = 0; m < 4; ++m) _Pragma("unroll") for (int k = 0; k < 2; ++k) dst[m][k] = *(const PG8_LAS bf16x8*)(lds + PG8_SA(b, h) + aoff + m * 2048 + k * 1024); } while (0)
; #define PG8_MMA(ai, bj, At, Bt) do { __builtin_amdgcn_s_setprio(1); _Pragma("unroll") for (int m = 0; m < 4; ++m) _Pragma("unroll") for (int n = 0; n < 2; ++n) _Pragma("unroll") for (int k = 0; k < 2; ++k) \
;         acc[ai][bj][m][n] = __builtin_amdgcn_mfma_f32_16x16x32_bf16(Bt[n][k], At[m][k], acc[ai][bj][m][n], 0, 0, 0); __builtin_amdgcn_s_setprio(0); } while (0)
; #define PG8_WAIT_V(n) asm volatile("s_waitcnt vmcnt(" #n ")" ::: "memory")
; #define PG8_WAIT_L(n) asm volatile("s_waitcnt lgkmcnt(" #n ")" ::: "memory")
; #define PG8_BAR __builtin_amdgcn_s_barrier()
; #define PG8_SCHED __builtin_amdgcn_sched_barrier(0)
; template <class Epi, class Sched, bool ALIGN_EPI = false, bool SP2 = false>
; __device__ __forceinline__ void gemm_phase(PG8_LAS unsigned char* lds, const Gemm g, const Sched& S, const Epi& E) {
;     ...
;             PG8_LDA(At, 1, 1); PG8_STAGE(PG8_SB(1, 0), b3, voffB); PG8_STAGE(PG8_SB(1, 1), b3 + hstep, voffB); PG8_STAGE(PG8_SA(1, 0), a3, voffA);
;             PG8_WAIT_V(8); PG8_WAIT_L(0); PG8_BAR; PG8_MMA(1, 0, At, B0); PG8_MMA(1, 1, At, B1); PG8_BAR; PG8_SCHED;
	s_mov_b32 m0, s71
	s_nop 0
	global_load_lds_dwordx4 v253, s[98:99]
	s_waitcnt vmcnt(8)
	s_waitcnt lgkmcnt(0)
	s_setprio 1
	s_barrier

; #define PG8_MMA(ai, bj, At, Bt) do { __builtin_amdgcn_s_setprio(1); _Pragma("unroll") for (int m = 0; m < 4; ++m) _Pragma("unroll") for (int n = 0; n < 2; ++n) _Pragma("unroll") for (int k = 0; k < 2; ++k) \
;         acc[ai][bj][m][n] = __builtin_amdgcn_mfma_f32_16x16x32_bf16(Bt[n][k], At[m][k], acc[ai][bj][m][n], 0, 0, 0); __builtin_amdgcn_s_setprio(0); } while (0)
; #define PG8_WAIT_V(n) asm volatile("s_waitcnt vmcnt(" #n ")" ::: "memory")
; #define PG8_WAIT_L(n) asm volatile("s_waitcnt lgkmcnt(" #n ")" ::: "memory")
; #define PG8_BAR __builtin_amdgcn_s_barrier()
; #define PG8_SCHED __builtin_amdgcn_sched_barrier(0)
; template <class Epi, class Sched, bool ALIGN_EPI = false, bool SP2 = false>
; __device__ __forceinline__ void gemm_phase(PG8_LAS unsigned char* lds, const Gemm g, const Sched& S, const Epi& E) {
;     ...
;             PG8_WAIT_V(8); PG8_WAIT_L(0); PG8_BAR; PG8_MMA(1, 0, At, B0); PG8_MMA(1, 1, At, B1); PG8_BAR; PG8_SCHED;
	v_mfma_f32_16x16x32_bf16 v[60:63], v[64:67], v[176:179], v[60:63]
	v_mfma_f32_16x16x32_bf16 v[56:59], v[72:75], v[176:179], v[56:59]
	v_mfma_f32_16x16x32_bf16 v[44:47], v[64:67], v[184:187], v[44:47]
	v_mfma_f32_16x16x32_bf16 v[40:43], v[72:75], v[184:187], v[40:43]
	v_mfma_f32_16x16x32_bf16 v[28:31], v[64:67], v[192:195], v[28:31]
	v_mfma_f32_16x16x32_bf16 v[24:27], v[72:75], v[192:195], v[24:27]
	v_mfma_f32_16x16x32_bf16 v[12:15], v[64:67], v[200:203], v[12:15]
	v_mfma_f32_16x16x32_bf16 v[8:11], v[72:75], v[200:203], v[8:11]
	v_mfma_f32_16x16x32_bf16 v[60:63], v[68:71], v[180:183], v[60:63]
	v_mfma_f32_16x16x32_bf16 v[56:59], v[76:79], v[180:183], v[56:59]
	v_mfma_f32_16x16x32_bf16 v[44:47], v[68:71], v[188:191], v[44:47]
	v_mfma_f32_16x16x32_bf16 v[40:43], v[76:79], v[188:191], v[40:43]
	v_mfma_f32_16x16x32_bf16 v[28:31], v[68:71], v[196:199], v[28:31]
	v_mfma_f32_16x16x32_bf16 v[24:27], v[76:79], v[196:199], v[24:27]
	v_mfma_f32_16x16x32_bf16 v[12:15], v[68:71], v[204:207], v[12:15]
	v_mfma_f32_16x16x32_bf16 v[8:11], v[76:79], v[204:207], v[8:11]


; #define PG8_MMA(ai, bj, At, Bt) do { __builtin_amdgcn_s_setprio(1); _Pragma("unroll") for (int m = 0; m < 4; ++m) _Pragma("unroll") for (int n = 0; n < 2; ++n) _Pragma("unroll") for (int k = 0; k < 2; ++k) \
;         acc[ai][bj][m][n] = __builtin_amdgcn_mfma_f32_16x16x32_bf16(Bt[n][k], At[m][k], acc[ai][bj][m][n], 0, 0, 0); __builtin_amdgcn_s_setprio(0); } while (0)
; #define PG8_WAIT_V(n) asm volatile("s_waitcnt vmcnt(" #n ")" ::: "memory")
; #define PG8_WAIT_L(n) asm volatile("s_waitcnt lgkmcnt(" #n ")" ::: "memory")
; #define PG8_BAR __builtin_amdgcn_s_barrier()
; #define PG8_SCHED __builtin_amdgcn_sched_barrier(0)
; template <class Epi, class Sched, bool ALIGN_EPI = false, bool SP2 = false>
; __device__ __forceinline__ void gemm_phase(PG8_LAS unsigned char* lds, const Gemm g, const Sched& S, const Epi& E) {
;     ...
;             PG8_WAIT_V(8); PG8_WAIT_L(0); PG8_BAR; PG8_MMA(1, 0, At, B0); PG8_MMA(1, 1, At, B1); PG8_BAR; PG8_SCHED;
	v_mfma_f32_16x16x32_bf16 v[52:55], v[144:147], v[176:179], v[52:55]
	v_mfma_f32_16x16x32_bf16 v[48:51], v[152:155], v[176:179], v[48:51]
	v_mfma_f32_16x16x32_bf16 v[36:39], v[144:147], v[184:187], v[36:39]
	v_mfma_f32_16x16x32_bf16 v[32:35], v[152:155], v[184:187], v[32:35]
	v_mfma_f32_16x16x32_bf16 v[20:23], v[144:147], v[192:195], v[20:23]
	v_mfma_f32_16x16x32_bf16 v[16:19], v[152:155], v[192:195], v[16:19]
	v_mfma_f32_16x16x32_bf16 v[4:7], v[144:147], v[200:203], v[4:7]
	v_mfma_f32_16x16x32_bf16 v[0:3], v[152:155], v[200:203], v[0:3]
	v_mfma_f32_16x16x32_bf16 v[52:55], v[148:151], v[180:183], v[52:55]
	v_mfma_f32_16x16x32_bf16 v[48:51], v[156:159], v[180:183], v[48:51]
	v_mfma_f32_16x16x32_bf16 v[36:39], v[148:151], v[188:191], v[36:39]
	v_mfma_f32_16x16x32_bf16 v[32:35], v[156:159], v[188:191], v[32:35]
	v_mfma_f32_16x16x32_bf16 v[20:23], v[148:151], v[196:199], v[20:23]
	v_mfma_f32_16x16x32_bf16 v[16:19], v[156:159], v[196:199], v[16:19]
	v_mfma_f32_16x16x32_bf16 v[4:7], v[148:151], v[204:207], v[4:7]
	v_mfma_f32_16x16x32_bf16 v[0:3], v[156:159], v[204:207], v[0:3]
	s_setprio 0
	s_barrier
	s_add_i32 s81, s81, 2
	s_add_u32 s58, s58, 0x100
	s_addc_u32 s59, s59, 0
	s_add_u32 s79, s79, 0x100
	s_addc_u32 s80, s80, 0
	s_cmpk_gt_u32 s81, 0x7d
	s_cbranch_scc0 .LBB0_509
	s_and_b64 vcc, exec, s[42:43]
	s_cbranch_vccz .LBB0_512
	s_barrier

; #define PG8_STAGE(bufoff, gbase, voff) do { _Pragma("unroll") for (int _i = 0; _i < 2; ++_i) \
;         __builtin_amdgcn_global_load_lds((const unsigned*)((const char*)(gbase) + (voff)[_i]), (PG8_LAS unsigned*)(lds + (bufoff) + ldsw + _i * 8192), 16, 0, 0); } while (0)
; #define PG8_LDA(dst, b, h) do { _Pragma("unroll") for (int m = 0; m < 4; ++m) _Pragma("unroll") for (int k = 0; k < 2; ++k) dst[m][k] = *(const PG8_LAS bf16x8*)(lds + PG8_SA(b, h) + aoff + m * 2048 + k * 1024); } while (0)
; #define PG8_LDB(dst, b, h) do { _Pragma("unroll") for (int n = 0; n < 2; ++n) _Pragma("unroll") for (int k = 0; k < 2; ++k) dst[n][k] = *(const PG8_LAS bf16x8*)(lds + PG8_SB(b, h) + boff + n * 2048 + k * 1024); } while (0)
; #define PG8_SCHED __builtin_amdgcn_sched_barrier(0)
; template <class Epi, class Sched, bool ALIGN_EPI = false, bool SP2 = false>
; __device__ __forceinline__ void gemm_phase(PG8_LAS unsigned char* lds, const Gemm g, const Sched& S, const Epi& E) {
;     ...
;             const bool last = (t == nt - 2);
;             const char* a1 = cA + (size_t)(t + 1) * kstep;
;             const char* a2 = last ? nA : cA + (size_t)(t + 2) * kstep; const char* b2 = last ? nB : cB + (size_t)(t + 2) * kstep;
;             const char* a3 = a2 + kstep; const char* b3 = b2 + kstep;
;             if (last && has_next) S.a_ready(nxt);
;             if constexpr (SP2) {
;             PG8_LDB(B0, 0, 0); PG8_LDB(B1, 0, 1); PG8_SCHED; PG8_LDA(At, 0, 0); PG8_STAGE(PG8_SA(1, 1), a1 + hstep, voffA);
.LBB0_679:
	ds_read_b128 v[128:131], v203
	ds_read_b128 v[132:135], v203 offset:1024
	ds_read_b128 v[136:139], v203 offset:2048
	ds_read_b128 v[140:143], v203 offset:3072
	ds_read_b128 v[144:147], v205
	ds_read_b128 v[148:151], v205 offset:1024
	ds_read_b128 v[152:155], v205 offset:2048
	ds_read_b128 v[156:159], v205 offset:3072
	s_add_u32 s12, s10, 0xfff80080
	s_addc_u32 s13, s11, -1
	s_cmp_eq_u32 s78, 28
	s_cselect_b32 s55, s49, s13
	s_cselect_b32 s54, s74, s12
	s_cselect_b32 s13, s47, s77
	s_cselect_b32 s12, s75, s76

; #define PG8_STAGE(bufoff, gbase, voff) do { _Pragma("unroll") for (int _i = 0; _i < 2; ++_i) \
;         __builtin_amdgcn_global_load_lds((const unsigned*)((const char*)(gbase) + (voff)[_i]), (PG8_LAS unsigned*)(lds + (bufoff) + ldsw + _i * 8192), 16, 0, 0); } while (0)
; #define PG8_LDA(dst, b, h) do { _Pragma("unroll") for (int m = 0; m < 4; ++m) _Pragma("unroll") for (int k = 0; k < 2; ++k) dst[m][k] = *(const PG8_LAS bf16x8*)(lds + PG8_SA(b, h) + aoff + m * 2048 + k * 1024); } while (0)
; #define PG8_LDB(dst, b, h) do { _Pragma("unroll") for (int n = 0; n < 2; ++n) _Pragma("unroll") for (int k = 0; k < 2; ++k) dst[n][k] = *(const PG8_LAS bf16x8*)(lds + PG8_SB(b, h) + boff + n * 2048 + k * 1024); } while (0)
; #define PG8_SCHED __builtin_amdgcn_sched_barrier(0)
; template <class Epi, class Sched, bool ALIGN_EPI = false, bool SP2 = false>
; __device__ __forceinline__ void gemm_phase(PG8_LAS unsigned char* lds, const Gemm g, const Sched& S, const Epi& E) {
;     ...
;             PG8_LDB(B0, 0, 0); PG8_LDB(B1, 0, 1); PG8_SCHED; PG8_LDA(At, 0, 0); PG8_STAGE(PG8_SA(1, 1), a1 + hstep, voffA);
	s_add_i32 m0, s60, 0xc000
	ds_read_b128 v[176:179], v207
	ds_read_b128 v[180:183], v207 offset:1024
	ds_read_b128 v[184:187], v207 offset:2048
	ds_read_b128 v[192:195], v207 offset:3072
	ds_read_b128 v[210:213], v207 offset:4096
	ds_read_b128 v[214:217], v207 offset:5120
	ds_read_b128 v[218:221], v207 offset:6144
	ds_read_b128 v[222:225], v207 offset:7168
	global_load_lds_dwordx4 v168, s[10:11]

; #define PG8_STAGE(bufoff, gbase, voff) do { _Pragma("unroll") for (int _i = 0; _i < 2; ++_i) \
;         __builtin_amdgcn_global_load_lds((const unsigned*)((const char*)(gbase) + (voff)[_i]), (PG8_LAS unsigned*)(lds + (bufoff) + ldsw + _i * 8192), 16, 0, 0); } while (0)
; #define PG8_LDA(dst, b, h) do { _Pragma("unroll") for (int m = 0; m < 4; ++m) _Pragma("unroll") for (int k = 0; k < 2; ++k) dst[m][k] = *(const PG8_LAS bf16x8*)(lds + PG8_SA(b, h) + aoff + m * 2048 + k * 1024); } while (0)
; #define PG8_LDB(dst, b, h) do { _Pragma("unroll") for (int n = 0; n < 2; ++n) _Pragma("unroll") for (int k = 0; k < 2; ++k) dst[n][k] = *(const PG8_LAS bf16x8*)(lds + PG8_SB(b, h) + boff + n * 2048 + k * 1024); } while (0)
; #define PG8_MMA(ai, bj, At, Bt) do { __builtin_amdgcn_s_setprio(1); _Pragma("unroll") for (int m = 0; m < 4; ++m) _Pragma("unroll") for (int n = 0; n < 2; ++n) _Pragma("unroll") for (int k = 0; k < 2; ++k) \
;         acc[ai][bj][m][n] = __builtin_amdgcn_mfma_f32_16x16x32_bf16(Bt[n][k], At[m][k], acc[ai][bj][m][n], 0, 0, 0); __builtin_amdgcn_s_setprio(0); } while (0)
; #define PG8_WAIT_V(n) asm volatile("s_waitcnt vmcnt(" #n ")" ::: "memory")
; #define PG8_WAIT_L(n) asm volatile("s_waitcnt lgkmcnt(" #n ")" ::: "memory")
; #define PG8_BAR __builtin_amdgcn_s_barrier()
; #define PG8_SCHED __builtin_amdgcn_sched_barrier(0)
; template <class Epi, class Sched, bool ALIGN_EPI = false, bool SP2 = false>
; __device__ __forceinline__ void gemm_phase(PG8_LAS unsigned char* lds, const Gemm g, const Sched& S, const Epi& E) {
;     ...
;             PG8_LDB(B0, 0, 0); PG8_LDB(B1, 0, 1); PG8_SCHED; PG8_LDA(At, 0, 0); PG8_STAGE(PG8_SA(1, 1), a1 + hstep, voffA);
;             PG8_WAIT_V(8); PG8_WAIT_L(0); PG8_BAR; PG8_MMA(0, 0, At, B0); PG8_MMA(0, 1, At, B1); PG8_BAR; PG8_SCHED;
	s_add_i32 m0, s60, 0xe000
	s_nop 0
	global_load_lds_dwordx4 v170, s[10:11]
	s_waitcnt vmcnt(8)
	s_waitcnt lgkmcnt(0)
	s_setprio 1
	s_barrier

; #define PG8_MMA(ai, bj, At, Bt) do { __builtin_amdgcn_s_setprio(1); _Pragma("unroll") for (int m = 0; m < 4; ++m) _Pragma("unroll") for (int n = 0; n < 2; ++n) _Pragma("unroll") for (int k = 0; k < 2; ++k) \
;         acc[ai][bj][m][n] = __builtin_amdgcn_mfma_f32_16x16x32_bf16(Bt[n][k], At[m][k], acc[ai][bj][m][n], 0, 0, 0); __builtin_amdgcn_s_setprio(0); } while (0)
; #define PG8_WAIT_V(n) asm volatile("s_waitcnt vmcnt(" #n ")" ::: "memory")
; #define PG8_WAIT_L(n) asm volatile("s_waitcnt lgkmcnt(" #n ")" ::: "memory")
; #define PG8_BAR __builtin_amdgcn_s_barrier()
; #define PG8_SCHED __builtin_amdgcn_sched_barrier(0)
; template <class Epi, class Sched, bool ALIGN_EPI = false, bool SP2 = false>
; __device__ __forceinline__ void gemm_phase(PG8_LAS unsigned char* lds, const Gemm g, const Sched& S, const Epi& E) {
;     ...
;             PG8_WAIT_V(8); PG8_WAIT_L(0); PG8_BAR; PG8_MMA(0, 0, At, B0); PG8_MMA(0, 1, At, B1); PG8_BAR; PG8_SCHED;
	v_mfma_f32_16x16x32_bf16 v[124:127], v[128:131], v[176:179], v[124:127]
	v_mfma_f32_16x16x32_bf16 v[120:123], v[136:139], v[176:179], v[120:123]
	v_mfma_f32_16x16x32_bf16 v[112:115], v[128:131], v[184:187], v[112:115]
	v_mfma_f32_16x16x32_bf16 v[104:107], v[136:139], v[184:187], v[104:107]
	v_mfma_f32_16x16x32_bf16 v[100:103], v[128:131], v[210:213], v[100:103]
	v_mfma_f32_16x16x32_bf16 v[88:91], v[136:139], v[210:213], v[88:91]
	v_mfma_f32_16x16x32_bf16 v[84:87], v[128:131], v[218:221], v[84:87]
	v_mfma_f32_16x16x32_bf16 v[72:75], v[136:139], v[218:221], v[72:75]
	v_mfma_f32_16x16x32_bf16 v[124:127], v[132:135], v[180:183], v[124:127]
	v_mfma_f32_16x16x32_bf16 v[120:123], v[140:143], v[180:183], v[120:123]
	v_mfma_f32_16x16x32_bf16 v[112:115], v[132:135], v[192:195], v[112:115]
	v_mfma_f32_16x16x32_bf16 v[104:107], v[140:143], v[192:195], v[104:107]
	v_mfma_f32_16x16x32_bf16 v[100:103], v[132:135], v[214:217], v[100:103]
	v_mfma_f32_16x16x32_bf16 v[88:91], v[140:143], v[214:217], v[88:91]
	v_mfma_f32_16x16x32_bf16 v[84:87], v[132:135], v[222:225], v[84:87]
	v_mfma_f32_16x16x32_bf16 v[72:75], v[140:143], v[222:225], v[72:75]


; #define PG8_MMA(ai, bj, At, Bt) do { __builtin_amdgcn_s_setprio(1); _Pragma("unroll") for (int m = 0; m < 4; ++m) _Pragma("unroll") for (int n = 0; n < 2; ++n) _Pragma("unroll") for (int k = 0; k < 2; ++k) \
;         acc[ai][bj][m][n] = __builtin_amdgcn_mfma_f32_16x16x32_bf16(Bt[n][k], At[m][k], acc[ai][bj][m][n], 0, 0, 0); __builtin_amdgcn_s_setprio(0); } while (0)
; #define PG8_WAIT_V(n) asm volatile("s_waitcnt vmcnt(" #n ")" ::: "memory")
; #define PG8_WAIT_L(n) asm volatile("s_waitcnt lgkmcnt(" #n ")" ::: "memory")
; #define PG8_BAR __builtin_amdgcn_s_barrier()
; #define PG8_SCHED __builtin_amdgcn_sched_barrier(0)
; template <class Epi, class Sched, bool ALIGN_EPI = false, bool SP2 = false>
; __device__ __forceinline__ void gemm_phase(PG8_LAS unsigned char* lds, const Gemm g, const Sched& S, const Epi& E) {
;     ...
;             PG8_WAIT_V(8); PG8_WAIT_L(0); PG8_BAR; PG8_MMA(0, 0, At, B0); PG8_MMA(0, 1, At, B1); PG8_BAR; PG8_SCHED;
	v_mfma_f32_16x16x32_bf16 v[116:119], v[144:147], v[176:179], v[116:119]
	v_mfma_f32_16x16x32_bf16 v[108:111], v[152:155], v[176:179], v[108:111]
	v_mfma_f32_16x16x32_bf16 v[96:99], v[144:147], v[184:187], v[96:99]
	v_mfma_f32_16x16x32_bf16 v[92:95], v[152:155], v[184:187], v[92:95]
	v_mfma_f32_16x16x32_bf16 v[80:83], v[144:147], v[210:213], v[80:83]
	v_mfma_f32_16x16x32_bf16 v[76:79], v[152:155], v[210:213], v[76:79]
	v_mfma_f32_16x16x32_bf16 v[68:71], v[144:147], v[218:221], v[68:71]
	v_mfma_f32_16x16x32_bf16 v[64:67], v[152:155], v[218:221], v[64:67]
	v_mfma_f32_16x16x32_bf16 v[116:119], v[148:151], v[180:183], v[116:119]
	v_mfma_f32_16x16x32_bf16 v[108:111], v[156:159], v[180:183], v[108:111]
	v_mfma_f32_16x16x32_bf16 v[96:99], v[148:151], v[192:195], v[96:99]
	v_mfma_f32_16x16x32_bf16 v[92:95], v[156:159], v[192:195], v[92:95]
	v_mfma_f32_16x16x32_bf16 v[80:83], v[148:151], v[214:217], v[80:83]
	v_mfma_f32_16x16x32_bf16 v[76:79], v[156:159], v[214:217], v[76:79]
	v_mfma_f32_16x16x32_bf16 v[68:71], v[148:151], v[222:225], v[68:71]
	v_mfma_f32_16x16x32_bf16 v[64:67], v[156:159], v[222:225], v[64:67]
	s_setprio 0
	s_barrier
	s_add_i32 s79, s70, s57
	s_mov_b64 s[96:97], s[12:13]

; #define PG8_STAGE(bufoff, gbase, voff) do { _Pragma("unroll") for (int _i = 0; _i < 2; ++_i) \
;         __builtin_amdgcn_global_load_lds((const unsigned*)((const char*)(gbase) + (voff)[_i]), (PG8_LAS unsigned*)(lds + (bufoff) + ldsw + _i * 8192), 16, 0, 0); } while (0)
; #define PG8_LDA(dst, b, h) do { _Pragma("unroll") for (int m = 0; m < 4; ++m) _Pragma("unroll") for (int k = 0; k < 2; ++k) dst[m][k] = *(const PG8_LAS bf16x8*)(lds + PG8_SA(b, h) + aoff + m * 2048 + k * 1024); } while (0)
; template <class Epi, class Sched, bool ALIGN_EPI = false, bool SP2 = false>
; __device__ __forceinline__ void gemm_phase(PG8_LAS unsigned char* lds, const Gemm g, const Sched& S, const Epi& E) {
;     ...
;             PG8_LDA(At, 0, 1); PG8_STAGE(PG8_SB(0, 0), b2, voffB); PG8_STAGE(PG8_SB(0, 1), b2 + hstep, voffB); PG8_STAGE(PG8_SA(0, 0), a2, voffA);
	s_mov_b32 m0, s79
	ds_read_b128 v[176:179], v207 offset:16384
	ds_read_b128 v[180:183], v207 offset:17408
	ds_read_b128 v[184:187], v207 offset:18432
	ds_read_b128 v[192:195], v207 offset:19456
	ds_read_b128 v[210:213], v207 offset:20480
	ds_read_b128 v[214:217], v207 offset:21504
	ds_read_b128 v[218:221], v207 offset:22528
	ds_read_b128 v[222:225], v207 offset:23552
	global_load_lds_dwordx4 v164, s[12:13]
	s_add_i32 m0, s79, 0x2000
	s_add_u32 s80, s12, 0x80000

; #define PG8_STAGE(bufoff, gbase, voff) do { _Pragma("unroll") for (int _i = 0; _i < 2; ++_i) \
;         __builtin_amdgcn_global_load_lds((const unsigned*)((const char*)(gbase) + (voff)[_i]), (PG8_LAS unsigned*)(lds + (bufoff) + ldsw + _i * 8192), 16, 0, 0); } while (0)
; #define PG8_LDA(dst, b, h) do { _Pragma("unroll") for (int m = 0; m < 4; ++m) _Pragma("unroll") for (int k = 0; k < 2; ++k) dst[m][k] = *(const PG8_LAS bf16x8*)(lds + PG8_SA(b, h) + aoff + m * 2048 + k * 1024); } while (0)
; template <class Epi, class Sched, bool ALIGN_EPI = false, bool SP2 = false>
; __device__ __forceinline__ void gemm_phase(PG8_LAS unsigned char* lds, const Gemm g, const Sched& S, const Epi& E) {
;     ...
;             PG8_LDA(At, 0, 1); PG8_STAGE(PG8_SB(0, 0), b2, voffB); PG8_STAGE(PG8_SB(0, 1), b2 + hstep, voffB); PG8_STAGE(PG8_SA(0, 0), a2, voffA);
	s_addc_u32 s81, s13, 0
	s_add_i32 s79, s71, s57
	global_load_lds_dwordx4 v160, s[12:13]

; #define PG8_STAGE(bufoff, gbase, voff) do { _Pragma("unroll") for (int _i = 0; _i < 2; ++_i) \
;         __builtin_amdgcn_global_load_lds((const unsigned*)((const char*)(gbase) + (voff)[_i]), (PG8_LAS unsigned*)(lds + (bufoff) + ldsw + _i * 8192), 16, 0, 0); } while (0)
; #define PG8_LDA(dst, b, h) do { _Pragma("unroll") for (int m = 0; m < 4; ++m) _Pragma("unroll") for (int k = 0; k < 2; ++k) dst[m][k] = *(const PG8_LAS bf16x8*)(lds + PG8_SA(b, h) + aoff + m * 2048 + k * 1024); } while (0)
; template <class Epi, class Sched, bool ALIGN_EPI = false, bool SP2 = false>
; __device__ __forceinline__ void gemm_phase(PG8_LAS unsigned char* lds, const Gemm g, const Sched& S, const Epi& E) {
;     ...
;             PG8_LDA(At, 0, 1); PG8_STAGE(PG8_SB(0, 0), b2, voffB); PG8_STAGE(PG8_SB(0, 1), b2 + hstep, voffB); PG8_STAGE(PG8_SA(0, 0), a2, voffA);
	s_mov_b32 m0, s79
	s_nop 0
	global_load_lds_dwordx4 v164, s[80:81]

; #define PG8_STAGE(bufoff, gbase, voff) do { _Pragma("unroll") for (int _i = 0; _i < 2; ++_i) \
;         __builtin_amdgcn_global_load_lds((const unsigned*)((const char*)(gbase) + (voff)[_i]), (PG8_LAS unsigned*)(lds + (bufoff) + ldsw + _i * 8192), 16, 0, 0); } while (0)
; #define PG8_LDA(dst, b, h) do { _Pragma("unroll") for (int m = 0; m < 4; ++m) _Pragma("unroll") for (int k = 0; k < 2; ++k) dst[m][k] = *(const PG8_LAS bf16x8*)(lds + PG8_SA(b, h) + aoff + m * 2048 + k * 1024); } while (0)
; template <class Epi, class Sched, bool ALIGN_EPI = false, bool SP2 = false>
; __device__ __forceinline__ void gemm_phase(PG8_LAS unsigned char* lds, const Gemm g, const Sched& S, const Epi& E) {
;     ...
;             PG8_LDA(At, 0, 1); PG8_STAGE(PG8_SB(0, 0), b2, voffB); PG8_STAGE(PG8_SB(0, 1), b2 + hstep, voffB); PG8_STAGE(PG8_SA(0, 0), a2, voffA);
	s_add_i32 m0, s79, 0x2000
	s_nop 0
	global_load_lds_dwordx4 v160, s[80:81]
	s_mov_b64 s[98:99], s[54:55]

; #define PG8_STAGE(bufoff, gbase, voff) do { _Pragma("unroll") for (int _i = 0; _i < 2; ++_i) \
;         __builtin_amdgcn_global_load_lds((const unsigned*)((const char*)(gbase) + (voff)[_i]), (PG8_LAS unsigned*)(lds + (bufoff) + ldsw + _i * 8192), 16, 0, 0); } while (0)
; #define PG8_LDA(dst, b, h) do { _Pragma("unroll") for (int m = 0; m < 4; ++m) _Pragma("unroll") for (int k = 0; k < 2; ++k) dst[m][k] = *(const PG8_LAS bf16x8*)(lds + PG8_SA(b, h) + aoff + m * 2048 + k * 1024); } while (0)
; #define PG8_MMA(ai, bj, At, Bt) do { __builtin_amdgcn_s_setprio(1); _Pragma("unroll") for (int m = 0; m < 4; ++m) _Pragma("unroll") for (int n = 0; n < 2; ++n) _Pragma("unroll") for (int k = 0; k < 2; ++k) \
;         acc[ai][bj][m][n] = __builtin_amdgcn_mfma_f32_16x16x32_bf16(Bt[n][k], At[m][k], acc[ai][bj][m][n], 0, 0, 0); __builtin_amdgcn_s_setprio(0); } while (0)
; #define PG8_WAIT_V(n) asm volatile("s_waitcnt vmcnt(" #n ")" ::: "memory")
; #define PG8_WAIT_L(n) asm volatile("s_waitcnt lgkmcnt(" #n ")" ::: "memory")
; #define PG8_BAR __builtin_amdgcn_s_barrier()
; #define PG8_SCHED __builtin_amdgcn_sched_barrier(0)
; template <class Epi, class Sched, bool ALIGN_EPI = false, bool SP2 = false>
; __device__ __forceinline__ void gemm_phase(PG8_LAS unsigned char* lds, const Gemm g, const Sched& S, const Epi& E) {
;     ...
;             PG8_LDA(At, 0, 1); PG8_STAGE(PG8_SB(0, 0), b2, voffB); PG8_STAGE(PG8_SB(0, 1), b2 + hstep, voffB); PG8_STAGE(PG8_SA(0, 0), a2, voffA);
;             PG8_WAIT_V(8); PG8_WAIT_L(0); PG8_BAR; PG8_MMA(1, 0, At, B0); PG8_MMA(1, 1, At, B1); PG8_BAR; PG8_SCHED;
	s_mov_b32 m0, s60
	s_nop 0
	global_load_lds_dwordx4 v166, s[54:55]
	s_mov_b32 m0, s61
	s_nop 0
	global_load_lds_dwordx4 v162, s[54:55]
	s_waitcnt vmcnt(8)
	s_waitcnt lgkmcnt(0)
	s_setprio 1
	s_barrier

; #define PG8_MMA(ai, bj, At, Bt) do { __builtin_amdgcn_s_setprio(1); _Pragma("unroll") for (int m = 0; m < 4; ++m) _Pragma("unroll") for (int n = 0; n < 2; ++n) _Pragma("unroll") for (int k = 0; k < 2; ++k) \
;         acc[ai][bj][m][n] = __builtin_amdgcn_mfma_f32_16x16x32_bf16(Bt[n][k], At[m][k], acc[ai][bj][m][n], 0, 0, 0); __builtin_amdgcn_s_setprio(0); } while (0)
; #define PG8_WAIT_V(n) asm volatile("s_waitcnt vmcnt(" #n ")" ::: "memory")
; #define PG8_WAIT_L(n) asm volatile("s_waitcnt lgkmcnt(" #n ")" ::: "memory")
; #define PG8_BAR __builtin_amdgcn_s_barrier()
; #define PG8_SCHED __builtin_amdgcn_sched_barrier(0)
; template <class Epi, class Sched, bool ALIGN_EPI = false, bool SP2 = false>
; __device__ __forceinline__ void gemm_phase(PG8_LAS unsigned char* lds, const Gemm g, const Sched& S, const Epi& E) {
;     ...
;             PG8_WAIT_V(8); PG8_WAIT_L(0); PG8_BAR; PG8_MMA(1, 0, At, B0); PG8_MMA(1, 1, At, B1); PG8_BAR; PG8_SCHED;
	v_mfma_f32_16x16x32_bf16 v[60:63], v[128:131], v[176:179], v[60:63]
	v_mfma_f32_16x16x32_bf16 v[56:59], v[136:139], v[176:179], v[56:59]
	v_mfma_f32_16x16x32_bf16 v[52:55], v[128:131], v[184:187], v[52:55]
	v_mfma_f32_16x16x32_bf16 v[40:43], v[136:139], v[184:187], v[40:43]
	v_mfma_f32_16x16x32_bf16 v[36:39], v[128:131], v[210:213], v[36:39]
	v_mfma_f32_16x16x32_bf16 v[24:27], v[136:139], v[210:213], v[24:27]
	v_mfma_f32_16x16x32_bf16 v[20:23], v[128:131], v[218:221], v[20:23]
	v_mfma_f32_16x16x32_bf16 v[8:11], v[136:139], v[218:221], v[8:11]
	v_mfma_f32_16x16x32_bf16 v[60:63], v[132:135], v[180:183], v[60:63]
	v_mfma_f32_16x16x32_bf16 v[56:59], v[140:143], v[180:183], v[56:59]
	v_mfma_f32_16x16x32_bf16 v[52:55], v[132:135], v[192:195], v[52:55]
	v_mfma_f32_16x16x32_bf16 v[40:43], v[140:143], v[192:195], v[40:43]
	v_mfma_f32_16x16x32_bf16 v[36:39], v[132:135], v[214:217], v[36:39]
	v_mfma_f32_16x16x32_bf16 v[24:27], v[140:143], v[214:217], v[24:27]
	v_mfma_f32_16x16x32_bf16 v[20:23], v[132:135], v[222:225], v[20:23]
	v_mfma_f32_16x16x32_bf16 v[8:11], v[140:143], v[222:225], v[8:11]


; #define PG8_STAGE(bufoff, gbase, voff) do { _Pragma("unroll") for (int _i = 0; _i < 2; ++_i) \
;         __builtin_amdgcn_global_load_lds((const unsigned*)((const char*)(gbase) + (voff)[_i]), (PG8_LAS unsigned*)(lds + (bufoff) + ldsw + _i * 8192), 16, 0, 0); } while (0)
; #define PG8_LDA(dst, b, h) do { _Pragma("unroll") for (int m = 0; m < 4; ++m) _Pragma("unroll") for (int k = 0; k < 2; ++k) dst[m][k] = *(const PG8_LAS bf16x8*)(lds + PG8_SA(b, h) + aoff + m * 2048 + k * 1024); } while (0)
; #define PG8_LDB(dst, b, h) do { _Pragma("unroll") for (int n = 0; n < 2; ++n) _Pragma("unroll") for (int k = 0; k < 2; ++k) dst[n][k] = *(const PG8_LAS bf16x8*)(lds + PG8_SB(b, h) + boff + n * 2048 + k * 1024); } while (0)
; #define PG8_MMA(ai, bj, At, Bt) do { __builtin_amdgcn_s_setprio(1); _Pragma("unroll") for (int m = 0; m < 4; ++m) _Pragma("unroll") for (int n = 0; n < 2; ++n) _Pragma("unroll") for (int k = 0; k < 2; ++k) \
;         acc[ai][bj][m][n] = __builtin_amdgcn_mfma_f32_16x16x32_bf16(Bt[n][k], At[m][k], acc[ai][bj][m][n], 0, 0, 0); __builtin_amdgcn_s_setprio(0); } while (0)
; #define PG8_WAIT_V(n) asm volatile("s_waitcnt vmcnt(" #n ")" ::: "memory")
; #define PG8_WAIT_L(n) asm volatile("s_waitcnt lgkmcnt(" #n ")" ::: "memory")
; #define PG8_BAR __builtin_amdgcn_s_barrier()
; #define PG8_SCHED __builtin_amdgcn_sched_barrier(0)
; template <class Epi, class Sched, bool ALIGN_EPI = false, bool SP2 = false>
; __device__ __forceinline__ void gemm_phase(PG8_LAS unsigned char* lds, const Gemm g, const Sched& S, const Epi& E) {
;     ...
;             PG8_WAIT_V(8); PG8_WAIT_L(0); PG8_BAR; PG8_MMA(1, 0, At, B0); PG8_MMA(1, 1, At, B1); PG8_BAR; PG8_SCHED;
;             PG8_LDB(B0, 1, 0); PG8_LDB(B1, 1, 1); PG8_SCHED; PG8_LDA(At, 1, 0); PG8_STAGE(PG8_SA(0, 1), a2 + hstep, voffA);
	v_mfma_f32_16x16x32_bf16 v[48:51], v[144:147], v[176:179], v[48:51]
	v_mfma_f32_16x16x32_bf16 v[44:47], v[152:155], v[176:179], v[44:47]
	v_mfma_f32_16x16x32_bf16 v[32:35], v[144:147], v[184:187], v[32:35]
	v_mfma_f32_16x16x32_bf16 v[28:31], v[152:155], v[184:187], v[28:31]
	v_mfma_f32_16x16x32_bf16 v[16:19], v[144:147], v[210:213], v[16:19]
	v_mfma_f32_16x16x32_bf16 v[12:15], v[152:155], v[210:213], v[12:15]
	v_mfma_f32_16x16x32_bf16 v[4:7], v[144:147], v[218:221], v[4:7]
	v_mfma_f32_16x16x32_bf16 v[0:3], v[152:155], v[218:221], v[0:3]
	v_mfma_f32_16x16x32_bf16 v[48:51], v[148:151], v[180:183], v[48:51]
	v_mfma_f32_16x16x32_bf16 v[44:47], v[156:159], v[180:183], v[44:47]
	v_mfma_f32_16x16x32_bf16 v[32:35], v[148:151], v[192:195], v[32:35]
	v_mfma_f32_16x16x32_bf16 v[28:31], v[156:159], v[192:195], v[28:31]
	v_mfma_f32_16x16x32_bf16 v[16:19], v[148:151], v[214:217], v[16:19]
	v_mfma_f32_16x16x32_bf16 v[12:15], v[156:159], v[214:217], v[12:15]
	v_mfma_f32_16x16x32_bf16 v[4:7], v[148:151], v[222:225], v[4:7]
	v_mfma_f32_16x16x32_bf16 v[0:3], v[156:159], v[222:225], v[0:3]
	s_setprio 0
	s_barrier
	s_add_i32 s79, 0, 0x18000
	s_add_i32 s80, 0, 0x1c000
	v_add_u32_e32 v140, s79, v197
	v_add_u32_e32 v156, s80, v197
	ds_read_b128 v[128:131], v140
	ds_read_b128 v[132:135], v140 offset:1024
	ds_read_b128 v[136:139], v140 offset:2048
	ds_read_b128 v[140:143], v140 offset:3072
	ds_read_b128 v[144:147], v156
	ds_read_b128 v[148:151], v156 offset:1024
	ds_read_b128 v[152:155], v156 offset:2048
	ds_read_b128 v[156:159], v156 offset:3072
	s_add_u32 s54, s54, 0x80000
	s_addc_u32 s55, s55, 0
	s_mov_b32 m0, s62

; #define PG8_STAGE(bufoff, gbase, voff) do { _Pragma("unroll") for (int _i = 0; _i < 2; ++_i) \
;         __builtin_amdgcn_global_load_lds((const unsigned*)((const char*)(gbase) + (voff)[_i]), (PG8_LAS unsigned*)(lds + (bufoff) + ldsw + _i * 8192), 16, 0, 0); } while (0)
; #define PG8_LDA(dst, b, h) do { _Pragma("unroll") for (int m = 0; m < 4; ++m) _Pragma("unroll") for (int k = 0; k < 2; ++k) dst[m][k] = *(const PG8_LAS bf16x8*)(lds + PG8_SA(b, h) + aoff + m * 2048 + k * 1024); } while (0)
; #define PG8_LDB(dst, b, h) do { _Pragma("unroll") for (int n = 0; n < 2; ++n) _Pragma("unroll") for (int k = 0; k < 2; ++k) dst[n][k] = *(const PG8_LAS bf16x8*)(lds + PG8_SB(b, h) + boff + n * 2048 + k * 1024); } while (0)
; #define PG8_SCHED __builtin_amdgcn_sched_barrier(0)
; template <class Epi, class Sched, bool ALIGN_EPI = false, bool SP2 = false>
; __device__ __forceinline__ void gemm_phase(PG8_LAS unsigned char* lds, const Gemm g, const Sched& S, const Epi& E) {
;     ...
;             PG8_LDB(B0, 1, 0); PG8_LDB(B1, 1, 1); PG8_SCHED; PG8_LDA(At, 1, 0); PG8_STAGE(PG8_SA(0, 1), a2 + hstep, voffA);
	ds_read_b128 v[176:179], v207 offset:32768
	ds_read_b128 v[180:183], v207 offset:33792
	ds_read_b128 v[184:187], v207 offset:34816
	ds_read_b128 v[192:195], v207 offset:35840
	ds_read_b128 v[210:213], v207 offset:36864
	ds_read_b128 v[214:217], v207 offset:37888
	ds_read_b128 v[218:221], v207 offset:38912
	ds_read_b128 v[222:225], v207 offset:39936
	global_load_lds_dwordx4 v166, s[54:55]

; #define PG8_STAGE(bufoff, gbase, voff) do { _Pragma("unroll") for (int _i = 0; _i < 2; ++_i) \
;         __builtin_amdgcn_global_load_lds((const unsigned*)((const char*)(gbase) + (voff)[_i]), (PG8_LAS unsigned*)(lds + (bufoff) + ldsw + _i * 8192), 16, 0, 0); } while (0)
; #define PG8_LDA(dst, b, h) do { _Pragma("unroll") for (int m = 0; m < 4; ++m) _Pragma("unroll") for (int k = 0; k < 2; ++k) dst[m][k] = *(const PG8_LAS bf16x8*)(lds + PG8_SA(b, h) + aoff + m * 2048 + k * 1024); } while (0)
; #define PG8_LDB(dst, b, h) do { _Pragma("unroll") for (int n = 0; n < 2; ++n) _Pragma("unroll") for (int k = 0; k < 2; ++k) dst[n][k] = *(const PG8_LAS bf16x8*)(lds + PG8_SB(b, h) + boff + n * 2048 + k * 1024); } while (0)
; #define PG8_MMA(ai, bj, At, Bt) do { __builtin_amdgcn_s_setprio(1); _Pragma("unroll") for (int m = 0; m < 4; ++m) _Pragma("unroll") for (int n = 0; n < 2; ++n) _Pragma("unroll") for (int k = 0; k < 2; ++k) \
;         acc[ai][bj][m][n] = __builtin_amdgcn_mfma_f32_16x16x32_bf16(Bt[n][k], At[m][k], acc[ai][bj][m][n], 0, 0, 0); __builtin_amdgcn_s_setprio(0); } while (0)
; #define PG8_WAIT_V(n) asm volatile("s_waitcnt vmcnt(" #n ")" ::: "memory")
; #define PG8_WAIT_L(n) asm volatile("s_waitcnt lgkmcnt(" #n ")" ::: "memory")
; #define PG8_BAR __builtin_amdgcn_s_barrier()
; #define PG8_SCHED __builtin_amdgcn_sched_barrier(0)
; template <class Epi, class Sched, bool ALIGN_EPI = false, bool SP2 = false>
; __device__ __forceinline__ void gemm_phase(PG8_LAS unsigned char* lds, const Gemm g, const Sched& S, const Epi& E) {
;     ...
;             PG8_LDB(B0, 1, 0); PG8_LDB(B1, 1, 1); PG8_SCHED; PG8_LDA(At, 1, 0); PG8_STAGE(PG8_SA(0, 1), a2 + hstep, voffA);
;             PG8_WAIT_V(8); PG8_WAIT_L(0); PG8_BAR; PG8_MMA(0, 0, At, B0); PG8_MMA(0, 1, At, B1); PG8_BAR; PG8_SCHED;
	s_mov_b32 m0, s63
	s_nop 0
	global_load_lds_dwordx4 v162, s[54:55]
	s_waitcnt vmcnt(8)
	s_waitcnt lgkmcnt(0)
	s_setprio 1
	s_barrier

; #define PG8_MMA(ai, bj, At, Bt) do { __builtin_amdgcn_s_setprio(1); _Pragma("unroll") for (int m = 0; m < 4; ++m) _Pragma("unroll") for (int n = 0; n < 2; ++n) _Pragma("unroll") for (int k = 0; k < 2; ++k) \
;         acc[ai][bj][m][n] = __builtin_amdgcn_mfma_f32_16x16x32_bf16(Bt[n][k], At[m][k], acc[ai][bj][m][n], 0, 0, 0); __builtin_amdgcn_s_setprio(0); } while (0)
; #define PG8_WAIT_V(n) asm volatile("s_waitcnt vmcnt(" #n ")" ::: "memory")
; #define PG8_WAIT_L(n) asm volatile("s_waitcnt lgkmcnt(" #n ")" ::: "memory")
; #define PG8_BAR __builtin_amdgcn_s_barrier()
; #define PG8_SCHED __builtin_amdgcn_sched_barrier(0)
; template <class Epi, class Sched, bool ALIGN_EPI = false, bool SP2 = false>
; __device__ __forceinline__ void gemm_phase(PG8_LAS unsigned char* lds, const Gemm g, const Sched& S, const Epi& E) {
;     ...
;             PG8_WAIT_V(8); PG8_WAIT_L(0); PG8_BAR; PG8_MMA(0, 0, At, B0); PG8_MMA(0, 1, At, B1); PG8_BAR; PG8_SCHED;
	v_mfma_f32_16x16x32_bf16 v[124:127], v[128:131], v[176:179], v[124:127]
	v_mfma_f32_16x16x32_bf16 v[120:123], v[136:139], v[176:179], v[120:123]
	v_mfma_f32_16x16x32_bf16 v[112:115], v[128:131], v[184:187], v[112:115]
	v_mfma_f32_16x16x32_bf16 v[104:107], v[136:139], v[184:187], v[104:107]
	v_mfma_f32_16x16x32_bf16 v[100:103], v[128:131], v[210:213], v[100:103]
	v_mfma_f32_16x16x32_bf16 v[88:91], v[136:139], v[210:213], v[88:91]
	v_mfma_f32_16x16x32_bf16 v[84:87], v[128:131], v[218:221], v[84:87]
	v_mfma_f32_16x16x32_bf16 v[72:75], v[136:139], v[218:221], v[72:75]
	v_mfma_f32_16x16x32_bf16 v[124:127], v[132:135], v[180:183], v[124:127]
	v_mfma_f32_16x16x32_bf16 v[120:123], v[140:143], v[180:183], v[120:123]
	v_mfma_f32_16x16x32_bf16 v[112:115], v[132:135], v[192:195], v[112:115]
	v_mfma_f32_16x16x32_bf16 v[104:107], v[140:143], v[192:195], v[104:107]
	v_mfma_f32_16x16x32_bf16 v[100:103], v[132:135], v[214:217], v[100:103]
	v_mfma_f32_16x16x32_bf16 v[88:91], v[140:143], v[214:217], v[88:91]
	v_mfma_f32_16x16x32_bf16 v[84:87], v[132:135], v[222:225], v[84:87]
	v_mfma_f32_16x16x32_bf16 v[72:75], v[140:143], v[222:225], v[72:75]


; #define PG8_MMA(ai, bj, At, Bt) do { __builtin_amdgcn_s_setprio(1); _Pragma("unroll") for (int m = 0; m < 4; ++m) _Pragma("unroll") for (int n = 0; n < 2; ++n) _Pragma("unroll") for (int k = 0; k < 2; ++k) \
;         acc[ai][bj][m][n] = __builtin_amdgcn_mfma_f32_16x16x32_bf16(Bt[n][k], At[m][k], acc[ai][bj][m][n], 0, 0, 0); __builtin_amdgcn_s_setprio(0); } while (0)
; #define PG8_WAIT_V(n) asm volatile("s_waitcnt vmcnt(" #n ")" ::: "memory")
; #define PG8_WAIT_L(n) asm volatile("s_waitcnt lgkmcnt(" #n ")" ::: "memory")
; #define PG8_BAR __builtin_amdgcn_s_barrier()
; #define PG8_SCHED __builtin_amdgcn_sched_barrier(0)
; template <class Epi, class Sched, bool ALIGN_EPI = false, bool SP2 = false>
; __device__ __forceinline__ void gemm_phase(PG8_LAS unsigned char* lds, const Gemm g, const Sched& S, const Epi& E) {
;     ...
;             PG8_WAIT_V(8); PG8_WAIT_L(0); PG8_BAR; PG8_MMA(0, 0, At, B0); PG8_MMA(0, 1, At, B1); PG8_BAR; PG8_SCHED;
	v_mfma_f32_16x16x32_bf16 v[116:119], v[144:147], v[176:179], v[116:119]
	v_mfma_f32_16x16x32_bf16 v[108:111], v[152:155], v[176:179], v[108:111]
	v_mfma_f32_16x16x32_bf16 v[96:99], v[144:147], v[184:187], v[96:99]
	v_mfma_f32_16x16x32_bf16 v[92:95], v[152:155], v[184:187], v[92:95]
	v_mfma_f32_16x16x32_bf16 v[80:83], v[144:147], v[210:213], v[80:83]
	v_mfma_f32_16x16x32_bf16 v[76:79], v[152:155], v[210:213], v[76:79]
	v_mfma_f32_16x16x32_bf16 v[68:71], v[144:147], v[218:221], v[68:71]
	v_mfma_f32_16x16x32_bf16 v[64:67], v[152:155], v[218:221], v[64:67]
	v_mfma_f32_16x16x32_bf16 v[116:119], v[148:151], v[180:183], v[116:119]
	v_mfma_f32_16x16x32_bf16 v[108:111], v[156:159], v[180:183], v[108:111]
	v_mfma_f32_16x16x32_bf16 v[96:99], v[148:151], v[192:195], v[96:99]
	v_mfma_f32_16x16x32_bf16 v[92:95], v[156:159], v[192:195], v[92:95]
	v_mfma_f32_16x16x32_bf16 v[80:83], v[148:151], v[214:217], v[80:83]
	v_mfma_f32_16x16x32_bf16 v[76:79], v[156:159], v[214:217], v[76:79]
	v_mfma_f32_16x16x32_bf16 v[68:71], v[148:151], v[222:225], v[68:71]
	v_mfma_f32_16x16x32_bf16 v[64:67], v[156:159], v[222:225], v[64:67]
	s_setprio 0
	s_barrier
	s_add_i32 s54, s79, s57

; #define PG8_STAGE(bufoff, gbase, voff) do { _Pragma("unroll") for (int _i = 0; _i < 2; ++_i) \
;         __builtin_amdgcn_global_load_lds((const unsigned*)((const char*)(gbase) + (voff)[_i]), (PG8_LAS unsigned*)(lds + (bufoff) + ldsw + _i * 8192), 16, 0, 0); } while (0)
; #define PG8_LDA(dst, b, h) do { _Pragma("unroll") for (int m = 0; m < 4; ++m) _Pragma("unroll") for (int k = 0; k < 2; ++k) dst[m][k] = *(const PG8_LAS bf16x8*)(lds + PG8_SA(b, h) + aoff + m * 2048 + k * 1024); } while (0)
; template <class Epi, class Sched, bool ALIGN_EPI = false, bool SP2 = false>
; __device__ __forceinline__ void gemm_phase(PG8_LAS unsigned char* lds, const Gemm g, const Sched& S, const Epi& E) {
;     ...
;             PG8_LDA(At, 1, 1); PG8_STAGE(PG8_SB(1, 0), b3, voffB); PG8_STAGE(PG8_SB(1, 1), b3 + hstep, voffB); PG8_STAGE(PG8_SA(1, 0), a3, voffA);
	s_mov_b32 m0, s54
	ds_read_b128 v[176:179], v207 offset:49152
	ds_read_b128 v[180:183], v207 offset:50176
	ds_read_b128 v[184:187], v207 offset:51200
	ds_read_b128 v[192:195], v207 offset:52224
	ds_read_b128 v[210:213], v207 offset:53248
	ds_read_b128 v[214:217], v207 offset:54272
	ds_read_b128 v[218:221], v207 offset:55296
	ds_read_b128 v[222:225], v207 offset:56320
	global_load_lds_dwordx4 v250, s[96:97]
	s_add_i32 m0, s54, 0x2000
	s_add_u32 s12, s12, 0x80080

; #define PG8_STAGE(bufoff, gbase, voff) do { _Pragma("unroll") for (int _i = 0; _i < 2; ++_i) \
;         __builtin_amdgcn_global_load_lds((const unsigned*)((const char*)(gbase) + (voff)[_i]), (PG8_LAS unsigned*)(lds + (bufoff) + ldsw + _i * 8192), 16, 0, 0); } while (0)
; #define PG8_LDA(dst, b, h) do { _Pragma("unroll") for (int m = 0; m < 4; ++m) _Pragma("unroll") for (int k = 0; k < 2; ++k) dst[m][k] = *(const PG8_LAS bf16x8*)(lds + PG8_SA(b, h) + aoff + m * 2048 + k * 1024); } while (0)
; template <class Epi, class Sched, bool ALIGN_EPI = false, bool SP2 = false>
; __device__ __forceinline__ void gemm_phase(PG8_LAS unsigned char* lds, const Gemm g, const Sched& S, const Epi& E) {
;     ...
;             PG8_LDA(At, 1, 1); PG8_STAGE(PG8_SB(1, 0), b3, voffB); PG8_STAGE(PG8_SB(1, 1), b3 + hstep, voffB); PG8_STAGE(PG8_SA(1, 0), a3, voffA);
	s_addc_u32 s13, s13, 0
	s_add_i32 s54, s80, s57
	global_load_lds_dwordx4 v251, s[96:97]

; #define PG8_STAGE(bufoff, gbase, voff) do { _Pragma("unroll") for (int _i = 0; _i < 2; ++_i) \
;         __builtin_amdgcn_global_load_lds((const unsigned*)((const char*)(gbase) + (voff)[_i]), (PG8_LAS unsigned*)(lds + (bufoff) + ldsw + _i * 8192), 16, 0, 0); } while (0)
; #define PG8_LDA(dst, b, h) do { _Pragma("unroll") for (int m = 0; m < 4; ++m) _Pragma("unroll") for (int k = 0; k < 2; ++k) dst[m][k] = *(const PG8_LAS bf16x8*)(lds + PG8_SA(b, h) + aoff + m * 2048 + k * 1024); } while (0)
; template <class Epi, class Sched, bool ALIGN_EPI = false, bool SP2 = false>
; __device__ __forceinline__ void gemm_phase(PG8_LAS unsigned char* lds, const Gemm g, const Sched& S, const Epi& E) {
;     ...
;             PG8_LDA(At, 1, 1); PG8_STAGE(PG8_SB(1, 0), b3, voffB); PG8_STAGE(PG8_SB(1, 1), b3 + hstep, voffB); PG8_STAGE(PG8_SA(1, 0), a3, voffA);
	s_mov_b32 m0, s54
	s_nop 0
	global_load_lds_dwordx4 v164, s[12:13]

; #define PG8_STAGE(bufoff, gbase, voff) do { _Pragma("unroll") for (int _i = 0; _i < 2; ++_i) \
;         __builtin_amdgcn_global_load_lds((const unsigned*)((const char*)(gbase) + (voff)[_i]), (PG8_LAS unsigned*)(lds + (bufoff) + ldsw + _i * 8192), 16, 0, 0); } while (0)
; #define PG8_LDA(dst, b, h) do { _Pragma("unroll") for (int m = 0; m < 4; ++m) _Pragma("unroll") for (int k = 0; k < 2; ++k) dst[m][k] = *(const PG8_LAS bf16x8*)(lds + PG8_SA(b, h) + aoff + m * 2048 + k * 1024); } while (0)
; template <class Epi, class Sched, bool ALIGN_EPI = false, bool SP2 = false>
; __device__ __forceinline__ void gemm_phase(PG8_LAS unsigned char* lds, const Gemm g, const Sched& S, const Epi& E) {
;     ...
;             PG8_LDA(At, 1, 1); PG8_STAGE(PG8_SB(1, 0), b3, voffB); PG8_STAGE(PG8_SB(1, 1), b3 + hstep, voffB); PG8_STAGE(PG8_SA(1, 0), a3, voffA);
	s_add_i32 m0, s54, 0x2000
	s_nop 0
	global_load_lds_dwordx4 v160, s[12:13]

; #define PG8_STAGE(bufoff, gbase, voff) do { _Pragma("unroll") for (int _i = 0; _i < 2; ++_i) \
;         __builtin_amdgcn_global_load_lds((const unsigned*)((const char*)(gbase) + (voff)[_i]), (PG8_LAS unsigned*)(lds + (bufoff) + ldsw + _i * 8192), 16, 0, 0); } while (0)
; #define PG8_LDA(dst, b, h) do { _Pragma("unroll") for (int m = 0; m < 4; ++m) _Pragma("unroll") for (int k = 0; k < 2; ++k) dst[m][k] = *(const PG8_LAS bf16x8*)(lds + PG8_SA(b, h) + aoff + m * 2048 + k * 1024); } while (0)
; template <class Epi, class Sched, bool ALIGN_EPI = false, bool SP2 = false>
; __device__ __forceinline__ void gemm_phase(PG8_LAS unsigned char* lds, const Gemm g, const Sched& S, const Epi& E) {
;     ...
;             PG8_LDA(At, 1, 1); PG8_STAGE(PG8_SB(1, 0), b3, voffB); PG8_STAGE(PG8_SB(1, 1), b3 + hstep, voffB); PG8_STAGE(PG8_SA(1, 0), a3, voffA);
	s_mov_b32 m0, s65
	s_nop 0
	global_load_lds_dwordx4 v252, s[98:99]

; #define PG8_STAGE(bufoff, gbase, voff) do { _Pragma("unroll") for (int _i = 0; _i < 2; ++_i) \
;         __builtin_amdgcn_global_load_lds((const unsigned*)((const char*)(gbase) + (voff)[_i]), (PG8_LAS unsigned*)(lds + (bufoff) + ldsw + _i * 8192), 16, 0, 0); } while (0)
; #define PG8_LDA(dst, b, h) do { _Pragma("unroll") for (int m = 0; m < 4; ++m) _Pragma("unroll") for (int k = 0; k < 2; ++k) dst[m][k] = *(const PG8_LAS bf16x8*)(lds + PG8_SA(b, h) + aoff + m * 2048 + k * 1024); } while (0)
; #define PG8_MMA(ai, bj, At, Bt) do { __builtin_amdgcn_s_setprio(1); _Pragma("unroll") for (int m = 0; m < 4; ++m) _Pragma("unroll") for (int n = 0; n < 2; ++n) _Pragma("unroll") for (int k = 0; k < 2; ++k) \
;         acc[ai][bj][m][n] = __builtin_amdgcn_mfma_f32_16x16x32_bf16(Bt[n][k], At[m][k], acc[ai][bj][m][n], 0, 0, 0); __builtin_amdgcn_s_setprio(0); } while (0)
; #define PG8_WAIT_V(n) asm volatile("s_waitcnt vmcnt(" #n ")" ::: "memory")
; #define PG8_WAIT_L(n) asm volatile("s_waitcnt lgkmcnt(" #n ")" ::: "memory")
; #define PG8_BAR __builtin_amdgcn_s_barrier()
; #define PG8_SCHED __builtin_amdgcn_sched_barrier(0)
; template <class Epi, class Sched, bool ALIGN_EPI = false, bool SP2 = false>
; __device__ __forceinline__ void gemm_phase(PG8_LAS unsigned char* lds, const Gemm g, const Sched& S, const Epi& E) {
;     ...
;             PG8_LDA(At, 1, 1); PG8_STAGE(PG8_SB(1, 0), b3, voffB); PG8_STAGE(PG8_SB(1, 1), b3 + hstep, voffB); PG8_STAGE(PG8_SA(1, 0), a3, voffA);
;             PG8_WAIT_V(8); PG8_WAIT_L(0); PG8_BAR; PG8_MMA(1, 0, At, B0); PG8_MMA(1, 1, At, B1); PG8_BAR; PG8_SCHED;
	s_mov_b32 m0, s67
	s_nop 0
	global_load_lds_dwordx4 v253, s[98:99]
	s_waitcnt vmcnt(8)
	s_waitcnt lgkmcnt(0)
	s_setprio 1
	s_barrier

; #define PG8_MMA(ai, bj, At, Bt) do { __builtin_amdgcn_s_setprio(1); _Pragma("unroll") for (int m = 0; m < 4; ++m) _Pragma("unroll") for (int n = 0; n < 2; ++n) _Pragma("unroll") for (int k = 0; k < 2; ++k) \
;         acc[ai][bj][m][n] = __builtin_amdgcn_mfma_f32_16x16x32_bf16(Bt[n][k], At[m][k], acc[ai][bj][m][n], 0, 0, 0); __builtin_amdgcn_s_setprio(0); } while (0)
; #define PG8_WAIT_V(n) asm volatile("s_waitcnt vmcnt(" #n ")" ::: "memory")
; #define PG8_WAIT_L(n) asm volatile("s_waitcnt lgkmcnt(" #n ")" ::: "memory")
; #define PG8_BAR __builtin_amdgcn_s_barrier()
; #define PG8_SCHED __builtin_amdgcn_sched_barrier(0)
; template <class Epi, class Sched, bool ALIGN_EPI = false, bool SP2 = false>
; __device__ __forceinline__ void gemm_phase(PG8_LAS unsigned char* lds, const Gemm g, const Sched& S, const Epi& E) {
;     ...
;             PG8_WAIT_V(8); PG8_WAIT_L(0); PG8_BAR; PG8_MMA(1, 0, At, B0); PG8_MMA(1, 1, At, B1); PG8_BAR; PG8_SCHED;
	v_mfma_f32_16x16x32_bf16 v[60:63], v[128:131], v[176:179], v[60:63]
	v_mfma_f32_16x16x32_bf16 v[56:59], v[136:139], v[176:179], v[56:59]
	v_mfma_f32_16x16x32_bf16 v[52:55], v[128:131], v[184:187], v[52:55]
	v_mfma_f32_16x16x32_bf16 v[40:43], v[136:139], v[184:187], v[40:43]
	v_mfma_f32_16x16x32_bf16 v[36:39], v[128:131], v[210:213], v[36:39]
	v_mfma_f32_16x16x32_bf16 v[24:27], v[136:139], v[210:213], v[24:27]
	v_mfma_f32_16x16x32_bf16 v[20:23], v[128:131], v[218:221], v[20:23]
	v_mfma_f32_16x16x32_bf16 v[8:11], v[136:139], v[218:221], v[8:11]
	v_mfma_f32_16x16x32_bf16 v[60:63], v[132:135], v[180:183], v[60:63]
	v_mfma_f32_16x16x32_bf16 v[56:59], v[140:143], v[180:183], v[56:59]
	v_mfma_f32_16x16x32_bf16 v[52:55], v[132:135], v[192:195], v[52:55]
	v_mfma_f32_16x16x32_bf16 v[40:43], v[140:143], v[192:195], v[40:43]
	v_mfma_f32_16x16x32_bf16 v[36:39], v[132:135], v[214:217], v[36:39]
	v_mfma_f32_16x16x32_bf16 v[24:27], v[140:143], v[214:217], v[24:27]
	v_mfma_f32_16x16x32_bf16 v[20:23], v[132:135], v[222:225], v[20:23]
	v_mfma_f32_16x16x32_bf16 v[8:11], v[140:143], v[222:225], v[8:11]


; #define PG8_MMA(ai, bj, At, Bt) do { __builtin_amdgcn_s_setprio(1); _Pragma("unroll") for (int m = 0; m < 4; ++m) _Pragma("unroll") for (int n = 0; n < 2; ++n) _Pragma("unroll") for (int k = 0; k < 2; ++k) \
;         acc[ai][bj][m][n] = __builtin_amdgcn_mfma_f32_16x16x32_bf16(Bt[n][k], At[m][k], acc[ai][bj][m][n], 0, 0, 0); __builtin_amdgcn_s_setprio(0); } while (0)
; #define PG8_WAIT_V(n) asm volatile("s_waitcnt vmcnt(" #n ")" ::: "memory")
; #define PG8_WAIT_L(n) asm volatile("s_waitcnt lgkmcnt(" #n ")" ::: "memory")
; #define PG8_BAR __builtin_amdgcn_s_barrier()
; #define PG8_SCHED __builtin_amdgcn_sched_barrier(0)
; template <class Epi, class Sched, bool ALIGN_EPI = false, bool SP2 = false>
; __device__ __forceinline__ void gemm_phase(PG8_LAS unsigned char* lds, const Gemm g, const Sched& S, const Epi& E) {
;     ...
;             PG8_WAIT_V(8); PG8_WAIT_L(0); PG8_BAR; PG8_MMA(1, 0, At, B0); PG8_MMA(1, 1, At, B1); PG8_BAR; PG8_SCHED;
	v_mfma_f32_16x16x32_bf16 v[48:51], v[144:147], v[176:179], v[48:51]
	v_mfma_f32_16x16x32_bf16 v[44:47], v[152:155], v[176:179], v[44:47]
	v_mfma_f32_16x16x32_bf16 v[32:35], v[144:147], v[184:187], v[32:35]
	v_mfma_f32_16x16x32_bf16 v[28:31], v[152:155], v[184:187], v[28:31]
	v_mfma_f32_16x16x32_bf16 v[16:19], v[144:147], v[210:213], v[16:19]
	v_mfma_f32_16x16x32_bf16 v[12:15], v[152:155], v[210:213], v[12:15]
	v_mfma_f32_16x16x32_bf16 v[4:7], v[144:147], v[218:221], v[4:7]
	v_mfma_f32_16x16x32_bf16 v[0:3], v[152:155], v[218:221], v[0:3]
	v_mfma_f32_16x16x32_bf16 v[48:51], v[148:151], v[180:183], v[48:51]
	v_mfma_f32_16x16x32_bf16 v[44:47], v[156:159], v[180:183], v[44:47]
	v_mfma_f32_16x16x32_bf16 v[32:35], v[148:151], v[192:195], v[32:35]
	v_mfma_f32_16x16x32_bf16 v[28:31], v[156:159], v[192:195], v[28:31]
	v_mfma_f32_16x16x32_bf16 v[16:19], v[148:151], v[214:217], v[16:19]
	v_mfma_f32_16x16x32_bf16 v[12:15], v[156:159], v[214:217], v[12:15]
	v_mfma_f32_16x16x32_bf16 v[4:7], v[148:151], v[222:225], v[4:7]
	v_mfma_f32_16x16x32_bf16 v[0:3], v[156:159], v[222:225], v[0:3]
	s_setprio 0
	s_barrier
	s_add_i32 s78, s78, 2
	s_add_u32 s10, s10, 0x100
	s_addc_u32 s11, s11, 0
	s_add_u32 s76, s76, 0x100
	s_addc_u32 s77, s77, 0
	s_cmp_gt_u32 s78, 29
	s_cbranch_scc0 .LBB0_679
	s_and_b64 vcc, exec, s[42:43]
	s_cbranch_vccz .LBB0_682
	s_barrier

; #define PG8_STAGE(bufoff, gbase, voff) do { _Pragma("unroll") for (int _i = 0; _i < 2; ++_i) \
;         __builtin_amdgcn_global_load_lds((const unsigned*)((const char*)(gbase) + (voff)[_i]), (PG8_LAS unsigned*)(lds + (bufoff) + ldsw + _i * 8192), 16, 0, 0); } while (0)
; #define PG8_LDA(dst, b, h) do { _Pragma("unroll") for (int m = 0; m < 4; ++m) _Pragma("unroll") for (int k = 0; k < 2; ++k) dst[m][k] = *(const PG8_LAS bf16x8*)(lds + PG8_SA(b, h) + aoff + m * 2048 + k * 1024); } while (0)
; #define PG8_LDB(dst, b, h) do { _Pragma("unroll") for (int n = 0; n < 2; ++n) _Pragma("unroll") for (int k = 0; k < 2; ++k) dst[n][k] = *(const PG8_LAS bf16x8*)(lds + PG8_SB(b, h) + boff + n * 2048 + k * 1024); } while (0)
; #define PG8_SCHED __builtin_amdgcn_sched_barrier(0)
; template <class Epi, class Sched, bool ALIGN_EPI = false, bool SP2 = false>
; __device__ __forceinline__ void gemm_phase(PG8_LAS unsigned char* lds, const Gemm g, const Sched& S, const Epi& E) {
;     ...
;             const bool last = (t == nt - 2);
;             const char* a1 = cA + (size_t)(t + 1) * kstep;
;             const char* a2 = last ? nA : cA + (size_t)(t + 2) * kstep; const char* b2 = last ? nB : cB + (size_t)(t + 2) * kstep;
;             const char* a3 = a2 + kstep; const char* b3 = b2 + kstep;
;             if (last && has_next) S.a_ready(nxt);
;             if constexpr (SP2) {
;             PG8_LDB(B0, 0, 0); PG8_LDB(B1, 0, 1); PG8_SCHED; PG8_LDA(At, 0, 0); PG8_STAGE(PG8_SA(1, 1), a1 + hstep, voffA);
.LBB0_939:
	ds_read_b128 v[64:67], v213
	ds_read_b128 v[68:71], v213 offset:1024
	ds_read_b128 v[72:75], v213 offset:2048
	ds_read_b128 v[76:79], v213 offset:3072
	ds_read_b128 v[144:147], v214
	ds_read_b128 v[148:151], v214 offset:1024
	ds_read_b128 v[152:155], v214 offset:2048
	ds_read_b128 v[156:159], v214 offset:3072
	s_add_u32 s60, s58, 0xfff80080
	s_addc_u32 s61, s59, -1
	s_cmp_eq_u32 s81, 28
	s_cselect_b32 s63, s11, s61
	s_cselect_b32 s62, s51, s60
	s_cselect_b32 s61, s49, s80
	s_cselect_b32 s60, s78, s79

; #define PG8_STAGE(bufoff, gbase, voff) do { _Pragma("unroll") for (int _i = 0; _i < 2; ++_i) \
;         __builtin_amdgcn_global_load_lds((const unsigned*)((const char*)(gbase) + (voff)[_i]), (PG8_LAS unsigned*)(lds + (bufoff) + ldsw + _i * 8192), 16, 0, 0); } while (0)
; #define PG8_LDA(dst, b, h) do { _Pragma("unroll") for (int m = 0; m < 4; ++m) _Pragma("unroll") for (int k = 0; k < 2; ++k) dst[m][k] = *(const PG8_LAS bf16x8*)(lds + PG8_SA(b, h) + aoff + m * 2048 + k * 1024); } while (0)
; #define PG8_LDB(dst, b, h) do { _Pragma("unroll") for (int n = 0; n < 2; ++n) _Pragma("unroll") for (int k = 0; k < 2; ++k) dst[n][k] = *(const PG8_LAS bf16x8*)(lds + PG8_SB(b, h) + boff + n * 2048 + k * 1024); } while (0)
; #define PG8_SCHED __builtin_amdgcn_sched_barrier(0)
; template <class Epi, class Sched, bool ALIGN_EPI = false, bool SP2 = false>
; __device__ __forceinline__ void gemm_phase(PG8_LAS unsigned char* lds, const Gemm g, const Sched& S, const Epi& E) {
;     ...
;             PG8_LDB(B0, 0, 0); PG8_LDB(B1, 0, 1); PG8_SCHED; PG8_LDA(At, 0, 0); PG8_STAGE(PG8_SA(1, 1), a1 + hstep, voffA);
	s_add_i32 m0, s57, 0xc000
	ds_read_b128 v[176:179], v215
	ds_read_b128 v[180:183], v215 offset:1024
	ds_read_b128 v[184:187], v215 offset:2048
	ds_read_b128 v[188:191], v215 offset:3072
	ds_read_b128 v[192:195], v215 offset:4096
	ds_read_b128 v[196:199], v215 offset:5120
	ds_read_b128 v[200:203], v215 offset:6144
	ds_read_b128 v[204:207], v215 offset:7168
	global_load_lds_dwordx4 v168, s[58:59]

; #define PG8_STAGE(bufoff, gbase, voff) do { _Pragma("unroll") for (int _i = 0; _i < 2; ++_i) \
;         __builtin_amdgcn_global_load_lds((const unsigned*)((const char*)(gbase) + (voff)[_i]), (PG8_LAS unsigned*)(lds + (bufoff) + ldsw + _i * 8192), 16, 0, 0); } while (0)
; #define PG8_LDA(dst, b, h) do { _Pragma("unroll") for (int m = 0; m < 4; ++m) _Pragma("unroll") for (int k = 0; k < 2; ++k) dst[m][k] = *(const PG8_LAS bf16x8*)(lds + PG8_SA(b, h) + aoff + m * 2048 + k * 1024); } while (0)
; #define PG8_LDB(dst, b, h) do { _Pragma("unroll") for (int n = 0; n < 2; ++n) _Pragma("unroll") for (int k = 0; k < 2; ++k) dst[n][k] = *(const PG8_LAS bf16x8*)(lds + PG8_SB(b, h) + boff + n * 2048 + k * 1024); } while (0)
; #define PG8_MMA(ai, bj, At, Bt) do { __builtin_amdgcn_s_setprio(1); _Pragma("unroll") for (int m = 0; m < 4; ++m) _Pragma("unroll") for (int n = 0; n < 2; ++n) _Pragma("unroll") for (int k = 0; k < 2; ++k) \
;         acc[ai][bj][m][n] = __builtin_amdgcn_mfma_f32_16x16x32_bf16(Bt[n][k], At[m][k], acc[ai][bj][m][n], 0, 0, 0); __builtin_amdgcn_s_setprio(0); } while (0)
; #define PG8_WAIT_V(n) asm volatile("s_waitcnt vmcnt(" #n ")" ::: "memory")
; #define PG8_WAIT_L(n) asm volatile("s_waitcnt lgkmcnt(" #n ")" ::: "memory")
; #define PG8_BAR __builtin_amdgcn_s_barrier()
; #define PG8_SCHED __builtin_amdgcn_sched_barrier(0)
; template <class Epi, class Sched, bool ALIGN_EPI = false, bool SP2 = false>
; __device__ __forceinline__ void gemm_phase(PG8_LAS unsigned char* lds, const Gemm g, const Sched& S, const Epi& E) {
;     ...
;             PG8_LDB(B0, 0, 0); PG8_LDB(B1, 0, 1); PG8_SCHED; PG8_LDA(At, 0, 0); PG8_STAGE(PG8_SA(1, 1), a1 + hstep, voffA);
;             PG8_WAIT_V(8); PG8_WAIT_L(0); PG8_BAR; PG8_MMA(0, 0, At, B0); PG8_MMA(0, 1, At, B1); PG8_BAR; PG8_SCHED;
	s_add_i32 m0, s57, 0xe000
	s_nop 0
	global_load_lds_dwordx4 v170, s[58:59]
	s_waitcnt vmcnt(8)
	s_waitcnt lgkmcnt(0)
	s_setprio 1
	s_barrier

; #define PG8_MMA(ai, bj, At, Bt) do { __builtin_amdgcn_s_setprio(1); _Pragma("unroll") for (int m = 0; m < 4; ++m) _Pragma("unroll") for (int n = 0; n < 2; ++n) _Pragma("unroll") for (int k = 0; k < 2; ++k) \
;         acc[ai][bj][m][n] = __builtin_amdgcn_mfma_f32_16x16x32_bf16(Bt[n][k], At[m][k], acc[ai][bj][m][n], 0, 0, 0); __builtin_amdgcn_s_setprio(0); } while (0)
; #define PG8_WAIT_V(n) asm volatile("s_waitcnt vmcnt(" #n ")" ::: "memory")
; #define PG8_WAIT_L(n) asm volatile("s_waitcnt lgkmcnt(" #n ")" ::: "memory")
; #define PG8_BAR __builtin_amdgcn_s_barrier()
; #define PG8_SCHED __builtin_amdgcn_sched_barrier(0)
; template <class Epi, class Sched, bool ALIGN_EPI = false, bool SP2 = false>
; __device__ __forceinline__ void gemm_phase(PG8_LAS unsigned char* lds, const Gemm g, const Sched& S, const Epi& E) {
;     ...
;             PG8_WAIT_V(8); PG8_WAIT_L(0); PG8_BAR; PG8_MMA(0, 0, At, B0); PG8_MMA(0, 1, At, B1); PG8_BAR; PG8_SCHED;
	v_mfma_f32_16x16x32_bf16 v[140:143], v[64:67], v[176:179], v[140:143]
	v_mfma_f32_16x16x32_bf16 v[136:139], v[72:75], v[176:179], v[136:139]
	v_mfma_f32_16x16x32_bf16 v[124:127], v[64:67], v[184:187], v[124:127]
	v_mfma_f32_16x16x32_bf16 v[120:123], v[72:75], v[184:187], v[120:123]
	v_mfma_f32_16x16x32_bf16 v[108:111], v[64:67], v[192:195], v[108:111]
	v_mfma_f32_16x16x32_bf16 v[104:107], v[72:75], v[192:195], v[104:107]
	v_mfma_f32_16x16x32_bf16 v[92:95], v[64:67], v[200:203], v[92:95]
	v_mfma_f32_16x16x32_bf16 v[88:91], v[72:75], v[200:203], v[88:91]
	v_mfma_f32_16x16x32_bf16 v[140:143], v[68:71], v[180:183], v[140:143]
	v_mfma_f32_16x16x32_bf16 v[136:139], v[76:79], v[180:183], v[136:139]
	v_mfma_f32_16x16x32_bf16 v[124:127], v[68:71], v[188:191], v[124:127]
	v_mfma_f32_16x16x32_bf16 v[120:123], v[76:79], v[188:191], v[120:123]
	v_mfma_f32_16x16x32_bf16 v[108:111], v[68:71], v[196:199], v[108:111]
	v_mfma_f32_16x16x32_bf16 v[104:107], v[76:79], v[196:199], v[104:107]
	v_mfma_f32_16x16x32_bf16 v[92:95], v[68:71], v[204:207], v[92:95]
	v_mfma_f32_16x16x32_bf16 v[88:91], v[76:79], v[204:207], v[88:91]


; #define PG8_STAGE(bufoff, gbase, voff) do { _Pragma("unroll") for (int _i = 0; _i < 2; ++_i) \
;         __builtin_amdgcn_global_load_lds((const unsigned*)((const char*)(gbase) + (voff)[_i]), (PG8_LAS unsigned*)(lds + (bufoff) + ldsw + _i * 8192), 16, 0, 0); } while (0)
; #define PG8_LDA(dst, b, h) do { _Pragma("unroll") for (int m = 0; m < 4; ++m) _Pragma("unroll") for (int k = 0; k < 2; ++k) dst[m][k] = *(const PG8_LAS bf16x8*)(lds + PG8_SA(b, h) + aoff + m * 2048 + k * 1024); } while (0)
; #define PG8_MMA(ai, bj, At, Bt) do { __builtin_amdgcn_s_setprio(1); _Pragma("unroll") for (int m = 0; m < 4; ++m) _Pragma("unroll") for (int n = 0; n < 2; ++n) _Pragma("unroll") for (int k = 0; k < 2; ++k) \
;         acc[ai][bj][m][n] = __builtin_amdgcn_mfma_f32_16x16x32_bf16(Bt[n][k], At[m][k], acc[ai][bj][m][n], 0, 0, 0); __builtin_amdgcn_s_setprio(0); } while (0)
; #define PG8_WAIT_V(n) asm volatile("s_waitcnt vmcnt(" #n ")" ::: "memory")
; #define PG8_WAIT_L(n) asm volatile("s_waitcnt lgkmcnt(" #n ")" ::: "memory")
; #define PG8_BAR __builtin_amdgcn_s_barrier()
; #define PG8_SCHED __builtin_amdgcn_sched_barrier(0)
; template <class Epi, class Sched, bool ALIGN_EPI = false, bool SP2 = false>
; __device__ __forceinline__ void gemm_phase(PG8_LAS unsigned char* lds, const Gemm g, const Sched& S, const Epi& E) {
;     ...
;             PG8_WAIT_V(8); PG8_WAIT_L(0); PG8_BAR; PG8_MMA(0, 0, At, B0); PG8_MMA(0, 1, At, B1); PG8_BAR; PG8_SCHED;
;             PG8_LDA(At, 0, 1); PG8_STAGE(PG8_SB(0, 0), b2, voffB); PG8_STAGE(PG8_SB(0, 1), b2 + hstep, voffB); PG8_STAGE(PG8_SA(0, 0), a2, voffA);
	v_mfma_f32_16x16x32_bf16 v[132:135], v[144:147], v[176:179], v[132:135]
	v_mfma_f32_16x16x32_bf16 v[128:131], v[152:155], v[176:179], v[128:131]
	v_mfma_f32_16x16x32_bf16 v[116:119], v[144:147], v[184:187], v[116:119]
	v_mfma_f32_16x16x32_bf16 v[112:115], v[152:155], v[184:187], v[112:115]
	v_mfma_f32_16x16x32_bf16 v[100:103], v[144:147], v[192:195], v[100:103]
	v_mfma_f32_16x16x32_bf16 v[96:99], v[152:155], v[192:195], v[96:99]
	v_mfma_f32_16x16x32_bf16 v[84:87], v[144:147], v[200:203], v[84:87]
	v_mfma_f32_16x16x32_bf16 v[80:83], v[152:155], v[200:203], v[80:83]
	v_mfma_f32_16x16x32_bf16 v[132:135], v[148:151], v[180:183], v[132:135]
	v_mfma_f32_16x16x32_bf16 v[128:131], v[156:159], v[180:183], v[128:131]
	v_mfma_f32_16x16x32_bf16 v[116:119], v[148:151], v[188:191], v[116:119]
	v_mfma_f32_16x16x32_bf16 v[112:115], v[156:159], v[188:191], v[112:115]
	v_mfma_f32_16x16x32_bf16 v[100:103], v[148:151], v[196:199], v[100:103]
	v_mfma_f32_16x16x32_bf16 v[96:99], v[156:159], v[196:199], v[96:99]
	v_mfma_f32_16x16x32_bf16 v[84:87], v[148:151], v[204:207], v[84:87]
	v_mfma_f32_16x16x32_bf16 v[80:83], v[156:159], v[204:207], v[80:83]
	s_setprio 0
	s_barrier
	s_add_i32 s82, s75, s64
	s_mov_b64 s[96:97], s[60:61]

; #define PG8_STAGE(bufoff, gbase, voff) do { _Pragma("unroll") for (int _i = 0; _i < 2; ++_i) \
;         __builtin_amdgcn_global_load_lds((const unsigned*)((const char*)(gbase) + (voff)[_i]), (PG8_LAS unsigned*)(lds + (bufoff) + ldsw + _i * 8192), 16, 0, 0); } while (0)
; #define PG8_LDA(dst, b, h) do { _Pragma("unroll") for (int m = 0; m < 4; ++m) _Pragma("unroll") for (int k = 0; k < 2; ++k) dst[m][k] = *(const PG8_LAS bf16x8*)(lds + PG8_SA(b, h) + aoff + m * 2048 + k * 1024); } while (0)
; template <class Epi, class Sched, bool ALIGN_EPI = false, bool SP2 = false>
; __device__ __forceinline__ void gemm_phase(PG8_LAS unsigned char* lds, const Gemm g, const Sched& S, const Epi& E) {
;     ...
;             PG8_LDA(At, 0, 1); PG8_STAGE(PG8_SB(0, 0), b2, voffB); PG8_STAGE(PG8_SB(0, 1), b2 + hstep, voffB); PG8_STAGE(PG8_SA(0, 0), a2, voffA);
	s_mov_b32 m0, s82
	ds_read_b128 v[176:179], v215 offset:16384
	ds_read_b128 v[180:183], v215 offset:17408
	ds_read_b128 v[184:187], v215 offset:18432
	ds_read_b128 v[188:191], v215 offset:19456
	ds_read_b128 v[192:195], v215 offset:20480
	ds_read_b128 v[196:199], v215 offset:21504
	ds_read_b128 v[200:203], v215 offset:22528
	ds_read_b128 v[204:207], v215 offset:23552
	global_load_lds_dwordx4 v162, s[60:61]
	s_add_i32 m0, s82, 0x2000
	s_add_u32 s82, s60, 0x80000

; #define PG8_STAGE(bufoff, gbase, voff) do { _Pragma("unroll") for (int _i = 0; _i < 2; ++_i) \
;         __builtin_amdgcn_global_load_lds((const unsigned*)((const char*)(gbase) + (voff)[_i]), (PG8_LAS unsigned*)(lds + (bufoff) + ldsw + _i * 8192), 16, 0, 0); } while (0)
; #define PG8_LDA(dst, b, h) do { _Pragma("unroll") for (int m = 0; m < 4; ++m) _Pragma("unroll") for (int k = 0; k < 2; ++k) dst[m][k] = *(const PG8_LAS bf16x8*)(lds + PG8_SA(b, h) + aoff + m * 2048 + k * 1024); } while (0)
; template <class Epi, class Sched, bool ALIGN_EPI = false, bool SP2 = false>
; __device__ __forceinline__ void gemm_phase(PG8_LAS unsigned char* lds, const Gemm g, const Sched& S, const Epi& E) {
;     ...
;             PG8_LDA(At, 0, 1); PG8_STAGE(PG8_SB(0, 0), b2, voffB); PG8_STAGE(PG8_SB(0, 1), b2 + hstep, voffB); PG8_STAGE(PG8_SA(0, 0), a2, voffA);
	s_addc_u32 s83, s61, 0
	s_add_i32 s84, s76, s64
	global_load_lds_dwordx4 v166, s[60:61]

; #define PG8_STAGE(bufoff, gbase, voff) do { _Pragma("unroll") for (int _i = 0; _i < 2; ++_i) \
;         __builtin_amdgcn_global_load_lds((const unsigned*)((const char*)(gbase) + (voff)[_i]), (PG8_LAS unsigned*)(lds + (bufoff) + ldsw + _i * 8192), 16, 0, 0); } while (0)
; #define PG8_LDA(dst, b, h) do { _Pragma("unroll") for (int m = 0; m < 4; ++m) _Pragma("unroll") for (int k = 0; k < 2; ++k) dst[m][k] = *(const PG8_LAS bf16x8*)(lds + PG8_SA(b, h) + aoff + m * 2048 + k * 1024); } while (0)
; template <class Epi, class Sched, bool ALIGN_EPI = false, bool SP2 = false>
; __device__ __forceinline__ void gemm_phase(PG8_LAS unsigned char* lds, const Gemm g, const Sched& S, const Epi& E) {
;     ...
;             PG8_LDA(At, 0, 1); PG8_STAGE(PG8_SB(0, 0), b2, voffB); PG8_STAGE(PG8_SB(0, 1), b2 + hstep, voffB); PG8_STAGE(PG8_SA(0, 0), a2, voffA);
	s_mov_b32 m0, s84
	s_nop 0
	global_load_lds_dwordx4 v162, s[82:83]

; #define PG8_STAGE(bufoff, gbase, voff) do { _Pragma("unroll") for (int _i = 0; _i < 2; ++_i) \
;         __builtin_amdgcn_global_load_lds((const unsigned*)((const char*)(gbase) + (voff)[_i]), (PG8_LAS unsigned*)(lds + (bufoff) + ldsw + _i * 8192), 16, 0, 0); } while (0)
; #define PG8_LDA(dst, b, h) do { _Pragma("unroll") for (int m = 0; m < 4; ++m) _Pragma("unroll") for (int k = 0; k < 2; ++k) dst[m][k] = *(const PG8_LAS bf16x8*)(lds + PG8_SA(b, h) + aoff + m * 2048 + k * 1024); } while (0)
; template <class Epi, class Sched, bool ALIGN_EPI = false, bool SP2 = false>
; __device__ __forceinline__ void gemm_phase(PG8_LAS unsigned char* lds, const Gemm g, const Sched& S, const Epi& E) {
;     ...
;             PG8_LDA(At, 0, 1); PG8_STAGE(PG8_SB(0, 0), b2, voffB); PG8_STAGE(PG8_SB(0, 1), b2 + hstep, voffB); PG8_STAGE(PG8_SA(0, 0), a2, voffA);
	s_add_i32 m0, s84, 0x2000
	s_nop 0
	global_load_lds_dwordx4 v166, s[82:83]
	s_mov_b64 s[98:99], s[62:63]

; #define PG8_STAGE(bufoff, gbase, voff) do { _Pragma("unroll") for (int _i = 0; _i < 2; ++_i) \
;         __builtin_amdgcn_global_load_lds((const unsigned*)((const char*)(gbase) + (voff)[_i]), (PG8_LAS unsigned*)(lds + (bufoff) + ldsw + _i * 8192), 16, 0, 0); } while (0)
; #define PG8_LDA(dst, b, h) do { _Pragma("unroll") for (int m = 0; m < 4; ++m) _Pragma("unroll") for (int k = 0; k < 2; ++k) dst[m][k] = *(const PG8_LAS bf16x8*)(lds + PG8_SA(b, h) + aoff + m * 2048 + k * 1024); } while (0)
; #define PG8_MMA(ai, bj, At, Bt) do { __builtin_amdgcn_s_setprio(1); _Pragma("unroll") for (int m = 0; m < 4; ++m) _Pragma("unroll") for (int n = 0; n < 2; ++n) _Pragma("unroll") for (int k = 0; k < 2; ++k) \
;         acc[ai][bj][m][n] = __builtin_amdgcn_mfma_f32_16x16x32_bf16(Bt[n][k], At[m][k], acc[ai][bj][m][n], 0, 0, 0); __builtin_amdgcn_s_setprio(0); } while (0)
; #define PG8_WAIT_V(n) asm volatile("s_waitcnt vmcnt(" #n ")" ::: "memory")
; #define PG8_WAIT_L(n) asm volatile("s_waitcnt lgkmcnt(" #n ")" ::: "memory")
; #define PG8_BAR __builtin_amdgcn_s_barrier()
; #define PG8_SCHED __builtin_amdgcn_sched_barrier(0)
; template <class Epi, class Sched, bool ALIGN_EPI = false, bool SP2 = false>
; __device__ __forceinline__ void gemm_phase(PG8_LAS unsigned char* lds, const Gemm g, const Sched& S, const Epi& E) {
;     ...
;             PG8_LDA(At, 0, 1); PG8_STAGE(PG8_SB(0, 0), b2, voffB); PG8_STAGE(PG8_SB(0, 1), b2 + hstep, voffB); PG8_STAGE(PG8_SA(0, 0), a2, voffA);
;             PG8_WAIT_V(8); PG8_WAIT_L(0); PG8_BAR; PG8_MMA(1, 0, At, B0); PG8_MMA(1, 1, At, B1); PG8_BAR; PG8_SCHED;
	s_mov_b32 m0, s57
	s_nop 0
	global_load_lds_dwordx4 v160, s[62:63]
	s_mov_b32 m0, s65
	s_nop 0
	global_load_lds_dwordx4 v164, s[62:63]
	s_waitcnt vmcnt(8)
	s_waitcnt lgkmcnt(0)
	s_setprio 1
	s_barrier

; #define PG8_MMA(ai, bj, At, Bt) do { __builtin_amdgcn_s_setprio(1); _Pragma("unroll") for (int m = 0; m < 4; ++m) _Pragma("unroll") for (int n = 0; n < 2; ++n) _Pragma("unroll") for (int k = 0; k < 2; ++k) \
;         acc[ai][bj][m][n] = __builtin_amdgcn_mfma_f32_16x16x32_bf16(Bt[n][k], At[m][k], acc[ai][bj][m][n], 0, 0, 0); __builtin_amdgcn_s_setprio(0); } while (0)
; #define PG8_WAIT_V(n) asm volatile("s_waitcnt vmcnt(" #n ")" ::: "memory")
; #define PG8_WAIT_L(n) asm volatile("s_waitcnt lgkmcnt(" #n ")" ::: "memory")
; #define PG8_BAR __builtin_amdgcn_s_barrier()
; #define PG8_SCHED __builtin_amdgcn_sched_barrier(0)
; template <class Epi, class Sched, bool ALIGN_EPI = false, bool SP2 = false>
; __device__ __forceinline__ void gemm_phase(PG8_LAS unsigned char* lds, const Gemm g, const Sched& S, const Epi& E) {
;     ...
;             PG8_WAIT_V(8); PG8_WAIT_L(0); PG8_BAR; PG8_MMA(1, 0, At, B0); PG8_MMA(1, 1, At, B1); PG8_BAR; PG8_SCHED;
	v_mfma_f32_16x16x32_bf16 v[60:63], v[64:67], v[176:179], v[60:63]
	v_mfma_f32_16x16x32_bf16 v[56:59], v[72:75], v[176:179], v[56:59]
	v_mfma_f32_16x16x32_bf16 v[44:47], v[64:67], v[184:187], v[44:47]
	v_mfma_f32_16x16x32_bf16 v[40:43], v[72:75], v[184:187], v[40:43]
	v_mfma_f32_16x16x32_bf16 v[28:31], v[64:67], v[192:195], v[28:31]
	v_mfma_f32_16x16x32_bf16 v[24:27], v[72:75], v[192:195], v[24:27]
	v_mfma_f32_16x16x32_bf16 v[12:15], v[64:67], v[200:203], v[12:15]
	v_mfma_f32_16x16x32_bf16 v[8:11], v[72:75], v[200:203], v[8:11]
	v_mfma_f32_16x16x32_bf16 v[60:63], v[68:71], v[180:183], v[60:63]
	v_mfma_f32_16x16x32_bf16 v[56:59], v[76:79], v[180:183], v[56:59]
	v_mfma_f32_16x16x32_bf16 v[44:47], v[68:71], v[188:191], v[44:47]
	v_mfma_f32_16x16x32_bf16 v[40:43], v[76:79], v[188:191], v[40:43]
	v_mfma_f32_16x16x32_bf16 v[28:31], v[68:71], v[196:199], v[28:31]
	v_mfma_f32_16x16x32_bf16 v[24:27], v[76:79], v[196:199], v[24:27]
	v_mfma_f32_16x16x32_bf16 v[12:15], v[68:71], v[204:207], v[12:15]
	v_mfma_f32_16x16x32_bf16 v[8:11], v[76:79], v[204:207], v[8:11]


; #define PG8_STAGE(bufoff, gbase, voff) do { _Pragma("unroll") for (int _i = 0; _i < 2; ++_i) \
;         __builtin_amdgcn_global_load_lds((const unsigned*)((const char*)(gbase) + (voff)[_i]), (PG8_LAS unsigned*)(lds + (bufoff) + ldsw + _i * 8192), 16, 0, 0); } while (0)
; #define PG8_LDA(dst, b, h) do { _Pragma("unroll") for (int m = 0; m < 4; ++m) _Pragma("unroll") for (int k = 0; k < 2; ++k) dst[m][k] = *(const PG8_LAS bf16x8*)(lds + PG8_SA(b, h) + aoff + m * 2048 + k * 1024); } while (0)
; #define PG8_LDB(dst, b, h) do { _Pragma("unroll") for (int n = 0; n < 2; ++n) _Pragma("unroll") for (int k = 0; k < 2; ++k) dst[n][k] = *(const PG8_LAS bf16x8*)(lds + PG8_SB(b, h) + boff + n * 2048 + k * 1024); } while (0)
; #define PG8_MMA(ai, bj, At, Bt) do { __builtin_amdgcn_s_setprio(1); _Pragma("unroll") for (int m = 0; m < 4; ++m) _Pragma("unroll") for (int n = 0; n < 2; ++n) _Pragma("unroll") for (int k = 0; k < 2; ++k) \
;         acc[ai][bj][m][n] = __builtin_amdgcn_mfma_f32_16x16x32_bf16(Bt[n][k], At[m][k], acc[ai][bj][m][n], 0, 0, 0); __builtin_amdgcn_s_setprio(0); } while (0)
; #define PG8_WAIT_V(n) asm volatile("s_waitcnt vmcnt(" #n ")" ::: "memory")
; #define PG8_WAIT_L(n) asm volatile("s_waitcnt lgkmcnt(" #n ")" ::: "memory")
; #define PG8_BAR __builtin_amdgcn_s_barrier()
; #define PG8_SCHED __builtin_amdgcn_sched_barrier(0)
; template <class Epi, class Sched, bool ALIGN_EPI = false, bool SP2 = false>
; __device__ __forceinline__ void gemm_phase(PG8_LAS unsigned char* lds, const Gemm g, const Sched& S, const Epi& E) {
;     ...
;             PG8_WAIT_V(8); PG8_WAIT_L(0); PG8_BAR; PG8_MMA(1, 0, At, B0); PG8_MMA(1, 1, At, B1); PG8_BAR; PG8_SCHED;
;             PG8_LDB(B0, 1, 0); PG8_LDB(B1, 1, 1); PG8_SCHED; PG8_LDA(At, 1, 0); PG8_STAGE(PG8_SA(0, 1), a2 + hstep, voffA);
	v_mfma_f32_16x16x32_bf16 v[52:55], v[144:147], v[176:179], v[52:55]
	v_mfma_f32_16x16x32_bf16 v[48:51], v[152:155], v[176:179], v[48:51]
	v_mfma_f32_16x16x32_bf16 v[36:39], v[144:147], v[184:187], v[36:39]
	v_mfma_f32_16x16x32_bf16 v[32:35], v[152:155], v[184:187], v[32:35]
	v_mfma_f32_16x16x32_bf16 v[20:23], v[144:147], v[192:195], v[20:23]
	v_mfma_f32_16x16x32_bf16 v[16:19], v[152:155], v[192:195], v[16:19]
	v_mfma_f32_16x16x32_bf16 v[4:7], v[144:147], v[200:203], v[4:7]
	v_mfma_f32_16x16x32_bf16 v[0:3], v[152:155], v[200:203], v[0:3]
	v_mfma_f32_16x16x32_bf16 v[52:55], v[148:151], v[180:183], v[52:55]
	v_mfma_f32_16x16x32_bf16 v[48:51], v[156:159], v[180:183], v[48:51]
	v_mfma_f32_16x16x32_bf16 v[36:39], v[148:151], v[188:191], v[36:39]
	v_mfma_f32_16x16x32_bf16 v[32:35], v[156:159], v[188:191], v[32:35]
	v_mfma_f32_16x16x32_bf16 v[20:23], v[148:151], v[196:199], v[20:23]
	v_mfma_f32_16x16x32_bf16 v[16:19], v[156:159], v[196:199], v[16:19]
	v_mfma_f32_16x16x32_bf16 v[4:7], v[148:151], v[204:207], v[4:7]
	v_mfma_f32_16x16x32_bf16 v[0:3], v[156:159], v[204:207], v[0:3]
	s_setprio 0
	s_barrier
	s_add_i32 s82, 0, 0x18000
	s_add_i32 s83, 0, 0x1c000
	v_add_u32_e32 v76, s82, v211
	v_add_u32_e32 v156, s83, v211
	ds_read_b128 v[64:67], v76
	ds_read_b128 v[68:71], v76 offset:1024
	ds_read_b128 v[72:75], v76 offset:2048
	ds_read_b128 v[76:79], v76 offset:3072
	ds_read_b128 v[144:147], v156
	ds_read_b128 v[148:151], v156 offset:1024
	ds_read_b128 v[152:155], v156 offset:2048
	ds_read_b128 v[156:159], v156 offset:3072
	s_add_u32 s62, s62, 0x80000
	s_addc_u32 s63, s63, 0
	s_mov_b32 m0, s67

; #define PG8_STAGE(bufoff, gbase, voff) do { _Pragma("unroll") for (int _i = 0; _i < 2; ++_i) \
;         __builtin_amdgcn_global_load_lds((const unsigned*)((const char*)(gbase) + (voff)[_i]), (PG8_LAS unsigned*)(lds + (bufoff) + ldsw + _i * 8192), 16, 0, 0); } while (0)
; #define PG8_LDA(dst, b, h) do { _Pragma("unroll") for (int m = 0; m < 4; ++m) _Pragma("unroll") for (int k = 0; k < 2; ++k) dst[m][k] = *(const PG8_LAS bf16x8*)(lds + PG8_SA(b, h) + aoff + m * 2048 + k * 1024); } while (0)
; #define PG8_LDB(dst, b, h) do { _Pragma("unroll") for (int n = 0; n < 2; ++n) _Pragma("unroll") for (int k = 0; k < 2; ++k) dst[n][k] = *(const PG8_LAS bf16x8*)(lds + PG8_SB(b, h) + boff + n * 2048 + k * 1024); } while (0)
; #define PG8_SCHED __builtin_amdgcn_sched_barrier(0)
; template <class Epi, class Sched, bool ALIGN_EPI = false, bool SP2 = false>
; __device__ __forceinline__ void gemm_phase(PG8_LAS unsigned char* lds, const Gemm g, const Sched& S, const Epi& E) {
;     ...
;             PG8_LDB(B0, 1, 0); PG8_LDB(B1, 1, 1); PG8_SCHED; PG8_LDA(At, 1, 0); PG8_STAGE(PG8_SA(0, 1), a2 + hstep, voffA);
	ds_read_b128 v[176:179], v215 offset:32768
	ds_read_b128 v[180:183], v215 offset:33792
	ds_read_b128 v[184:187], v215 offset:34816
	ds_read_b128 v[188:191], v215 offset:35840
	ds_read_b128 v[192:195], v215 offset:36864
	ds_read_b128 v[196:199], v215 offset:37888
	ds_read_b128 v[200:203], v215 offset:38912
	ds_read_b128 v[204:207], v215 offset:39936
	global_load_lds_dwordx4 v160, s[62:63]

; #define PG8_STAGE(bufoff, gbase, voff) do { _Pragma("unroll") for (int _i = 0; _i < 2; ++_i) \
;         __builtin_amdgcn_global_load_lds((const unsigned*)((const char*)(gbase) + (voff)[_i]), (PG8_LAS unsigned*)(lds + (bufoff) + ldsw + _i * 8192), 16, 0, 0); } while (0)
; #define PG8_LDA(dst, b, h) do { _Pragma("unroll") for (int m = 0; m < 4; ++m) _Pragma("unroll") for (int k = 0; k < 2; ++k) dst[m][k] = *(const PG8_LAS bf16x8*)(lds + PG8_SA(b, h) + aoff + m * 2048 + k * 1024); } while (0)
; #define PG8_LDB(dst, b, h) do { _Pragma("unroll") for (int n = 0; n < 2; ++n) _Pragma("unroll") for (int k = 0; k < 2; ++k) dst[n][k] = *(const PG8_LAS bf16x8*)(lds + PG8_SB(b, h) + boff + n * 2048 + k * 1024); } while (0)
; #define PG8_MMA(ai, bj, At, Bt) do { __builtin_amdgcn_s_setprio(1); _Pragma("unroll") for (int m = 0; m < 4; ++m) _Pragma("unroll") for (int n = 0; n < 2; ++n) _Pragma("unroll") for (int k = 0; k < 2; ++k) \
;         acc[ai][bj][m][n] = __builtin_amdgcn_mfma_f32_16x16x32_bf16(Bt[n][k], At[m][k], acc[ai][bj][m][n], 0, 0, 0); __builtin_amdgcn_s_setprio(0); } while (0)
; #define PG8_WAIT_V(n) asm volatile("s_waitcnt vmcnt(" #n ")" ::: "memory")
; #define PG8_WAIT_L(n) asm volatile("s_waitcnt lgkmcnt(" #n ")" ::: "memory")
; #define PG8_BAR __builtin_amdgcn_s_barrier()
; #define PG8_SCHED __builtin_amdgcn_sched_barrier(0)
; template <class Epi, class Sched, bool ALIGN_EPI = false, bool SP2 = false>
; __device__ __forceinline__ void gemm_phase(PG8_LAS unsigned char* lds, const Gemm g, const Sched& S, const Epi& E) {
;     ...
;             PG8_LDB(B0, 1, 0); PG8_LDB(B1, 1, 1); PG8_SCHED; PG8_LDA(At, 1, 0); PG8_STAGE(PG8_SA(0, 1), a2 + hstep, voffA);
;             PG8_WAIT_V(8); PG8_WAIT_L(0); PG8_BAR; PG8_MMA(0, 0, At, B0); PG8_MMA(0, 1, At, B1); PG8_BAR; PG8_SCHED;
	s_mov_b32 m0, s68
	s_nop 0
	global_load_lds_dwordx4 v164, s[62:63]
	s_waitcnt vmcnt(8)
	s_waitcnt lgkmcnt(0)
	s_setprio 1
	s_barrier

; #define PG8_MMA(ai, bj, At, Bt) do { __builtin_amdgcn_s_setprio(1); _Pragma("unroll") for (int m = 0; m < 4; ++m) _Pragma("unroll") for (int n = 0; n < 2; ++n) _Pragma("unroll") for (int k = 0; k < 2; ++k) \
;         acc[ai][bj][m][n] = __builtin_amdgcn_mfma_f32_16x16x32_bf16(Bt[n][k], At[m][k], acc[ai][bj][m][n], 0, 0, 0); __builtin_amdgcn_s_setprio(0); } while (0)
; #define PG8_WAIT_V(n) asm volatile("s_waitcnt vmcnt(" #n ")" ::: "memory")
; #define PG8_WAIT_L(n) asm volatile("s_waitcnt lgkmcnt(" #n ")" ::: "memory")
; #define PG8_BAR __builtin_amdgcn_s_barrier()
; #define PG8_SCHED __builtin_amdgcn_sched_barrier(0)
; template <class Epi, class Sched, bool ALIGN_EPI = false, bool SP2 = false>
; __device__ __forceinline__ void gemm_phase(PG8_LAS unsigned char* lds, const Gemm g, const Sched& S, const Epi& E) {
;     ...
;             PG8_WAIT_V(8); PG8_WAIT_L(0); PG8_BAR; PG8_MMA(0, 0, At, B0); PG8_MMA(0, 1, At, B1); PG8_BAR; PG8_SCHED;
	v_mfma_f32_16x16x32_bf16 v[140:143], v[64:67], v[176:179], v[140:143]
	v_mfma_f32_16x16x32_bf16 v[136:139], v[72:75], v[176:179], v[136:139]
	v_mfma_f32_16x16x32_bf16 v[124:127], v[64:67], v[184:187], v[124:127]
	v_mfma_f32_16x16x32_bf16 v[120:123], v[72:75], v[184:187], v[120:123]
	v_mfma_f32_16x16x32_bf16 v[108:111], v[64:67], v[192:195], v[108:111]
	v_mfma_f32_16x16x32_bf16 v[104:107], v[72:75], v[192:195], v[104:107]
	v_mfma_f32_16x16x32_bf16 v[92:95], v[64:67], v[200:203], v[92:95]
	v_mfma_f32_16x16x32_bf16 v[88:91], v[72:75], v[200:203], v[88:91]
	v_mfma_f32_16x16x32_bf16 v[140:143], v[68:71], v[180:183], v[140:143]
	v_mfma_f32_16x16x32_bf16 v[136:139], v[76:79], v[180:183], v[136:139]
	v_mfma_f32_16x16x32_bf16 v[124:127], v[68:71], v[188:191], v[124:127]
	v_mfma_f32_16x16x32_bf16 v[120:123], v[76:79], v[188:191], v[120:123]
	v_mfma_f32_16x16x32_bf16 v[108:111], v[68:71], v[196:199], v[108:111]
	v_mfma_f32_16x16x32_bf16 v[104:107], v[76:79], v[196:199], v[104:107]
	v_mfma_f32_16x16x32_bf16 v[92:95], v[68:71], v[204:207], v[92:95]
	v_mfma_f32_16x16x32_bf16 v[88:91], v[76:79], v[204:207], v[88:91]


; #define PG8_STAGE(bufoff, gbase, voff) do { _Pragma("unroll") for (int _i = 0; _i < 2; ++_i) \
;         __builtin_amdgcn_global_load_lds((const unsigned*)((const char*)(gbase) + (voff)[_i]), (PG8_LAS unsigned*)(lds + (bufoff) + ldsw + _i * 8192), 16, 0, 0); } while (0)
; #define PG8_LDA(dst, b, h) do { _Pragma("unroll") for (int m = 0; m < 4; ++m) _Pragma("unroll") for (int k = 0; k < 2; ++k) dst[m][k] = *(const PG8_LAS bf16x8*)(lds + PG8_SA(b, h) + aoff + m * 2048 + k * 1024); } while (0)
; #define PG8_MMA(ai, bj, At, Bt) do { __builtin_amdgcn_s_setprio(1); _Pragma("unroll") for (int m = 0; m < 4; ++m) _Pragma("unroll") for (int n = 0; n < 2; ++n) _Pragma("unroll") for (int k = 0; k < 2; ++k) \
;         acc[ai][bj][m][n] = __builtin_amdgcn_mfma_f32_16x16x32_bf16(Bt[n][k], At[m][k], acc[ai][bj][m][n], 0, 0, 0); __builtin_amdgcn_s_setprio(0); } while (0)
; #define PG8_WAIT_V(n) asm volatile("s_waitcnt vmcnt(" #n ")" ::: "memory")
; #define PG8_WAIT_L(n) asm volatile("s_waitcnt lgkmcnt(" #n ")" ::: "memory")
; #define PG8_BAR __builtin_amdgcn_s_barrier()
; #define PG8_SCHED __builtin_amdgcn_sched_barrier(0)
; template <class Epi, class Sched, bool ALIGN_EPI = false, bool SP2 = false>
; __device__ __forceinline__ void gemm_phase(PG8_LAS unsigned char* lds, const Gemm g, const Sched& S, const Epi& E) {
;     ...
;             PG8_WAIT_V(8); PG8_WAIT_L(0); PG8_BAR; PG8_MMA(0, 0, At, B0); PG8_MMA(0, 1, At, B1); PG8_BAR; PG8_SCHED;
;             PG8_LDA(At, 1, 1); PG8_STAGE(PG8_SB(1, 0), b3, voffB); PG8_STAGE(PG8_SB(1, 1), b3 + hstep, voffB); PG8_STAGE(PG8_SA(1, 0), a3, voffA);
	v_mfma_f32_16x16x32_bf16 v[132:135], v[144:147], v[176:179], v[132:135]
	v_mfma_f32_16x16x32_bf16 v[128:131], v[152:155], v[176:179], v[128:131]
	v_mfma_f32_16x16x32_bf16 v[116:119], v[144:147], v[184:187], v[116:119]
	v_mfma_f32_16x16x32_bf16 v[112:115], v[152:155], v[184:187], v[112:115]
	v_mfma_f32_16x16x32_bf16 v[100:103], v[144:147], v[192:195], v[100:103]
	v_mfma_f32_16x16x32_bf16 v[96:99], v[152:155], v[192:195], v[96:99]
	v_mfma_f32_16x16x32_bf16 v[84:87], v[144:147], v[200:203], v[84:87]
	v_mfma_f32_16x16x32_bf16 v[80:83], v[152:155], v[200:203], v[80:83]
	v_mfma_f32_16x16x32_bf16 v[132:135], v[148:151], v[180:183], v[132:135]
	v_mfma_f32_16x16x32_bf16 v[128:131], v[156:159], v[180:183], v[128:131]
	v_mfma_f32_16x16x32_bf16 v[116:119], v[148:151], v[188:191], v[116:119]
	v_mfma_f32_16x16x32_bf16 v[112:115], v[156:159], v[188:191], v[112:115]
	v_mfma_f32_16x16x32_bf16 v[100:103], v[148:151], v[196:199], v[100:103]
	v_mfma_f32_16x16x32_bf16 v[96:99], v[156:159], v[196:199], v[96:99]
	v_mfma_f32_16x16x32_bf16 v[84:87], v[148:151], v[204:207], v[84:87]
	v_mfma_f32_16x16x32_bf16 v[80:83], v[156:159], v[204:207], v[80:83]
	s_setprio 0
	s_barrier
	s_add_i32 s62, s82, s64

; #define PG8_STAGE(bufoff, gbase, voff) do { _Pragma("unroll") for (int _i = 0; _i < 2; ++_i) \
;         __builtin_amdgcn_global_load_lds((const unsigned*)((const char*)(gbase) + (voff)[_i]), (PG8_LAS unsigned*)(lds + (bufoff) + ldsw + _i * 8192), 16, 0, 0); } while (0)
; #define PG8_LDA(dst, b, h) do { _Pragma("unroll") for (int m = 0; m < 4; ++m) _Pragma("unroll") for (int k = 0; k < 2; ++k) dst[m][k] = *(const PG8_LAS bf16x8*)(lds + PG8_SA(b, h) + aoff + m * 2048 + k * 1024); } while (0)
; template <class Epi, class Sched, bool ALIGN_EPI = false, bool SP2 = false>
; __device__ __forceinline__ void gemm_phase(PG8_LAS unsigned char* lds, const Gemm g, const Sched& S, const Epi& E) {
;     ...
;             PG8_LDA(At, 1, 1); PG8_STAGE(PG8_SB(1, 0), b3, voffB); PG8_STAGE(PG8_SB(1, 1), b3 + hstep, voffB); PG8_STAGE(PG8_SA(1, 0), a3, voffA);
	s_mov_b32 m0, s62
	ds_read_b128 v[176:179], v215 offset:49152
	ds_read_b128 v[180:183], v215 offset:50176
	ds_read_b128 v[184:187], v215 offset:51200
	ds_read_b128 v[188:191], v215 offset:52224
	ds_read_b128 v[192:195], v215 offset:53248
	ds_read_b128 v[196:199], v215 offset:54272
	ds_read_b128 v[200:203], v215 offset:55296
	ds_read_b128 v[204:207], v215 offset:56320
	global_load_lds_dwordx4 v250, s[96:97]
	s_add_i32 m0, s62, 0x2000
	s_add_u32 s60, s60, 0x80080

; #define PG8_STAGE(bufoff, gbase, voff) do { _Pragma("unroll") for (int _i = 0; _i < 2; ++_i) \
;         __builtin_amdgcn_global_load_lds((const unsigned*)((const char*)(gbase) + (voff)[_i]), (PG8_LAS unsigned*)(lds + (bufoff) + ldsw + _i * 8192), 16, 0, 0); } while (0)
; #define PG8_LDA(dst, b, h) do { _Pragma("unroll") for (int m = 0; m < 4; ++m) _Pragma("unroll") for (int k = 0; k < 2; ++k) dst[m][k] = *(const PG8_LAS bf16x8*)(lds + PG8_SA(b, h) + aoff + m * 2048 + k * 1024); } while (0)
; template <class Epi, class Sched, bool ALIGN_EPI = false, bool SP2 = false>
; __device__ __forceinline__ void gemm_phase(PG8_LAS unsigned char* lds, const Gemm g, const Sched& S, const Epi& E) {
;     ...
;             PG8_LDA(At, 1, 1); PG8_STAGE(PG8_SB(1, 0), b3, voffB); PG8_STAGE(PG8_SB(1, 1), b3 + hstep, voffB); PG8_STAGE(PG8_SA(1, 0), a3, voffA);
	s_addc_u32 s61, s61, 0
	s_add_i32 s62, s83, s64
	global_load_lds_dwordx4 v251, s[96:97]

; #define PG8_STAGE(bufoff, gbase, voff) do { _Pragma("unroll") for (int _i = 0; _i < 2; ++_i) \
;         __builtin_amdgcn_global_load_lds((const unsigned*)((const char*)(gbase) + (voff)[_i]), (PG8_LAS unsigned*)(lds + (bufoff) + ldsw + _i * 8192), 16, 0, 0); } while (0)
; #define PG8_LDA(dst, b, h) do { _Pragma("unroll") for (int m = 0; m < 4; ++m) _Pragma("unroll") for (int k = 0; k < 2; ++k) dst[m][k] = *(const PG8_LAS bf16x8*)(lds + PG8_SA(b, h) + aoff + m * 2048 + k * 1024); } while (0)
; template <class Epi, class Sched, bool ALIGN_EPI = false, bool SP2 = false>
; __device__ __forceinline__ void gemm_phase(PG8_LAS unsigned char* lds, const Gemm g, const Sched& S, const Epi& E) {
;     ...
;             PG8_LDA(At, 1, 1); PG8_STAGE(PG8_SB(1, 0), b3, voffB); PG8_STAGE(PG8_SB(1, 1), b3 + hstep, voffB); PG8_STAGE(PG8_SA(1, 0), a3, voffA);
	s_mov_b32 m0, s62
	s_nop 0
	global_load_lds_dwordx4 v162, s[60:61]

; #define PG8_STAGE(bufoff, gbase, voff) do { _Pragma("unroll") for (int _i = 0; _i < 2; ++_i) \
;         __builtin_amdgcn_global_load_lds((const unsigned*)((const char*)(gbase) + (voff)[_i]), (PG8_LAS unsigned*)(lds + (bufoff) + ldsw + _i * 8192), 16, 0, 0); } while (0)
; #define PG8_LDA(dst, b, h) do { _Pragma("unroll") for (int m = 0; m < 4; ++m) _Pragma("unroll") for (int k = 0; k < 2; ++k) dst[m][k] = *(const PG8_LAS bf16x8*)(lds + PG8_SA(b, h) + aoff + m * 2048 + k * 1024); } while (0)
; template <class Epi, class Sched, bool ALIGN_EPI = false, bool SP2 = false>
; __device__ __forceinline__ void gemm_phase(PG8_LAS unsigned char* lds, const Gemm g, const Sched& S, const Epi& E) {
;     ...
;             PG8_LDA(At, 1, 1); PG8_STAGE(PG8_SB(1, 0), b3, voffB); PG8_STAGE(PG8_SB(1, 1), b3 + hstep, voffB); PG8_STAGE(PG8_SA(1, 0), a3, voffA);
	s_add_i32 m0, s62, 0x2000
	s_nop 0
	global_load_lds_dwordx4 v166, s[60:61]

; #define PG8_STAGE(bufoff, gbase, voff) do { _Pragma("unroll") for (int _i = 0; _i < 2; ++_i) \
;         __builtin_amdgcn_global_load_lds((const unsigned*)((const char*)(gbase) + (voff)[_i]), (PG8_LAS unsigned*)(lds + (bufoff) + ldsw + _i * 8192), 16, 0, 0); } while (0)
; #define PG8_LDA(dst, b, h) do { _Pragma("unroll") for (int m = 0; m < 4; ++m) _Pragma("unroll") for (int k = 0; k < 2; ++k) dst[m][k] = *(const PG8_LAS bf16x8*)(lds + PG8_SA(b, h) + aoff + m * 2048 + k * 1024); } while (0)
; template <class Epi, class Sched, bool ALIGN_EPI = false, bool SP2 = false>
; __device__ __forceinline__ void gemm_phase(PG8_LAS unsigned char* lds, const Gemm g, const Sched& S, const Epi& E) {
;     ...
;             PG8_LDA(At, 1, 1); PG8_STAGE(PG8_SB(1, 0), b3, voffB); PG8_STAGE(PG8_SB(1, 1), b3 + hstep, voffB); PG8_STAGE(PG8_SA(1, 0), a3, voffA);
	s_mov_b32 m0, s70
	s_nop 0
	global_load_lds_dwordx4 v252, s[98:99]

; #define PG8_STAGE(bufoff, gbase, voff) do { _Pragma("unroll") for (int _i = 0; _i < 2; ++_i) \
;         __builtin_amdgcn_global_load_lds((const unsigned*)((const char*)(gbase) + (voff)[_i]), (PG8_LAS unsigned*)(lds + (bufoff) + ldsw + _i * 8192), 16, 0, 0); } while (0)
; #define PG8_LDA(dst, b, h) do { _Pragma("unroll") for (int m = 0; m < 4; ++m) _Pragma("unroll") for (int k = 0; k < 2; ++k) dst[m][k] = *(const PG8_LAS bf16x8*)(lds + PG8_SA(b, h) + aoff + m * 2048 + k * 1024); } while (0)
; #define PG8_MMA(ai, bj, At, Bt) do { __builtin_amdgcn_s_setprio(1); _Pragma("unroll") for (int m = 0; m < 4; ++m) _Pragma("unroll") for (int n = 0; n < 2; ++n) _Pragma("unroll") for (int k = 0; k < 2; ++k) \
;         acc[ai][bj][m][n] = __builtin_amdgcn_mfma_f32_16x16x32_bf16(Bt[n][k], At[m][k], acc[ai][bj][m][n], 0, 0, 0); __builtin_amdgcn_s_setprio(0); } while (0)
; #define PG8_WAIT_V(n) asm volatile("s_waitcnt vmcnt(" #n ")" ::: "memory")
; #define PG8_WAIT_L(n) asm volatile("s_waitcnt lgkmcnt(" #n ")" ::: "memory")
; #define PG8_BAR __builtin_amdgcn_s_barrier()
; #define PG8_SCHED __builtin_amdgcn_sched_barrier(0)
; template <class Epi, class Sched, bool ALIGN_EPI = false, bool SP2 = false>
; __device__ __forceinline__ void gemm_phase(PG8_LAS unsigned char* lds, const Gemm g, const Sched& S, const Epi& E) {
;     ...
;             PG8_LDA(At, 1, 1); PG8_STAGE(PG8_SB(1, 0), b3, voffB); PG8_STAGE(PG8_SB(1, 1), b3 + hstep, voffB); PG8_STAGE(PG8_SA(1, 0), a3, voffA);
;             PG8_WAIT_V(8); PG8_WAIT_L(0); PG8_BAR; PG8_MMA(1, 0, At, B0); PG8_MMA(1, 1, At, B1); PG8_BAR; PG8_SCHED;
	s_mov_b32 m0, s71
	s_nop 0
	global_load_lds_dwordx4 v253, s[98:99]
	s_waitcnt vmcnt(8)
	s_waitcnt lgkmcnt(0)
	s_setprio 1
	s_barrier

; #define PG8_MMA(ai, bj, At, Bt) do { __builtin_amdgcn_s_setprio(1); _Pragma("unroll") for (int m = 0; m < 4; ++m) _Pragma("unroll") for (int n = 0; n < 2; ++n) _Pragma("unroll") for (int k = 0; k < 2; ++k) \
;         acc[ai][bj][m][n] = __builtin_amdgcn_mfma_f32_16x16x32_bf16(Bt[n][k], At[m][k], acc[ai][bj][m][n], 0, 0, 0); __builtin_amdgcn_s_setprio(0); } while (0)
; #define PG8_WAIT_V(n) asm volatile("s_waitcnt vmcnt(" #n ")" ::: "memory")
; #define PG8_WAIT_L(n) asm volatile("s_waitcnt lgkmcnt(" #n ")" ::: "memory")
; #define PG8_BAR __builtin_amdgcn_s_barrier()
; #define PG8_SCHED __builtin_amdgcn_sched_barrier(0)
; template <class Epi, class Sched, bool ALIGN_EPI = false, bool SP2 = false>
; __device__ __forceinline__ void gemm_phase(PG8_LAS unsigned char* lds, const Gemm g, const Sched& S, const Epi& E) {
;     ...
;             PG8_WAIT_V(8); PG8_WAIT_L(0); PG8_BAR; PG8_MMA(1, 0, At, B0); PG8_MMA(1, 1, At, B1); PG8_BAR; PG8_SCHED;
	v_mfma_f32_16x16x32_bf16 v[60:63], v[64:67], v[176:179], v[60:63]
	v_mfma_f32_16x16x32_bf16 v[56:59], v[72:75], v[176:179], v[56:59]
	v_mfma_f32_16x16x32_bf16 v[44:47], v[64:67], v[184:187], v[44:47]
	v_mfma_f32_16x16x32_bf16 v[40:43], v[72:75], v[184:187], v[40:43]
	v_mfma_f32_16x16x32_bf16 v[28:31], v[64:67], v[192:195], v[28:31]
	v_mfma_f32_16x16x32_bf16 v[24:27], v[72:75], v[192:195], v[24:27]
	v_mfma_f32_16x16x32_bf16 v[12:15], v[64:67], v[200:203], v[12:15]
	v_mfma_f32_16x16x32_bf16 v[8:11], v[72:75], v[200:203], v[8:11]
	v_mfma_f32_16x16x32_bf16 v[60:63], v[68:71], v[180:183], v[60:63]
	v_mfma_f32_16x16x32_bf16 v[56:59], v[76:79], v[180:183], v[56:59]
	v_mfma_f32_16x16x32_bf16 v[44:47], v[68:71], v[188:191], v[44:47]
	v_mfma_f32_16x16x32_bf16 v[40:43], v[76:79], v[188:191], v[40:43]
	v_mfma_f32_16x16x32_bf16 v[28:31], v[68:71], v[196:199], v[28:31]
	v_mfma_f32_16x16x32_bf16 v[24:27], v[76:79], v[196:199], v[24:27]
	v_mfma_f32_16x16x32_bf16 v[12:15], v[68:71], v[204:207], v[12:15]
	v_mfma_f32_16x16x32_bf16 v[8:11], v[76:79], v[204:207], v[8:11]


; #define PG8_MMA(ai, bj, At, Bt) do { __builtin_amdgcn_s_setprio(1); _Pragma("unroll") for (int m = 0; m < 4; ++m) _Pragma("unroll") for (int n = 0; n < 2; ++n) _Pragma("unroll") for (int k = 0; k < 2; ++k) \
;         acc[ai][bj][m][n] = __builtin_amdgcn_mfma_f32_16x16x32_bf16(Bt[n][k], At[m][k], acc[ai][bj][m][n], 0, 0, 0); __builtin_amdgcn_s_setprio(0); } while (0)
; #define PG8_WAIT_V(n) asm volatile("s_waitcnt vmcnt(" #n ")" ::: "memory")
; #define PG8_WAIT_L(n) asm volatile("s_waitcnt lgkmcnt(" #n ")" ::: "memory")
; #define PG8_BAR __builtin_amdgcn_s_barrier()
; #define PG8_SCHED __builtin_amdgcn_sched_barrier(0)
; template <class Epi, class Sched, bool ALIGN_EPI = false, bool SP2 = false>
; __device__ __forceinline__ void gemm_phase(PG8_LAS unsigned char* lds, const Gemm g, const Sched& S, const Epi& E) {
;     ...
;         for (int t = 0; t < nt; t += 2) {
;     ...
;             PG8_WAIT_V(8); PG8_WAIT_L(0); PG8_BAR; PG8_MMA(1, 0, At, B0); PG8_MMA(1, 1, At, B1); PG8_BAR; PG8_SCHED;
;     ...
;         if constexpr (ALIGN_EPI) { if (wr == 0) PG8_BAR; }
	v_mfma_f32_16x16x32_bf16 v[52:55], v[144:147], v[176:179], v[52:55]
	v_mfma_f32_16x16x32_bf16 v[48:51], v[152:155], v[176:179], v[48:51]
	v_mfma_f32_16x16x32_bf16 v[36:39], v[144:147], v[184:187], v[36:39]
	v_mfma_f32_16x16x32_bf16 v[32:35], v[152:155], v[184:187], v[32:35]
	v_mfma_f32_16x16x32_bf16 v[20:23], v[144:147], v[192:195], v[20:23]
	v_mfma_f32_16x16x32_bf16 v[16:19], v[152:155], v[192:195], v[16:19]
	v_mfma_f32_16x16x32_bf16 v[4:7], v[144:147], v[200:203], v[4:7]
	v_mfma_f32_16x16x32_bf16 v[0:3], v[152:155], v[200:203], v[0:3]
	v_mfma_f32_16x16x32_bf16 v[52:55], v[148:151], v[180:183], v[52:55]
	v_mfma_f32_16x16x32_bf16 v[48:51], v[156:159], v[180:183], v[48:51]
	v_mfma_f32_16x16x32_bf16 v[36:39], v[148:151], v[188:191], v[36:39]
	v_mfma_f32_16x16x32_bf16 v[32:35], v[156:159], v[188:191], v[32:35]
	v_mfma_f32_16x16x32_bf16 v[20:23], v[148:151], v[196:199], v[20:23]
	v_mfma_f32_16x16x32_bf16 v[16:19], v[156:159], v[196:199], v[16:19]
	v_mfma_f32_16x16x32_bf16 v[4:7], v[148:151], v[204:207], v[4:7]
	v_mfma_f32_16x16x32_bf16 v[0:3], v[156:159], v[204:207], v[0:3]
	s_setprio 0
	s_barrier
	s_add_i32 s81, s81, 2
	s_add_u32 s58, s58, 0x100
	s_addc_u32 s59, s59, 0
	s_add_u32 s79, s79, 0x100
	s_addc_u32 s80, s80, 0
	s_cmp_gt_u32 s81, 29
	s_cbranch_scc0 .LBB0_939
	s_and_b64 vcc, exec, s[42:43]
	s_cbranch_vccz .LBB0_942
	s_barrier

; #define PG8_STAGE(bufoff, gbase, voff) do { _Pragma("unroll") for (int _i = 0; _i < 2; ++_i) \
;         __builtin_amdgcn_global_load_lds((const unsigned*)((const char*)(gbase) + (voff)[_i]), (PG8_LAS unsigned*)(lds + (bufoff) + ldsw + _i * 8192), 16, 0, 0); } while (0)
; #define PG8_LDA(dst, b, h) do { _Pragma("unroll") for (int m = 0; m < 4; ++m) _Pragma("unroll") for (int k = 0; k < 2; ++k) dst[m][k] = *(const PG8_LAS bf16x8*)(lds + PG8_SA(b, h) + aoff + m * 2048 + k * 1024); } while (0)
; #define PG8_LDB(dst, b, h) do { _Pragma("unroll") for (int n = 0; n < 2; ++n) _Pragma("unroll") for (int k = 0; k < 2; ++k) dst[n][k] = *(const PG8_LAS bf16x8*)(lds + PG8_SB(b, h) + boff + n * 2048 + k * 1024); } while (0)
; #define PG8_SCHED __builtin_amdgcn_sched_barrier(0)
; template <class Epi, class Sched, bool ALIGN_EPI = false, bool SP2 = false>
; __device__ __forceinline__ void gemm_phase(PG8_LAS unsigned char* lds, const Gemm g, const Sched& S, const Epi& E) {
;     ...
;             const char* a1 = cA + (size_t)(t + 1) * kstep;
;             const char* a2 = last ? nA : cA + (size_t)(t + 2) * kstep; const char* b2 = last ? nB : cB + (size_t)(t + 2) * kstep;
;             const char* a3 = a2 + kstep; const char* b3 = b2 + kstep;
;             if (last && has_next) S.a_ready(nxt);
;             if constexpr (SP2) {
;             PG8_LDB(B0, 0, 0); PG8_LDB(B1, 0, 1); PG8_SCHED; PG8_LDA(At, 0, 0); PG8_STAGE(PG8_SA(1, 1), a1 + hstep, voffA);
.LBB0_1034:
	ds_read_b128 v[128:131], v201
	ds_read_b128 v[132:135], v201 offset:1024
	ds_read_b128 v[136:139], v201 offset:2048
	ds_read_b128 v[140:143], v201 offset:3072
	ds_read_b128 v[144:147], v205
	ds_read_b128 v[148:151], v205 offset:1024
	ds_read_b128 v[152:155], v205 offset:2048
	ds_read_b128 v[156:159], v205 offset:3072
	s_add_u32 s12, s10, 0xfff80080
	s_addc_u32 s13, s11, -1
	s_cmp_eq_u32 s83, 28
	s_cselect_b32 s59, s53, s13
	s_cselect_b32 s58, s79, s12
	s_cselect_b32 s13, s51, s82
	s_cselect_b32 s12, s80, s81

; #define PG8_STAGE(bufoff, gbase, voff) do { _Pragma("unroll") for (int _i = 0; _i < 2; ++_i) \
;         __builtin_amdgcn_global_load_lds((const unsigned*)((const char*)(gbase) + (voff)[_i]), (PG8_LAS unsigned*)(lds + (bufoff) + ldsw + _i * 8192), 16, 0, 0); } while (0)
; #define PG8_LDA(dst, b, h) do { _Pragma("unroll") for (int m = 0; m < 4; ++m) _Pragma("unroll") for (int k = 0; k < 2; ++k) dst[m][k] = *(const PG8_LAS bf16x8*)(lds + PG8_SA(b, h) + aoff + m * 2048 + k * 1024); } while (0)
; #define PG8_LDB(dst, b, h) do { _Pragma("unroll") for (int n = 0; n < 2; ++n) _Pragma("unroll") for (int k = 0; k < 2; ++k) dst[n][k] = *(const PG8_LAS bf16x8*)(lds + PG8_SB(b, h) + boff + n * 2048 + k * 1024); } while (0)
; #define PG8_SCHED __builtin_amdgcn_sched_barrier(0)
; template <class Epi, class Sched, bool ALIGN_EPI = false, bool SP2 = false>
; __device__ __forceinline__ void gemm_phase(PG8_LAS unsigned char* lds, const Gemm g, const Sched& S, const Epi& E) {
;     ...
;             PG8_LDB(B0, 0, 0); PG8_LDB(B1, 0, 1); PG8_SCHED; PG8_LDA(At, 0, 0); PG8_STAGE(PG8_SA(1, 1), a1 + hstep, voffA);
	s_add_i32 m0, s63, 0xc000
	ds_read_b128 v[176:179], v207
	ds_read_b128 v[184:187], v207 offset:1024
	ds_read_b128 v[190:193], v207 offset:2048
	ds_read_b128 v[210:213], v207 offset:3072
	ds_read_b128 v[214:217], v207 offset:4096
	ds_read_b128 v[218:221], v207 offset:5120
	ds_read_b128 v[222:225], v207 offset:6144
	ds_read_b128 v[226:229], v207 offset:7168
	global_load_lds_dwordx4 v168, s[10:11]

; #define PG8_STAGE(bufoff, gbase, voff) do { _Pragma("unroll") for (int _i = 0; _i < 2; ++_i) \
;         __builtin_amdgcn_global_load_lds((const unsigned*)((const char*)(gbase) + (voff)[_i]), (PG8_LAS unsigned*)(lds + (bufoff) + ldsw + _i * 8192), 16, 0, 0); } while (0)
; #define PG8_LDA(dst, b, h) do { _Pragma("unroll") for (int m = 0; m < 4; ++m) _Pragma("unroll") for (int k = 0; k < 2; ++k) dst[m][k] = *(const PG8_LAS bf16x8*)(lds + PG8_SA(b, h) + aoff + m * 2048 + k * 1024); } while (0)
; #define PG8_LDB(dst, b, h) do { _Pragma("unroll") for (int n = 0; n < 2; ++n) _Pragma("unroll") for (int k = 0; k < 2; ++k) dst[n][k] = *(const PG8_LAS bf16x8*)(lds + PG8_SB(b, h) + boff + n * 2048 + k * 1024); } while (0)
; #define PG8_MMA(ai, bj, At, Bt) do { __builtin_amdgcn_s_setprio(1); _Pragma("unroll") for (int m = 0; m < 4; ++m) _Pragma("unroll") for (int n = 0; n < 2; ++n) _Pragma("unroll") for (int k = 0; k < 2; ++k) \
;         acc[ai][bj][m][n] = __builtin_amdgcn_mfma_f32_16x16x32_bf16(Bt[n][k], At[m][k], acc[ai][bj][m][n], 0, 0, 0); __builtin_amdgcn_s_setprio(0); } while (0)
; #define PG8_WAIT_V(n) asm volatile("s_waitcnt vmcnt(" #n ")" ::: "memory")
; #define PG8_WAIT_L(n) asm volatile("s_waitcnt lgkmcnt(" #n ")" ::: "memory")
; #define PG8_BAR __builtin_amdgcn_s_barrier()
; #define PG8_SCHED __builtin_amdgcn_sched_barrier(0)
; template <class Epi, class Sched, bool ALIGN_EPI = false, bool SP2 = false>
; __device__ __forceinline__ void gemm_phase(PG8_LAS unsigned char* lds, const Gemm g, const Sched& S, const Epi& E) {
;     ...
;             PG8_LDB(B0, 0, 0); PG8_LDB(B1, 0, 1); PG8_SCHED; PG8_LDA(At, 0, 0); PG8_STAGE(PG8_SA(1, 1), a1 + hstep, voffA);
;             PG8_WAIT_V(8); PG8_WAIT_L(0); PG8_BAR; PG8_MMA(0, 0, At, B0); PG8_MMA(0, 1, At, B1); PG8_BAR; PG8_SCHED;
	s_add_i32 m0, s63, 0xe000
	s_nop 0
	global_load_lds_dwordx4 v170, s[10:11]
	s_waitcnt vmcnt(8)
	s_waitcnt lgkmcnt(0)
	s_setprio 1
	s_barrier

; #define PG8_MMA(ai, bj, At, Bt) do { __builtin_amdgcn_s_setprio(1); _Pragma("unroll") for (int m = 0; m < 4; ++m) _Pragma("unroll") for (int n = 0; n < 2; ++n) _Pragma("unroll") for (int k = 0; k < 2; ++k) \
;         acc[ai][bj][m][n] = __builtin_amdgcn_mfma_f32_16x16x32_bf16(Bt[n][k], At[m][k], acc[ai][bj][m][n], 0, 0, 0); __builtin_amdgcn_s_setprio(0); } while (0)
; #define PG8_WAIT_V(n) asm volatile("s_waitcnt vmcnt(" #n ")" ::: "memory")
; #define PG8_WAIT_L(n) asm volatile("s_waitcnt lgkmcnt(" #n ")" ::: "memory")
; #define PG8_BAR __builtin_amdgcn_s_barrier()
; #define PG8_SCHED __builtin_amdgcn_sched_barrier(0)
; template <class Epi, class Sched, bool ALIGN_EPI = false, bool SP2 = false>
; __device__ __forceinline__ void gemm_phase(PG8_LAS unsigned char* lds, const Gemm g, const Sched& S, const Epi& E) {
;     ...
;             PG8_WAIT_V(8); PG8_WAIT_L(0); PG8_BAR; PG8_MMA(0, 0, At, B0); PG8_MMA(0, 1, At, B1); PG8_BAR; PG8_SCHED;
	v_mfma_f32_16x16x32_bf16 v[124:127], v[128:131], v[176:179], v[124:127]
	v_mfma_f32_16x16x32_bf16 v[120:123], v[136:139], v[176:179], v[120:123]
	v_mfma_f32_16x16x32_bf16 v[108:111], v[128:131], v[190:193], v[108:111]
	v_mfma_f32_16x16x32_bf16 v[104:107], v[136:139], v[190:193], v[104:107]
	v_mfma_f32_16x16x32_bf16 v[92:95], v[128:131], v[214:217], v[92:95]
	v_mfma_f32_16x16x32_bf16 v[88:91], v[136:139], v[214:217], v[88:91]
	v_mfma_f32_16x16x32_bf16 v[76:79], v[128:131], v[222:225], v[76:79]
	v_mfma_f32_16x16x32_bf16 v[72:75], v[136:139], v[222:225], v[72:75]
	v_mfma_f32_16x16x32_bf16 v[124:127], v[132:135], v[184:187], v[124:127]
	v_mfma_f32_16x16x32_bf16 v[120:123], v[140:143], v[184:187], v[120:123]
	v_mfma_f32_16x16x32_bf16 v[108:111], v[132:135], v[210:213], v[108:111]
	v_mfma_f32_16x16x32_bf16 v[104:107], v[140:143], v[210:213], v[104:107]
	v_mfma_f32_16x16x32_bf16 v[92:95], v[132:135], v[218:221], v[92:95]
	v_mfma_f32_16x16x32_bf16 v[88:91], v[140:143], v[218:221], v[88:91]
	v_mfma_f32_16x16x32_bf16 v[76:79], v[132:135], v[226:229], v[76:79]
	v_mfma_f32_16x16x32_bf16 v[72:75], v[140:143], v[226:229], v[72:75]


; #define PG8_STAGE(bufoff, gbase, voff) do { _Pragma("unroll") for (int _i = 0; _i < 2; ++_i) \
;         __builtin_amdgcn_global_load_lds((const unsigned*)((const char*)(gbase) + (voff)[_i]), (PG8_LAS unsigned*)(lds + (bufoff) + ldsw + _i * 8192), 16, 0, 0); } while (0)
; #define PG8_LDA(dst, b, h) do { _Pragma("unroll") for (int m = 0; m < 4; ++m) _Pragma("unroll") for (int k = 0; k < 2; ++k) dst[m][k] = *(const PG8_LAS bf16x8*)(lds + PG8_SA(b, h) + aoff + m * 2048 + k * 1024); } while (0)
; #define PG8_MMA(ai, bj, At, Bt) do { __builtin_amdgcn_s_setprio(1); _Pragma("unroll") for (int m = 0; m < 4; ++m) _Pragma("unroll") for (int n = 0; n < 2; ++n) _Pragma("unroll") for (int k = 0; k < 2; ++k) \
;         acc[ai][bj][m][n] = __builtin_amdgcn_mfma_f32_16x16x32_bf16(Bt[n][k], At[m][k], acc[ai][bj][m][n], 0, 0, 0); __builtin_amdgcn_s_setprio(0); } while (0)
; #define PG8_WAIT_V(n) asm volatile("s_waitcnt vmcnt(" #n ")" ::: "memory")
; #define PG8_WAIT_L(n) asm volatile("s_waitcnt lgkmcnt(" #n ")" ::: "memory")
; #define PG8_BAR __builtin_amdgcn_s_barrier()
; #define PG8_SCHED __builtin_amdgcn_sched_barrier(0)
; template <class Epi, class Sched, bool ALIGN_EPI = false, bool SP2 = false>
; __device__ __forceinline__ void gemm_phase(PG8_LAS unsigned char* lds, const Gemm g, const Sched& S, const Epi& E) {
;     ...
;             PG8_WAIT_V(8); PG8_WAIT_L(0); PG8_BAR; PG8_MMA(0, 0, At, B0); PG8_MMA(0, 1, At, B1); PG8_BAR; PG8_SCHED;
;             PG8_LDA(At, 0, 1); PG8_STAGE(PG8_SB(0, 0), b2, voffB); PG8_STAGE(PG8_SB(0, 1), b2 + hstep, voffB); PG8_STAGE(PG8_SA(0, 0), a2, voffA);
	v_mfma_f32_16x16x32_bf16 v[116:119], v[144:147], v[176:179], v[116:119]
	v_mfma_f32_16x16x32_bf16 v[112:115], v[152:155], v[176:179], v[112:115]
	v_mfma_f32_16x16x32_bf16 v[100:103], v[144:147], v[190:193], v[100:103]
	v_mfma_f32_16x16x32_bf16 v[96:99], v[152:155], v[190:193], v[96:99]
	v_mfma_f32_16x16x32_bf16 v[84:87], v[144:147], v[214:217], v[84:87]
	v_mfma_f32_16x16x32_bf16 v[80:83], v[152:155], v[214:217], v[80:83]
	v_mfma_f32_16x16x32_bf16 v[68:71], v[144:147], v[222:225], v[68:71]
	v_mfma_f32_16x16x32_bf16 v[64:67], v[152:155], v[222:225], v[64:67]
	v_mfma_f32_16x16x32_bf16 v[116:119], v[148:151], v[184:187], v[116:119]
	v_mfma_f32_16x16x32_bf16 v[112:115], v[156:159], v[184:187], v[112:115]
	v_mfma_f32_16x16x32_bf16 v[100:103], v[148:151], v[210:213], v[100:103]
	v_mfma_f32_16x16x32_bf16 v[96:99], v[156:159], v[210:213], v[96:99]
	v_mfma_f32_16x16x32_bf16 v[84:87], v[148:151], v[218:221], v[84:87]
	v_mfma_f32_16x16x32_bf16 v[80:83], v[156:159], v[218:221], v[80:83]
	v_mfma_f32_16x16x32_bf16 v[68:71], v[148:151], v[226:229], v[68:71]
	v_mfma_f32_16x16x32_bf16 v[64:67], v[156:159], v[226:229], v[64:67]
	s_setprio 0
	s_barrier
	s_add_i32 s84, s73, s62
	s_mov_b64 s[96:97], s[12:13]

; #define PG8_STAGE(bufoff, gbase, voff) do { _Pragma("unroll") for (int _i = 0; _i < 2; ++_i) \
;         __builtin_amdgcn_global_load_lds((const unsigned*)((const char*)(gbase) + (voff)[_i]), (PG8_LAS unsigned*)(lds + (bufoff) + ldsw + _i * 8192), 16, 0, 0); } while (0)
; #define PG8_LDA(dst, b, h) do { _Pragma("unroll") for (int m = 0; m < 4; ++m) _Pragma("unroll") for (int k = 0; k < 2; ++k) dst[m][k] = *(const PG8_LAS bf16x8*)(lds + PG8_SA(b, h) + aoff + m * 2048 + k * 1024); } while (0)
; template <class Epi, class Sched, bool ALIGN_EPI = false, bool SP2 = false>
; __device__ __forceinline__ void gemm_phase(PG8_LAS unsigned char* lds, const Gemm g, const Sched& S, const Epi& E) {
;     ...
;             PG8_LDA(At, 0, 1); PG8_STAGE(PG8_SB(0, 0), b2, voffB); PG8_STAGE(PG8_SB(0, 1), b2 + hstep, voffB); PG8_STAGE(PG8_SA(0, 0), a2, voffA);
	s_mov_b32 m0, s84
	ds_read_b128 v[176:179], v207 offset:16384
	ds_read_b128 v[184:187], v207 offset:17408
	ds_read_b128 v[190:193], v207 offset:18432
	ds_read_b128 v[210:213], v207 offset:19456
	ds_read_b128 v[214:217], v207 offset:20480
	ds_read_b128 v[218:221], v207 offset:21504
	ds_read_b128 v[222:225], v207 offset:22528
	ds_read_b128 v[226:229], v207 offset:23552
	global_load_lds_dwordx4 v162, s[12:13]
	s_add_i32 m0, s84, 0x2000
	s_add_u32 s84, s12, 0x80000

; #define PG8_STAGE(bufoff, gbase, voff) do { _Pragma("unroll") for (int _i = 0; _i < 2; ++_i) \
;         __builtin_amdgcn_global_load_lds((const unsigned*)((const char*)(gbase) + (voff)[_i]), (PG8_LAS unsigned*)(lds + (bufoff) + ldsw + _i * 8192), 16, 0, 0); } while (0)
; #define PG8_LDA(dst, b, h) do { _Pragma("unroll") for (int m = 0; m < 4; ++m) _Pragma("unroll") for (int k = 0; k < 2; ++k) dst[m][k] = *(const PG8_LAS bf16x8*)(lds + PG8_SA(b, h) + aoff + m * 2048 + k * 1024); } while (0)
; template <class Epi, class Sched, bool ALIGN_EPI = false, bool SP2 = false>
; __device__ __forceinline__ void gemm_phase(PG8_LAS unsigned char* lds, const Gemm g, const Sched& S, const Epi& E) {
;     ...
;             PG8_LDA(At, 0, 1); PG8_STAGE(PG8_SB(0, 0), b2, voffB); PG8_STAGE(PG8_SB(0, 1), b2 + hstep, voffB); PG8_STAGE(PG8_SA(0, 0), a2, voffA);
	s_addc_u32 s85, s13, 0
	s_add_i32 s86, s74, s62
	global_load_lds_dwordx4 v166, s[12:13]

; #define PG8_STAGE(bufoff, gbase, voff) do { _Pragma("unroll") for (int _i = 0; _i < 2; ++_i) \
;         __builtin_amdgcn_global_load_lds((const unsigned*)((const char*)(gbase) + (voff)[_i]), (PG8_LAS unsigned*)(lds + (bufoff) + ldsw + _i * 8192), 16, 0, 0); } while (0)
; #define PG8_LDA(dst, b, h) do { _Pragma("unroll") for (int m = 0; m < 4; ++m) _Pragma("unroll") for (int k = 0; k < 2; ++k) dst[m][k] = *(const PG8_LAS bf16x8*)(lds + PG8_SA(b, h) + aoff + m * 2048 + k * 1024); } while (0)
; template <class Epi, class Sched, bool ALIGN_EPI = false, bool SP2 = false>
; __device__ __forceinline__ void gemm_phase(PG8_LAS unsigned char* lds, const Gemm g, const Sched& S, const Epi& E) {
;     ...
;             PG8_LDA(At, 0, 1); PG8_STAGE(PG8_SB(0, 0), b2, voffB); PG8_STAGE(PG8_SB(0, 1), b2 + hstep, voffB); PG8_STAGE(PG8_SA(0, 0), a2, voffA);
	s_mov_b32 m0, s86
	s_nop 0
	global_load_lds_dwordx4 v162, s[84:85]

; #define PG8_STAGE(bufoff, gbase, voff) do { _Pragma("unroll") for (int _i = 0; _i < 2; ++_i) \
;         __builtin_amdgcn_global_load_lds((const unsigned*)((const char*)(gbase) + (voff)[_i]), (PG8_LAS unsigned*)(lds + (bufoff) + ldsw + _i * 8192), 16, 0, 0); } while (0)
; #define PG8_LDA(dst, b, h) do { _Pragma("unroll") for (int m = 0; m < 4; ++m) _Pragma("unroll") for (int k = 0; k < 2; ++k) dst[m][k] = *(const PG8_LAS bf16x8*)(lds + PG8_SA(b, h) + aoff + m * 2048 + k * 1024); } while (0)
; template <class Epi, class Sched, bool ALIGN_EPI = false, bool SP2 = false>
; __device__ __forceinline__ void gemm_phase(PG8_LAS unsigned char* lds, const Gemm g, const Sched& S, const Epi& E) {
;     ...
;             PG8_LDA(At, 0, 1); PG8_STAGE(PG8_SB(0, 0), b2, voffB); PG8_STAGE(PG8_SB(0, 1), b2 + hstep, voffB); PG8_STAGE(PG8_SA(0, 0), a2, voffA);
	s_add_i32 m0, s86, 0x2000
	s_nop 0
	global_load_lds_dwordx4 v166, s[84:85]
	s_mov_b64 s[98:99], s[58:59]

; #define PG8_STAGE(bufoff, gbase, voff) do { _Pragma("unroll") for (int _i = 0; _i < 2; ++_i) \
;         __builtin_amdgcn_global_load_lds((const unsigned*)((const char*)(gbase) + (voff)[_i]), (PG8_LAS unsigned*)(lds + (bufoff) + ldsw + _i * 8192), 16, 0, 0); } while (0)
; #define PG8_LDA(dst, b, h) do { _Pragma("unroll") for (int m = 0; m < 4; ++m) _Pragma("unroll") for (int k = 0; k < 2; ++k) dst[m][k] = *(const PG8_LAS bf16x8*)(lds + PG8_SA(b, h) + aoff + m * 2048 + k * 1024); } while (0)
; #define PG8_MMA(ai, bj, At, Bt) do { __builtin_amdgcn_s_setprio(1); _Pragma("unroll") for (int m = 0; m < 4; ++m) _Pragma("unroll") for (int n = 0; n < 2; ++n) _Pragma("unroll") for (int k = 0; k < 2; ++k) \
;         acc[ai][bj][m][n] = __builtin_amdgcn_mfma_f32_16x16x32_bf16(Bt[n][k], At[m][k], acc[ai][bj][m][n], 0, 0, 0); __builtin_amdgcn_s_setprio(0); } while (0)
; #define PG8_WAIT_V(n) asm volatile("s_waitcnt vmcnt(" #n ")" ::: "memory")
; #define PG8_WAIT_L(n) asm volatile("s_waitcnt lgkmcnt(" #n ")" ::: "memory")
; #define PG8_BAR __builtin_amdgcn_s_barrier()
; #define PG8_SCHED __builtin_amdgcn_sched_barrier(0)
; template <class Epi, class Sched, bool ALIGN_EPI = false, bool SP2 = false>
; __device__ __forceinline__ void gemm_phase(PG8_LAS unsigned char* lds, const Gemm g, const Sched& S, const Epi& E) {
;     ...
;             PG8_LDA(At, 0, 1); PG8_STAGE(PG8_SB(0, 0), b2, voffB); PG8_STAGE(PG8_SB(0, 1), b2 + hstep, voffB); PG8_STAGE(PG8_SA(0, 0), a2, voffA);
;             PG8_WAIT_V(8); PG8_WAIT_L(0); PG8_BAR; PG8_MMA(1, 0, At, B0); PG8_MMA(1, 1, At, B1); PG8_BAR; PG8_SCHED;
	s_mov_b32 m0, s63
	s_nop 0
	global_load_lds_dwordx4 v160, s[58:59]
	s_mov_b32 m0, s64
	s_nop 0
	global_load_lds_dwordx4 v164, s[58:59]
	s_waitcnt vmcnt(8)
	s_waitcnt lgkmcnt(0)
	s_setprio 1
	s_barrier

; #define PG8_MMA(ai, bj, At, Bt) do { __builtin_amdgcn_s_setprio(1); _Pragma("unroll") for (int m = 0; m < 4; ++m) _Pragma("unroll") for (int n = 0; n < 2; ++n) _Pragma("unroll") for (int k = 0; k < 2; ++k) \
;         acc[ai][bj][m][n] = __builtin_amdgcn_mfma_f32_16x16x32_bf16(Bt[n][k], At[m][k], acc[ai][bj][m][n], 0, 0, 0); __builtin_amdgcn_s_setprio(0); } while (0)
; #define PG8_WAIT_V(n) asm volatile("s_waitcnt vmcnt(" #n ")" ::: "memory")
; #define PG8_WAIT_L(n) asm volatile("s_waitcnt lgkmcnt(" #n ")" ::: "memory")
; #define PG8_BAR __builtin_amdgcn_s_barrier()
; #define PG8_SCHED __builtin_amdgcn_sched_barrier(0)
; template <class Epi, class Sched, bool ALIGN_EPI = false, bool SP2 = false>
; __device__ __forceinline__ void gemm_phase(PG8_LAS unsigned char* lds, const Gemm g, const Sched& S, const Epi& E) {
;     ...
;             PG8_WAIT_V(8); PG8_WAIT_L(0); PG8_BAR; PG8_MMA(1, 0, At, B0); PG8_MMA(1, 1, At, B1); PG8_BAR; PG8_SCHED;
	v_mfma_f32_16x16x32_bf16 v[60:63], v[128:131], v[176:179], v[60:63]
	v_mfma_f32_16x16x32_bf16 v[56:59], v[136:139], v[176:179], v[56:59]
	v_mfma_f32_16x16x32_bf16 v[44:47], v[128:131], v[190:193], v[44:47]
	v_mfma_f32_16x16x32_bf16 v[40:43], v[136:139], v[190:193], v[40:43]
	v_mfma_f32_16x16x32_bf16 v[28:31], v[128:131], v[214:217], v[28:31]
	v_mfma_f32_16x16x32_bf16 v[24:27], v[136:139], v[214:217], v[24:27]
	v_mfma_f32_16x16x32_bf16 v[12:15], v[128:131], v[222:225], v[12:15]
	v_mfma_f32_16x16x32_bf16 v[8:11], v[136:139], v[222:225], v[8:11]
	v_mfma_f32_16x16x32_bf16 v[60:63], v[132:135], v[184:187], v[60:63]
	v_mfma_f32_16x16x32_bf16 v[56:59], v[140:143], v[184:187], v[56:59]
	v_mfma_f32_16x16x32_bf16 v[44:47], v[132:135], v[210:213], v[44:47]
	v_mfma_f32_16x16x32_bf16 v[40:43], v[140:143], v[210:213], v[40:43]
	v_mfma_f32_16x16x32_bf16 v[28:31], v[132:135], v[218:221], v[28:31]
	v_mfma_f32_16x16x32_bf16 v[24:27], v[140:143], v[218:221], v[24:27]
	v_mfma_f32_16x16x32_bf16 v[12:15], v[132:135], v[226:229], v[12:15]
	v_mfma_f32_16x16x32_bf16 v[8:11], v[140:143], v[226:229], v[8:11]


; #define PG8_STAGE(bufoff, gbase, voff) do { _Pragma("unroll") for (int _i = 0; _i < 2; ++_i) \
;         __builtin_amdgcn_global_load_lds((const unsigned*)((const char*)(gbase) + (voff)[_i]), (PG8_LAS unsigned*)(lds + (bufoff) + ldsw + _i * 8192), 16, 0, 0); } while (0)
; #define PG8_LDA(dst, b, h) do { _Pragma("unroll") for (int m = 0; m < 4; ++m) _Pragma("unroll") for (int k = 0; k < 2; ++k) dst[m][k] = *(const PG8_LAS bf16x8*)(lds + PG8_SA(b, h) + aoff + m * 2048 + k * 1024); } while (0)
; #define PG8_LDB(dst, b, h) do { _Pragma("unroll") for (int n = 0; n < 2; ++n) _Pragma("unroll") for (int k = 0; k < 2; ++k) dst[n][k] = *(const PG8_LAS bf16x8*)(lds + PG8_SB(b, h) + boff + n * 2048 + k * 1024); } while (0)
; #define PG8_MMA(ai, bj, At, Bt) do { __builtin_amdgcn_s_setprio(1); _Pragma("unroll") for (int m = 0; m < 4; ++m) _Pragma("unroll") for (int n = 0; n < 2; ++n) _Pragma("unroll") for (int k = 0; k < 2; ++k) \
;         acc[ai][bj][m][n] = __builtin_amdgcn_mfma_f32_16x16x32_bf16(Bt[n][k], At[m][k], acc[ai][bj][m][n], 0, 0, 0); __builtin_amdgcn_s_setprio(0); } while (0)
; #define PG8_WAIT_V(n) asm volatile("s_waitcnt vmcnt(" #n ")" ::: "memory")
; #define PG8_WAIT_L(n) asm volatile("s_waitcnt lgkmcnt(" #n ")" ::: "memory")
; #define PG8_BAR __builtin_amdgcn_s_barrier()
; #define PG8_SCHED __builtin_amdgcn_sched_barrier(0)
; template <class Epi, class Sched, bool ALIGN_EPI = false, bool SP2 = false>
; __device__ __forceinline__ void gemm_phase(PG8_LAS unsigned char* lds, const Gemm g, const Sched& S, const Epi& E) {
;     ...
;             PG8_WAIT_V(8); PG8_WAIT_L(0); PG8_BAR; PG8_MMA(1, 0, At, B0); PG8_MMA(1, 1, At, B1); PG8_BAR; PG8_SCHED;
;             PG8_LDB(B0, 1, 0); PG8_LDB(B1, 1, 1); PG8_SCHED; PG8_LDA(At, 1, 0); PG8_STAGE(PG8_SA(0, 1), a2 + hstep, voffA);
	v_mfma_f32_16x16x32_bf16 v[52:55], v[144:147], v[176:179], v[52:55]
	v_mfma_f32_16x16x32_bf16 v[48:51], v[152:155], v[176:179], v[48:51]
	v_mfma_f32_16x16x32_bf16 v[36:39], v[144:147], v[190:193], v[36:39]
	v_mfma_f32_16x16x32_bf16 v[32:35], v[152:155], v[190:193], v[32:35]
	v_mfma_f32_16x16x32_bf16 v[20:23], v[144:147], v[214:217], v[20:23]
	v_mfma_f32_16x16x32_bf16 v[16:19], v[152:155], v[214:217], v[16:19]
	v_mfma_f32_16x16x32_bf16 v[4:7], v[144:147], v[222:225], v[4:7]
	v_mfma_f32_16x16x32_bf16 v[0:3], v[152:155], v[222:225], v[0:3]
	v_mfma_f32_16x16x32_bf16 v[52:55], v[148:151], v[184:187], v[52:55]
	v_mfma_f32_16x16x32_bf16 v[48:51], v[156:159], v[184:187], v[48:51]
	v_mfma_f32_16x16x32_bf16 v[36:39], v[148:151], v[210:213], v[36:39]
	v_mfma_f32_16x16x32_bf16 v[32:35], v[156:159], v[210:213], v[32:35]
	v_mfma_f32_16x16x32_bf16 v[20:23], v[148:151], v[218:221], v[20:23]
	v_mfma_f32_16x16x32_bf16 v[16:19], v[156:159], v[218:221], v[16:19]
	v_mfma_f32_16x16x32_bf16 v[4:7], v[148:151], v[226:229], v[4:7]
	v_mfma_f32_16x16x32_bf16 v[0:3], v[156:159], v[226:229], v[0:3]
	s_setprio 0
	s_barrier
	s_add_i32 s84, 0, 0x18000
	s_add_i32 s85, 0, 0x1c000
	v_add_u32_e32 v140, s84, v189
	v_add_u32_e32 v156, s85, v189
	ds_read_b128 v[128:131], v140
	ds_read_b128 v[132:135], v140 offset:1024
	ds_read_b128 v[136:139], v140 offset:2048
	ds_read_b128 v[140:143], v140 offset:3072
	ds_read_b128 v[144:147], v156
	ds_read_b128 v[148:151], v156 offset:1024
	ds_read_b128 v[152:155], v156 offset:2048
	ds_read_b128 v[156:159], v156 offset:3072
	s_add_u32 s58, s58, 0x80000
	s_addc_u32 s59, s59, 0
	s_mov_b32 m0, s65

; #define PG8_STAGE(bufoff, gbase, voff) do { _Pragma("unroll") for (int _i = 0; _i < 2; ++_i) \
;         __builtin_amdgcn_global_load_lds((const unsigned*)((const char*)(gbase) + (voff)[_i]), (PG8_LAS unsigned*)(lds + (bufoff) + ldsw + _i * 8192), 16, 0, 0); } while (0)
; #define PG8_LDA(dst, b, h) do { _Pragma("unroll") for (int m = 0; m < 4; ++m) _Pragma("unroll") for (int k = 0; k < 2; ++k) dst[m][k] = *(const PG8_LAS bf16x8*)(lds + PG8_SA(b, h) + aoff + m * 2048 + k * 1024); } while (0)
; #define PG8_LDB(dst, b, h) do { _Pragma("unroll") for (int n = 0; n < 2; ++n) _Pragma("unroll") for (int k = 0; k < 2; ++k) dst[n][k] = *(const PG8_LAS bf16x8*)(lds + PG8_SB(b, h) + boff + n * 2048 + k * 1024); } while (0)
; #define PG8_SCHED __builtin_amdgcn_sched_barrier(0)
; template <class Epi, class Sched, bool ALIGN_EPI = false, bool SP2 = false>
; __device__ __forceinline__ void gemm_phase(PG8_LAS unsigned char* lds, const Gemm g, const Sched& S, const Epi& E) {
;     ...
;             PG8_LDB(B0, 1, 0); PG8_LDB(B1, 1, 1); PG8_SCHED; PG8_LDA(At, 1, 0); PG8_STAGE(PG8_SA(0, 1), a2 + hstep, voffA);
	ds_read_b128 v[176:179], v207 offset:32768
	ds_read_b128 v[184:187], v207 offset:33792
	ds_read_b128 v[190:193], v207 offset:34816
	ds_read_b128 v[210:213], v207 offset:35840
	ds_read_b128 v[214:217], v207 offset:36864
	ds_read_b128 v[218:221], v207 offset:37888
	ds_read_b128 v[222:225], v207 offset:38912
	ds_read_b128 v[226:229], v207 offset:39936
	global_load_lds_dwordx4 v160, s[58:59]

; #define PG8_STAGE(bufoff, gbase, voff) do { _Pragma("unroll") for (int _i = 0; _i < 2; ++_i) \
;         __builtin_amdgcn_global_load_lds((const unsigned*)((const char*)(gbase) + (voff)[_i]), (PG8_LAS unsigned*)(lds + (bufoff) + ldsw + _i * 8192), 16, 0, 0); } while (0)
; #define PG8_LDA(dst, b, h) do { _Pragma("unroll") for (int m = 0; m < 4; ++m) _Pragma("unroll") for (int k = 0; k < 2; ++k) dst[m][k] = *(const PG8_LAS bf16x8*)(lds + PG8_SA(b, h) + aoff + m * 2048 + k * 1024); } while (0)
; #define PG8_LDB(dst, b, h) do { _Pragma("unroll") for (int n = 0; n < 2; ++n) _Pragma("unroll") for (int k = 0; k < 2; ++k) dst[n][k] = *(const PG8_LAS bf16x8*)(lds + PG8_SB(b, h) + boff + n * 2048 + k * 1024); } while (0)
; #define PG8_MMA(ai, bj, At, Bt) do { __builtin_amdgcn_s_setprio(1); _Pragma("unroll") for (int m = 0; m < 4; ++m) _Pragma("unroll") for (int n = 0; n < 2; ++n) _Pragma("unroll") for (int k = 0; k < 2; ++k) \
;         acc[ai][bj][m][n] = __builtin_amdgcn_mfma_f32_16x16x32_bf16(Bt[n][k], At[m][k], acc[ai][bj][m][n], 0, 0, 0); __builtin_amdgcn_s_setprio(0); } while (0)
; #define PG8_WAIT_V(n) asm volatile("s_waitcnt vmcnt(" #n ")" ::: "memory")
; #define PG8_WAIT_L(n) asm volatile("s_waitcnt lgkmcnt(" #n ")" ::: "memory")
; #define PG8_BAR __builtin_amdgcn_s_barrier()
; #define PG8_SCHED __builtin_amdgcn_sched_barrier(0)
; template <class Epi, class Sched, bool ALIGN_EPI = false, bool SP2 = false>
; __device__ __forceinline__ void gemm_phase(PG8_LAS unsigned char* lds, const Gemm g, const Sched& S, const Epi& E) {
;     ...
;             PG8_LDB(B0, 1, 0); PG8_LDB(B1, 1, 1); PG8_SCHED; PG8_LDA(At, 1, 0); PG8_STAGE(PG8_SA(0, 1), a2 + hstep, voffA);
;             PG8_WAIT_V(8); PG8_WAIT_L(0); PG8_BAR; PG8_MMA(0, 0, At, B0); PG8_MMA(0, 1, At, B1); PG8_BAR; PG8_SCHED;
	s_mov_b32 m0, s67
	s_nop 0
	global_load_lds_dwordx4 v164, s[58:59]
	s_waitcnt vmcnt(8)
	s_waitcnt lgkmcnt(0)
	s_setprio 1
	s_barrier

; #define PG8_MMA(ai, bj, At, Bt) do { __builtin_amdgcn_s_setprio(1); _Pragma("unroll") for (int m = 0; m < 4; ++m) _Pragma("unroll") for (int n = 0; n < 2; ++n) _Pragma("unroll") for (int k = 0; k < 2; ++k) \
;         acc[ai][bj][m][n] = __builtin_amdgcn_mfma_f32_16x16x32_bf16(Bt[n][k], At[m][k], acc[ai][bj][m][n], 0, 0, 0); __builtin_amdgcn_s_setprio(0); } while (0)
; #define PG8_WAIT_V(n) asm volatile("s_waitcnt vmcnt(" #n ")" ::: "memory")
; #define PG8_WAIT_L(n) asm volatile("s_waitcnt lgkmcnt(" #n ")" ::: "memory")
; #define PG8_BAR __builtin_amdgcn_s_barrier()
; #define PG8_SCHED __builtin_amdgcn_sched_barrier(0)
; template <class Epi, class Sched, bool ALIGN_EPI = false, bool SP2 = false>
; __device__ __forceinline__ void gemm_phase(PG8_LAS unsigned char* lds, const Gemm g, const Sched& S, const Epi& E) {
;     ...
;             PG8_WAIT_V(8); PG8_WAIT_L(0); PG8_BAR; PG8_MMA(0, 0, At, B0); PG8_MMA(0, 1, At, B1); PG8_BAR; PG8_SCHED;
	v_mfma_f32_16x16x32_bf16 v[124:127], v[128:131], v[176:179], v[124:127]
	v_mfma_f32_16x16x32_bf16 v[120:123], v[136:139], v[176:179], v[120:123]
	v_mfma_f32_16x16x32_bf16 v[108:111], v[128:131], v[190:193], v[108:111]
	v_mfma_f32_16x16x32_bf16 v[104:107], v[136:139], v[190:193], v[104:107]
	v_mfma_f32_16x16x32_bf16 v[92:95], v[128:131], v[214:217], v[92:95]
	v_mfma_f32_16x16x32_bf16 v[88:91], v[136:139], v[214:217], v[88:91]
	v_mfma_f32_16x16x32_bf16 v[76:79], v[128:131], v[222:225], v[76:79]
	v_mfma_f32_16x16x32_bf16 v[72:75], v[136:139], v[222:225], v[72:75]
	v_mfma_f32_16x16x32_bf16 v[124:127], v[132:135], v[184:187], v[124:127]
	v_mfma_f32_16x16x32_bf16 v[120:123], v[140:143], v[184:187], v[120:123]
	v_mfma_f32_16x16x32_bf16 v[108:111], v[132:135], v[210:213], v[108:111]
	v_mfma_f32_16x16x32_bf16 v[104:107], v[140:143], v[210:213], v[104:107]
	v_mfma_f32_16x16x32_bf16 v[92:95], v[132:135], v[218:221], v[92:95]
	v_mfma_f32_16x16x32_bf16 v[88:91], v[140:143], v[218:221], v[88:91]
	v_mfma_f32_16x16x32_bf16 v[76:79], v[132:135], v[226:229], v[76:79]
	v_mfma_f32_16x16x32_bf16 v[72:75], v[140:143], v[226:229], v[72:75]


; #define PG8_STAGE(bufoff, gbase, voff) do { _Pragma("unroll") for (int _i = 0; _i < 2; ++_i) \
;         __builtin_amdgcn_global_load_lds((const unsigned*)((const char*)(gbase) + (voff)[_i]), (PG8_LAS unsigned*)(lds + (bufoff) + ldsw + _i * 8192), 16, 0, 0); } while (0)
; #define PG8_LDA(dst, b, h) do { _Pragma("unroll") for (int m = 0; m < 4; ++m) _Pragma("unroll") for (int k = 0; k < 2; ++k) dst[m][k] = *(const PG8_LAS bf16x8*)(lds + PG8_SA(b, h) + aoff + m * 2048 + k * 1024); } while (0)
; #define PG8_MMA(ai, bj, At, Bt) do { __builtin_amdgcn_s_setprio(1); _Pragma("unroll") for (int m = 0; m < 4; ++m) _Pragma("unroll") for (int n = 0; n < 2; ++n) _Pragma("unroll") for (int k = 0; k < 2; ++k) \
;         acc[ai][bj][m][n] = __builtin_amdgcn_mfma_f32_16x16x32_bf16(Bt[n][k], At[m][k], acc[ai][bj][m][n], 0, 0, 0); __builtin_amdgcn_s_setprio(0); } while (0)
; #define PG8_WAIT_V(n) asm volatile("s_waitcnt vmcnt(" #n ")" ::: "memory")
; #define PG8_WAIT_L(n) asm volatile("s_waitcnt lgkmcnt(" #n ")" ::: "memory")
; #define PG8_BAR __builtin_amdgcn_s_barrier()
; #define PG8_SCHED __builtin_amdgcn_sched_barrier(0)
; template <class Epi, class Sched, bool ALIGN_EPI = false, bool SP2 = false>
; __device__ __forceinline__ void gemm_phase(PG8_LAS unsigned char* lds, const Gemm g, const Sched& S, const Epi& E) {
;     ...
;             PG8_WAIT_V(8); PG8_WAIT_L(0); PG8_BAR; PG8_MMA(0, 0, At, B0); PG8_MMA(0, 1, At, B1); PG8_BAR; PG8_SCHED;
;             PG8_LDA(At, 1, 1); PG8_STAGE(PG8_SB(1, 0), b3, voffB); PG8_STAGE(PG8_SB(1, 1), b3 + hstep, voffB); PG8_STAGE(PG8_SA(1, 0), a3, voffA);
	v_mfma_f32_16x16x32_bf16 v[116:119], v[144:147], v[176:179], v[116:119]
	v_mfma_f32_16x16x32_bf16 v[112:115], v[152:155], v[176:179], v[112:115]
	v_mfma_f32_16x16x32_bf16 v[100:103], v[144:147], v[190:193], v[100:103]
	v_mfma_f32_16x16x32_bf16 v[96:99], v[152:155], v[190:193], v[96:99]
	v_mfma_f32_16x16x32_bf16 v[84:87], v[144:147], v[214:217], v[84:87]
	v_mfma_f32_16x16x32_bf16 v[80:83], v[152:155], v[214:217], v[80:83]
	v_mfma_f32_16x16x32_bf16 v[68:71], v[144:147], v[222:225], v[68:71]
	v_mfma_f32_16x16x32_bf16 v[64:67], v[152:155], v[222:225], v[64:67]
	v_mfma_f32_16x16x32_bf16 v[116:119], v[148:151], v[184:187], v[116:119]
	v_mfma_f32_16x16x32_bf16 v[112:115], v[156:159], v[184:187], v[112:115]
	v_mfma_f32_16x16x32_bf16 v[100:103], v[148:151], v[210:213], v[100:103]
	v_mfma_f32_16x16x32_bf16 v[96:99], v[156:159], v[210:213], v[96:99]
	v_mfma_f32_16x16x32_bf16 v[84:87], v[148:151], v[218:221], v[84:87]
	v_mfma_f32_16x16x32_bf16 v[80:83], v[156:159], v[218:221], v[80:83]
	v_mfma_f32_16x16x32_bf16 v[68:71], v[148:151], v[226:229], v[68:71]
	v_mfma_f32_16x16x32_bf16 v[64:67], v[156:159], v[226:229], v[64:67]
	s_setprio 0
	s_barrier
	s_add_i32 s58, s84, s62

; #define PG8_STAGE(bufoff, gbase, voff) do { _Pragma("unroll") for (int _i = 0; _i < 2; ++_i) \
;         __builtin_amdgcn_global_load_lds((const unsigned*)((const char*)(gbase) + (voff)[_i]), (PG8_LAS unsigned*)(lds + (bufoff) + ldsw + _i * 8192), 16, 0, 0); } while (0)
; #define PG8_LDA(dst, b, h) do { _Pragma("unroll") for (int m = 0; m < 4; ++m) _Pragma("unroll") for (int k = 0; k < 2; ++k) dst[m][k] = *(const PG8_LAS bf16x8*)(lds + PG8_SA(b, h) + aoff + m * 2048 + k * 1024); } while (0)
; template <class Epi, class Sched, bool ALIGN_EPI = false, bool SP2 = false>
; __device__ __forceinline__ void gemm_phase(PG8_LAS unsigned char* lds, const Gemm g, const Sched& S, const Epi& E) {
;     ...
;             PG8_LDA(At, 1, 1); PG8_STAGE(PG8_SB(1, 0), b3, voffB); PG8_STAGE(PG8_SB(1, 1), b3 + hstep, voffB); PG8_STAGE(PG8_SA(1, 0), a3, voffA);
	s_mov_b32 m0, s58
	ds_read_b128 v[176:179], v207 offset:49152
	ds_read_b128 v[184:187], v207 offset:50176
	ds_read_b128 v[190:193], v207 offset:51200
	ds_read_b128 v[210:213], v207 offset:52224
	ds_read_b128 v[214:217], v207 offset:53248
	ds_read_b128 v[218:221], v207 offset:54272
	ds_read_b128 v[222:225], v207 offset:55296
	ds_read_b128 v[226:229], v207 offset:56320
	global_load_lds_dwordx4 v250, s[96:97]
	s_add_i32 m0, s58, 0x2000
	s_add_u32 s12, s12, 0x80080

; #define PG8_STAGE(bufoff, gbase, voff) do { _Pragma("unroll") for (int _i = 0; _i < 2; ++_i) \
;         __builtin_amdgcn_global_load_lds((const unsigned*)((const char*)(gbase) + (voff)[_i]), (PG8_LAS unsigned*)(lds + (bufoff) + ldsw + _i * 8192), 16, 0, 0); } while (0)
; #define PG8_LDA(dst, b, h) do { _Pragma("unroll") for (int m = 0; m < 4; ++m) _Pragma("unroll") for (int k = 0; k < 2; ++k) dst[m][k] = *(const PG8_LAS bf16x8*)(lds + PG8_SA(b, h) + aoff + m * 2048 + k * 1024); } while (0)
; template <class Epi, class Sched, bool ALIGN_EPI = false, bool SP2 = false>
; __device__ __forceinline__ void gemm_phase(PG8_LAS unsigned char* lds, const Gemm g, const Sched& S, const Epi& E) {
;     ...
;             PG8_LDA(At, 1, 1); PG8_STAGE(PG8_SB(1, 0), b3, voffB); PG8_STAGE(PG8_SB(1, 1), b3 + hstep, voffB); PG8_STAGE(PG8_SA(1, 0), a3, voffA);
	s_addc_u32 s13, s13, 0
	s_add_i32 s58, s85, s62
	global_load_lds_dwordx4 v251, s[96:97]

; #define PG8_STAGE(bufoff, gbase, voff) do { _Pragma("unroll") for (int _i = 0; _i < 2; ++_i) \
;         __builtin_amdgcn_global_load_lds((const unsigned*)((const char*)(gbase) + (voff)[_i]), (PG8_LAS unsigned*)(lds + (bufoff) + ldsw + _i * 8192), 16, 0, 0); } while (0)
; #define PG8_LDA(dst, b, h) do { _Pragma("unroll") for (int m = 0; m < 4; ++m) _Pragma("unroll") for (int k = 0; k < 2; ++k) dst[m][k] = *(const PG8_LAS bf16x8*)(lds + PG8_SA(b, h) + aoff + m * 2048 + k * 1024); } while (0)
; template <class Epi, class Sched, bool ALIGN_EPI = false, bool SP2 = false>
; __device__ __forceinline__ void gemm_phase(PG8_LAS unsigned char* lds, const Gemm g, const Sched& S, const Epi& E) {
;     ...
;             PG8_LDA(At, 1, 1); PG8_STAGE(PG8_SB(1, 0), b3, voffB); PG8_STAGE(PG8_SB(1, 1), b3 + hstep, voffB); PG8_STAGE(PG8_SA(1, 0), a3, voffA);
	s_mov_b32 m0, s58
	s_nop 0
	global_load_lds_dwordx4 v162, s[12:13]

; #define PG8_STAGE(bufoff, gbase, voff) do { _Pragma("unroll") for (int _i = 0; _i < 2; ++_i) \
;         __builtin_amdgcn_global_load_lds((const unsigned*)((const char*)(gbase) + (voff)[_i]), (PG8_LAS unsigned*)(lds + (bufoff) + ldsw + _i * 8192), 16, 0, 0); } while (0)
; #define PG8_LDA(dst, b, h) do { _Pragma("unroll") for (int m = 0; m < 4; ++m) _Pragma("unroll") for (int k = 0; k < 2; ++k) dst[m][k] = *(const PG8_LAS bf16x8*)(lds + PG8_SA(b, h) + aoff + m * 2048 + k * 1024); } while (0)
; template <class Epi, class Sched, bool ALIGN_EPI = false, bool SP2 = false>
; __device__ __forceinline__ void gemm_phase(PG8_LAS unsigned char* lds, const Gemm g, const Sched& S, const Epi& E) {
;     ...
;             PG8_LDA(At, 1, 1); PG8_STAGE(PG8_SB(1, 0), b3, voffB); PG8_STAGE(PG8_SB(1, 1), b3 + hstep, voffB); PG8_STAGE(PG8_SA(1, 0), a3, voffA);
	s_add_i32 m0, s58, 0x2000
	s_nop 0
	global_load_lds_dwordx4 v166, s[12:13]

; #define PG8_STAGE(bufoff, gbase, voff) do { _Pragma("unroll") for (int _i = 0; _i < 2; ++_i) \
;         __builtin_amdgcn_global_load_lds((const unsigned*)((const char*)(gbase) + (voff)[_i]), (PG8_LAS unsigned*)(lds + (bufoff) + ldsw + _i * 8192), 16, 0, 0); } while (0)
; #define PG8_LDA(dst, b, h) do { _Pragma("unroll") for (int m = 0; m < 4; ++m) _Pragma("unroll") for (int k = 0; k < 2; ++k) dst[m][k] = *(const PG8_LAS bf16x8*)(lds + PG8_SA(b, h) + aoff + m * 2048 + k * 1024); } while (0)
; template <class Epi, class Sched, bool ALIGN_EPI = false, bool SP2 = false>
; __device__ __forceinline__ void gemm_phase(PG8_LAS unsigned char* lds, const Gemm g, const Sched& S, const Epi& E) {
;     ...
;             PG8_LDA(At, 1, 1); PG8_STAGE(PG8_SB(1, 0), b3, voffB); PG8_STAGE(PG8_SB(1, 1), b3 + hstep, voffB); PG8_STAGE(PG8_SA(1, 0), a3, voffA);
	s_mov_b32 m0, s69
	s_nop 0
	global_load_lds_dwordx4 v252, s[98:99]

; #define PG8_STAGE(bufoff, gbase, voff) do { _Pragma("unroll") for (int _i = 0; _i < 2; ++_i) \
;         __builtin_amdgcn_global_load_lds((const unsigned*)((const char*)(gbase) + (voff)[_i]), (PG8_LAS unsigned*)(lds + (bufoff) + ldsw + _i * 8192), 16, 0, 0); } while (0)
; #define PG8_LDA(dst, b, h) do { _Pragma("unroll") for (int m = 0; m < 4; ++m) _Pragma("unroll") for (int k = 0; k < 2; ++k) dst[m][k] = *(const PG8_LAS bf16x8*)(lds + PG8_SA(b, h) + aoff + m * 2048 + k * 1024); } while (0)
; #define PG8_MMA(ai, bj, At, Bt) do { __builtin_amdgcn_s_setprio(1); _Pragma("unroll") for (int m = 0; m < 4; ++m) _Pragma("unroll") for (int n = 0; n < 2; ++n) _Pragma("unroll") for (int k = 0; k < 2; ++k) \
;         acc[ai][bj][m][n] = __builtin_amdgcn_mfma_f32_16x16x32_bf16(Bt[n][k], At[m][k], acc[ai][bj][m][n], 0, 0, 0); __builtin_amdgcn_s_setprio(0); } while (0)
; #define PG8_WAIT_V(n) asm volatile("s_waitcnt vmcnt(" #n ")" ::: "memory")
; #define PG8_WAIT_L(n) asm volatile("s_waitcnt lgkmcnt(" #n ")" ::: "memory")
; #define PG8_BAR __builtin_amdgcn_s_barrier()
; #define PG8_SCHED __builtin_amdgcn_sched_barrier(0)
; template <class Epi, class Sched, bool ALIGN_EPI = false, bool SP2 = false>
; __device__ __forceinline__ void gemm_phase(PG8_LAS unsigned char* lds, const Gemm g, const Sched& S, const Epi& E) {
;     ...
;             PG8_LDA(At, 1, 1); PG8_STAGE(PG8_SB(1, 0), b3, voffB); PG8_STAGE(PG8_SB(1, 1), b3 + hstep, voffB); PG8_STAGE(PG8_SA(1, 0), a3, voffA);
;             PG8_WAIT_V(8); PG8_WAIT_L(0); PG8_BAR; PG8_MMA(1, 0, At, B0); PG8_MMA(1, 1, At, B1); PG8_BAR; PG8_SCHED;
	s_mov_b32 m0, s70
	s_nop 0
	global_load_lds_dwordx4 v253, s[98:99]
	s_waitcnt vmcnt(8)
	s_waitcnt lgkmcnt(0)
	s_setprio 1
	s_barrier

; #define PG8_MMA(ai, bj, At, Bt) do { __builtin_amdgcn_s_setprio(1); _Pragma("unroll") for (int m = 0; m < 4; ++m) _Pragma("unroll") for (int n = 0; n < 2; ++n) _Pragma("unroll") for (int k = 0; k < 2; ++k) \
;         acc[ai][bj][m][n] = __builtin_amdgcn_mfma_f32_16x16x32_bf16(Bt[n][k], At[m][k], acc[ai][bj][m][n], 0, 0, 0); __builtin_amdgcn_s_setprio(0); } while (0)
; #define PG8_WAIT_V(n) asm volatile("s_waitcnt vmcnt(" #n ")" ::: "memory")
; #define PG8_WAIT_L(n) asm volatile("s_waitcnt lgkmcnt(" #n ")" ::: "memory")
; #define PG8_BAR __builtin_amdgcn_s_barrier()
; #define PG8_SCHED __builtin_amdgcn_sched_barrier(0)
; template <class Epi, class Sched, bool ALIGN_EPI = false, bool SP2 = false>
; __device__ __forceinline__ void gemm_phase(PG8_LAS unsigned char* lds, const Gemm g, const Sched& S, const Epi& E) {
;     ...
;             PG8_WAIT_V(8); PG8_WAIT_L(0); PG8_BAR; PG8_MMA(1, 0, At, B0); PG8_MMA(1, 1, At, B1); PG8_BAR; PG8_SCHED;
	v_mfma_f32_16x16x32_bf16 v[60:63], v[128:131], v[176:179], v[60:63]
	v_mfma_f32_16x16x32_bf16 v[56:59], v[136:139], v[176:179], v[56:59]
	v_mfma_f32_16x16x32_bf16 v[44:47], v[128:131], v[190:193], v[44:47]
	v_mfma_f32_16x16x32_bf16 v[40:43], v[136:139], v[190:193], v[40:43]
	v_mfma_f32_16x16x32_bf16 v[28:31], v[128:131], v[214:217], v[28:31]
	v_mfma_f32_16x16x32_bf16 v[24:27], v[136:139], v[214:217], v[24:27]
	v_mfma_f32_16x16x32_bf16 v[12:15], v[128:131], v[222:225], v[12:15]
	v_mfma_f32_16x16x32_bf16 v[8:11], v[136:139], v[222:225], v[8:11]
	v_mfma_f32_16x16x32_bf16 v[60:63], v[132:135], v[184:187], v[60:63]
	v_mfma_f32_16x16x32_bf16 v[56:59], v[140:143], v[184:187], v[56:59]
	v_mfma_f32_16x16x32_bf16 v[44:47], v[132:135], v[210:213], v[44:47]
	v_mfma_f32_16x16x32_bf16 v[40:43], v[140:143], v[210:213], v[40:43]
	v_mfma_f32_16x16x32_bf16 v[28:31], v[132:135], v[218:221], v[28:31]
	v_mfma_f32_16x16x32_bf16 v[24:27], v[140:143], v[218:221], v[24:27]
	v_mfma_f32_16x16x32_bf16 v[12:15], v[132:135], v[226:229], v[12:15]
	v_mfma_f32_16x16x32_bf16 v[8:11], v[140:143], v[226:229], v[8:11]


; #define PG8_MMA(ai, bj, At, Bt) do { __builtin_amdgcn_s_setprio(1); _Pragma("unroll") for (int m = 0; m < 4; ++m) _Pragma("unroll") for (int n = 0; n < 2; ++n) _Pragma("unroll") for (int k = 0; k < 2; ++k) \
;         acc[ai][bj][m][n] = __builtin_amdgcn_mfma_f32_16x16x32_bf16(Bt[n][k], At[m][k], acc[ai][bj][m][n], 0, 0, 0); __builtin_amdgcn_s_setprio(0); } while (0)
; #define PG8_WAIT_V(n) asm volatile("s_waitcnt vmcnt(" #n ")" ::: "memory")
; #define PG8_WAIT_L(n) asm volatile("s_waitcnt lgkmcnt(" #n ")" ::: "memory")
; #define PG8_BAR __builtin_amdgcn_s_barrier()
; #define PG8_SCHED __builtin_amdgcn_sched_barrier(0)
; template <class Epi, class Sched, bool ALIGN_EPI = false, bool SP2 = false>
; __device__ __forceinline__ void gemm_phase(PG8_LAS unsigned char* lds, const Gemm g, const Sched& S, const Epi& E) {
;     ...
;         for (int t = 0; t < nt; t += 2) {
;     ...
;             PG8_WAIT_V(8); PG8_WAIT_L(0); PG8_BAR; PG8_MMA(1, 0, At, B0); PG8_MMA(1, 1, At, B1); PG8_BAR; PG8_SCHED;
;     ...
;         if constexpr (ALIGN_EPI) { if (wr == 0) PG8_BAR; }
	v_mfma_f32_16x16x32_bf16 v[52:55], v[144:147], v[176:179], v[52:55]
	v_mfma_f32_16x16x32_bf16 v[48:51], v[152:155], v[176:179], v[48:51]
	v_mfma_f32_16x16x32_bf16 v[36:39], v[144:147], v[190:193], v[36:39]
	v_mfma_f32_16x16x32_bf16 v[32:35], v[152:155], v[190:193], v[32:35]
	v_mfma_f32_16x16x32_bf16 v[20:23], v[144:147], v[214:217], v[20:23]
	v_mfma_f32_16x16x32_bf16 v[16:19], v[152:155], v[214:217], v[16:19]
	v_mfma_f32_16x16x32_bf16 v[4:7], v[144:147], v[222:225], v[4:7]
	v_mfma_f32_16x16x32_bf16 v[0:3], v[152:155], v[222:225], v[0:3]
	v_mfma_f32_16x16x32_bf16 v[52:55], v[148:151], v[184:187], v[52:55]
	v_mfma_f32_16x16x32_bf16 v[48:51], v[156:159], v[184:187], v[48:51]
	v_mfma_f32_16x16x32_bf16 v[36:39], v[148:151], v[210:213], v[36:39]
	v_mfma_f32_16x16x32_bf16 v[32:35], v[156:159], v[210:213], v[32:35]
	v_mfma_f32_16x16x32_bf16 v[20:23], v[148:151], v[218:221], v[20:23]
	v_mfma_f32_16x16x32_bf16 v[16:19], v[156:159], v[218:221], v[16:19]
	v_mfma_f32_16x16x32_bf16 v[4:7], v[148:151], v[226:229], v[4:7]
	v_mfma_f32_16x16x32_bf16 v[0:3], v[156:159], v[226:229], v[0:3]
	s_setprio 0
	s_barrier
	s_add_i32 s83, s83, 2
	s_add_u32 s10, s10, 0x100
	s_addc_u32 s11, s11, 0
	s_add_u32 s81, s81, 0x100
	s_addc_u32 s82, s82, 0
	s_cmp_gt_u32 s83, 29
	s_cbranch_scc0 .LBB0_1034
	s_and_b64 vcc, exec, s[40:41]
	s_cbranch_vccz .LBB0_1037
	s_barrier

; #define PG8_STAGE(bufoff, gbase, voff) do { _Pragma("unroll") for (int _i = 0; _i < 2; ++_i) \
;         __builtin_amdgcn_global_load_lds((const unsigned*)((const char*)(gbase) + (voff)[_i]), (PG8_LAS unsigned*)(lds + (bufoff) + ldsw + _i * 8192), 16, 0, 0); } while (0)
; #define PG8_LDA(dst, b, h) do { _Pragma("unroll") for (int m = 0; m < 4; ++m) _Pragma("unroll") for (int k = 0; k < 2; ++k) dst[m][k] = *(const PG8_LAS bf16x8*)(lds + PG8_SA(b, h) + aoff + m * 2048 + k * 1024); } while (0)
; #define PG8_LDB(dst, b, h) do { _Pragma("unroll") for (int n = 0; n < 2; ++n) _Pragma("unroll") for (int k = 0; k < 2; ++k) dst[n][k] = *(const PG8_LAS bf16x8*)(lds + PG8_SB(b, h) + boff + n * 2048 + k * 1024); } while (0)
; #define PG8_SCHED __builtin_amdgcn_sched_barrier(0)
; template <class Epi, class Sched, bool ALIGN_EPI = false, bool SP2 = false>
; __device__ __forceinline__ void gemm_phase(PG8_LAS unsigned char* lds, const Gemm g, const Sched& S, const Epi& E) {
;     ...
;             const char* a1 = cA + (size_t)(t + 1) * kstep;
;             const char* a2 = last ? nA : cA + (size_t)(t + 2) * kstep; const char* b2 = last ? nB : cB + (size_t)(t + 2) * kstep;
;             const char* a3 = a2 + kstep; const char* b3 = b2 + kstep;
;             if (last && has_next) S.a_ready(nxt);
;             if constexpr (SP2) {
;             PG8_LDB(B0, 0, 0); PG8_LDB(B1, 0, 1); PG8_SCHED; PG8_LDA(At, 0, 0); PG8_STAGE(PG8_SA(1, 1), a1 + hstep, voffA);
.LBB0_1114:
	ds_read_b128 v[96:99], v197
	ds_read_b128 v[100:103], v197 offset:1024
	ds_read_b128 v[104:107], v197 offset:2048
	ds_read_b128 v[112:115], v197 offset:3072
	ds_read_b128 v[144:147], v198
	ds_read_b128 v[148:151], v198 offset:1024
	ds_read_b128 v[152:155], v198 offset:2048
	ds_read_b128 v[172:175], v198 offset:3072
	s_add_u32 s50, s48, 0xffe00080
	s_addc_u32 s51, s49, -1
	s_cmpk_eq_i32 s73, 0x7c
	s_cselect_b32 s53, s43, s51
	s_cselect_b32 s52, s69, s50
	s_cselect_b32 s51, s41, s72
	s_cselect_b32 s50, s70, s71

; #define PG8_STAGE(bufoff, gbase, voff) do { _Pragma("unroll") for (int _i = 0; _i < 2; ++_i) \
;         __builtin_amdgcn_global_load_lds((const unsigned*)((const char*)(gbase) + (voff)[_i]), (PG8_LAS unsigned*)(lds + (bufoff) + ldsw + _i * 8192), 16, 0, 0); } while (0)
; #define PG8_LDA(dst, b, h) do { _Pragma("unroll") for (int m = 0; m < 4; ++m) _Pragma("unroll") for (int k = 0; k < 2; ++k) dst[m][k] = *(const PG8_LAS bf16x8*)(lds + PG8_SA(b, h) + aoff + m * 2048 + k * 1024); } while (0)
; #define PG8_LDB(dst, b, h) do { _Pragma("unroll") for (int n = 0; n < 2; ++n) _Pragma("unroll") for (int k = 0; k < 2; ++k) dst[n][k] = *(const PG8_LAS bf16x8*)(lds + PG8_SB(b, h) + boff + n * 2048 + k * 1024); } while (0)
; #define PG8_SCHED __builtin_amdgcn_sched_barrier(0)
; template <class Epi, class Sched, bool ALIGN_EPI = false, bool SP2 = false>
; __device__ __forceinline__ void gemm_phase(PG8_LAS unsigned char* lds, const Gemm g, const Sched& S, const Epi& E) {
;     ...
;             PG8_LDB(B0, 0, 0); PG8_LDB(B1, 0, 1); PG8_SCHED; PG8_LDA(At, 0, 0); PG8_STAGE(PG8_SA(1, 1), a1 + hstep, voffA);
	s_add_i32 m0, s56, 0xc000
	ds_read_b128 v[176:179], v199
	ds_read_b128 v[180:183], v199 offset:1024
	ds_read_b128 v[184:187], v199 offset:2048
	ds_read_b128 v[188:191], v199 offset:3072
	ds_read_b128 v[202:205], v199 offset:4096
	ds_read_b128 v[206:209], v199 offset:5120
	ds_read_b128 v[210:213], v199 offset:6144
	ds_read_b128 v[214:217], v199 offset:7168
	global_load_lds_dwordx4 v164, s[48:49]

; #define PG8_STAGE(bufoff, gbase, voff) do { _Pragma("unroll") for (int _i = 0; _i < 2; ++_i) \
;         __builtin_amdgcn_global_load_lds((const unsigned*)((const char*)(gbase) + (voff)[_i]), (PG8_LAS unsigned*)(lds + (bufoff) + ldsw + _i * 8192), 16, 0, 0); } while (0)
; #define PG8_LDA(dst, b, h) do { _Pragma("unroll") for (int m = 0; m < 4; ++m) _Pragma("unroll") for (int k = 0; k < 2; ++k) dst[m][k] = *(const PG8_LAS bf16x8*)(lds + PG8_SA(b, h) + aoff + m * 2048 + k * 1024); } while (0)
; #define PG8_LDB(dst, b, h) do { _Pragma("unroll") for (int n = 0; n < 2; ++n) _Pragma("unroll") for (int k = 0; k < 2; ++k) dst[n][k] = *(const PG8_LAS bf16x8*)(lds + PG8_SB(b, h) + boff + n * 2048 + k * 1024); } while (0)
; #define PG8_MMA(ai, bj, At, Bt) do { __builtin_amdgcn_s_setprio(1); _Pragma("unroll") for (int m = 0; m < 4; ++m) _Pragma("unroll") for (int n = 0; n < 2; ++n) _Pragma("unroll") for (int k = 0; k < 2; ++k) \
;         acc[ai][bj][m][n] = __builtin_amdgcn_mfma_f32_16x16x32_bf16(Bt[n][k], At[m][k], acc[ai][bj][m][n], 0, 0, 0); __builtin_amdgcn_s_setprio(0); } while (0)
; #define PG8_WAIT_V(n) asm volatile("s_waitcnt vmcnt(" #n ")" ::: "memory")
; #define PG8_WAIT_L(n) asm volatile("s_waitcnt lgkmcnt(" #n ")" ::: "memory")
; #define PG8_BAR __builtin_amdgcn_s_barrier()
; #define PG8_SCHED __builtin_amdgcn_sched_barrier(0)
; template <class Epi, class Sched, bool ALIGN_EPI = false, bool SP2 = false>
; __device__ __forceinline__ void gemm_phase(PG8_LAS unsigned char* lds, const Gemm g, const Sched& S, const Epi& E) {
;     ...
;             PG8_LDB(B0, 0, 0); PG8_LDB(B1, 0, 1); PG8_SCHED; PG8_LDA(At, 0, 0); PG8_STAGE(PG8_SA(1, 1), a1 + hstep, voffA);
;             PG8_WAIT_V(8); PG8_WAIT_L(0); PG8_BAR; PG8_MMA(0, 0, At, B0); PG8_MMA(0, 1, At, B1); PG8_BAR; PG8_SCHED;
	s_add_i32 m0, s56, 0xe000
	s_nop 0
	global_load_lds_dwordx4 v166, s[48:49]
	s_waitcnt vmcnt(8)
	s_waitcnt lgkmcnt(0)
	s_setprio 1
	s_barrier

; #define PG8_MMA(ai, bj, At, Bt) do { __builtin_amdgcn_s_setprio(1); _Pragma("unroll") for (int m = 0; m < 4; ++m) _Pragma("unroll") for (int n = 0; n < 2; ++n) _Pragma("unroll") for (int k = 0; k < 2; ++k) \
;         acc[ai][bj][m][n] = __builtin_amdgcn_mfma_f32_16x16x32_bf16(Bt[n][k], At[m][k], acc[ai][bj][m][n], 0, 0, 0); __builtin_amdgcn_s_setprio(0); } while (0)
; #define PG8_WAIT_V(n) asm volatile("s_waitcnt vmcnt(" #n ")" ::: "memory")
; #define PG8_WAIT_L(n) asm volatile("s_waitcnt lgkmcnt(" #n ")" ::: "memory")
; #define PG8_BAR __builtin_amdgcn_s_barrier()
; #define PG8_SCHED __builtin_amdgcn_sched_barrier(0)
; template <class Epi, class Sched, bool ALIGN_EPI = false, bool SP2 = false>
; __device__ __forceinline__ void gemm_phase(PG8_LAS unsigned char* lds, const Gemm g, const Sched& S, const Epi& E) {
;     ...
;             PG8_WAIT_V(8); PG8_WAIT_L(0); PG8_BAR; PG8_MMA(0, 0, At, B0); PG8_MMA(0, 1, At, B1); PG8_BAR; PG8_SCHED;
	v_mfma_f32_16x16x32_bf16 v[140:143], v[96:99], v[176:179], v[140:143]
	v_mfma_f32_16x16x32_bf16 v[136:139], v[104:107], v[176:179], v[136:139]
	v_mfma_f32_16x16x32_bf16 v[124:127], v[96:99], v[184:187], v[124:127]
	v_mfma_f32_16x16x32_bf16 v[120:123], v[104:107], v[184:187], v[120:123]
	v_mfma_f32_16x16x32_bf16 v[92:95], v[96:99], v[202:205], v[92:95]
	v_mfma_f32_16x16x32_bf16 v[88:91], v[104:107], v[202:205], v[88:91]
	v_mfma_f32_16x16x32_bf16 v[76:79], v[96:99], v[210:213], v[76:79]
	v_mfma_f32_16x16x32_bf16 v[72:75], v[104:107], v[210:213], v[72:75]
	v_mfma_f32_16x16x32_bf16 v[140:143], v[100:103], v[180:183], v[140:143]
	v_mfma_f32_16x16x32_bf16 v[136:139], v[112:115], v[180:183], v[136:139]
	v_mfma_f32_16x16x32_bf16 v[124:127], v[100:103], v[188:191], v[124:127]
	v_mfma_f32_16x16x32_bf16 v[120:123], v[112:115], v[188:191], v[120:123]
	v_mfma_f32_16x16x32_bf16 v[92:95], v[100:103], v[206:209], v[92:95]
	v_mfma_f32_16x16x32_bf16 v[88:91], v[112:115], v[206:209], v[88:91]
	v_mfma_f32_16x16x32_bf16 v[76:79], v[100:103], v[214:217], v[76:79]
	v_mfma_f32_16x16x32_bf16 v[72:75], v[112:115], v[214:217], v[72:75]


; #define PG8_STAGE(bufoff, gbase, voff) do { _Pragma("unroll") for (int _i = 0; _i < 2; ++_i) \
;         __builtin_amdgcn_global_load_lds((const unsigned*)((const char*)(gbase) + (voff)[_i]), (PG8_LAS unsigned*)(lds + (bufoff) + ldsw + _i * 8192), 16, 0, 0); } while (0)
; #define PG8_LDA(dst, b, h) do { _Pragma("unroll") for (int m = 0; m < 4; ++m) _Pragma("unroll") for (int k = 0; k < 2; ++k) dst[m][k] = *(const PG8_LAS bf16x8*)(lds + PG8_SA(b, h) + aoff + m * 2048 + k * 1024); } while (0)
; #define PG8_MMA(ai, bj, At, Bt) do { __builtin_amdgcn_s_setprio(1); _Pragma("unroll") for (int m = 0; m < 4; ++m) _Pragma("unroll") for (int n = 0; n < 2; ++n) _Pragma("unroll") for (int k = 0; k < 2; ++k) \
;         acc[ai][bj][m][n] = __builtin_amdgcn_mfma_f32_16x16x32_bf16(Bt[n][k], At[m][k], acc[ai][bj][m][n], 0, 0, 0); __builtin_amdgcn_s_setprio(0); } while (0)
; #define PG8_WAIT_V(n) asm volatile("s_waitcnt vmcnt(" #n ")" ::: "memory")
; #define PG8_WAIT_L(n) asm volatile("s_waitcnt lgkmcnt(" #n ")" ::: "memory")
; #define PG8_BAR __builtin_amdgcn_s_barrier()
; #define PG8_SCHED __builtin_amdgcn_sched_barrier(0)
; template <class Epi, class Sched, bool ALIGN_EPI = false, bool SP2 = false>
; __device__ __forceinline__ void gemm_phase(PG8_LAS unsigned char* lds, const Gemm g, const Sched& S, const Epi& E) {
;     ...
;             PG8_WAIT_V(8); PG8_WAIT_L(0); PG8_BAR; PG8_MMA(0, 0, At, B0); PG8_MMA(0, 1, At, B1); PG8_BAR; PG8_SCHED;
;             PG8_LDA(At, 0, 1); PG8_STAGE(PG8_SB(0, 0), b2, voffB); PG8_STAGE(PG8_SB(0, 1), b2 + hstep, voffB); PG8_STAGE(PG8_SA(0, 0), a2, voffA);
	v_mfma_f32_16x16x32_bf16 v[132:135], v[144:147], v[176:179], v[132:135]
	v_mfma_f32_16x16x32_bf16 v[128:131], v[152:155], v[176:179], v[128:131]
	v_mfma_f32_16x16x32_bf16 v[116:119], v[144:147], v[184:187], v[116:119]
	v_mfma_f32_16x16x32_bf16 v[108:111], v[152:155], v[184:187], v[108:111]
	v_mfma_f32_16x16x32_bf16 v[84:87], v[144:147], v[202:205], v[84:87]
	v_mfma_f32_16x16x32_bf16 v[80:83], v[152:155], v[202:205], v[80:83]
	v_mfma_f32_16x16x32_bf16 v[68:71], v[144:147], v[210:213], v[68:71]
	v_mfma_f32_16x16x32_bf16 v[64:67], v[152:155], v[210:213], v[64:67]
	v_mfma_f32_16x16x32_bf16 v[132:135], v[148:151], v[180:183], v[132:135]
	v_mfma_f32_16x16x32_bf16 v[128:131], v[172:175], v[180:183], v[128:131]
	v_mfma_f32_16x16x32_bf16 v[116:119], v[148:151], v[188:191], v[116:119]
	v_mfma_f32_16x16x32_bf16 v[108:111], v[172:175], v[188:191], v[108:111]
	v_mfma_f32_16x16x32_bf16 v[84:87], v[148:151], v[206:209], v[84:87]
	v_mfma_f32_16x16x32_bf16 v[80:83], v[172:175], v[206:209], v[80:83]
	v_mfma_f32_16x16x32_bf16 v[68:71], v[148:151], v[214:217], v[68:71]
	v_mfma_f32_16x16x32_bf16 v[64:67], v[172:175], v[214:217], v[64:67]
	s_setprio 0
	s_barrier
	s_add_i32 s74, s65, s55
	s_mov_b64 s[96:97], s[50:51]

; #define PG8_STAGE(bufoff, gbase, voff) do { _Pragma("unroll") for (int _i = 0; _i < 2; ++_i) \
;         __builtin_amdgcn_global_load_lds((const unsigned*)((const char*)(gbase) + (voff)[_i]), (PG8_LAS unsigned*)(lds + (bufoff) + ldsw + _i * 8192), 16, 0, 0); } while (0)
; #define PG8_LDA(dst, b, h) do { _Pragma("unroll") for (int m = 0; m < 4; ++m) _Pragma("unroll") for (int k = 0; k < 2; ++k) dst[m][k] = *(const PG8_LAS bf16x8*)(lds + PG8_SA(b, h) + aoff + m * 2048 + k * 1024); } while (0)
; template <class Epi, class Sched, bool ALIGN_EPI = false, bool SP2 = false>
; __device__ __forceinline__ void gemm_phase(PG8_LAS unsigned char* lds, const Gemm g, const Sched& S, const Epi& E) {
;     ...
;             PG8_LDA(At, 0, 1); PG8_STAGE(PG8_SB(0, 0), b2, voffB); PG8_STAGE(PG8_SB(0, 1), b2 + hstep, voffB); PG8_STAGE(PG8_SA(0, 0), a2, voffA);
	s_mov_b32 m0, s74
	ds_read_b128 v[176:179], v199 offset:16384
	ds_read_b128 v[180:183], v199 offset:17408
	ds_read_b128 v[184:187], v199 offset:18432
	ds_read_b128 v[188:191], v199 offset:19456
	ds_read_b128 v[202:205], v199 offset:20480
	ds_read_b128 v[206:209], v199 offset:21504
	ds_read_b128 v[210:213], v199 offset:22528
	ds_read_b128 v[214:217], v199 offset:23552
	global_load_lds_dwordx4 v158, s[50:51]
	s_add_i32 m0, s74, 0x2000
	s_add_u32 s74, s50, 0x200000

; #define PG8_STAGE(bufoff, gbase, voff) do { _Pragma("unroll") for (int _i = 0; _i < 2; ++_i) \
;         __builtin_amdgcn_global_load_lds((const unsigned*)((const char*)(gbase) + (voff)[_i]), (PG8_LAS unsigned*)(lds + (bufoff) + ldsw + _i * 8192), 16, 0, 0); } while (0)
; #define PG8_LDA(dst, b, h) do { _Pragma("unroll") for (int m = 0; m < 4; ++m) _Pragma("unroll") for (int k = 0; k < 2; ++k) dst[m][k] = *(const PG8_LAS bf16x8*)(lds + PG8_SA(b, h) + aoff + m * 2048 + k * 1024); } while (0)
; template <class Epi, class Sched, bool ALIGN_EPI = false, bool SP2 = false>
; __device__ __forceinline__ void gemm_phase(PG8_LAS unsigned char* lds, const Gemm g, const Sched& S, const Epi& E) {
;     ...
;             PG8_LDA(At, 0, 1); PG8_STAGE(PG8_SB(0, 0), b2, voffB); PG8_STAGE(PG8_SB(0, 1), b2 + hstep, voffB); PG8_STAGE(PG8_SA(0, 0), a2, voffA);
	s_addc_u32 s75, s51, 0
	s_add_i32 s76, s67, s55
	global_load_lds_dwordx4 v162, s[50:51]

; #define PG8_STAGE(bufoff, gbase, voff) do { _Pragma("unroll") for (int _i = 0; _i < 2; ++_i) \
;         __builtin_amdgcn_global_load_lds((const unsigned*)((const char*)(gbase) + (voff)[_i]), (PG8_LAS unsigned*)(lds + (bufoff) + ldsw + _i * 8192), 16, 0, 0); } while (0)
; #define PG8_LDA(dst, b, h) do { _Pragma("unroll") for (int m = 0; m < 4; ++m) _Pragma("unroll") for (int k = 0; k < 2; ++k) dst[m][k] = *(const PG8_LAS bf16x8*)(lds + PG8_SA(b, h) + aoff + m * 2048 + k * 1024); } while (0)
; template <class Epi, class Sched, bool ALIGN_EPI = false, bool SP2 = false>
; __device__ __forceinline__ void gemm_phase(PG8_LAS unsigned char* lds, const Gemm g, const Sched& S, const Epi& E) {
;     ...
;             PG8_LDA(At, 0, 1); PG8_STAGE(PG8_SB(0, 0), b2, voffB); PG8_STAGE(PG8_SB(0, 1), b2 + hstep, voffB); PG8_STAGE(PG8_SA(0, 0), a2, voffA);
	s_mov_b32 m0, s76
	s_nop 0
	global_load_lds_dwordx4 v158, s[74:75]

; #define PG8_STAGE(bufoff, gbase, voff) do { _Pragma("unroll") for (int _i = 0; _i < 2; ++_i) \
;         __builtin_amdgcn_global_load_lds((const unsigned*)((const char*)(gbase) + (voff)[_i]), (PG8_LAS unsigned*)(lds + (bufoff) + ldsw + _i * 8192), 16, 0, 0); } while (0)
; #define PG8_LDA(dst, b, h) do { _Pragma("unroll") for (int m = 0; m < 4; ++m) _Pragma("unroll") for (int k = 0; k < 2; ++k) dst[m][k] = *(const PG8_LAS bf16x8*)(lds + PG8_SA(b, h) + aoff + m * 2048 + k * 1024); } while (0)
; template <class Epi, class Sched, bool ALIGN_EPI = false, bool SP2 = false>
; __device__ __forceinline__ void gemm_phase(PG8_LAS unsigned char* lds, const Gemm g, const Sched& S, const Epi& E) {
;     ...
;             PG8_LDA(At, 0, 1); PG8_STAGE(PG8_SB(0, 0), b2, voffB); PG8_STAGE(PG8_SB(0, 1), b2 + hstep, voffB); PG8_STAGE(PG8_SA(0, 0), a2, voffA);
	s_add_i32 m0, s76, 0x2000
	s_nop 0
	global_load_lds_dwordx4 v162, s[74:75]
	s_mov_b64 s[98:99], s[52:53]

; #define PG8_STAGE(bufoff, gbase, voff) do { _Pragma("unroll") for (int _i = 0; _i < 2; ++_i) \
;         __builtin_amdgcn_global_load_lds((const unsigned*)((const char*)(gbase) + (voff)[_i]), (PG8_LAS unsigned*)(lds + (bufoff) + ldsw + _i * 8192), 16, 0, 0); } while (0)
; #define PG8_LDA(dst, b, h) do { _Pragma("unroll") for (int m = 0; m < 4; ++m) _Pragma("unroll") for (int k = 0; k < 2; ++k) dst[m][k] = *(const PG8_LAS bf16x8*)(lds + PG8_SA(b, h) + aoff + m * 2048 + k * 1024); } while (0)
; #define PG8_MMA(ai, bj, At, Bt) do { __builtin_amdgcn_s_setprio(1); _Pragma("unroll") for (int m = 0; m < 4; ++m) _Pragma("unroll") for (int n = 0; n < 2; ++n) _Pragma("unroll") for (int k = 0; k < 2; ++k) \
;         acc[ai][bj][m][n] = __builtin_amdgcn_mfma_f32_16x16x32_bf16(Bt[n][k], At[m][k], acc[ai][bj][m][n], 0, 0, 0); __builtin_amdgcn_s_setprio(0); } while (0)
; #define PG8_WAIT_V(n) asm volatile("s_waitcnt vmcnt(" #n ")" ::: "memory")
; #define PG8_WAIT_L(n) asm volatile("s_waitcnt lgkmcnt(" #n ")" ::: "memory")
; #define PG8_BAR __builtin_amdgcn_s_barrier()
; #define PG8_SCHED __builtin_amdgcn_sched_barrier(0)
; template <class Epi, class Sched, bool ALIGN_EPI = false, bool SP2 = false>
; __device__ __forceinline__ void gemm_phase(PG8_LAS unsigned char* lds, const Gemm g, const Sched& S, const Epi& E) {
;     ...
;             PG8_LDA(At, 0, 1); PG8_STAGE(PG8_SB(0, 0), b2, voffB); PG8_STAGE(PG8_SB(0, 1), b2 + hstep, voffB); PG8_STAGE(PG8_SA(0, 0), a2, voffA);
;             PG8_WAIT_V(8); PG8_WAIT_L(0); PG8_BAR; PG8_MMA(1, 0, At, B0); PG8_MMA(1, 1, At, B1); PG8_BAR; PG8_SCHED;
	s_mov_b32 m0, s56
	s_nop 0
	global_load_lds_dwordx4 v156, s[52:53]
	s_mov_b32 m0, s57
	s_nop 0
	global_load_lds_dwordx4 v160, s[52:53]
	s_waitcnt vmcnt(8)
	s_waitcnt lgkmcnt(0)
	s_setprio 1
	s_barrier

; #define PG8_MMA(ai, bj, At, Bt) do { __builtin_amdgcn_s_setprio(1); _Pragma("unroll") for (int m = 0; m < 4; ++m) _Pragma("unroll") for (int n = 0; n < 2; ++n) _Pragma("unroll") for (int k = 0; k < 2; ++k) \
;         acc[ai][bj][m][n] = __builtin_amdgcn_mfma_f32_16x16x32_bf16(Bt[n][k], At[m][k], acc[ai][bj][m][n], 0, 0, 0); __builtin_amdgcn_s_setprio(0); } while (0)
; #define PG8_WAIT_V(n) asm volatile("s_waitcnt vmcnt(" #n ")" ::: "memory")
; #define PG8_WAIT_L(n) asm volatile("s_waitcnt lgkmcnt(" #n ")" ::: "memory")
; #define PG8_BAR __builtin_amdgcn_s_barrier()
; #define PG8_SCHED __builtin_amdgcn_sched_barrier(0)
; template <class Epi, class Sched, bool ALIGN_EPI = false, bool SP2 = false>
; __device__ __forceinline__ void gemm_phase(PG8_LAS unsigned char* lds, const Gemm g, const Sched& S, const Epi& E) {
;     ...
;             PG8_WAIT_V(8); PG8_WAIT_L(0); PG8_BAR; PG8_MMA(1, 0, At, B0); PG8_MMA(1, 1, At, B1); PG8_BAR; PG8_SCHED;
	v_mfma_f32_16x16x32_bf16 v[60:63], v[96:99], v[176:179], v[60:63]
	v_mfma_f32_16x16x32_bf16 v[56:59], v[104:107], v[176:179], v[56:59]
	v_mfma_f32_16x16x32_bf16 v[44:47], v[96:99], v[184:187], v[44:47]
	v_mfma_f32_16x16x32_bf16 v[40:43], v[104:107], v[184:187], v[40:43]
	v_mfma_f32_16x16x32_bf16 v[28:31], v[96:99], v[202:205], v[28:31]
	v_mfma_f32_16x16x32_bf16 v[24:27], v[104:107], v[202:205], v[24:27]
	v_mfma_f32_16x16x32_bf16 v[12:15], v[96:99], v[210:213], v[12:15]
	v_mfma_f32_16x16x32_bf16 v[8:11], v[104:107], v[210:213], v[8:11]
	v_mfma_f32_16x16x32_bf16 v[60:63], v[100:103], v[180:183], v[60:63]
	v_mfma_f32_16x16x32_bf16 v[56:59], v[112:115], v[180:183], v[56:59]
	v_mfma_f32_16x16x32_bf16 v[44:47], v[100:103], v[188:191], v[44:47]
	v_mfma_f32_16x16x32_bf16 v[40:43], v[112:115], v[188:191], v[40:43]
	v_mfma_f32_16x16x32_bf16 v[28:31], v[100:103], v[206:209], v[28:31]
	v_mfma_f32_16x16x32_bf16 v[24:27], v[112:115], v[206:209], v[24:27]
	v_mfma_f32_16x16x32_bf16 v[12:15], v[100:103], v[214:217], v[12:15]
	v_mfma_f32_16x16x32_bf16 v[8:11], v[112:115], v[214:217], v[8:11]


; #define PG8_STAGE(bufoff, gbase, voff) do { _Pragma("unroll") for (int _i = 0; _i < 2; ++_i) \
;         __builtin_amdgcn_global_load_lds((const unsigned*)((const char*)(gbase) + (voff)[_i]), (PG8_LAS unsigned*)(lds + (bufoff) + ldsw + _i * 8192), 16, 0, 0); } while (0)
; #define PG8_LDA(dst, b, h) do { _Pragma("unroll") for (int m = 0; m < 4; ++m) _Pragma("unroll") for (int k = 0; k < 2; ++k) dst[m][k] = *(const PG8_LAS bf16x8*)(lds + PG8_SA(b, h) + aoff + m * 2048 + k * 1024); } while (0)
; #define PG8_LDB(dst, b, h) do { _Pragma("unroll") for (int n = 0; n < 2; ++n) _Pragma("unroll") for (int k = 0; k < 2; ++k) dst[n][k] = *(const PG8_LAS bf16x8*)(lds + PG8_SB(b, h) + boff + n * 2048 + k * 1024); } while (0)
; #define PG8_MMA(ai, bj, At, Bt) do { __builtin_amdgcn_s_setprio(1); _Pragma("unroll") for (int m = 0; m < 4; ++m) _Pragma("unroll") for (int n = 0; n < 2; ++n) _Pragma("unroll") for (int k = 0; k < 2; ++k) \
;         acc[ai][bj][m][n] = __builtin_amdgcn_mfma_f32_16x16x32_bf16(Bt[n][k], At[m][k], acc[ai][bj][m][n], 0, 0, 0); __builtin_amdgcn_s_setprio(0); } while (0)
; #define PG8_WAIT_V(n) asm volatile("s_waitcnt vmcnt(" #n ")" ::: "memory")
; #define PG8_WAIT_L(n) asm volatile("s_waitcnt lgkmcnt(" #n ")" ::: "memory")
; #define PG8_BAR __builtin_amdgcn_s_barrier()
; #define PG8_SCHED __builtin_amdgcn_sched_barrier(0)
; template <class Epi, class Sched, bool ALIGN_EPI = false, bool SP2 = false>
; __device__ __forceinline__ void gemm_phase(PG8_LAS unsigned char* lds, const Gemm g, const Sched& S, const Epi& E) {
;     ...
;             PG8_WAIT_V(8); PG8_WAIT_L(0); PG8_BAR; PG8_MMA(1, 0, At, B0); PG8_MMA(1, 1, At, B1); PG8_BAR; PG8_SCHED;
;             PG8_LDB(B0, 1, 0); PG8_LDB(B1, 1, 1); PG8_SCHED; PG8_LDA(At, 1, 0); PG8_STAGE(PG8_SA(0, 1), a2 + hstep, voffA);
	v_mfma_f32_16x16x32_bf16 v[52:55], v[144:147], v[176:179], v[52:55]
	v_mfma_f32_16x16x32_bf16 v[48:51], v[152:155], v[176:179], v[48:51]
	v_mfma_f32_16x16x32_bf16 v[36:39], v[144:147], v[184:187], v[36:39]
	v_mfma_f32_16x16x32_bf16 v[32:35], v[152:155], v[184:187], v[32:35]
	v_mfma_f32_16x16x32_bf16 v[20:23], v[144:147], v[202:205], v[20:23]
	v_mfma_f32_16x16x32_bf16 v[16:19], v[152:155], v[202:205], v[16:19]
	v_mfma_f32_16x16x32_bf16 v[4:7], v[144:147], v[210:213], v[4:7]
	v_mfma_f32_16x16x32_bf16 v[0:3], v[152:155], v[210:213], v[0:3]
	v_mfma_f32_16x16x32_bf16 v[52:55], v[148:151], v[180:183], v[52:55]
	v_mfma_f32_16x16x32_bf16 v[48:51], v[172:175], v[180:183], v[48:51]
	v_mfma_f32_16x16x32_bf16 v[36:39], v[148:151], v[188:191], v[36:39]
	v_mfma_f32_16x16x32_bf16 v[32:35], v[172:175], v[188:191], v[32:35]
	v_mfma_f32_16x16x32_bf16 v[20:23], v[148:151], v[206:209], v[20:23]
	v_mfma_f32_16x16x32_bf16 v[16:19], v[172:175], v[206:209], v[16:19]
	v_mfma_f32_16x16x32_bf16 v[4:7], v[148:151], v[214:217], v[4:7]
	v_mfma_f32_16x16x32_bf16 v[0:3], v[172:175], v[214:217], v[0:3]
	s_setprio 0
	s_barrier
	s_add_i32 s74, 0, 0x18000
	s_add_i32 s75, 0, 0x1c000
	v_add_u32_e32 v112, s74, v195
	v_add_u32_e32 v172, s75, v195
	ds_read_b128 v[96:99], v112
	ds_read_b128 v[100:103], v112 offset:1024
	ds_read_b128 v[104:107], v112 offset:2048
	ds_read_b128 v[112:115], v112 offset:3072
	ds_read_b128 v[144:147], v172
	ds_read_b128 v[148:151], v172 offset:1024
	ds_read_b128 v[152:155], v172 offset:2048
	ds_read_b128 v[172:175], v172 offset:3072
	s_add_u32 s52, s52, 0x200000
	s_addc_u32 s53, s53, 0
	s_mov_b32 m0, s58

; #define PG8_STAGE(bufoff, gbase, voff) do { _Pragma("unroll") for (int _i = 0; _i < 2; ++_i) \
;         __builtin_amdgcn_global_load_lds((const unsigned*)((const char*)(gbase) + (voff)[_i]), (PG8_LAS unsigned*)(lds + (bufoff) + ldsw + _i * 8192), 16, 0, 0); } while (0)
; #define PG8_LDA(dst, b, h) do { _Pragma("unroll") for (int m = 0; m < 4; ++m) _Pragma("unroll") for (int k = 0; k < 2; ++k) dst[m][k] = *(const PG8_LAS bf16x8*)(lds + PG8_SA(b, h) + aoff + m * 2048 + k * 1024); } while (0)
; #define PG8_LDB(dst, b, h) do { _Pragma("unroll") for (int n = 0; n < 2; ++n) _Pragma("unroll") for (int k = 0; k < 2; ++k) dst[n][k] = *(const PG8_LAS bf16x8*)(lds + PG8_SB(b, h) + boff + n * 2048 + k * 1024); } while (0)
; #define PG8_SCHED __builtin_amdgcn_sched_barrier(0)
; template <class Epi, class Sched, bool ALIGN_EPI = false, bool SP2 = false>
; __device__ __forceinline__ void gemm_phase(PG8_LAS unsigned char* lds, const Gemm g, const Sched& S, const Epi& E) {
;     ...
;             PG8_LDB(B0, 1, 0); PG8_LDB(B1, 1, 1); PG8_SCHED; PG8_LDA(At, 1, 0); PG8_STAGE(PG8_SA(0, 1), a2 + hstep, voffA);
	ds_read_b128 v[176:179], v199 offset:32768
	ds_read_b128 v[180:183], v199 offset:33792
	ds_read_b128 v[184:187], v199 offset:34816
	ds_read_b128 v[188:191], v199 offset:35840
	ds_read_b128 v[202:205], v199 offset:36864
	ds_read_b128 v[206:209], v199 offset:37888
	ds_read_b128 v[210:213], v199 offset:38912
	ds_read_b128 v[214:217], v199 offset:39936
	global_load_lds_dwordx4 v156, s[52:53]

; #define PG8_STAGE(bufoff, gbase, voff) do { _Pragma("unroll") for (int _i = 0; _i < 2; ++_i) \
;         __builtin_amdgcn_global_load_lds((const unsigned*)((const char*)(gbase) + (voff)[_i]), (PG8_LAS unsigned*)(lds + (bufoff) + ldsw + _i * 8192), 16, 0, 0); } while (0)
; #define PG8_LDA(dst, b, h) do { _Pragma("unroll") for (int m = 0; m < 4; ++m) _Pragma("unroll") for (int k = 0; k < 2; ++k) dst[m][k] = *(const PG8_LAS bf16x8*)(lds + PG8_SA(b, h) + aoff + m * 2048 + k * 1024); } while (0)
; #define PG8_LDB(dst, b, h) do { _Pragma("unroll") for (int n = 0; n < 2; ++n) _Pragma("unroll") for (int k = 0; k < 2; ++k) dst[n][k] = *(const PG8_LAS bf16x8*)(lds + PG8_SB(b, h) + boff + n * 2048 + k * 1024); } while (0)
; #define PG8_MMA(ai, bj, At, Bt) do { __builtin_amdgcn_s_setprio(1); _Pragma("unroll") for (int m = 0; m < 4; ++m) _Pragma("unroll") for (int n = 0; n < 2; ++n) _Pragma("unroll") for (int k = 0; k < 2; ++k) \
;         acc[ai][bj][m][n] = __builtin_amdgcn_mfma_f32_16x16x32_bf16(Bt[n][k], At[m][k], acc[ai][bj][m][n], 0, 0, 0); __builtin_amdgcn_s_setprio(0); } while (0)
; #define PG8_WAIT_V(n) asm volatile("s_waitcnt vmcnt(" #n ")" ::: "memory")
; #define PG8_WAIT_L(n) asm volatile("s_waitcnt lgkmcnt(" #n ")" ::: "memory")
; #define PG8_BAR __builtin_amdgcn_s_barrier()
; #define PG8_SCHED __builtin_amdgcn_sched_barrier(0)
; template <class Epi, class Sched, bool ALIGN_EPI = false, bool SP2 = false>
; __device__ __forceinline__ void gemm_phase(PG8_LAS unsigned char* lds, const Gemm g, const Sched& S, const Epi& E) {
;     ...
;             PG8_LDB(B0, 1, 0); PG8_LDB(B1, 1, 1); PG8_SCHED; PG8_LDA(At, 1, 0); PG8_STAGE(PG8_SA(0, 1), a2 + hstep, voffA);
;             PG8_WAIT_V(8); PG8_WAIT_L(0); PG8_BAR; PG8_MMA(0, 0, At, B0); PG8_MMA(0, 1, At, B1); PG8_BAR; PG8_SCHED;
	s_mov_b32 m0, s59
	s_nop 0
	global_load_lds_dwordx4 v160, s[52:53]
	s_waitcnt vmcnt(8)
	s_waitcnt lgkmcnt(0)
	s_setprio 1
	s_barrier

; #define PG8_MMA(ai, bj, At, Bt) do { __builtin_amdgcn_s_setprio(1); _Pragma("unroll") for (int m = 0; m < 4; ++m) _Pragma("unroll") for (int n = 0; n < 2; ++n) _Pragma("unroll") for (int k = 0; k < 2; ++k) \
;         acc[ai][bj][m][n] = __builtin_amdgcn_mfma_f32_16x16x32_bf16(Bt[n][k], At[m][k], acc[ai][bj][m][n], 0, 0, 0); __builtin_amdgcn_s_setprio(0); } while (0)
; #define PG8_WAIT_V(n) asm volatile("s_waitcnt vmcnt(" #n ")" ::: "memory")
; #define PG8_WAIT_L(n) asm volatile("s_waitcnt lgkmcnt(" #n ")" ::: "memory")
; #define PG8_BAR __builtin_amdgcn_s_barrier()
; #define PG8_SCHED __builtin_amdgcn_sched_barrier(0)
; template <class Epi, class Sched, bool ALIGN_EPI = false, bool SP2 = false>
; __device__ __forceinline__ void gemm_phase(PG8_LAS unsigned char* lds, const Gemm g, const Sched& S, const Epi& E) {
;     ...
;             PG8_WAIT_V(8); PG8_WAIT_L(0); PG8_BAR; PG8_MMA(0, 0, At, B0); PG8_MMA(0, 1, At, B1); PG8_BAR; PG8_SCHED;
	v_mfma_f32_16x16x32_bf16 v[140:143], v[96:99], v[176:179], v[140:143]
	v_mfma_f32_16x16x32_bf16 v[136:139], v[104:107], v[176:179], v[136:139]
	v_mfma_f32_16x16x32_bf16 v[124:127], v[96:99], v[184:187], v[124:127]
	v_mfma_f32_16x16x32_bf16 v[120:123], v[104:107], v[184:187], v[120:123]
	v_mfma_f32_16x16x32_bf16 v[92:95], v[96:99], v[202:205], v[92:95]
	v_mfma_f32_16x16x32_bf16 v[88:91], v[104:107], v[202:205], v[88:91]
	v_mfma_f32_16x16x32_bf16 v[76:79], v[96:99], v[210:213], v[76:79]
	v_mfma_f32_16x16x32_bf16 v[72:75], v[104:107], v[210:213], v[72:75]
	v_mfma_f32_16x16x32_bf16 v[140:143], v[100:103], v[180:183], v[140:143]
	v_mfma_f32_16x16x32_bf16 v[136:139], v[112:115], v[180:183], v[136:139]
	v_mfma_f32_16x16x32_bf16 v[124:127], v[100:103], v[188:191], v[124:127]
	v_mfma_f32_16x16x32_bf16 v[120:123], v[112:115], v[188:191], v[120:123]
	v_mfma_f32_16x16x32_bf16 v[92:95], v[100:103], v[206:209], v[92:95]
	v_mfma_f32_16x16x32_bf16 v[88:91], v[112:115], v[206:209], v[88:91]
	v_mfma_f32_16x16x32_bf16 v[76:79], v[100:103], v[214:217], v[76:79]
	v_mfma_f32_16x16x32_bf16 v[72:75], v[112:115], v[214:217], v[72:75]


; #define PG8_STAGE(bufoff, gbase, voff) do { _Pragma("unroll") for (int _i = 0; _i < 2; ++_i) \
;         __builtin_amdgcn_global_load_lds((const unsigned*)((const char*)(gbase) + (voff)[_i]), (PG8_LAS unsigned*)(lds + (bufoff) + ldsw + _i * 8192), 16, 0, 0); } while (0)
; #define PG8_LDA(dst, b, h) do { _Pragma("unroll") for (int m = 0; m < 4; ++m) _Pragma("unroll") for (int k = 0; k < 2; ++k) dst[m][k] = *(const PG8_LAS bf16x8*)(lds + PG8_SA(b, h) + aoff + m * 2048 + k * 1024); } while (0)
; #define PG8_MMA(ai, bj, At, Bt) do { __builtin_amdgcn_s_setprio(1); _Pragma("unroll") for (int m = 0; m < 4; ++m) _Pragma("unroll") for (int n = 0; n < 2; ++n) _Pragma("unroll") for (int k = 0; k < 2; ++k) \
;         acc[ai][bj][m][n] = __builtin_amdgcn_mfma_f32_16x16x32_bf16(Bt[n][k], At[m][k], acc[ai][bj][m][n], 0, 0, 0); __builtin_amdgcn_s_setprio(0); } while (0)
; #define PG8_WAIT_V(n) asm volatile("s_waitcnt vmcnt(" #n ")" ::: "memory")
; #define PG8_WAIT_L(n) asm volatile("s_waitcnt lgkmcnt(" #n ")" ::: "memory")
; #define PG8_BAR __builtin_amdgcn_s_barrier()
; #define PG8_SCHED __builtin_amdgcn_sched_barrier(0)
; template <class Epi, class Sched, bool ALIGN_EPI = false, bool SP2 = false>
; __device__ __forceinline__ void gemm_phase(PG8_LAS unsigned char* lds, const Gemm g, const Sched& S, const Epi& E) {
;     ...
;             PG8_WAIT_V(8); PG8_WAIT_L(0); PG8_BAR; PG8_MMA(0, 0, At, B0); PG8_MMA(0, 1, At, B1); PG8_BAR; PG8_SCHED;
;             PG8_LDA(At, 1, 1); PG8_STAGE(PG8_SB(1, 0), b3, voffB); PG8_STAGE(PG8_SB(1, 1), b3 + hstep, voffB); PG8_STAGE(PG8_SA(1, 0), a3, voffA);
	v_mfma_f32_16x16x32_bf16 v[132:135], v[144:147], v[176:179], v[132:135]
	v_mfma_f32_16x16x32_bf16 v[128:131], v[152:155], v[176:179], v[128:131]
	v_mfma_f32_16x16x32_bf16 v[116:119], v[144:147], v[184:187], v[116:119]
	v_mfma_f32_16x16x32_bf16 v[108:111], v[152:155], v[184:187], v[108:111]
	v_mfma_f32_16x16x32_bf16 v[84:87], v[144:147], v[202:205], v[84:87]
	v_mfma_f32_16x16x32_bf16 v[80:83], v[152:155], v[202:205], v[80:83]
	v_mfma_f32_16x16x32_bf16 v[68:71], v[144:147], v[210:213], v[68:71]
	v_mfma_f32_16x16x32_bf16 v[64:67], v[152:155], v[210:213], v[64:67]
	v_mfma_f32_16x16x32_bf16 v[132:135], v[148:151], v[180:183], v[132:135]
	v_mfma_f32_16x16x32_bf16 v[128:131], v[172:175], v[180:183], v[128:131]
	v_mfma_f32_16x16x32_bf16 v[116:119], v[148:151], v[188:191], v[116:119]
	v_mfma_f32_16x16x32_bf16 v[108:111], v[172:175], v[188:191], v[108:111]
	v_mfma_f32_16x16x32_bf16 v[84:87], v[148:151], v[206:209], v[84:87]
	v_mfma_f32_16x16x32_bf16 v[80:83], v[172:175], v[206:209], v[80:83]
	v_mfma_f32_16x16x32_bf16 v[68:71], v[148:151], v[214:217], v[68:71]
	v_mfma_f32_16x16x32_bf16 v[64:67], v[172:175], v[214:217], v[64:67]
	s_setprio 0
	s_barrier
	s_add_i32 s52, s74, s55

; #define PG8_STAGE(bufoff, gbase, voff) do { _Pragma("unroll") for (int _i = 0; _i < 2; ++_i) \
;         __builtin_amdgcn_global_load_lds((const unsigned*)((const char*)(gbase) + (voff)[_i]), (PG8_LAS unsigned*)(lds + (bufoff) + ldsw + _i * 8192), 16, 0, 0); } while (0)
; #define PG8_LDA(dst, b, h) do { _Pragma("unroll") for (int m = 0; m < 4; ++m) _Pragma("unroll") for (int k = 0; k < 2; ++k) dst[m][k] = *(const PG8_LAS bf16x8*)(lds + PG8_SA(b, h) + aoff + m * 2048 + k * 1024); } while (0)
; template <class Epi, class Sched, bool ALIGN_EPI = false, bool SP2 = false>
; __device__ __forceinline__ void gemm_phase(PG8_LAS unsigned char* lds, const Gemm g, const Sched& S, const Epi& E) {
;     ...
;             PG8_LDA(At, 1, 1); PG8_STAGE(PG8_SB(1, 0), b3, voffB); PG8_STAGE(PG8_SB(1, 1), b3 + hstep, voffB); PG8_STAGE(PG8_SA(1, 0), a3, voffA);
	s_mov_b32 m0, s52
	ds_read_b128 v[176:179], v199 offset:49152
	ds_read_b128 v[180:183], v199 offset:50176
	ds_read_b128 v[184:187], v199 offset:51200
	ds_read_b128 v[188:191], v199 offset:52224
	ds_read_b128 v[202:205], v199 offset:53248
	ds_read_b128 v[206:209], v199 offset:54272
	ds_read_b128 v[210:213], v199 offset:55296
	ds_read_b128 v[214:217], v199 offset:56320
	global_load_lds_dwordx4 v250, s[96:97]
	s_add_i32 m0, s52, 0x2000
	s_add_u32 s50, s50, 0x200080

; #define PG8_STAGE(bufoff, gbase, voff) do { _Pragma("unroll") for (int _i = 0; _i < 2; ++_i) \
;         __builtin_amdgcn_global_load_lds((const unsigned*)((const char*)(gbase) + (voff)[_i]), (PG8_LAS unsigned*)(lds + (bufoff) + ldsw + _i * 8192), 16, 0, 0); } while (0)
; #define PG8_LDA(dst, b, h) do { _Pragma("unroll") for (int m = 0; m < 4; ++m) _Pragma("unroll") for (int k = 0; k < 2; ++k) dst[m][k] = *(const PG8_LAS bf16x8*)(lds + PG8_SA(b, h) + aoff + m * 2048 + k * 1024); } while (0)
; template <class Epi, class Sched, bool ALIGN_EPI = false, bool SP2 = false>
; __device__ __forceinline__ void gemm_phase(PG8_LAS unsigned char* lds, const Gemm g, const Sched& S, const Epi& E) {
;     ...
;             PG8_LDA(At, 1, 1); PG8_STAGE(PG8_SB(1, 0), b3, voffB); PG8_STAGE(PG8_SB(1, 1), b3 + hstep, voffB); PG8_STAGE(PG8_SA(1, 0), a3, voffA);
	s_addc_u32 s51, s51, 0
	s_add_i32 s52, s75, s55
	global_load_lds_dwordx4 v251, s[96:97]

; #define PG8_STAGE(bufoff, gbase, voff) do { _Pragma("unroll") for (int _i = 0; _i < 2; ++_i) \
;         __builtin_amdgcn_global_load_lds((const unsigned*)((const char*)(gbase) + (voff)[_i]), (PG8_LAS unsigned*)(lds + (bufoff) + ldsw + _i * 8192), 16, 0, 0); } while (0)
; #define PG8_LDA(dst, b, h) do { _Pragma("unroll") for (int m = 0; m < 4; ++m) _Pragma("unroll") for (int k = 0; k < 2; ++k) dst[m][k] = *(const PG8_LAS bf16x8*)(lds + PG8_SA(b, h) + aoff + m * 2048 + k * 1024); } while (0)
; template <class Epi, class Sched, bool ALIGN_EPI = false, bool SP2 = false>
; __device__ __forceinline__ void gemm_phase(PG8_LAS unsigned char* lds, const Gemm g, const Sched& S, const Epi& E) {
;     ...
;             PG8_LDA(At, 1, 1); PG8_STAGE(PG8_SB(1, 0), b3, voffB); PG8_STAGE(PG8_SB(1, 1), b3 + hstep, voffB); PG8_STAGE(PG8_SA(1, 0), a3, voffA);
	s_mov_b32 m0, s52
	s_nop 0
	global_load_lds_dwordx4 v158, s[50:51]

; #define PG8_STAGE(bufoff, gbase, voff) do { _Pragma("unroll") for (int _i = 0; _i < 2; ++_i) \
;         __builtin_amdgcn_global_load_lds((const unsigned*)((const char*)(gbase) + (voff)[_i]), (PG8_LAS unsigned*)(lds + (bufoff) + ldsw + _i * 8192), 16, 0, 0); } while (0)
; #define PG8_LDA(dst, b, h) do { _Pragma("unroll") for (int m = 0; m < 4; ++m) _Pragma("unroll") for (int k = 0; k < 2; ++k) dst[m][k] = *(const PG8_LAS bf16x8*)(lds + PG8_SA(b, h) + aoff + m * 2048 + k * 1024); } while (0)
; template <class Epi, class Sched, bool ALIGN_EPI = false, bool SP2 = false>
; __device__ __forceinline__ void gemm_phase(PG8_LAS unsigned char* lds, const Gemm g, const Sched& S, const Epi& E) {
;     ...
;             PG8_LDA(At, 1, 1); PG8_STAGE(PG8_SB(1, 0), b3, voffB); PG8_STAGE(PG8_SB(1, 1), b3 + hstep, voffB); PG8_STAGE(PG8_SA(1, 0), a3, voffA);
	s_add_i32 m0, s52, 0x2000
	s_nop 0
	global_load_lds_dwordx4 v162, s[50:51]

; #define PG8_STAGE(bufoff, gbase, voff) do { _Pragma("unroll") for (int _i = 0; _i < 2; ++_i) \
;         __builtin_amdgcn_global_load_lds((const unsigned*)((const char*)(gbase) + (voff)[_i]), (PG8_LAS unsigned*)(lds + (bufoff) + ldsw + _i * 8192), 16, 0, 0); } while (0)
; #define PG8_LDA(dst, b, h) do { _Pragma("unroll") for (int m = 0; m < 4; ++m) _Pragma("unroll") for (int k = 0; k < 2; ++k) dst[m][k] = *(const PG8_LAS bf16x8*)(lds + PG8_SA(b, h) + aoff + m * 2048 + k * 1024); } while (0)
; template <class Epi, class Sched, bool ALIGN_EPI = false, bool SP2 = false>
; __device__ __forceinline__ void gemm_phase(PG8_LAS unsigned char* lds, const Gemm g, const Sched& S, const Epi& E) {
;     ...
;             PG8_LDA(At, 1, 1); PG8_STAGE(PG8_SB(1, 0), b3, voffB); PG8_STAGE(PG8_SB(1, 1), b3 + hstep, voffB); PG8_STAGE(PG8_SA(1, 0), a3, voffA);
	s_mov_b32 m0, s61
	s_nop 0
	global_load_lds_dwordx4 v252, s[98:99]

; #define PG8_STAGE(bufoff, gbase, voff) do { _Pragma("unroll") for (int _i = 0; _i < 2; ++_i) \
;         __builtin_amdgcn_global_load_lds((const unsigned*)((const char*)(gbase) + (voff)[_i]), (PG8_LAS unsigned*)(lds + (bufoff) + ldsw + _i * 8192), 16, 0, 0); } while (0)
; #define PG8_LDA(dst, b, h) do { _Pragma("unroll") for (int m = 0; m < 4; ++m) _Pragma("unroll") for (int k = 0; k < 2; ++k) dst[m][k] = *(const PG8_LAS bf16x8*)(lds + PG8_SA(b, h) + aoff + m * 2048 + k * 1024); } while (0)
; #define PG8_MMA(ai, bj, At, Bt) do { __builtin_amdgcn_s_setprio(1); _Pragma("unroll") for (int m = 0; m < 4; ++m) _Pragma("unroll") for (int n = 0; n < 2; ++n) _Pragma("unroll") for (int k = 0; k < 2; ++k) \
;         acc[ai][bj][m][n] = __builtin_amdgcn_mfma_f32_16x16x32_bf16(Bt[n][k], At[m][k], acc[ai][bj][m][n], 0, 0, 0); __builtin_amdgcn_s_setprio(0); } while (0)
; #define PG8_WAIT_V(n) asm volatile("s_waitcnt vmcnt(" #n ")" ::: "memory")
; #define PG8_WAIT_L(n) asm volatile("s_waitcnt lgkmcnt(" #n ")" ::: "memory")
; #define PG8_BAR __builtin_amdgcn_s_barrier()
; #define PG8_SCHED __builtin_amdgcn_sched_barrier(0)
; template <class Epi, class Sched, bool ALIGN_EPI = false, bool SP2 = false>
; __device__ __forceinline__ void gemm_phase(PG8_LAS unsigned char* lds, const Gemm g, const Sched& S, const Epi& E) {
;     ...
;             PG8_LDA(At, 1, 1); PG8_STAGE(PG8_SB(1, 0), b3, voffB); PG8_STAGE(PG8_SB(1, 1), b3 + hstep, voffB); PG8_STAGE(PG8_SA(1, 0), a3, voffA);
;             PG8_WAIT_V(8); PG8_WAIT_L(0); PG8_BAR; PG8_MMA(1, 0, At, B0); PG8_MMA(1, 1, At, B1); PG8_BAR; PG8_SCHED;
	s_mov_b32 m0, s62
	s_nop 0
	global_load_lds_dwordx4 v253, s[98:99]
	s_waitcnt vmcnt(8)
	s_waitcnt lgkmcnt(0)
	s_setprio 1
	s_barrier

; #define PG8_MMA(ai, bj, At, Bt) do { __builtin_amdgcn_s_setprio(1); _Pragma("unroll") for (int m = 0; m < 4; ++m) _Pragma("unroll") for (int n = 0; n < 2; ++n) _Pragma("unroll") for (int k = 0; k < 2; ++k) \
;         acc[ai][bj][m][n] = __builtin_amdgcn_mfma_f32_16x16x32_bf16(Bt[n][k], At[m][k], acc[ai][bj][m][n], 0, 0, 0); __builtin_amdgcn_s_setprio(0); } while (0)
; #define PG8_WAIT_V(n) asm volatile("s_waitcnt vmcnt(" #n ")" ::: "memory")
; #define PG8_WAIT_L(n) asm volatile("s_waitcnt lgkmcnt(" #n ")" ::: "memory")
; #define PG8_BAR __builtin_amdgcn_s_barrier()
; #define PG8_SCHED __builtin_amdgcn_sched_barrier(0)
; template <class Epi, class Sched, bool ALIGN_EPI = false, bool SP2 = false>
; __device__ __forceinline__ void gemm_phase(PG8_LAS unsigned char* lds, const Gemm g, const Sched& S, const Epi& E) {
;     ...
;             PG8_WAIT_V(8); PG8_WAIT_L(0); PG8_BAR; PG8_MMA(1, 0, At, B0); PG8_MMA(1, 1, At, B1); PG8_BAR; PG8_SCHED;
	v_mfma_f32_16x16x32_bf16 v[60:63], v[96:99], v[176:179], v[60:63]
	v_mfma_f32_16x16x32_bf16 v[56:59], v[104:107], v[176:179], v[56:59]
	v_mfma_f32_16x16x32_bf16 v[44:47], v[96:99], v[184:187], v[44:47]
	v_mfma_f32_16x16x32_bf16 v[40:43], v[104:107], v[184:187], v[40:43]
	v_mfma_f32_16x16x32_bf16 v[28:31], v[96:99], v[202:205], v[28:31]
	v_mfma_f32_16x16x32_bf16 v[24:27], v[104:107], v[202:205], v[24:27]
	v_mfma_f32_16x16x32_bf16 v[12:15], v[96:99], v[210:213], v[12:15]
	v_mfma_f32_16x16x32_bf16 v[8:11], v[104:107], v[210:213], v[8:11]
	v_mfma_f32_16x16x32_bf16 v[60:63], v[100:103], v[180:183], v[60:63]
	v_mfma_f32_16x16x32_bf16 v[56:59], v[112:115], v[180:183], v[56:59]
	v_mfma_f32_16x16x32_bf16 v[44:47], v[100:103], v[188:191], v[44:47]
	v_mfma_f32_16x16x32_bf16 v[40:43], v[112:115], v[188:191], v[40:43]
	v_mfma_f32_16x16x32_bf16 v[28:31], v[100:103], v[206:209], v[28:31]
	v_mfma_f32_16x16x32_bf16 v[24:27], v[112:115], v[206:209], v[24:27]
	v_mfma_f32_16x16x32_bf16 v[12:15], v[100:103], v[214:217], v[12:15]
	v_mfma_f32_16x16x32_bf16 v[8:11], v[112:115], v[214:217], v[8:11]


; #define PG8_STAGE(bufoff, gbase, voff) do { _Pragma("unroll") for (int _i = 0; _i < 2; ++_i) \
;         __builtin_amdgcn_global_load_lds((const unsigned*)((const char*)(gbase) + (voff)[_i]), (PG8_LAS unsigned*)(lds + (bufoff) + ldsw + _i * 8192), 16, 0, 0); } while (0)
; #define PG8_LDA(dst, b, h) do { _Pragma("unroll") for (int m = 0; m < 4; ++m) _Pragma("unroll") for (int k = 0; k < 2; ++k) dst[m][k] = *(const PG8_LAS bf16x8*)(lds + PG8_SA(b, h) + aoff + m * 2048 + k * 1024); } while (0)
; #define PG8_LDB(dst, b, h) do { _Pragma("unroll") for (int n = 0; n < 2; ++n) _Pragma("unroll") for (int k = 0; k < 2; ++k) dst[n][k] = *(const PG8_LAS bf16x8*)(lds + PG8_SB(b, h) + boff + n * 2048 + k * 1024); } while (0)
; template <class Epi, class Sched, bool ALIGN_EPI = false, bool SP2 = false>
; __device__ __forceinline__ void gemm_phase(PG8_LAS unsigned char* lds, const Gemm g, const Sched& S, const Epi& E) {
;     ...
;             PG8_WAIT_V(8); PG8_WAIT_L(0); PG8_BAR; PG8_MMA(1, 0, At, B0); PG8_MMA(1, 1, At, B1); PG8_BAR; PG8_SCHED;
;             } else {
;             PG8_LDB(B0, 0, 0); PG8_SCHED; PG8_LDA(At, 0, 0); PG8_STAGE(PG8_SA(1, 1), a1 + hstep, voffA);
;             PG8_WAIT_L(8); PG8_BAR; PG8_WAIT_L(0); PG8_MMA(0, 0, At, B0); PG8_BAR; PG8_SCHED;
;             PG8_LDB(B1, 0, 1); PG8_STAGE(PG8_SB(0, 0), b2, voffB);
;             PG8_BAR; PG8_WAIT_L(0); PG8_MMA(0, 1, At, B1); PG8_BAR;
;             PG8_LDA(At, 0, 1); PG8_STAGE(PG8_SA(0, 0), a2, voffA);
;             PG8_BAR; PG8_WAIT_L(0); PG8_MMA(1, 0, At, B0); PG8_BAR; PG8_SCHED;
;             PG8_STAGE(PG8_SB(0, 1), b2 + hstep, voffB);
;             PG8_WAIT_V(6); PG8_BAR; PG8_MMA(1, 1, At, B1); PG8_BAR;
;             PG8_LDB(B0, 1, 0); PG8_SCHED; PG8_LDA(At, 1, 0); PG8_STAGE(PG8_SA(0, 1), a2 + hstep, voffA);
;             PG8_WAIT_L(8); PG8_BAR; PG8_WAIT_L(0); PG8_MMA(0, 0, At, B0); PG8_BAR; PG8_SCHED;
;             PG8_LDB(B1, 1, 1); PG8_STAGE(PG8_SB(1, 0), b3, voffB);
;             PG8_BAR; PG8_WAIT_L(0); PG8_MMA(0, 1, At, B1); PG8_BAR;
;             PG8_LDA(At, 1, 1); PG8_STAGE(PG8_SA(1, 0), a3, voffA);
;             PG8_BAR; PG8_WAIT_L(0); PG8_MMA(1, 0, At, B0); PG8_BAR; PG8_SCHED;
;             PG8_STAGE(PG8_SB(1, 1), b3 + hstep, voffB);
;             PG8_WAIT_V(6); PG8_BAR; PG8_MMA(1, 1, At, B1); PG8_BAR;
;             }
;         }
;         if constexpr (ALIGN_EPI) { if (wr == 0) PG8_BAR; }
	v_mfma_f32_16x16x32_bf16 v[52:55], v[144:147], v[176:179], v[52:55]
	v_mfma_f32_16x16x32_bf16 v[48:51], v[152:155], v[176:179], v[48:51]
	v_mfma_f32_16x16x32_bf16 v[36:39], v[144:147], v[184:187], v[36:39]
	v_mfma_f32_16x16x32_bf16 v[32:35], v[152:155], v[184:187], v[32:35]
	v_mfma_f32_16x16x32_bf16 v[20:23], v[144:147], v[202:205], v[20:23]
	v_mfma_f32_16x16x32_bf16 v[16:19], v[152:155], v[202:205], v[16:19]
	v_mfma_f32_16x16x32_bf16 v[4:7], v[144:147], v[210:213], v[4:7]
	v_mfma_f32_16x16x32_bf16 v[0:3], v[152:155], v[210:213], v[0:3]
	v_mfma_f32_16x16x32_bf16 v[52:55], v[148:151], v[180:183], v[52:55]
	v_mfma_f32_16x16x32_bf16 v[48:51], v[172:175], v[180:183], v[48:51]
	v_mfma_f32_16x16x32_bf16 v[36:39], v[148:151], v[188:191], v[36:39]
	v_mfma_f32_16x16x32_bf16 v[32:35], v[172:175], v[188:191], v[32:35]
	v_mfma_f32_16x16x32_bf16 v[20:23], v[148:151], v[206:209], v[20:23]
	v_mfma_f32_16x16x32_bf16 v[16:19], v[172:175], v[206:209], v[16:19]
	v_mfma_f32_16x16x32_bf16 v[4:7], v[148:151], v[214:217], v[4:7]
	v_mfma_f32_16x16x32_bf16 v[0:3], v[172:175], v[214:217], v[0:3]
	s_setprio 0
	s_barrier
	s_add_i32 s73, s73, 2
	s_add_u32 s48, s48, 0x100
	s_addc_u32 s49, s49, 0
	s_add_u32 s71, s71, 0x100
	s_addc_u32 s72, s72, 0
	s_cmpk_gt_u32 s73, 0x7d
	s_cbranch_scc0 .LBB0_1114
	s_and_b64 vcc, exec, s[34:35]
	s_cbranch_vccz .LBB0_1117
	s_barrier
